# adds P2 epilogue scale-load hoist and P8 pooling row loops waiting on the exact 2-rows-ahead load count
# speedup vs baseline: 1.0036x; 1.0036x over previous
; __device__ __forceinline__ unsigned cvt_pk_bf16(float lo, float hi) { unsigned r; asm volatile("v_cvt_pk_bf16_f32 %0, %1, %2" : "=v"(r) : "v"(lo), "v"(hi)); return r; }
; __device__ __forceinline__ float silu_f(float x) { return x * fast_sigmoid(x); }
;     __device__ __forceinline__ void operator()(const f32x4 (&acc)[2][2][4][2], const Unit& u, int wr, int wc, int fr, int fq) const {
;     ...
;             for (int m = 0; m < 4; ++m) { const int row = row0 + ai * HALF + m * 16;
;                 bf16* rowp = g_ ? base + ((size_t)((row >> 13) * NG + (col0 >> 4)) * SEQ + (row & (SEQ - 1))) * 16 + (col0 & 15) : base + (size_t)row * EI + col0;
;                 const int bjs = g_ ? 8 * SEQ * 16 : HALF;
;                 float dq = 1.0f; if (Q8) dq = rowscale[(size_t)row * 32] * (qr[0] * (1.0f / ::Q8));
; #pragma unroll
;                 for (int bj = 0; bj < 2; ++bj) { f32x4 v0 = acc[ai][bj][m][0], v1 = acc[ai][bj][m][1];
;                     if (Q8) { const i32x4 q0 = __builtin_bit_cast(i32x4, v0), q1 = __builtin_bit_cast(i32x4, v1);
;                         v0 = (f32x4){(float)q0[0], (float)q0[1], (float)q0[2], (float)q0[3]} * dq; v1 = (f32x4){(float)q1[0], (float)q1[1], (float)q1[2], (float)q1[3]} * dq; }
;                     if (isz) {
; #pragma unroll
;                         for (int j = 0; j < 4; ++j) { v0[j] = silu_f(v0[j]); v1[j] = silu_f(v1[j]); } }
;                     u32x4 w; w.x = cvt_pk_bf16(v0[0], v0[1]); w.y = cvt_pk_bf16(v0[2], v0[3]); w.z = cvt_pk_bf16(v1[0], v1[1]); w.w = cvt_pk_bf16(v1[2], v1[3]);
.LBB0_233:
	v_add_u32_e32 v160, 32, v128
	v_add_u32_e32 v162, 0xa0, v128
	v_ashrrev_i32_e32 v161, 31, v160
	v_ashrrev_i32_e32 v163, 31, v162
	v_lshlrev_b64 v[160:161], 7, v[160:161]
	v_lshlrev_b64 v[162:163], 7, v[162:163]
	v_lshl_add_u64 v[160:161], s[8:9], 0, v[160:161]
	v_lshl_add_u64 v[162:163], s[8:9], 0, v[162:163]
	global_load_dword v150, v201, s[10:11]
	global_load_dword v151, v[160:161], off offset:-4096
	global_load_dword v152, v[160:161], off offset:-2048
	global_load_dword v153, v[160:161], off
	global_load_dword v154, v[160:161], off offset:2048
	global_load_dword v155, v[162:163], off offset:-4096
	global_load_dword v156, v[162:163], off offset:-2048
	global_load_dword v157, v[162:163], off
	global_load_dword v158, v[162:163], off offset:2048
	v_cvt_f32_i32_e32 v125, v125
	v_cvt_f32_i32_e32 v124, v124
	v_cvt_f32_i32_e32 v127, v127
	v_cvt_f32_i32_e32 v126, v126
	v_cvt_f32_i32_e32 v143, v121
	v_cvt_f32_i32_e32 v142, v120
	v_cvt_f32_i32_e32 v123, v123
	v_cvt_f32_i32_e32 v122, v122
	v_cndmask_b32_e64 v120, 0, 1, s[56:57]
	v_cmp_ne_u32_e64 s[0:1], 1, v120
	s_andn2_b64 vcc, exec, s[56:57]
	s_waitcnt vmcnt(0)
	v_mul_f32_e32 v120, 0x3c000100, v150
	v_mul_f32_e32 v120, v151, v120
	v_pk_mul_f32 v[126:127], v[120:121], v[126:127] op_sel_hi:[0,1]
	v_pk_mul_f32 v[138:139], v[120:121], v[124:125] op_sel_hi:[0,1]
	v_pk_mul_f32 v[122:123], v[120:121], v[122:123] op_sel_hi:[0,1]
	v_pk_mul_f32 v[124:125], v[120:121], v[142:143] op_sel_hi:[0,1]
	s_cbranch_vccnz .LBB0_235
	v_mul_f32_e32 v121, 0xbfb8aa3b, v138
	v_exp_f32_e32 v121, v121
	v_mul_f32_e32 v129, 0xbfb8aa3b, v124
	v_mul_f32_e32 v141, 0xbfb8aa3b, v139
	v_exp_f32_e32 v129, v129
	v_exp_f32_e32 v141, v141
	v_add_f32_e32 v121, 1.0, v121
	v_rcp_f32_e32 v142, v121
	v_add_f32_e32 v121, 1.0, v129
	v_mul_f32_e32 v129, 0xbfb8aa3b, v126
	v_rcp_f32_e32 v144, v121
	v_add_f32_e32 v121, 1.0, v141
	v_exp_f32_e32 v129, v129
	v_mul_f32_e32 v141, 0xbfb8aa3b, v122
	v_exp_f32_e32 v141, v141
	v_rcp_f32_e32 v143, v121
	v_add_f32_e32 v129, 1.0, v129
	v_rcp_f32_e32 v146, v129
	v_add_f32_e32 v129, 1.0, v141
	v_mul_f32_e32 v141, 0xbfb8aa3b, v127
	v_mul_f32_e32 v121, 0xbfb8aa3b, v125
	v_exp_f32_e32 v141, v141
	v_mul_f32_e32 v145, 0xbfb8aa3b, v123
	v_exp_f32_e32 v121, v121
	v_exp_f32_e32 v145, v145
	v_rcp_f32_e32 v148, v129
	v_add_f32_e32 v129, 1.0, v141
	v_add_f32_e32 v121, 1.0, v121
	v_rcp_f32_e32 v147, v129
	v_add_f32_e32 v129, 1.0, v145
	v_rcp_f32_e32 v149, v129
	v_rcp_f32_e32 v145, v121
	v_pk_mul_f32 v[126:127], v[126:127], v[146:147]
	v_pk_mul_f32 v[138:139], v[138:139], v[142:143]
	v_pk_mul_f32 v[122:123], v[122:123], v[148:149]
	v_pk_mul_f32 v[124:125], v[124:125], v[144:145]

; __device__ __forceinline__ unsigned cvt_pk_bf16(float lo, float hi) { unsigned r; asm volatile("v_cvt_pk_bf16_f32 %0, %1, %2" : "=v"(r) : "v"(lo), "v"(hi)); return r; }
; __device__ __forceinline__ float silu_f(float x) { return x * fast_sigmoid(x); }
;     __device__ __forceinline__ void operator()(const f32x4 (&acc)[2][2][4][2], const Unit& u, int wr, int wc, int fr, int fq) const {
;     ...
;             for (int m = 0; m < 4; ++m) { const int row = row0 + ai * HALF + m * 16;
;                 bf16* rowp = g_ ? base + ((size_t)((row >> 13) * NG + (col0 >> 4)) * SEQ + (row & (SEQ - 1))) * 16 + (col0 & 15) : base + (size_t)row * EI + col0;
;                 const int bjs = g_ ? 8 * SEQ * 16 : HALF;
;                 float dq = 1.0f; if (Q8) dq = rowscale[(size_t)row * 32] * (qr[0] * (1.0f / ::Q8));
; #pragma unroll
;                 for (int bj = 0; bj < 2; ++bj) { f32x4 v0 = acc[ai][bj][m][0], v1 = acc[ai][bj][m][1];
;                     if (Q8) { const i32x4 q0 = __builtin_bit_cast(i32x4, v0), q1 = __builtin_bit_cast(i32x4, v1);
;                         v0 = (f32x4){(float)q0[0], (float)q0[1], (float)q0[2], (float)q0[3]} * dq; v1 = (f32x4){(float)q1[0], (float)q1[1], (float)q1[2], (float)q1[3]} * dq; }
;                     if (isz) {
; #pragma unroll
;                         for (int j = 0; j < 4; ++j) { v0[j] = silu_f(v0[j]); v1[j] = silu_f(v1[j]); } }
;                     u32x4 w; w.x = cvt_pk_bf16(v0[0], v0[1]); w.y = cvt_pk_bf16(v0[2], v0[3]); w.z = cvt_pk_bf16(v1[0], v1[1]); w.w = cvt_pk_bf16(v1[2], v1[3]);
.LBB0_241:
	v_cvt_f32_i32_e32 v109, v109
	v_cvt_f32_i32_e32 v108, v108
	v_cvt_f32_i32_e32 v111, v111
	v_cvt_f32_i32_e32 v110, v110
	v_cvt_f32_i32_e32 v117, v105
	v_cvt_f32_i32_e32 v116, v104
	v_cvt_f32_i32_e32 v107, v107
	v_cvt_f32_i32_e32 v106, v106
	s_and_b64 vcc, exec, s[0:1]
	v_mul_f32_e32 v104, 0x3c000100, v150
	v_mul_f32_e32 v104, v152, v104
	v_pk_mul_f32 v[110:111], v[104:105], v[110:111] op_sel_hi:[0,1]
	v_pk_mul_f32 v[114:115], v[104:105], v[108:109] op_sel_hi:[0,1]
	v_pk_mul_f32 v[106:107], v[104:105], v[106:107] op_sel_hi:[0,1]
	v_pk_mul_f32 v[108:109], v[104:105], v[116:117] op_sel_hi:[0,1]
	s_cbranch_vccnz .LBB0_243
	v_mul_f32_e32 v105, 0xbfb8aa3b, v114
	v_exp_f32_e32 v105, v105
	v_mul_f32_e32 v116, 0xbfb8aa3b, v108
	v_mul_f32_e32 v119, 0xbfb8aa3b, v110
	v_mul_f32_e32 v117, 0xbfb8aa3b, v115
	v_exp_f32_e32 v118, v116
	v_exp_f32_e32 v119, v119
	v_mul_f32_e32 v120, 0xbfb8aa3b, v106
	v_exp_f32_e32 v117, v117
	v_exp_f32_e32 v121, v120
	v_add_f32_e32 v105, 1.0, v105
	v_rcp_f32_e32 v116, v105
	v_add_f32_e32 v105, 1.0, v118
	v_add_f32_e32 v119, 1.0, v119
	v_rcp_f32_e32 v118, v105
	v_add_f32_e32 v105, 1.0, v117
	v_rcp_f32_e32 v120, v119
	v_add_f32_e32 v119, 1.0, v121
	v_mul_f32_e32 v121, 0xbfb8aa3b, v111
	v_rcp_f32_e32 v117, v105
	v_mul_f32_e32 v105, 0xbfb8aa3b, v109
	v_exp_f32_e32 v121, v121
	v_mul_f32_e32 v122, 0xbfb8aa3b, v107
	v_exp_f32_e32 v105, v105
	v_exp_f32_e32 v123, v122
	v_rcp_f32_e32 v122, v119
	v_add_f32_e32 v119, 1.0, v121
	v_add_f32_e32 v105, 1.0, v105
	v_rcp_f32_e32 v121, v119
	v_add_f32_e32 v119, 1.0, v123
	v_rcp_f32_e32 v123, v119
	v_rcp_f32_e32 v119, v105
	v_pk_mul_f32 v[110:111], v[110:111], v[120:121]
	v_pk_mul_f32 v[114:115], v[114:115], v[116:117]
	v_pk_mul_f32 v[106:107], v[106:107], v[122:123]
	v_pk_mul_f32 v[108:109], v[108:109], v[118:119]

; __device__ __forceinline__ unsigned cvt_pk_bf16(float lo, float hi) { unsigned r; asm volatile("v_cvt_pk_bf16_f32 %0, %1, %2" : "=v"(r) : "v"(lo), "v"(hi)); return r; }
; __device__ __forceinline__ float silu_f(float x) { return x * fast_sigmoid(x); }
;     __device__ __forceinline__ void operator()(const f32x4 (&acc)[2][2][4][2], const Unit& u, int wr, int wc, int fr, int fq) const {
;     ...
;             for (int m = 0; m < 4; ++m) { const int row = row0 + ai * HALF + m * 16;
;                 bf16* rowp = g_ ? base + ((size_t)((row >> 13) * NG + (col0 >> 4)) * SEQ + (row & (SEQ - 1))) * 16 + (col0 & 15) : base + (size_t)row * EI + col0;
;                 const int bjs = g_ ? 8 * SEQ * 16 : HALF;
;                 float dq = 1.0f; if (Q8) dq = rowscale[(size_t)row * 32] * (qr[0] * (1.0f / ::Q8));
; #pragma unroll
;                 for (int bj = 0; bj < 2; ++bj) { f32x4 v0 = acc[ai][bj][m][0], v1 = acc[ai][bj][m][1];
;                     if (Q8) { const i32x4 q0 = __builtin_bit_cast(i32x4, v0), q1 = __builtin_bit_cast(i32x4, v1);
;                         v0 = (f32x4){(float)q0[0], (float)q0[1], (float)q0[2], (float)q0[3]} * dq; v1 = (f32x4){(float)q1[0], (float)q1[1], (float)q1[2], (float)q1[3]} * dq; }
;                     if (isz) {
; #pragma unroll
;                         for (int j = 0; j < 4; ++j) { v0[j] = silu_f(v0[j]); v1[j] = silu_f(v1[j]); } }
;                     u32x4 w; w.x = cvt_pk_bf16(v0[0], v0[1]); w.y = cvt_pk_bf16(v0[2], v0[3]); w.z = cvt_pk_bf16(v1[0], v1[1]); w.w = cvt_pk_bf16(v1[2], v1[3]);
.LBB0_249:
	v_cvt_f32_i32_e32 v93, v93
	v_cvt_f32_i32_e32 v92, v92
	v_cvt_f32_i32_e32 v95, v95
	v_cvt_f32_i32_e32 v94, v94
	v_cvt_f32_i32_e32 v101, v89
	v_cvt_f32_i32_e32 v100, v88
	v_cvt_f32_i32_e32 v91, v91
	v_cvt_f32_i32_e32 v90, v90
	s_and_b64 vcc, exec, s[0:1]
	v_mul_f32_e32 v88, 0x3c000100, v150
	v_mul_f32_e32 v88, v153, v88
	v_pk_mul_f32 v[94:95], v[88:89], v[94:95] op_sel_hi:[0,1]
	v_pk_mul_f32 v[98:99], v[88:89], v[92:93] op_sel_hi:[0,1]
	v_pk_mul_f32 v[90:91], v[88:89], v[90:91] op_sel_hi:[0,1]
	v_pk_mul_f32 v[92:93], v[88:89], v[100:101] op_sel_hi:[0,1]
	s_cbranch_vccnz .LBB0_251
	v_mul_f32_e32 v89, 0xbfb8aa3b, v98
	v_exp_f32_e32 v89, v89
	v_mul_f32_e32 v100, 0xbfb8aa3b, v92
	v_mul_f32_e32 v103, 0xbfb8aa3b, v94
	v_mul_f32_e32 v101, 0xbfb8aa3b, v99
	v_exp_f32_e32 v102, v100
	v_exp_f32_e32 v103, v103
	v_mul_f32_e32 v104, 0xbfb8aa3b, v90
	v_exp_f32_e32 v101, v101
	v_exp_f32_e32 v105, v104
	v_add_f32_e32 v89, 1.0, v89
	v_rcp_f32_e32 v100, v89
	v_add_f32_e32 v89, 1.0, v102
	v_add_f32_e32 v103, 1.0, v103
	v_rcp_f32_e32 v102, v89
	v_add_f32_e32 v89, 1.0, v101
	v_rcp_f32_e32 v104, v103
	v_add_f32_e32 v103, 1.0, v105
	v_mul_f32_e32 v105, 0xbfb8aa3b, v95
	v_rcp_f32_e32 v101, v89
	v_mul_f32_e32 v89, 0xbfb8aa3b, v93
	v_exp_f32_e32 v105, v105
	v_mul_f32_e32 v106, 0xbfb8aa3b, v91
	v_exp_f32_e32 v89, v89
	v_exp_f32_e32 v107, v106
	v_rcp_f32_e32 v106, v103
	v_add_f32_e32 v103, 1.0, v105
	v_add_f32_e32 v89, 1.0, v89
	v_rcp_f32_e32 v105, v103
	v_add_f32_e32 v103, 1.0, v107
	v_rcp_f32_e32 v107, v103
	v_rcp_f32_e32 v103, v89
	v_pk_mul_f32 v[94:95], v[94:95], v[104:105]
	v_pk_mul_f32 v[98:99], v[98:99], v[100:101]
	v_pk_mul_f32 v[90:91], v[90:91], v[106:107]
	v_pk_mul_f32 v[92:93], v[92:93], v[102:103]

; __device__ __forceinline__ unsigned cvt_pk_bf16(float lo, float hi) { unsigned r; asm volatile("v_cvt_pk_bf16_f32 %0, %1, %2" : "=v"(r) : "v"(lo), "v"(hi)); return r; }
; __device__ __forceinline__ float silu_f(float x) { return x * fast_sigmoid(x); }
;     __device__ __forceinline__ void operator()(const f32x4 (&acc)[2][2][4][2], const Unit& u, int wr, int wc, int fr, int fq) const {
;     ...
;             for (int m = 0; m < 4; ++m) { const int row = row0 + ai * HALF + m * 16;
;                 bf16* rowp = g_ ? base + ((size_t)((row >> 13) * NG + (col0 >> 4)) * SEQ + (row & (SEQ - 1))) * 16 + (col0 & 15) : base + (size_t)row * EI + col0;
;                 const int bjs = g_ ? 8 * SEQ * 16 : HALF;
;                 float dq = 1.0f; if (Q8) dq = rowscale[(size_t)row * 32] * (qr[0] * (1.0f / ::Q8));
; #pragma unroll
;                 for (int bj = 0; bj < 2; ++bj) { f32x4 v0 = acc[ai][bj][m][0], v1 = acc[ai][bj][m][1];
;                     if (Q8) { const i32x4 q0 = __builtin_bit_cast(i32x4, v0), q1 = __builtin_bit_cast(i32x4, v1);
;                         v0 = (f32x4){(float)q0[0], (float)q0[1], (float)q0[2], (float)q0[3]} * dq; v1 = (f32x4){(float)q1[0], (float)q1[1], (float)q1[2], (float)q1[3]} * dq; }
;                     if (isz) {
; #pragma unroll
;                         for (int j = 0; j < 4; ++j) { v0[j] = silu_f(v0[j]); v1[j] = silu_f(v1[j]); } }
;                     u32x4 w; w.x = cvt_pk_bf16(v0[0], v0[1]); w.y = cvt_pk_bf16(v0[2], v0[3]); w.z = cvt_pk_bf16(v1[0], v1[1]); w.w = cvt_pk_bf16(v1[2], v1[3]);
.LBB0_257:
	v_cvt_f32_i32_e32 v77, v77
	v_cvt_f32_i32_e32 v76, v76
	v_cvt_f32_i32_e32 v79, v79
	v_cvt_f32_i32_e32 v78, v78
	v_cvt_f32_i32_e32 v85, v73
	v_cvt_f32_i32_e32 v84, v72
	v_cvt_f32_i32_e32 v75, v75
	v_cvt_f32_i32_e32 v74, v74
	s_and_b64 vcc, exec, s[0:1]
	v_mul_f32_e32 v72, 0x3c000100, v150
	v_mul_f32_e32 v72, v154, v72
	v_pk_mul_f32 v[78:79], v[72:73], v[78:79] op_sel_hi:[0,1]
	v_pk_mul_f32 v[82:83], v[72:73], v[76:77] op_sel_hi:[0,1]
	v_pk_mul_f32 v[74:75], v[72:73], v[74:75] op_sel_hi:[0,1]
	v_pk_mul_f32 v[76:77], v[72:73], v[84:85] op_sel_hi:[0,1]
	s_cbranch_vccnz .LBB0_259
	v_mul_f32_e32 v73, 0xbfb8aa3b, v82
	v_exp_f32_e32 v73, v73
	v_mul_f32_e32 v84, 0xbfb8aa3b, v76
	v_mul_f32_e32 v87, 0xbfb8aa3b, v78
	v_mul_f32_e32 v85, 0xbfb8aa3b, v83
	v_exp_f32_e32 v86, v84
	v_exp_f32_e32 v87, v87
	v_mul_f32_e32 v88, 0xbfb8aa3b, v74
	v_exp_f32_e32 v85, v85
	v_exp_f32_e32 v89, v88
	v_add_f32_e32 v73, 1.0, v73
	v_rcp_f32_e32 v84, v73
	v_add_f32_e32 v73, 1.0, v86
	v_add_f32_e32 v87, 1.0, v87
	v_rcp_f32_e32 v86, v73
	v_add_f32_e32 v73, 1.0, v85
	v_rcp_f32_e32 v88, v87
	v_add_f32_e32 v87, 1.0, v89
	v_mul_f32_e32 v89, 0xbfb8aa3b, v79
	v_rcp_f32_e32 v85, v73
	v_mul_f32_e32 v73, 0xbfb8aa3b, v77
	v_exp_f32_e32 v89, v89
	v_mul_f32_e32 v90, 0xbfb8aa3b, v75
	v_exp_f32_e32 v73, v73
	v_exp_f32_e32 v91, v90
	v_rcp_f32_e32 v90, v87
	v_add_f32_e32 v87, 1.0, v89
	v_add_f32_e32 v73, 1.0, v73
	v_rcp_f32_e32 v89, v87
	v_add_f32_e32 v87, 1.0, v91
	v_rcp_f32_e32 v91, v87
	v_rcp_f32_e32 v87, v73
	v_pk_mul_f32 v[78:79], v[78:79], v[88:89]
	v_pk_mul_f32 v[82:83], v[82:83], v[84:85]
	v_pk_mul_f32 v[74:75], v[74:75], v[90:91]
	v_pk_mul_f32 v[76:77], v[76:77], v[86:87]

; __device__ __forceinline__ unsigned cvt_pk_bf16(float lo, float hi) { unsigned r; asm volatile("v_cvt_pk_bf16_f32 %0, %1, %2" : "=v"(r) : "v"(lo), "v"(hi)); return r; }
; __device__ __forceinline__ float silu_f(float x) { return x * fast_sigmoid(x); }
;     __device__ __forceinline__ void operator()(const f32x4 (&acc)[2][2][4][2], const Unit& u, int wr, int wc, int fr, int fq) const {
;     ...
;             for (int m = 0; m < 4; ++m) { const int row = row0 + ai * HALF + m * 16;
;                 bf16* rowp = g_ ? base + ((size_t)((row >> 13) * NG + (col0 >> 4)) * SEQ + (row & (SEQ - 1))) * 16 + (col0 & 15) : base + (size_t)row * EI + col0;
;                 const int bjs = g_ ? 8 * SEQ * 16 : HALF;
;                 float dq = 1.0f; if (Q8) dq = rowscale[(size_t)row * 32] * (qr[0] * (1.0f / ::Q8));
; #pragma unroll
;                 for (int bj = 0; bj < 2; ++bj) { f32x4 v0 = acc[ai][bj][m][0], v1 = acc[ai][bj][m][1];
;                     if (Q8) { const i32x4 q0 = __builtin_bit_cast(i32x4, v0), q1 = __builtin_bit_cast(i32x4, v1);
;                         v0 = (f32x4){(float)q0[0], (float)q0[1], (float)q0[2], (float)q0[3]} * dq; v1 = (f32x4){(float)q1[0], (float)q1[1], (float)q1[2], (float)q1[3]} * dq; }
;                     if (isz) {
; #pragma unroll
;                         for (int j = 0; j < 4; ++j) { v0[j] = silu_f(v0[j]); v1[j] = silu_f(v1[j]); } }
;                     u32x4 w; w.x = cvt_pk_bf16(v0[0], v0[1]); w.y = cvt_pk_bf16(v0[2], v0[3]); w.z = cvt_pk_bf16(v1[0], v1[1]); w.w = cvt_pk_bf16(v1[2], v1[3]);
.LBB0_265:
	v_cvt_f32_i32_e32 v61, v61
	v_cvt_f32_i32_e32 v60, v60
	v_cvt_f32_i32_e32 v63, v63
	v_cvt_f32_i32_e32 v62, v62
	v_cvt_f32_i32_e32 v71, v57
	v_cvt_f32_i32_e32 v70, v56
	v_cvt_f32_i32_e32 v59, v59
	v_cvt_f32_i32_e32 v58, v58
	s_and_b64 vcc, exec, s[0:1]
	v_mul_f32_e32 v56, 0x3c000100, v150
	v_mul_f32_e32 v56, v155, v56
	v_pk_mul_f32 v[62:63], v[56:57], v[62:63] op_sel_hi:[0,1]
	v_pk_mul_f32 v[68:69], v[56:57], v[60:61] op_sel_hi:[0,1]
	v_pk_mul_f32 v[58:59], v[56:57], v[58:59] op_sel_hi:[0,1]
	v_pk_mul_f32 v[60:61], v[56:57], v[70:71] op_sel_hi:[0,1]
	s_cbranch_vccnz .LBB0_267
	v_mul_f32_e32 v57, 0xbfb8aa3b, v68
	v_exp_f32_e32 v57, v57
	v_mul_f32_e32 v70, 0xbfb8aa3b, v60
	v_mul_f32_e32 v73, 0xbfb8aa3b, v62
	v_mul_f32_e32 v71, 0xbfb8aa3b, v69
	v_exp_f32_e32 v72, v70
	v_exp_f32_e32 v73, v73
	v_mul_f32_e32 v74, 0xbfb8aa3b, v58
	v_exp_f32_e32 v71, v71
	v_exp_f32_e32 v75, v74
	v_add_f32_e32 v57, 1.0, v57
	v_rcp_f32_e32 v70, v57
	v_add_f32_e32 v57, 1.0, v72
	v_add_f32_e32 v73, 1.0, v73
	v_rcp_f32_e32 v72, v57
	v_add_f32_e32 v57, 1.0, v71
	v_rcp_f32_e32 v74, v73
	v_add_f32_e32 v73, 1.0, v75
	v_mul_f32_e32 v75, 0xbfb8aa3b, v63
	v_rcp_f32_e32 v71, v57
	v_mul_f32_e32 v57, 0xbfb8aa3b, v61
	v_exp_f32_e32 v75, v75
	v_mul_f32_e32 v76, 0xbfb8aa3b, v59
	v_exp_f32_e32 v57, v57
	v_exp_f32_e32 v77, v76
	v_rcp_f32_e32 v76, v73
	v_add_f32_e32 v73, 1.0, v75
	v_add_f32_e32 v57, 1.0, v57
	v_rcp_f32_e32 v75, v73
	v_add_f32_e32 v73, 1.0, v77
	v_rcp_f32_e32 v77, v73
	v_rcp_f32_e32 v73, v57
	v_pk_mul_f32 v[62:63], v[62:63], v[74:75]
	v_pk_mul_f32 v[68:69], v[68:69], v[70:71]
	v_pk_mul_f32 v[58:59], v[58:59], v[76:77]
	v_pk_mul_f32 v[60:61], v[60:61], v[72:73]

; __device__ __forceinline__ unsigned cvt_pk_bf16(float lo, float hi) { unsigned r; asm volatile("v_cvt_pk_bf16_f32 %0, %1, %2" : "=v"(r) : "v"(lo), "v"(hi)); return r; }
; __device__ __forceinline__ float silu_f(float x) { return x * fast_sigmoid(x); }
;     __device__ __forceinline__ void operator()(const f32x4 (&acc)[2][2][4][2], const Unit& u, int wr, int wc, int fr, int fq) const {
;     ...
;             for (int m = 0; m < 4; ++m) { const int row = row0 + ai * HALF + m * 16;
;                 bf16* rowp = g_ ? base + ((size_t)((row >> 13) * NG + (col0 >> 4)) * SEQ + (row & (SEQ - 1))) * 16 + (col0 & 15) : base + (size_t)row * EI + col0;
;                 const int bjs = g_ ? 8 * SEQ * 16 : HALF;
;                 float dq = 1.0f; if (Q8) dq = rowscale[(size_t)row * 32] * (qr[0] * (1.0f / ::Q8));
; #pragma unroll
;                 for (int bj = 0; bj < 2; ++bj) { f32x4 v0 = acc[ai][bj][m][0], v1 = acc[ai][bj][m][1];
;                     if (Q8) { const i32x4 q0 = __builtin_bit_cast(i32x4, v0), q1 = __builtin_bit_cast(i32x4, v1);
;                         v0 = (f32x4){(float)q0[0], (float)q0[1], (float)q0[2], (float)q0[3]} * dq; v1 = (f32x4){(float)q1[0], (float)q1[1], (float)q1[2], (float)q1[3]} * dq; }
;                     if (isz) {
; #pragma unroll
;                         for (int j = 0; j < 4; ++j) { v0[j] = silu_f(v0[j]); v1[j] = silu_f(v1[j]); } }
;                     u32x4 w; w.x = cvt_pk_bf16(v0[0], v0[1]); w.y = cvt_pk_bf16(v0[2], v0[3]); w.z = cvt_pk_bf16(v1[0], v1[1]); w.w = cvt_pk_bf16(v1[2], v1[3]);
.LBB0_273:
	v_cvt_f32_i32_e32 v45, v45
	v_cvt_f32_i32_e32 v44, v44
	v_cvt_f32_i32_e32 v47, v47
	v_cvt_f32_i32_e32 v46, v46
	v_cvt_f32_i32_e32 v53, v41
	v_cvt_f32_i32_e32 v52, v40
	v_cvt_f32_i32_e32 v43, v43
	v_cvt_f32_i32_e32 v42, v42
	s_and_b64 vcc, exec, s[0:1]
	v_mul_f32_e32 v40, 0x3c000100, v150
	v_mul_f32_e32 v40, v156, v40
	v_pk_mul_f32 v[46:47], v[40:41], v[46:47] op_sel_hi:[0,1]
	v_pk_mul_f32 v[50:51], v[40:41], v[44:45] op_sel_hi:[0,1]
	v_pk_mul_f32 v[42:43], v[40:41], v[42:43] op_sel_hi:[0,1]
	v_pk_mul_f32 v[44:45], v[40:41], v[52:53] op_sel_hi:[0,1]
	s_cbranch_vccnz .LBB0_275
	v_mul_f32_e32 v41, 0xbfb8aa3b, v50
	v_exp_f32_e32 v41, v41
	v_mul_f32_e32 v52, 0xbfb8aa3b, v44
	v_mul_f32_e32 v55, 0xbfb8aa3b, v46
	v_mul_f32_e32 v53, 0xbfb8aa3b, v51
	v_exp_f32_e32 v54, v52
	v_exp_f32_e32 v55, v55
	v_mul_f32_e32 v56, 0xbfb8aa3b, v42
	v_exp_f32_e32 v53, v53
	v_exp_f32_e32 v57, v56
	v_add_f32_e32 v41, 1.0, v41
	v_rcp_f32_e32 v52, v41
	v_add_f32_e32 v41, 1.0, v54
	v_add_f32_e32 v55, 1.0, v55
	v_rcp_f32_e32 v54, v41
	v_add_f32_e32 v41, 1.0, v53
	v_rcp_f32_e32 v56, v55
	v_add_f32_e32 v55, 1.0, v57
	v_mul_f32_e32 v57, 0xbfb8aa3b, v47
	v_rcp_f32_e32 v53, v41
	v_mul_f32_e32 v41, 0xbfb8aa3b, v45
	v_exp_f32_e32 v57, v57
	v_mul_f32_e32 v58, 0xbfb8aa3b, v43
	v_exp_f32_e32 v41, v41
	v_exp_f32_e32 v59, v58
	v_rcp_f32_e32 v58, v55
	v_add_f32_e32 v55, 1.0, v57
	v_add_f32_e32 v41, 1.0, v41
	v_rcp_f32_e32 v57, v55
	v_add_f32_e32 v55, 1.0, v59
	v_rcp_f32_e32 v59, v55
	v_rcp_f32_e32 v55, v41
	v_pk_mul_f32 v[46:47], v[46:47], v[56:57]
	v_pk_mul_f32 v[50:51], v[50:51], v[52:53]
	v_pk_mul_f32 v[42:43], v[42:43], v[58:59]
	v_pk_mul_f32 v[44:45], v[44:45], v[54:55]

; __device__ __forceinline__ unsigned cvt_pk_bf16(float lo, float hi) { unsigned r; asm volatile("v_cvt_pk_bf16_f32 %0, %1, %2" : "=v"(r) : "v"(lo), "v"(hi)); return r; }
; __device__ __forceinline__ float silu_f(float x) { return x * fast_sigmoid(x); }
;     __device__ __forceinline__ void operator()(const f32x4 (&acc)[2][2][4][2], const Unit& u, int wr, int wc, int fr, int fq) const {
;     ...
;             for (int m = 0; m < 4; ++m) { const int row = row0 + ai * HALF + m * 16;
;                 bf16* rowp = g_ ? base + ((size_t)((row >> 13) * NG + (col0 >> 4)) * SEQ + (row & (SEQ - 1))) * 16 + (col0 & 15) : base + (size_t)row * EI + col0;
;                 const int bjs = g_ ? 8 * SEQ * 16 : HALF;
;                 float dq = 1.0f; if (Q8) dq = rowscale[(size_t)row * 32] * (qr[0] * (1.0f / ::Q8));
; #pragma unroll
;                 for (int bj = 0; bj < 2; ++bj) { f32x4 v0 = acc[ai][bj][m][0], v1 = acc[ai][bj][m][1];
;                     if (Q8) { const i32x4 q0 = __builtin_bit_cast(i32x4, v0), q1 = __builtin_bit_cast(i32x4, v1);
;                         v0 = (f32x4){(float)q0[0], (float)q0[1], (float)q0[2], (float)q0[3]} * dq; v1 = (f32x4){(float)q1[0], (float)q1[1], (float)q1[2], (float)q1[3]} * dq; }
;                     if (isz) {
; #pragma unroll
;                         for (int j = 0; j < 4; ++j) { v0[j] = silu_f(v0[j]); v1[j] = silu_f(v1[j]); } }
;                     u32x4 w; w.x = cvt_pk_bf16(v0[0], v0[1]); w.y = cvt_pk_bf16(v0[2], v0[3]); w.z = cvt_pk_bf16(v1[0], v1[1]); w.w = cvt_pk_bf16(v1[2], v1[3]);
.LBB0_281:
	v_cvt_f32_i32_e32 v29, v29
	v_cvt_f32_i32_e32 v28, v28
	v_cvt_f32_i32_e32 v31, v31
	v_cvt_f32_i32_e32 v30, v30
	v_cvt_f32_i32_e32 v37, v25
	v_cvt_f32_i32_e32 v36, v24
	v_cvt_f32_i32_e32 v27, v27
	v_cvt_f32_i32_e32 v26, v26
	s_and_b64 vcc, exec, s[0:1]
	v_mul_f32_e32 v24, 0x3c000100, v150
	v_mul_f32_e32 v24, v157, v24
	v_pk_mul_f32 v[30:31], v[24:25], v[30:31] op_sel_hi:[0,1]
	v_pk_mul_f32 v[34:35], v[24:25], v[28:29] op_sel_hi:[0,1]
	v_pk_mul_f32 v[26:27], v[24:25], v[26:27] op_sel_hi:[0,1]
	v_pk_mul_f32 v[28:29], v[24:25], v[36:37] op_sel_hi:[0,1]
	s_cbranch_vccnz .LBB0_283
	v_mul_f32_e32 v25, 0xbfb8aa3b, v34
	v_exp_f32_e32 v25, v25
	v_mul_f32_e32 v36, 0xbfb8aa3b, v28
	v_mul_f32_e32 v39, 0xbfb8aa3b, v30
	v_mul_f32_e32 v37, 0xbfb8aa3b, v35
	v_exp_f32_e32 v38, v36
	v_exp_f32_e32 v39, v39
	v_mul_f32_e32 v40, 0xbfb8aa3b, v26
	v_exp_f32_e32 v37, v37
	v_exp_f32_e32 v41, v40
	v_add_f32_e32 v25, 1.0, v25
	v_rcp_f32_e32 v36, v25
	v_add_f32_e32 v25, 1.0, v38
	v_add_f32_e32 v39, 1.0, v39
	v_rcp_f32_e32 v38, v25
	v_add_f32_e32 v25, 1.0, v37
	v_rcp_f32_e32 v40, v39
	v_add_f32_e32 v39, 1.0, v41
	v_mul_f32_e32 v41, 0xbfb8aa3b, v31
	v_rcp_f32_e32 v37, v25
	v_mul_f32_e32 v25, 0xbfb8aa3b, v29
	v_exp_f32_e32 v41, v41
	v_mul_f32_e32 v42, 0xbfb8aa3b, v27
	v_exp_f32_e32 v25, v25
	v_exp_f32_e32 v43, v42
	v_rcp_f32_e32 v42, v39
	v_add_f32_e32 v39, 1.0, v41
	v_add_f32_e32 v25, 1.0, v25
	v_rcp_f32_e32 v41, v39
	v_add_f32_e32 v39, 1.0, v43
	v_rcp_f32_e32 v43, v39
	v_rcp_f32_e32 v39, v25
	v_pk_mul_f32 v[30:31], v[30:31], v[40:41]
	v_pk_mul_f32 v[34:35], v[34:35], v[36:37]
	v_pk_mul_f32 v[26:27], v[26:27], v[42:43]
	v_pk_mul_f32 v[28:29], v[28:29], v[38:39]

; __device__ __forceinline__ unsigned cvt_pk_bf16(float lo, float hi) { unsigned r; asm volatile("v_cvt_pk_bf16_f32 %0, %1, %2" : "=v"(r) : "v"(lo), "v"(hi)); return r; }
; __device__ __forceinline__ float silu_f(float x) { return x * fast_sigmoid(x); }
;     __device__ __forceinline__ void operator()(const f32x4 (&acc)[2][2][4][2], const Unit& u, int wr, int wc, int fr, int fq) const {
;     ...
;             for (int m = 0; m < 4; ++m) { const int row = row0 + ai * HALF + m * 16;
;                 bf16* rowp = g_ ? base + ((size_t)((row >> 13) * NG + (col0 >> 4)) * SEQ + (row & (SEQ - 1))) * 16 + (col0 & 15) : base + (size_t)row * EI + col0;
;                 const int bjs = g_ ? 8 * SEQ * 16 : HALF;
;                 float dq = 1.0f; if (Q8) dq = rowscale[(size_t)row * 32] * (qr[0] * (1.0f / ::Q8));
; #pragma unroll
;                 for (int bj = 0; bj < 2; ++bj) { f32x4 v0 = acc[ai][bj][m][0], v1 = acc[ai][bj][m][1];
;                     if (Q8) { const i32x4 q0 = __builtin_bit_cast(i32x4, v0), q1 = __builtin_bit_cast(i32x4, v1);
;                         v0 = (f32x4){(float)q0[0], (float)q0[1], (float)q0[2], (float)q0[3]} * dq; v1 = (f32x4){(float)q1[0], (float)q1[1], (float)q1[2], (float)q1[3]} * dq; }
;                     if (isz) {
; #pragma unroll
;                         for (int j = 0; j < 4; ++j) { v0[j] = silu_f(v0[j]); v1[j] = silu_f(v1[j]); } }
;                     u32x4 w; w.x = cvt_pk_bf16(v0[0], v0[1]); w.y = cvt_pk_bf16(v0[2], v0[3]); w.z = cvt_pk_bf16(v1[0], v1[1]); w.w = cvt_pk_bf16(v1[2], v1[3]);
.LBB0_289:
	v_cvt_f32_i32_e32 v13, v13
	v_cvt_f32_i32_e32 v12, v12
	v_cvt_f32_i32_e32 v15, v15
	v_cvt_f32_i32_e32 v14, v14
	v_cvt_f32_i32_e32 v21, v9
	v_cvt_f32_i32_e32 v20, v8
	v_cvt_f32_i32_e32 v11, v11
	v_cvt_f32_i32_e32 v10, v10
	s_and_b64 vcc, exec, s[0:1]
	v_mul_f32_e32 v8, 0x3c000100, v150
	v_mul_f32_e32 v8, v158, v8
	v_pk_mul_f32 v[14:15], v[8:9], v[14:15] op_sel_hi:[0,1]
	v_pk_mul_f32 v[18:19], v[8:9], v[12:13] op_sel_hi:[0,1]
	v_pk_mul_f32 v[10:11], v[8:9], v[10:11] op_sel_hi:[0,1]
	v_pk_mul_f32 v[12:13], v[8:9], v[20:21] op_sel_hi:[0,1]
	s_cbranch_vccnz .LBB0_291
	v_mul_f32_e32 v9, 0xbfb8aa3b, v18
	v_exp_f32_e32 v9, v9
	v_mul_f32_e32 v20, 0xbfb8aa3b, v12
	v_mul_f32_e32 v23, 0xbfb8aa3b, v14
	v_mul_f32_e32 v21, 0xbfb8aa3b, v19
	v_exp_f32_e32 v22, v20
	v_exp_f32_e32 v23, v23
	v_mul_f32_e32 v24, 0xbfb8aa3b, v10
	v_exp_f32_e32 v21, v21
	v_exp_f32_e32 v25, v24
	v_add_f32_e32 v9, 1.0, v9
	v_rcp_f32_e32 v20, v9
	v_add_f32_e32 v9, 1.0, v22
	v_add_f32_e32 v23, 1.0, v23
	v_rcp_f32_e32 v22, v9
	v_add_f32_e32 v9, 1.0, v21
	v_rcp_f32_e32 v24, v23
	v_add_f32_e32 v23, 1.0, v25
	v_mul_f32_e32 v25, 0xbfb8aa3b, v15
	v_rcp_f32_e32 v21, v9
	v_mul_f32_e32 v9, 0xbfb8aa3b, v13
	v_exp_f32_e32 v25, v25
	v_mul_f32_e32 v26, 0xbfb8aa3b, v11
	v_exp_f32_e32 v9, v9
	v_exp_f32_e32 v27, v26
	v_rcp_f32_e32 v26, v23
	v_add_f32_e32 v23, 1.0, v25
	v_add_f32_e32 v9, 1.0, v9
	v_rcp_f32_e32 v25, v23
	v_add_f32_e32 v23, 1.0, v27
	v_rcp_f32_e32 v27, v23
	v_rcp_f32_e32 v23, v9
	v_pk_mul_f32 v[14:15], v[14:15], v[24:25]
	v_pk_mul_f32 v[18:19], v[18:19], v[20:21]
	v_pk_mul_f32 v[10:11], v[10:11], v[26:27]
	v_pk_mul_f32 v[12:13], v[12:13], v[22:23]

; #define GAS __attribute__((address_space(1)))
; #define LAS __attribute__((address_space(3)))
; __device__ __forceinline__ unsigned cvt_pk_bf16(float lo, float hi) { unsigned r; asm volatile("v_cvt_pk_bf16_f32 %0, %1, %2" : "=v"(r) : "v"(lo), "v"(hi)); return r; }
; __device__ __forceinline__ float bf_lo(unsigned w) { return __uint_as_float(w << 16); }
; __device__ __forceinline__ float bf_hi(unsigned w) { return __uint_as_float(w & 0xffff0000u); }
; template <int W>
; __device__ __forceinline__ void pool_item(const Ctx& F, const bf16* Ub, bf16* Db, int r0, int nr) {
;     ...
;         for (int u = 0; u < NS; ++u) {
;             const int r = base + u;
;             if (r < re) {
;                 POOL_LOAD((u + 2) % NS, r + 2);
;                 const int e = r + HW - 1;
;                 const float me = (e >= 0 && e < 128) ? 1.0f : 0.0f, ml = (r >= r0 && r - HW >= 0) ? 1.0f : 0.0f;
; #pragma unroll
;                 for (int j = 0; j < 8; ++j) { Vv[j].x += me * bf_lo(ring[u][j]); Vv[j].y += me * bf_hi(ring[u][j]); }
;                 if (r >= r0) {
;                     LAS f32x2* row = buf + ((r & 1) * 80 + 8) * 64 + lane;
; #pragma unroll
;                     for (int j = 0; j < 8; ++j) row[(c0 + j) * 64] = Vv[j];
;                     asm volatile("s_waitcnt lgkmcnt(0)" ::: "memory"); __builtin_amdgcn_s_barrier(); asm volatile("" ::: "memory");
;                     const int rlo = r - HW > 0 ? r - HW : 0, rhi = r + HW < 128 ? r + HW : 128; const float icr = 1.0f / (float)(rhi - rlo);
;                     f32x2 h = (f32x2){0.f, 0.f};
; #pragma unroll
;                     for (int c = -HW; c < HW; ++c) h += row[(c0 + c) * 64];
; #pragma unroll
;                     for (int j = 0; j < 8; ++j) {
;                         const float ic = icr * icc[j]; const unsigned m = ring[(u + NS - HW + 1) % NS][j];
;                         *(GAS unsigned*)(Db + ((size_t)r * 64 + c0 + j) * EI) = cvt_pk_bf16(h.x * ic - bf_lo(m), h.y * ic - bf_hi(m));
;                         h += row[(c0 + j + HW) * 64] - row[(c0 + j - HW) * 64];
;                     }
; #pragma unroll
;                     for (int j = 0; j < 8; ++j) { const unsigned l = ring[(u + NS - W + 1) % NS][j]; Vv[j].x -= ml * bf_lo(l); Vv[j].y -= ml * bf_hi(l); }
;                 }
.LBB0_832:
	v_med3_i32 v2, s42, -9, v93
	v_add_u32_e32 v2, 9, v2
	v_lshlrev_b64 v[34:35], 20, v[2:3]
	v_lshl_add_u64 v[34:35], v[12:13], 0, v[34:35]
	v_add_co_u32_e32 v36, vcc, s54, v34
	s_add_i32 s44, s42, 7
	s_nop 0
	v_addc_co_u32_e32 v37, vcc, 0, v35, vcc
	v_add_co_u32_e32 v38, vcc, s55, v34
	s_cmpk_lt_u32 s44, 0x80
	s_nop 0
	v_addc_co_u32_e32 v39, vcc, 0, v35, vcc
	v_add_co_u32_e32 v40, vcc, s56, v34
	s_cselect_b64 s[50:51], -1, 0
	s_nop 0
	v_addc_co_u32_e32 v41, vcc, 0, v35, vcc
	v_add_co_u32_e32 v42, vcc, s57, v34
	v_cndmask_b32_e64 v2, 0, 1.0, s[50:51]
	s_nop 0
	v_addc_co_u32_e32 v43, vcc, 0, v35, vcc
	v_add_co_u32_e32 v44, vcc, s58, v34
	s_cmp_lt_i32 s42, s62
	s_nop 0
	v_addc_co_u32_e32 v45, vcc, 0, v35, vcc
	v_add_co_u32_e32 v46, vcc, s59, v34
	s_nop 1
	v_addc_co_u32_e32 v47, vcc, 0, v35, vcc
	v_add_co_u32_e32 v48, vcc, s60, v34
	s_nop 1
	v_addc_co_u32_e32 v49, vcc, 0, v35, vcc
	global_load_dword v233, v[34:35], off
	global_load_dword v232, v[36:37], off
	global_load_dword v231, v[38:39], off
	global_load_dword v230, v[40:41], off
	global_load_dword v229, v[42:43], off
	global_load_dword v228, v[44:45], off
	global_load_dword v227, v[46:47], off
	global_load_dword v226, v[48:49], off
	s_waitcnt vmcnt(23)
	v_lshlrev_b32_e32 v34, 16, v53
	v_and_b32_e32 v35, 0xffff0000, v53
	s_waitcnt vmcnt(22)
	v_lshlrev_b32_e32 v36, 16, v54
	v_and_b32_e32 v37, 0xffff0000, v54
	s_waitcnt vmcnt(21)
	v_lshlrev_b32_e32 v38, 16, v55
	v_and_b32_e32 v39, 0xffff0000, v55
	s_waitcnt vmcnt(20)
	v_lshlrev_b32_e32 v40, 16, v56
	v_and_b32_e32 v41, 0xffff0000, v56
	s_waitcnt vmcnt(19)
	v_lshlrev_b32_e32 v42, 16, v57
	v_and_b32_e32 v43, 0xffff0000, v57
	s_waitcnt vmcnt(18)
	v_lshlrev_b32_e32 v44, 16, v95
	v_and_b32_e32 v45, 0xffff0000, v95
	s_waitcnt vmcnt(17)
	v_lshlrev_b32_e32 v46, 16, v96
	v_and_b32_e32 v47, 0xffff0000, v96
	s_waitcnt vmcnt(16)
	v_lshlrev_b32_e32 v48, 16, v102
	v_and_b32_e32 v49, 0xffff0000, v102
	v_pk_fma_f32 v[18:19], v[2:3], v[34:35], v[18:19] op_sel_hi:[0,1,1]
	v_pk_fma_f32 v[20:21], v[2:3], v[36:37], v[20:21] op_sel_hi:[0,1,1]
	v_pk_fma_f32 v[22:23], v[2:3], v[38:39], v[22:23] op_sel_hi:[0,1,1]
	v_pk_fma_f32 v[24:25], v[2:3], v[40:41], v[24:25] op_sel_hi:[0,1,1]
	v_pk_fma_f32 v[26:27], v[2:3], v[42:43], v[26:27] op_sel_hi:[0,1,1]
	v_pk_fma_f32 v[28:29], v[2:3], v[44:45], v[28:29] op_sel_hi:[0,1,1]
	v_pk_fma_f32 v[30:31], v[2:3], v[46:47], v[30:31] op_sel_hi:[0,1,1]
	v_pk_fma_f32 v[32:33], v[2:3], v[48:49], v[32:33] op_sel_hi:[0,1,1]
	s_cbranch_scc1 .LBB0_834
	ds_write2st64_b64 v92, v[18:19], v[20:21] offset0:88 offset1:89
	ds_write2st64_b64 v92, v[22:23], v[24:25] offset0:90 offset1:91
	ds_write2st64_b64 v92, v[26:27], v[28:29] offset0:92 offset1:93
	ds_write2st64_b64 v92, v[30:31], v[32:33] offset0:94 offset1:95
	s_waitcnt lgkmcnt(0)
	s_barrier
	ds_read2st64_b64 v[236:239], v92 offset0:80 offset1:81
	s_cmp_gt_i32 s42, 7
	s_cselect_b64 s[50:51], -1, 0
	s_max_i32 s10, s42, 8
	s_min_i32 s16, s42, 0x78
	s_waitcnt lgkmcnt(0)
	v_pk_add_f32 v[50:51], v[236:237], 0 op_sel_hi:[1,0]
	s_sub_i32 s10, s16, s10
	v_pk_add_f32 v[50:51], v[50:51], v[238:239]
	ds_read2st64_b64 v[236:239], v92 offset0:82 offset1:83
	s_add_i32 s10, s10, 16
	v_cvt_f32_i32_e32 v242, s10
	v_cndmask_b32_e64 v2, 0, 1.0, s[50:51]
	s_mov_b32 s43, s17
	s_waitcnt lgkmcnt(0)
	v_pk_add_f32 v[50:51], v[50:51], v[236:237]
	s_nop 0
	v_pk_add_f32 v[50:51], v[50:51], v[238:239]
	ds_read2st64_b64 v[236:239], v92 offset0:84 offset1:85
	s_waitcnt lgkmcnt(0)
	v_pk_add_f32 v[50:51], v[50:51], v[236:237]
	s_nop 0
	v_pk_add_f32 v[50:51], v[50:51], v[238:239]
	ds_read2st64_b64 v[236:239], v92 offset0:86 offset1:87
	s_waitcnt lgkmcnt(0)
	v_pk_add_f32 v[50:51], v[50:51], v[236:237]
	s_nop 0
	v_pk_add_f32 v[50:51], v[50:51], v[238:239]
	ds_read2st64_b64 v[236:239], v92 offset0:88 offset1:89
	s_waitcnt lgkmcnt(0)
	v_pk_add_f32 v[50:51], v[50:51], v[236:237]
	s_nop 0
	v_pk_add_f32 v[50:51], v[50:51], v[238:239]
	ds_read2st64_b64 v[236:239], v92 offset0:90 offset1:91
	s_waitcnt lgkmcnt(0)
	v_pk_add_f32 v[50:51], v[50:51], v[236:237]
	s_nop 0
	v_pk_add_f32 v[50:51], v[50:51], v[238:239]
	ds_read2st64_b64 v[236:239], v92 offset0:92 offset1:93
	s_waitcnt lgkmcnt(0)
	v_pk_add_f32 v[50:51], v[50:51], v[236:237]
	s_nop 0
	v_pk_add_f32 v[50:51], v[50:51], v[238:239]
	ds_read2st64_b64 v[236:239], v92 offset0:94 offset1:95
	s_waitcnt lgkmcnt(0)
	v_pk_add_f32 v[50:51], v[50:51], v[236:237]
	s_nop 0
	v_pk_add_f32 v[240:241], v[50:51], v[238:239]
	v_div_scale_f32 v50, s[50:51], v242, v242, 1.0
	v_rcp_f32_e32 v51, v50
	s_lshl_b64 s[50:51], s[42:43], 20
	v_fma_f32 v236, -v50, v51, 1.0
	v_fmac_f32_e32 v51, v236, v51
	v_div_scale_f32 v236, vcc, 1.0, v242, 1.0
	v_mul_f32_e32 v237, v236, v51
	v_fma_f32 v238, -v50, v237, v236
	v_fmac_f32_e32 v237, v238, v51
	v_fma_f32 v50, -v50, v237, v236
	v_div_fmas_f32 v50, v50, v51, v237
	v_div_fixup_f32 v242, v50, v242, 1.0
	v_mul_f32_e32 v50, v74, v242
	v_lshlrev_b32_e32 v51, 16, v126
	v_and_b32_e32 v236, 0xffff0000, v126
	v_fma_f32 v51, v50, v240, -v51
	v_fma_f32 v50, v50, v241, -v236
	v_cvt_pk_bf16_f32 v236, v51, v50
	v_lshl_add_u64 v[50:51], v[14:15], 0, s[50:51]
	global_store_dword v[50:51], v236, off
	ds_read2st64_b64 v[236:239], v92 offset0:80 offset1:96
	s_waitcnt lgkmcnt(0)
	v_pk_add_f32 v[236:237], v[238:239], v[236:237] neg_lo:[0,1] neg_hi:[0,1]
	s_nop 0
	v_pk_add_f32 v[240:241], v[240:241], v[236:237]
	v_mul_f32_e32 v236, v75, v242
	v_lshlrev_b32_e32 v237, 16, v134
	v_and_b32_e32 v238, 0xffff0000, v134
	v_fma_f32 v237, v236, v240, -v237
	v_fma_f32 v236, v236, v241, -v238
	v_cvt_pk_bf16_f32 v238, v237, v236
	v_add_co_u32_e32 v236, vcc, s54, v50
	s_nop 1
	v_addc_co_u32_e32 v237, vcc, 0, v51, vcc
	global_store_dword v[236:237], v238, off
	ds_read2st64_b64 v[236:239], v92 offset0:81 offset1:97
	s_waitcnt lgkmcnt(0)
; #define GAS __attribute__((address_space(1)))
; __device__ __forceinline__ unsigned cvt_pk_bf16(float lo, float hi) { unsigned r; asm volatile("v_cvt_pk_bf16_f32 %0, %1, %2" : "=v"(r) : "v"(lo), "v"(hi)); return r; }
; __device__ __forceinline__ float bf_lo(unsigned w) { return __uint_as_float(w << 16); }
; __device__ __forceinline__ float bf_hi(unsigned w) { return __uint_as_float(w & 0xffff0000u); }
; template <int W>
; __device__ __forceinline__ void pool_item(const Ctx& F, const bf16* Ub, bf16* Db, int r0, int nr) {
;     ...
;                     for (int j = 0; j < 8; ++j) {
;                         const float ic = icr * icc[j]; const unsigned m = ring[(u + NS - HW + 1) % NS][j];
;                         *(GAS unsigned*)(Db + ((size_t)r * 64 + c0 + j) * EI) = cvt_pk_bf16(h.x * ic - bf_lo(m), h.y * ic - bf_hi(m));
;                         h += row[(c0 + j + HW) * 64] - row[(c0 + j - HW) * 64];
;                     }
; #pragma unroll
;                     for (int j = 0; j < 8; ++j) { const unsigned l = ring[(u + NS - W + 1) % NS][j]; Vv[j].x -= ml * bf_lo(l); Vv[j].y -= ml * bf_hi(l); }
	v_pk_add_f32 v[236:237], v[238:239], v[236:237] neg_lo:[0,1] neg_hi:[0,1]
	s_nop 0
	v_pk_add_f32 v[240:241], v[240:241], v[236:237]
	v_mul_f32_e32 v236, v76, v242
	v_lshlrev_b32_e32 v237, 16, v143
	v_and_b32_e32 v238, 0xffff0000, v143
	v_fma_f32 v237, v236, v240, -v237
	v_fma_f32 v236, v236, v241, -v238
	v_cvt_pk_bf16_f32 v238, v237, v236
	v_add_co_u32_e32 v236, vcc, s55, v50
	s_nop 1
	v_addc_co_u32_e32 v237, vcc, 0, v51, vcc
	global_store_dword v[236:237], v238, off
	ds_read2st64_b64 v[236:239], v92 offset0:82 offset1:98
	s_waitcnt lgkmcnt(0)
	v_pk_add_f32 v[236:237], v[238:239], v[236:237] neg_lo:[0,1] neg_hi:[0,1]
	s_nop 0
	v_pk_add_f32 v[240:241], v[240:241], v[236:237]
	v_mul_f32_e32 v236, v77, v242
	v_lshlrev_b32_e32 v237, 16, v151
	v_and_b32_e32 v238, 0xffff0000, v151
	v_fma_f32 v237, v236, v240, -v237
	v_fma_f32 v236, v236, v241, -v238
	v_cvt_pk_bf16_f32 v238, v237, v236
	v_add_co_u32_e32 v236, vcc, s56, v50
	s_nop 1
	v_addc_co_u32_e32 v237, vcc, 0, v51, vcc
	global_store_dword v[236:237], v238, off
	ds_read2st64_b64 v[236:239], v92 offset0:83 offset1:99
	s_waitcnt lgkmcnt(0)
	v_pk_add_f32 v[236:237], v[238:239], v[236:237] neg_lo:[0,1] neg_hi:[0,1]
	s_nop 0
	v_pk_add_f32 v[240:241], v[240:241], v[236:237]
	v_mul_f32_e32 v236, v78, v242
	v_lshlrev_b32_e32 v237, 16, v160
	v_and_b32_e32 v238, 0xffff0000, v160
	v_fma_f32 v237, v236, v240, -v237
	v_fma_f32 v236, v236, v241, -v238
	v_cvt_pk_bf16_f32 v238, v237, v236
	v_add_co_u32_e32 v236, vcc, s57, v50
	s_nop 1
	v_addc_co_u32_e32 v237, vcc, 0, v51, vcc
	global_store_dword v[236:237], v238, off
	ds_read2st64_b64 v[236:239], v92 offset0:84 offset1:100
	s_waitcnt lgkmcnt(0)
	v_pk_add_f32 v[236:237], v[238:239], v[236:237] neg_lo:[0,1] neg_hi:[0,1]
	s_nop 0
	v_pk_add_f32 v[240:241], v[240:241], v[236:237]
	v_mul_f32_e32 v236, v79, v242
	v_lshlrev_b32_e32 v237, 16, v169
	v_and_b32_e32 v238, 0xffff0000, v169
	v_fma_f32 v237, v236, v240, -v237
	v_fma_f32 v236, v236, v241, -v238
	v_cvt_pk_bf16_f32 v238, v237, v236
	v_add_co_u32_e32 v236, vcc, s58, v50
	s_nop 1
	v_addc_co_u32_e32 v237, vcc, 0, v51, vcc
	global_store_dword v[236:237], v238, off
	ds_read2st64_b64 v[236:239], v92 offset0:85 offset1:101
	s_waitcnt lgkmcnt(0)
	v_pk_add_f32 v[236:237], v[238:239], v[236:237] neg_lo:[0,1] neg_hi:[0,1]
	s_nop 0
	v_pk_add_f32 v[240:241], v[240:241], v[236:237]
	v_mul_f32_e32 v236, v80, v242
	v_lshlrev_b32_e32 v237, 16, v181
	v_and_b32_e32 v238, 0xffff0000, v181
	v_fma_f32 v237, v236, v240, -v237
	v_fma_f32 v236, v236, v241, -v238
	v_cvt_pk_bf16_f32 v238, v237, v236
	v_add_co_u32_e32 v236, vcc, s59, v50
	s_nop 1
	v_addc_co_u32_e32 v237, vcc, 0, v51, vcc
	global_store_dword v[236:237], v238, off
	ds_read2st64_b64 v[236:239], v92 offset0:86 offset1:102
	v_add_co_u32_e32 v50, vcc, s60, v50
	s_waitcnt lgkmcnt(0)
	v_pk_add_f32 v[236:237], v[238:239], v[236:237] neg_lo:[0,1] neg_hi:[0,1]
	s_nop 0
	v_pk_add_f32 v[236:237], v[240:241], v[236:237]
	v_mul_f32_e32 v238, v81, v242
	v_lshlrev_b32_e32 v239, 16, v207
	v_fma_f32 v236, v238, v236, -v239
	v_and_b32_e32 v239, 0xffff0000, v207
	v_addc_co_u32_e32 v51, vcc, 0, v51, vcc
	v_fma_f32 v237, v238, v237, -v239
	v_cvt_pk_bf16_f32 v236, v236, v237
	global_store_dword v[50:51], v236, off
	v_lshlrev_b32_e32 v50, 16, v187
	v_and_b32_e32 v51, 0xffff0000, v187
	v_pk_fma_f32 v[18:19], v[2:3], v[50:51], v[18:19] op_sel_hi:[0,1,1] neg_lo:[1,0,0] neg_hi:[1,0,0]
	v_lshlrev_b32_e32 v50, 16, v192
	v_and_b32_e32 v51, 0xffff0000, v192
	v_pk_fma_f32 v[20:21], v[2:3], v[50:51], v[20:21] op_sel_hi:[0,1,1] neg_lo:[1,0,0] neg_hi:[1,0,0]
	v_lshlrev_b32_e32 v50, 16, v200
	v_and_b32_e32 v51, 0xffff0000, v200
	v_pk_fma_f32 v[22:23], v[2:3], v[50:51], v[22:23] op_sel_hi:[0,1,1] neg_lo:[1,0,0] neg_hi:[1,0,0]
	v_lshlrev_b32_e32 v50, 16, v208
	v_and_b32_e32 v51, 0xffff0000, v208
	v_pk_fma_f32 v[24:25], v[2:3], v[50:51], v[24:25] op_sel_hi:[0,1,1] neg_lo:[1,0,0] neg_hi:[1,0,0]
	v_lshlrev_b32_e32 v50, 16, v213
	v_and_b32_e32 v51, 0xffff0000, v213
	v_pk_fma_f32 v[26:27], v[2:3], v[50:51], v[26:27] op_sel_hi:[0,1,1] neg_lo:[1,0,0] neg_hi:[1,0,0]
	v_lshlrev_b32_e32 v50, 16, v217
	v_and_b32_e32 v51, 0xffff0000, v217
	v_pk_fma_f32 v[28:29], v[2:3], v[50:51], v[28:29] op_sel_hi:[0,1,1] neg_lo:[1,0,0] neg_hi:[1,0,0]
	v_lshlrev_b32_e32 v50, 16, v221
	v_and_b32_e32 v51, 0xffff0000, v221
	v_pk_fma_f32 v[30:31], v[2:3], v[50:51], v[30:31] op_sel_hi:[0,1,1] neg_lo:[1,0,0] neg_hi:[1,0,0]
	v_lshlrev_b32_e32 v50, 16, v225
	v_and_b32_e32 v51, 0xffff0000, v225
	v_pk_fma_f32 v[32:33], v[2:3], v[50:51], v[32:33] op_sel_hi:[0,1,1] neg_lo:[1,0,0] neg_hi:[1,0,0]
; #define GAS __attribute__((address_space(1)))
; #define LAS __attribute__((address_space(3)))
; __device__ __forceinline__ unsigned cvt_pk_bf16(float lo, float hi) { unsigned r; asm volatile("v_cvt_pk_bf16_f32 %0, %1, %2" : "=v"(r) : "v"(lo), "v"(hi)); return r; }
; __device__ __forceinline__ float bf_lo(unsigned w) { return __uint_as_float(w << 16); }
; __device__ __forceinline__ float bf_hi(unsigned w) { return __uint_as_float(w & 0xffff0000u); }
; template <int W>
; __device__ __forceinline__ void pool_item(const Ctx& F, const bf16* Ub, bf16* Db, int r0, int nr) {
;     ...
;         for (int u = 0; u < NS; ++u) {
;             const int r = base + u;
;             if (r < re) {
;                 POOL_LOAD((u + 2) % NS, r + 2);
;                 const int e = r + HW - 1;
;                 const float me = (e >= 0 && e < 128) ? 1.0f : 0.0f, ml = (r >= r0 && r - HW >= 0) ? 1.0f : 0.0f;
; #pragma unroll
;                 for (int j = 0; j < 8; ++j) { Vv[j].x += me * bf_lo(ring[u][j]); Vv[j].y += me * bf_hi(ring[u][j]); }
;                 if (r >= r0) {
;                     LAS f32x2* row = buf + ((r & 1) * 80 + 8) * 64 + lane;
; #pragma unroll
;                     for (int j = 0; j < 8; ++j) row[(c0 + j) * 64] = Vv[j];
;                     asm volatile("s_waitcnt lgkmcnt(0)" ::: "memory"); __builtin_amdgcn_s_barrier(); asm volatile("" ::: "memory");
;                     const int rlo = r - HW > 0 ? r - HW : 0, rhi = r + HW < 128 ? r + HW : 128; const float icr = 1.0f / (float)(rhi - rlo);
;                     f32x2 h = (f32x2){0.f, 0.f};
; #pragma unroll
;                     for (int c = -HW; c < HW; ++c) h += row[(c0 + c) * 64];
; #pragma unroll
;                     for (int j = 0; j < 8; ++j) {
;                         const float ic = icr * icc[j]; const unsigned m = ring[(u + NS - HW + 1) % NS][j];
;                         *(GAS unsigned*)(Db + ((size_t)r * 64 + c0 + j) * EI) = cvt_pk_bf16(h.x * ic - bf_lo(m), h.y * ic - bf_hi(m));
;                         h += row[(c0 + j + HW) * 64] - row[(c0 + j - HW) * 64];
;                     }
; #pragma unroll
;                     for (int j = 0; j < 8; ++j) { const unsigned l = ring[(u + NS - W + 1) % NS][j]; Vv[j].x -= ml * bf_lo(l); Vv[j].y -= ml * bf_hi(l); }
;                 }
.LBB0_834:
	s_add_i32 s16, s42, 1
	s_cmp_ge_i32 s16, s46
	s_cbranch_scc1 .LBB0_837
	v_med3_i32 v2, s16, -9, v93
	v_add_u32_e32 v2, 9, v2
	v_lshlrev_b64 v[50:51], 20, v[2:3]
	v_lshl_add_u64 v[50:51], v[12:13], 0, v[50:51]
	v_add_co_u32_e32 v236, vcc, 0x4000, v50
	global_load_dword v187, v[50:51], off
	s_nop 0
	v_addc_co_u32_e32 v237, vcc, 0, v51, vcc
	global_load_dword v192, v[236:237], off
	v_add_co_u32_e32 v236, vcc, 0x8000, v50
	s_add_i32 s10, s42, 8
	s_nop 0
	v_addc_co_u32_e32 v237, vcc, 0, v51, vcc
	global_load_dword v200, v[236:237], off
	v_add_co_u32_e32 v236, vcc, 0xc000, v50
	s_cmpk_lt_u32 s10, 0x80
	s_nop 0
	v_addc_co_u32_e32 v237, vcc, 0, v51, vcc
	global_load_dword v208, v[236:237], off
	v_add_co_u32_e32 v236, vcc, 0x10000, v50
	s_cselect_b64 s[50:51], -1, 0
	s_nop 0
	v_addc_co_u32_e32 v237, vcc, 0, v51, vcc
	global_load_dword v213, v[236:237], off
	v_add_co_u32_e32 v236, vcc, 0x14000, v50
	v_cndmask_b32_e64 v2, 0, 1.0, s[50:51]
	s_nop 0
	v_addc_co_u32_e32 v237, vcc, 0, v51, vcc
	global_load_dword v217, v[236:237], off
	v_add_co_u32_e32 v236, vcc, 0x18000, v50
	s_cmp_lt_i32 s16, s62
	s_nop 0
	v_addc_co_u32_e32 v237, vcc, 0, v51, vcc
	v_add_co_u32_e32 v50, vcc, 0x1c000, v50
	global_load_dword v221, v[236:237], off
	s_nop 0
	v_addc_co_u32_e32 v51, vcc, 0, v51, vcc
	global_load_dword v225, v[50:51], off
	s_waitcnt vmcnt(16)
	v_lshlrev_b32_e32 v50, 16, v97
	v_and_b32_e32 v51, 0xffff0000, v97
	v_pk_fma_f32 v[18:19], v[2:3], v[50:51], v[18:19] op_sel_hi:[0,1,1]
	v_lshlrev_b32_e32 v50, 16, v98
	v_and_b32_e32 v51, 0xffff0000, v98
	v_pk_fma_f32 v[20:21], v[2:3], v[50:51], v[20:21] op_sel_hi:[0,1,1]
	v_lshlrev_b32_e32 v50, 16, v99
	v_and_b32_e32 v51, 0xffff0000, v99
	v_pk_fma_f32 v[22:23], v[2:3], v[50:51], v[22:23] op_sel_hi:[0,1,1]
	v_lshlrev_b32_e32 v50, 16, v100
	v_and_b32_e32 v51, 0xffff0000, v100
	v_pk_fma_f32 v[24:25], v[2:3], v[50:51], v[24:25] op_sel_hi:[0,1,1]
	v_lshlrev_b32_e32 v50, 16, v104
	v_and_b32_e32 v51, 0xffff0000, v104
	v_pk_fma_f32 v[26:27], v[2:3], v[50:51], v[26:27] op_sel_hi:[0,1,1]
	v_lshlrev_b32_e32 v50, 16, v109
	v_and_b32_e32 v51, 0xffff0000, v109
	v_pk_fma_f32 v[28:29], v[2:3], v[50:51], v[28:29] op_sel_hi:[0,1,1]
	v_lshlrev_b32_e32 v50, 16, v114
	v_and_b32_e32 v51, 0xffff0000, v114
	v_pk_fma_f32 v[30:31], v[2:3], v[50:51], v[30:31] op_sel_hi:[0,1,1]
	v_lshlrev_b32_e32 v50, 16, v141
	v_and_b32_e32 v51, 0xffff0000, v141
	v_pk_fma_f32 v[32:33], v[2:3], v[50:51], v[32:33] op_sel_hi:[0,1,1]
	s_cbranch_scc1 .LBB0_837
	ds_write2st64_b64 v92, v[18:19], v[20:21] offset0:8 offset1:9
	ds_write2st64_b64 v92, v[22:23], v[24:25] offset0:10 offset1:11
	ds_write2st64_b64 v92, v[26:27], v[28:29] offset0:12 offset1:13
	ds_write2st64_b64 v92, v[30:31], v[32:33] offset0:14 offset1:15
	s_waitcnt lgkmcnt(0)
	s_barrier
	ds_read2st64_b64 v[236:239], v92 offset1:1
	s_cmp_gt_i32 s42, 6
	s_cselect_b64 s[50:51], -1, 0
	s_max_i32 s10, s16, 8
	s_min_i32 s23, s16, 0x78
	s_waitcnt lgkmcnt(0)
	v_pk_add_f32 v[50:51], v[236:237], 0 op_sel_hi:[1,0]
	s_sub_i32 s10, s23, s10
	v_pk_add_f32 v[50:51], v[50:51], v[238:239]
	ds_read2st64_b64 v[236:239], v92 offset0:2 offset1:3
	s_add_i32 s10, s10, 16
	v_cvt_f32_i32_e32 v242, s10
	v_cndmask_b32_e64 v2, 0, 1.0, s[50:51]
	s_waitcnt lgkmcnt(0)
	v_pk_add_f32 v[50:51], v[50:51], v[236:237]
	s_nop 0
	v_pk_add_f32 v[50:51], v[50:51], v[238:239]
	ds_read2st64_b64 v[236:239], v92 offset0:4 offset1:5
	s_waitcnt lgkmcnt(0)
	v_pk_add_f32 v[50:51], v[50:51], v[236:237]
	s_nop 0
	v_pk_add_f32 v[50:51], v[50:51], v[238:239]
	ds_read2st64_b64 v[236:239], v92 offset0:6 offset1:7
	s_waitcnt lgkmcnt(0)
	v_pk_add_f32 v[50:51], v[50:51], v[236:237]
	s_nop 0
	v_pk_add_f32 v[50:51], v[50:51], v[238:239]
	ds_read2st64_b64 v[236:239], v92 offset0:8 offset1:9
	s_waitcnt lgkmcnt(0)
	v_pk_add_f32 v[50:51], v[50:51], v[236:237]
	s_nop 0
	v_pk_add_f32 v[50:51], v[50:51], v[238:239]
	ds_read2st64_b64 v[236:239], v92 offset0:10 offset1:11
	s_waitcnt lgkmcnt(0)
	v_pk_add_f32 v[50:51], v[50:51], v[236:237]
	s_nop 0
	v_pk_add_f32 v[50:51], v[50:51], v[238:239]
	ds_read2st64_b64 v[236:239], v92 offset0:12 offset1:13
	s_waitcnt lgkmcnt(0)
	v_pk_add_f32 v[50:51], v[50:51], v[236:237]
	s_nop 0
	v_pk_add_f32 v[50:51], v[50:51], v[238:239]
	ds_read2st64_b64 v[236:239], v92 offset0:14 offset1:15
	s_waitcnt lgkmcnt(0)
	v_pk_add_f32 v[50:51], v[50:51], v[236:237]
	s_nop 0
	v_pk_add_f32 v[240:241], v[50:51], v[238:239]
	v_div_scale_f32 v50, s[50:51], v242, v242, 1.0
	v_rcp_f32_e32 v51, v50
	s_lshl_b64 s[50:51], s[16:17], 20
	v_fma_f32 v236, -v50, v51, 1.0
	v_fmac_f32_e32 v51, v236, v51
	v_div_scale_f32 v236, vcc, 1.0, v242, 1.0
	v_mul_f32_e32 v237, v236, v51
	v_fma_f32 v238, -v50, v237, v236
	v_fmac_f32_e32 v237, v238, v51
	v_fma_f32 v50, -v50, v237, v236
	v_div_fmas_f32 v50, v50, v51, v237
	v_div_fixup_f32 v242, v50, v242, 1.0
	v_mul_f32_e32 v50, v74, v242
	v_lshlrev_b32_e32 v51, 16, v121
	v_and_b32_e32 v236, 0xffff0000, v121
	v_fma_f32 v51, v50, v240, -v51
	v_fma_f32 v50, v50, v241, -v236
	v_cvt_pk_bf16_f32 v236, v51, v50
	v_lshl_add_u64 v[50:51], v[14:15], 0, s[50:51]
	global_store_dword v[50:51], v236, off
	ds_read2st64_b64 v[236:239], v92 offset1:16
	s_waitcnt lgkmcnt(0)
	v_pk_add_f32 v[236:237], v[238:239], v[236:237] neg_lo:[0,1] neg_hi:[0,1]
	s_nop 0
	v_pk_add_f32 v[240:241], v[240:241], v[236:237]
	v_mul_f32_e32 v236, v75, v242
	v_lshlrev_b32_e32 v237, 16, v128
	v_and_b32_e32 v238, 0xffff0000, v128
	v_fma_f32 v237, v236, v240, -v237
	v_fma_f32 v236, v236, v241, -v238
	v_cvt_pk_bf16_f32 v238, v237, v236
	v_add_co_u32_e32 v236, vcc, s54, v50
	s_nop 1
	v_addc_co_u32_e32 v237, vcc, 0, v51, vcc
	global_store_dword v[236:237], v238, off
	ds_read2st64_b64 v[236:239], v92 offset0:1 offset1:17
	s_waitcnt lgkmcnt(0)
; #define GAS __attribute__((address_space(1)))
; __device__ __forceinline__ unsigned cvt_pk_bf16(float lo, float hi) { unsigned r; asm volatile("v_cvt_pk_bf16_f32 %0, %1, %2" : "=v"(r) : "v"(lo), "v"(hi)); return r; }
; __device__ __forceinline__ float bf_lo(unsigned w) { return __uint_as_float(w << 16); }
; __device__ __forceinline__ float bf_hi(unsigned w) { return __uint_as_float(w & 0xffff0000u); }
; template <int W>
; __device__ __forceinline__ void pool_item(const Ctx& F, const bf16* Ub, bf16* Db, int r0, int nr) {
;     ...
;                     for (int j = 0; j < 8; ++j) {
;                         const float ic = icr * icc[j]; const unsigned m = ring[(u + NS - HW + 1) % NS][j];
;                         *(GAS unsigned*)(Db + ((size_t)r * 64 + c0 + j) * EI) = cvt_pk_bf16(h.x * ic - bf_lo(m), h.y * ic - bf_hi(m));
;                         h += row[(c0 + j + HW) * 64] - row[(c0 + j - HW) * 64];
;                     }
; #pragma unroll
;                     for (int j = 0; j < 8; ++j) { const unsigned l = ring[(u + NS - W + 1) % NS][j]; Vv[j].x -= ml * bf_lo(l); Vv[j].y -= ml * bf_hi(l); }
	v_pk_add_f32 v[236:237], v[238:239], v[236:237] neg_lo:[0,1] neg_hi:[0,1]
	s_nop 0
	v_pk_add_f32 v[240:241], v[240:241], v[236:237]
	v_mul_f32_e32 v236, v76, v242
	v_lshlrev_b32_e32 v237, 16, v135
	v_and_b32_e32 v238, 0xffff0000, v135
	v_fma_f32 v237, v236, v240, -v237
	v_fma_f32 v236, v236, v241, -v238
	v_cvt_pk_bf16_f32 v238, v237, v236
	v_add_co_u32_e32 v236, vcc, s55, v50
	s_nop 1
	v_addc_co_u32_e32 v237, vcc, 0, v51, vcc
	global_store_dword v[236:237], v238, off
	ds_read2st64_b64 v[236:239], v92 offset0:2 offset1:18
	s_waitcnt lgkmcnt(0)
	v_pk_add_f32 v[236:237], v[238:239], v[236:237] neg_lo:[0,1] neg_hi:[0,1]
	s_nop 0
	v_pk_add_f32 v[240:241], v[240:241], v[236:237]
	v_mul_f32_e32 v236, v77, v242
	v_lshlrev_b32_e32 v237, 16, v144
	v_and_b32_e32 v238, 0xffff0000, v144
	v_fma_f32 v237, v236, v240, -v237
	v_fma_f32 v236, v236, v241, -v238
	v_cvt_pk_bf16_f32 v238, v237, v236
	v_add_co_u32_e32 v236, vcc, s56, v50
	s_nop 1
	v_addc_co_u32_e32 v237, vcc, 0, v51, vcc
	global_store_dword v[236:237], v238, off
	ds_read2st64_b64 v[236:239], v92 offset0:3 offset1:19
	s_waitcnt lgkmcnt(0)
	v_pk_add_f32 v[236:237], v[238:239], v[236:237] neg_lo:[0,1] neg_hi:[0,1]
	s_nop 0
	v_pk_add_f32 v[240:241], v[240:241], v[236:237]
	v_mul_f32_e32 v236, v78, v242
	v_lshlrev_b32_e32 v237, 16, v152
	v_and_b32_e32 v238, 0xffff0000, v152
	v_fma_f32 v237, v236, v240, -v237
	v_fma_f32 v236, v236, v241, -v238
	v_cvt_pk_bf16_f32 v238, v237, v236
	v_add_co_u32_e32 v236, vcc, s57, v50
	s_nop 1
	v_addc_co_u32_e32 v237, vcc, 0, v51, vcc
	global_store_dword v[236:237], v238, off
	ds_read2st64_b64 v[236:239], v92 offset0:4 offset1:20
	s_waitcnt lgkmcnt(0)
	v_pk_add_f32 v[236:237], v[238:239], v[236:237] neg_lo:[0,1] neg_hi:[0,1]
	s_nop 0
	v_pk_add_f32 v[240:241], v[240:241], v[236:237]
	v_mul_f32_e32 v236, v79, v242
	v_lshlrev_b32_e32 v237, 16, v162
	v_and_b32_e32 v238, 0xffff0000, v162
	v_fma_f32 v237, v236, v240, -v237
	v_fma_f32 v236, v236, v241, -v238
	v_cvt_pk_bf16_f32 v238, v237, v236
	v_add_co_u32_e32 v236, vcc, s58, v50
	s_nop 1
	v_addc_co_u32_e32 v237, vcc, 0, v51, vcc
	global_store_dword v[236:237], v238, off
	ds_read2st64_b64 v[236:239], v92 offset0:5 offset1:21
	s_waitcnt lgkmcnt(0)
	v_pk_add_f32 v[236:237], v[238:239], v[236:237] neg_lo:[0,1] neg_hi:[0,1]
	s_nop 0
	v_pk_add_f32 v[240:241], v[240:241], v[236:237]
	v_mul_f32_e32 v236, v80, v242
	v_lshlrev_b32_e32 v237, 16, v173
	v_and_b32_e32 v238, 0xffff0000, v173
	v_fma_f32 v237, v236, v240, -v237
	v_fma_f32 v236, v236, v241, -v238
	v_cvt_pk_bf16_f32 v238, v237, v236
	v_add_co_u32_e32 v236, vcc, s59, v50
	s_nop 1
	v_addc_co_u32_e32 v237, vcc, 0, v51, vcc
	global_store_dword v[236:237], v238, off
	ds_read2st64_b64 v[236:239], v92 offset0:6 offset1:22
	v_add_co_u32_e32 v50, vcc, s60, v50
	s_waitcnt lgkmcnt(0)
	v_pk_add_f32 v[236:237], v[238:239], v[236:237] neg_lo:[0,1] neg_hi:[0,1]
	s_nop 0
	v_pk_add_f32 v[236:237], v[240:241], v[236:237]
	v_mul_f32_e32 v238, v81, v242
	v_lshlrev_b32_e32 v239, 16, v201
	v_fma_f32 v236, v238, v236, -v239
	v_and_b32_e32 v239, 0xffff0000, v201
	v_addc_co_u32_e32 v51, vcc, 0, v51, vcc
	v_fma_f32 v237, v238, v237, -v239
	v_cvt_pk_bf16_f32 v236, v236, v237
	global_store_dword v[50:51], v236, off
	v_lshlrev_b32_e32 v50, 16, v179
	v_and_b32_e32 v51, 0xffff0000, v179
	v_pk_fma_f32 v[18:19], v[2:3], v[50:51], v[18:19] op_sel_hi:[0,1,1] neg_lo:[1,0,0] neg_hi:[1,0,0]
	v_lshlrev_b32_e32 v50, 16, v184
	v_and_b32_e32 v51, 0xffff0000, v184
	v_pk_fma_f32 v[20:21], v[2:3], v[50:51], v[20:21] op_sel_hi:[0,1,1] neg_lo:[1,0,0] neg_hi:[1,0,0]
	v_lshlrev_b32_e32 v50, 16, v194
	v_and_b32_e32 v51, 0xffff0000, v194
	v_pk_fma_f32 v[22:23], v[2:3], v[50:51], v[22:23] op_sel_hi:[0,1,1] neg_lo:[1,0,0] neg_hi:[1,0,0]
	v_lshlrev_b32_e32 v50, 16, v203
	v_and_b32_e32 v51, 0xffff0000, v203
	v_pk_fma_f32 v[24:25], v[2:3], v[50:51], v[24:25] op_sel_hi:[0,1,1] neg_lo:[1,0,0] neg_hi:[1,0,0]
	v_lshlrev_b32_e32 v50, 16, v209
	v_and_b32_e32 v51, 0xffff0000, v209
	v_pk_fma_f32 v[26:27], v[2:3], v[50:51], v[26:27] op_sel_hi:[0,1,1] neg_lo:[1,0,0] neg_hi:[1,0,0]
	v_lshlrev_b32_e32 v50, 16, v214
	v_and_b32_e32 v51, 0xffff0000, v214
	v_pk_fma_f32 v[28:29], v[2:3], v[50:51], v[28:29] op_sel_hi:[0,1,1] neg_lo:[1,0,0] neg_hi:[1,0,0]
	v_lshlrev_b32_e32 v50, 16, v218
	v_and_b32_e32 v51, 0xffff0000, v218
	v_pk_fma_f32 v[30:31], v[2:3], v[50:51], v[30:31] op_sel_hi:[0,1,1] neg_lo:[1,0,0] neg_hi:[1,0,0]
	v_lshlrev_b32_e32 v50, 16, v224
	v_and_b32_e32 v51, 0xffff0000, v224
	v_pk_fma_f32 v[32:33], v[2:3], v[50:51], v[32:33] op_sel_hi:[0,1,1] neg_lo:[1,0,0] neg_hi:[1,0,0]
; #define GAS __attribute__((address_space(1)))
; #define LAS __attribute__((address_space(3)))
; __device__ __forceinline__ unsigned cvt_pk_bf16(float lo, float hi) { unsigned r; asm volatile("v_cvt_pk_bf16_f32 %0, %1, %2" : "=v"(r) : "v"(lo), "v"(hi)); return r; }
; __device__ __forceinline__ float bf_lo(unsigned w) { return __uint_as_float(w << 16); }
; __device__ __forceinline__ float bf_hi(unsigned w) { return __uint_as_float(w & 0xffff0000u); }
; template <int W>
; __device__ __forceinline__ void pool_item(const Ctx& F, const bf16* Ub, bf16* Db, int r0, int nr) {
;     ...
;         for (int u = 0; u < NS; ++u) {
;             const int r = base + u;
;             if (r < re) {
;                 POOL_LOAD((u + 2) % NS, r + 2);
;                 const int e = r + HW - 1;
;                 const float me = (e >= 0 && e < 128) ? 1.0f : 0.0f, ml = (r >= r0 && r - HW >= 0) ? 1.0f : 0.0f;
; #pragma unroll
;                 for (int j = 0; j < 8; ++j) { Vv[j].x += me * bf_lo(ring[u][j]); Vv[j].y += me * bf_hi(ring[u][j]); }
;                 if (r >= r0) {
;                     LAS f32x2* row = buf + ((r & 1) * 80 + 8) * 64 + lane;
; #pragma unroll
;                     for (int j = 0; j < 8; ++j) row[(c0 + j) * 64] = Vv[j];
;                     asm volatile("s_waitcnt lgkmcnt(0)" ::: "memory"); __builtin_amdgcn_s_barrier(); asm volatile("" ::: "memory");
;                     const int rlo = r - HW > 0 ? r - HW : 0, rhi = r + HW < 128 ? r + HW : 128; const float icr = 1.0f / (float)(rhi - rlo);
;                     f32x2 h = (f32x2){0.f, 0.f};
; #pragma unroll
;                     for (int c = -HW; c < HW; ++c) h += row[(c0 + c) * 64];
; #pragma unroll
;                     for (int j = 0; j < 8; ++j) {
;                         const float ic = icr * icc[j]; const unsigned m = ring[(u + NS - HW + 1) % NS][j];
;                         *(GAS unsigned*)(Db + ((size_t)r * 64 + c0 + j) * EI) = cvt_pk_bf16(h.x * ic - bf_lo(m), h.y * ic - bf_hi(m));
;                         h += row[(c0 + j + HW) * 64] - row[(c0 + j - HW) * 64];
;                     }
; #pragma unroll
;                     for (int j = 0; j < 8; ++j) { const unsigned l = ring[(u + NS - W + 1) % NS][j]; Vv[j].x -= ml * bf_lo(l); Vv[j].y -= ml * bf_hi(l); }
;                 }
.LBB0_837:
	s_add_i32 s16, s42, 2
	s_cmp_ge_i32 s16, s46
	s_cbranch_scc1 .LBB0_840
	v_med3_i32 v2, s16, -9, v93
	v_add_u32_e32 v2, 9, v2
	v_lshlrev_b64 v[50:51], 20, v[2:3]
	v_lshl_add_u64 v[50:51], v[12:13], 0, v[50:51]
	v_add_co_u32_e32 v236, vcc, 0x4000, v50
	global_load_dword v179, v[50:51], off
	s_nop 0
	v_addc_co_u32_e32 v237, vcc, 0, v51, vcc
	global_load_dword v184, v[236:237], off
	v_add_co_u32_e32 v236, vcc, 0x8000, v50
	s_add_i32 s10, s42, 9
	s_nop 0
	v_addc_co_u32_e32 v237, vcc, 0, v51, vcc
	global_load_dword v194, v[236:237], off
	v_add_co_u32_e32 v236, vcc, 0xc000, v50
	s_cmpk_lt_u32 s10, 0x80
	s_nop 0
	v_addc_co_u32_e32 v237, vcc, 0, v51, vcc
	global_load_dword v203, v[236:237], off
	v_add_co_u32_e32 v236, vcc, 0x10000, v50
	s_cselect_b64 s[50:51], -1, 0
	s_nop 0
	v_addc_co_u32_e32 v237, vcc, 0, v51, vcc
	global_load_dword v209, v[236:237], off
	v_add_co_u32_e32 v236, vcc, 0x14000, v50
	v_cndmask_b32_e64 v2, 0, 1.0, s[50:51]
	s_nop 0
	v_addc_co_u32_e32 v237, vcc, 0, v51, vcc
	global_load_dword v214, v[236:237], off
	v_add_co_u32_e32 v236, vcc, 0x18000, v50
	s_cmp_lt_i32 s16, s62
	s_nop 0
	v_addc_co_u32_e32 v237, vcc, 0, v51, vcc
	v_add_co_u32_e32 v50, vcc, 0x1c000, v50
	global_load_dword v218, v[236:237], off
	s_nop 0
	v_addc_co_u32_e32 v51, vcc, 0, v51, vcc
	global_load_dword v224, v[50:51], off
	s_waitcnt vmcnt(23)
	v_lshlrev_b32_e32 v50, 16, v233
	v_and_b32_e32 v51, 0xffff0000, v233
	v_pk_fma_f32 v[18:19], v[2:3], v[50:51], v[18:19] op_sel_hi:[0,1,1]
	s_waitcnt vmcnt(22)
	v_lshlrev_b32_e32 v50, 16, v232
	v_and_b32_e32 v51, 0xffff0000, v232
	v_pk_fma_f32 v[20:21], v[2:3], v[50:51], v[20:21] op_sel_hi:[0,1,1]
	s_waitcnt vmcnt(21)
	v_lshlrev_b32_e32 v50, 16, v231
	v_and_b32_e32 v51, 0xffff0000, v231
	v_pk_fma_f32 v[22:23], v[2:3], v[50:51], v[22:23] op_sel_hi:[0,1,1]
	s_waitcnt vmcnt(20)
	v_lshlrev_b32_e32 v50, 16, v230
	v_and_b32_e32 v51, 0xffff0000, v230
	v_pk_fma_f32 v[24:25], v[2:3], v[50:51], v[24:25] op_sel_hi:[0,1,1]
	s_waitcnt vmcnt(19)
	v_lshlrev_b32_e32 v50, 16, v229
	v_and_b32_e32 v51, 0xffff0000, v229
	v_pk_fma_f32 v[26:27], v[2:3], v[50:51], v[26:27] op_sel_hi:[0,1,1]
	s_waitcnt vmcnt(18)
	v_lshlrev_b32_e32 v50, 16, v228
	v_and_b32_e32 v51, 0xffff0000, v228
	v_pk_fma_f32 v[28:29], v[2:3], v[50:51], v[28:29] op_sel_hi:[0,1,1]
	s_waitcnt vmcnt(17)
	v_lshlrev_b32_e32 v50, 16, v227
	v_and_b32_e32 v51, 0xffff0000, v227
	v_pk_fma_f32 v[30:31], v[2:3], v[50:51], v[30:31] op_sel_hi:[0,1,1]
	s_waitcnt vmcnt(16)
	v_lshlrev_b32_e32 v50, 16, v226
	v_and_b32_e32 v51, 0xffff0000, v226
	v_pk_fma_f32 v[32:33], v[2:3], v[50:51], v[32:33] op_sel_hi:[0,1,1]
	s_cbranch_scc1 .LBB0_840
	ds_write2st64_b64 v92, v[18:19], v[20:21] offset0:88 offset1:89
	ds_write2st64_b64 v92, v[22:23], v[24:25] offset0:90 offset1:91
	ds_write2st64_b64 v92, v[26:27], v[28:29] offset0:92 offset1:93
	ds_write2st64_b64 v92, v[30:31], v[32:33] offset0:94 offset1:95
	s_waitcnt lgkmcnt(0)
	s_barrier
	ds_read2st64_b64 v[236:239], v92 offset0:80 offset1:81
	s_cmp_gt_i32 s42, 5
	s_cselect_b64 s[50:51], -1, 0
	s_max_i32 s10, s16, 8
	s_min_i32 s23, s16, 0x78
	s_waitcnt lgkmcnt(0)
	v_pk_add_f32 v[50:51], v[236:237], 0 op_sel_hi:[1,0]
	s_sub_i32 s10, s23, s10
	v_pk_add_f32 v[50:51], v[50:51], v[238:239]
	ds_read2st64_b64 v[236:239], v92 offset0:82 offset1:83
	s_add_i32 s10, s10, 16
	v_cvt_f32_i32_e32 v242, s10
	v_cndmask_b32_e64 v2, 0, 1.0, s[50:51]
	s_waitcnt lgkmcnt(0)
	v_pk_add_f32 v[50:51], v[50:51], v[236:237]
	s_nop 0
	v_pk_add_f32 v[50:51], v[50:51], v[238:239]
	ds_read2st64_b64 v[236:239], v92 offset0:84 offset1:85
	s_waitcnt lgkmcnt(0)
	v_pk_add_f32 v[50:51], v[50:51], v[236:237]
	s_nop 0
	v_pk_add_f32 v[50:51], v[50:51], v[238:239]
	ds_read2st64_b64 v[236:239], v92 offset0:86 offset1:87
	s_waitcnt lgkmcnt(0)
	v_pk_add_f32 v[50:51], v[50:51], v[236:237]
	s_nop 0
	v_pk_add_f32 v[50:51], v[50:51], v[238:239]
	ds_read2st64_b64 v[236:239], v92 offset0:88 offset1:89
	s_waitcnt lgkmcnt(0)
	v_pk_add_f32 v[50:51], v[50:51], v[236:237]
	s_nop 0
	v_pk_add_f32 v[50:51], v[50:51], v[238:239]
	ds_read2st64_b64 v[236:239], v92 offset0:90 offset1:91
	s_waitcnt lgkmcnt(0)
	v_pk_add_f32 v[50:51], v[50:51], v[236:237]
	s_nop 0
	v_pk_add_f32 v[50:51], v[50:51], v[238:239]
	ds_read2st64_b64 v[236:239], v92 offset0:92 offset1:93
	s_waitcnt lgkmcnt(0)
	v_pk_add_f32 v[50:51], v[50:51], v[236:237]
	s_nop 0
	v_pk_add_f32 v[50:51], v[50:51], v[238:239]
	ds_read2st64_b64 v[236:239], v92 offset0:94 offset1:95
	s_waitcnt lgkmcnt(0)
	v_pk_add_f32 v[50:51], v[50:51], v[236:237]
	s_nop 0
	v_pk_add_f32 v[240:241], v[50:51], v[238:239]
	v_div_scale_f32 v50, s[50:51], v242, v242, 1.0
	v_rcp_f32_e32 v51, v50
	s_lshl_b64 s[50:51], s[16:17], 20
	v_fma_f32 v236, -v50, v51, 1.0
	v_fmac_f32_e32 v51, v236, v51
	v_div_scale_f32 v236, vcc, 1.0, v242, 1.0
	v_mul_f32_e32 v237, v236, v51
	v_fma_f32 v238, -v50, v237, v236
	v_fmac_f32_e32 v237, v238, v51
	v_fma_f32 v50, -v50, v237, v236
	v_div_fmas_f32 v50, v50, v51, v237
	v_div_fixup_f32 v242, v50, v242, 1.0
	v_mul_f32_e32 v50, v74, v242
	v_lshlrev_b32_e32 v51, 16, v116
	v_and_b32_e32 v236, 0xffff0000, v116
	v_fma_f32 v51, v50, v240, -v51
	v_fma_f32 v50, v50, v241, -v236
	v_cvt_pk_bf16_f32 v236, v51, v50
	v_lshl_add_u64 v[50:51], v[14:15], 0, s[50:51]
	global_store_dword v[50:51], v236, off
	ds_read2st64_b64 v[236:239], v92 offset0:80 offset1:96
	s_waitcnt lgkmcnt(0)
	v_pk_add_f32 v[236:237], v[238:239], v[236:237] neg_lo:[0,1] neg_hi:[0,1]
	s_nop 0
	v_pk_add_f32 v[240:241], v[240:241], v[236:237]
	v_mul_f32_e32 v236, v75, v242
	v_lshlrev_b32_e32 v237, 16, v122
	v_and_b32_e32 v238, 0xffff0000, v122
	v_fma_f32 v237, v236, v240, -v237
	v_fma_f32 v236, v236, v241, -v238
	v_cvt_pk_bf16_f32 v238, v237, v236
	v_add_co_u32_e32 v236, vcc, s54, v50
	s_nop 1
	v_addc_co_u32_e32 v237, vcc, 0, v51, vcc
	global_store_dword v[236:237], v238, off
	ds_read2st64_b64 v[236:239], v92 offset0:81 offset1:97
	s_waitcnt lgkmcnt(0)
; #define GAS __attribute__((address_space(1)))
; __device__ __forceinline__ unsigned cvt_pk_bf16(float lo, float hi) { unsigned r; asm volatile("v_cvt_pk_bf16_f32 %0, %1, %2" : "=v"(r) : "v"(lo), "v"(hi)); return r; }
; __device__ __forceinline__ float bf_lo(unsigned w) { return __uint_as_float(w << 16); }
; __device__ __forceinline__ float bf_hi(unsigned w) { return __uint_as_float(w & 0xffff0000u); }
; template <int W>
; __device__ __forceinline__ void pool_item(const Ctx& F, const bf16* Ub, bf16* Db, int r0, int nr) {
;     ...
;                     for (int j = 0; j < 8; ++j) {
;                         const float ic = icr * icc[j]; const unsigned m = ring[(u + NS - HW + 1) % NS][j];
;                         *(GAS unsigned*)(Db + ((size_t)r * 64 + c0 + j) * EI) = cvt_pk_bf16(h.x * ic - bf_lo(m), h.y * ic - bf_hi(m));
;                         h += row[(c0 + j + HW) * 64] - row[(c0 + j - HW) * 64];
;                     }
; #pragma unroll
;                     for (int j = 0; j < 8; ++j) { const unsigned l = ring[(u + NS - W + 1) % NS][j]; Vv[j].x -= ml * bf_lo(l); Vv[j].y -= ml * bf_hi(l); }
	v_pk_add_f32 v[236:237], v[238:239], v[236:237] neg_lo:[0,1] neg_hi:[0,1]
	s_nop 0
	v_pk_add_f32 v[240:241], v[240:241], v[236:237]
	v_mul_f32_e32 v236, v76, v242
	v_lshlrev_b32_e32 v237, 16, v129
	v_and_b32_e32 v238, 0xffff0000, v129
	v_fma_f32 v237, v236, v240, -v237
	v_fma_f32 v236, v236, v241, -v238
	v_cvt_pk_bf16_f32 v238, v237, v236
	v_add_co_u32_e32 v236, vcc, s55, v50
	s_nop 1
	v_addc_co_u32_e32 v237, vcc, 0, v51, vcc
	global_store_dword v[236:237], v238, off
	ds_read2st64_b64 v[236:239], v92 offset0:82 offset1:98
	s_waitcnt lgkmcnt(0)
	v_pk_add_f32 v[236:237], v[238:239], v[236:237] neg_lo:[0,1] neg_hi:[0,1]
	s_nop 0
	v_pk_add_f32 v[240:241], v[240:241], v[236:237]
	v_mul_f32_e32 v236, v77, v242
	v_lshlrev_b32_e32 v237, 16, v136
	v_and_b32_e32 v238, 0xffff0000, v136
	v_fma_f32 v237, v236, v240, -v237
	v_fma_f32 v236, v236, v241, -v238
	v_cvt_pk_bf16_f32 v238, v237, v236
	v_add_co_u32_e32 v236, vcc, s56, v50
	s_nop 1
	v_addc_co_u32_e32 v237, vcc, 0, v51, vcc
	global_store_dword v[236:237], v238, off
	ds_read2st64_b64 v[236:239], v92 offset0:83 offset1:99
	s_waitcnt lgkmcnt(0)
	v_pk_add_f32 v[236:237], v[238:239], v[236:237] neg_lo:[0,1] neg_hi:[0,1]
	s_nop 0
	v_pk_add_f32 v[240:241], v[240:241], v[236:237]
	v_mul_f32_e32 v236, v78, v242
	v_lshlrev_b32_e32 v237, 16, v145
	v_and_b32_e32 v238, 0xffff0000, v145
	v_fma_f32 v237, v236, v240, -v237
	v_fma_f32 v236, v236, v241, -v238
	v_cvt_pk_bf16_f32 v238, v237, v236
	v_add_co_u32_e32 v236, vcc, s57, v50
	s_nop 1
	v_addc_co_u32_e32 v237, vcc, 0, v51, vcc
	global_store_dword v[236:237], v238, off
	ds_read2st64_b64 v[236:239], v92 offset0:84 offset1:100
	s_waitcnt lgkmcnt(0)
	v_pk_add_f32 v[236:237], v[238:239], v[236:237] neg_lo:[0,1] neg_hi:[0,1]
	s_nop 0
	v_pk_add_f32 v[240:241], v[240:241], v[236:237]
	v_mul_f32_e32 v236, v79, v242
	v_lshlrev_b32_e32 v237, 16, v153
	v_and_b32_e32 v238, 0xffff0000, v153
	v_fma_f32 v237, v236, v240, -v237
	v_fma_f32 v236, v236, v241, -v238
	v_cvt_pk_bf16_f32 v238, v237, v236
	v_add_co_u32_e32 v236, vcc, s58, v50
	s_nop 1
	v_addc_co_u32_e32 v237, vcc, 0, v51, vcc
	global_store_dword v[236:237], v238, off
	ds_read2st64_b64 v[236:239], v92 offset0:85 offset1:101
	s_waitcnt lgkmcnt(0)
	v_pk_add_f32 v[236:237], v[238:239], v[236:237] neg_lo:[0,1] neg_hi:[0,1]
	s_nop 0
	v_pk_add_f32 v[240:241], v[240:241], v[236:237]
	v_mul_f32_e32 v236, v80, v242
	v_lshlrev_b32_e32 v237, 16, v164
	v_and_b32_e32 v238, 0xffff0000, v164
	v_fma_f32 v237, v236, v240, -v237
	v_fma_f32 v236, v236, v241, -v238
	v_cvt_pk_bf16_f32 v238, v237, v236
	v_add_co_u32_e32 v236, vcc, s59, v50
	s_nop 1
	v_addc_co_u32_e32 v237, vcc, 0, v51, vcc
	global_store_dword v[236:237], v238, off
	ds_read2st64_b64 v[236:239], v92 offset0:86 offset1:102
	v_add_co_u32_e32 v50, vcc, s60, v50
	s_waitcnt lgkmcnt(0)
	v_pk_add_f32 v[236:237], v[238:239], v[236:237] neg_lo:[0,1] neg_hi:[0,1]
	s_nop 0
	v_pk_add_f32 v[236:237], v[240:241], v[236:237]
	v_mul_f32_e32 v238, v81, v242
	v_lshlrev_b32_e32 v239, 16, v195
	v_fma_f32 v236, v238, v236, -v239
	v_and_b32_e32 v239, 0xffff0000, v195
	v_addc_co_u32_e32 v51, vcc, 0, v51, vcc
	v_fma_f32 v237, v238, v237, -v239
	v_cvt_pk_bf16_f32 v236, v236, v237
	global_store_dword v[50:51], v236, off
	v_lshlrev_b32_e32 v50, 16, v171
	v_and_b32_e32 v51, 0xffff0000, v171
	v_pk_fma_f32 v[18:19], v[2:3], v[50:51], v[18:19] op_sel_hi:[0,1,1] neg_lo:[1,0,0] neg_hi:[1,0,0]
	v_lshlrev_b32_e32 v50, 16, v176
	v_and_b32_e32 v51, 0xffff0000, v176
	v_pk_fma_f32 v[20:21], v[2:3], v[50:51], v[20:21] op_sel_hi:[0,1,1] neg_lo:[1,0,0] neg_hi:[1,0,0]
	v_lshlrev_b32_e32 v50, 16, v186
	v_and_b32_e32 v51, 0xffff0000, v186
	v_pk_fma_f32 v[22:23], v[2:3], v[50:51], v[22:23] op_sel_hi:[0,1,1] neg_lo:[1,0,0] neg_hi:[1,0,0]
	v_lshlrev_b32_e32 v50, 16, v197
	v_and_b32_e32 v51, 0xffff0000, v197
	v_pk_fma_f32 v[24:25], v[2:3], v[50:51], v[24:25] op_sel_hi:[0,1,1] neg_lo:[1,0,0] neg_hi:[1,0,0]
	v_lshlrev_b32_e32 v50, 16, v204
	v_and_b32_e32 v51, 0xffff0000, v204
	v_pk_fma_f32 v[26:27], v[2:3], v[50:51], v[26:27] op_sel_hi:[0,1,1] neg_lo:[1,0,0] neg_hi:[1,0,0]
	v_lshlrev_b32_e32 v50, 16, v210
	v_and_b32_e32 v51, 0xffff0000, v210
	v_pk_fma_f32 v[28:29], v[2:3], v[50:51], v[28:29] op_sel_hi:[0,1,1] neg_lo:[1,0,0] neg_hi:[1,0,0]
	v_lshlrev_b32_e32 v50, 16, v215
	v_and_b32_e32 v51, 0xffff0000, v215
	v_pk_fma_f32 v[30:31], v[2:3], v[50:51], v[30:31] op_sel_hi:[0,1,1] neg_lo:[1,0,0] neg_hi:[1,0,0]
	v_lshlrev_b32_e32 v50, 16, v223
	v_and_b32_e32 v51, 0xffff0000, v223
	v_pk_fma_f32 v[32:33], v[2:3], v[50:51], v[32:33] op_sel_hi:[0,1,1] neg_lo:[1,0,0] neg_hi:[1,0,0]
; #define GAS __attribute__((address_space(1)))
; #define LAS __attribute__((address_space(3)))
; __device__ __forceinline__ unsigned cvt_pk_bf16(float lo, float hi) { unsigned r; asm volatile("v_cvt_pk_bf16_f32 %0, %1, %2" : "=v"(r) : "v"(lo), "v"(hi)); return r; }
; __device__ __forceinline__ float bf_lo(unsigned w) { return __uint_as_float(w << 16); }
; __device__ __forceinline__ float bf_hi(unsigned w) { return __uint_as_float(w & 0xffff0000u); }
; template <int W>
; __device__ __forceinline__ void pool_item(const Ctx& F, const bf16* Ub, bf16* Db, int r0, int nr) {
;     ...
;         for (int u = 0; u < NS; ++u) {
;             const int r = base + u;
;             if (r < re) {
;                 POOL_LOAD((u + 2) % NS, r + 2);
;                 const int e = r + HW - 1;
;                 const float me = (e >= 0 && e < 128) ? 1.0f : 0.0f, ml = (r >= r0 && r - HW >= 0) ? 1.0f : 0.0f;
; #pragma unroll
;                 for (int j = 0; j < 8; ++j) { Vv[j].x += me * bf_lo(ring[u][j]); Vv[j].y += me * bf_hi(ring[u][j]); }
;                 if (r >= r0) {
;                     LAS f32x2* row = buf + ((r & 1) * 80 + 8) * 64 + lane;
; #pragma unroll
;                     for (int j = 0; j < 8; ++j) row[(c0 + j) * 64] = Vv[j];
;                     asm volatile("s_waitcnt lgkmcnt(0)" ::: "memory"); __builtin_amdgcn_s_barrier(); asm volatile("" ::: "memory");
;                     const int rlo = r - HW > 0 ? r - HW : 0, rhi = r + HW < 128 ? r + HW : 128; const float icr = 1.0f / (float)(rhi - rlo);
;                     f32x2 h = (f32x2){0.f, 0.f};
; #pragma unroll
;                     for (int c = -HW; c < HW; ++c) h += row[(c0 + c) * 64];
; #pragma unroll
;                     for (int j = 0; j < 8; ++j) {
;                         const float ic = icr * icc[j]; const unsigned m = ring[(u + NS - HW + 1) % NS][j];
;                         *(GAS unsigned*)(Db + ((size_t)r * 64 + c0 + j) * EI) = cvt_pk_bf16(h.x * ic - bf_lo(m), h.y * ic - bf_hi(m));
;                         h += row[(c0 + j + HW) * 64] - row[(c0 + j - HW) * 64];
;                     }
; #pragma unroll
;                     for (int j = 0; j < 8; ++j) { const unsigned l = ring[(u + NS - W + 1) % NS][j]; Vv[j].x -= ml * bf_lo(l); Vv[j].y -= ml * bf_hi(l); }
;                 }
.LBB0_840:
	s_add_i32 s16, s42, 3
	s_cmp_ge_i32 s16, s46
	s_cbranch_scc1 .LBB0_843
	v_med3_i32 v2, s16, -9, v93
	v_add_u32_e32 v2, 9, v2
	v_lshlrev_b64 v[50:51], 20, v[2:3]
	v_lshl_add_u64 v[50:51], v[12:13], 0, v[50:51]
	v_add_co_u32_e32 v236, vcc, 0x4000, v50
	global_load_dword v171, v[50:51], off
	s_nop 0
	v_addc_co_u32_e32 v237, vcc, 0, v51, vcc
	global_load_dword v176, v[236:237], off
	v_add_co_u32_e32 v236, vcc, 0x8000, v50
	s_add_i32 s10, s42, 10
	s_nop 0
	v_addc_co_u32_e32 v237, vcc, 0, v51, vcc
	global_load_dword v186, v[236:237], off
	v_add_co_u32_e32 v236, vcc, 0xc000, v50
	s_cmpk_lt_u32 s10, 0x80
	s_nop 0
	v_addc_co_u32_e32 v237, vcc, 0, v51, vcc
	global_load_dword v197, v[236:237], off
	v_add_co_u32_e32 v236, vcc, 0x10000, v50
	s_cselect_b64 s[50:51], -1, 0
	s_nop 0
	v_addc_co_u32_e32 v237, vcc, 0, v51, vcc
	global_load_dword v204, v[236:237], off
	v_add_co_u32_e32 v236, vcc, 0x14000, v50
	v_cndmask_b32_e64 v2, 0, 1.0, s[50:51]
	s_nop 0
	v_addc_co_u32_e32 v237, vcc, 0, v51, vcc
	global_load_dword v210, v[236:237], off
	v_add_co_u32_e32 v236, vcc, 0x18000, v50
	s_cmp_lt_i32 s16, s62
	s_nop 0
	v_addc_co_u32_e32 v237, vcc, 0, v51, vcc
	v_add_co_u32_e32 v50, vcc, 0x1c000, v50
	global_load_dword v215, v[236:237], off
	s_nop 0
	v_addc_co_u32_e32 v51, vcc, 0, v51, vcc
	global_load_dword v223, v[50:51], off
	s_waitcnt vmcnt(23)
	v_lshlrev_b32_e32 v50, 16, v187
	v_and_b32_e32 v51, 0xffff0000, v187
	v_pk_fma_f32 v[18:19], v[2:3], v[50:51], v[18:19] op_sel_hi:[0,1,1]
	s_waitcnt vmcnt(22)
	v_lshlrev_b32_e32 v50, 16, v192
	v_and_b32_e32 v51, 0xffff0000, v192
	v_pk_fma_f32 v[20:21], v[2:3], v[50:51], v[20:21] op_sel_hi:[0,1,1]
	s_waitcnt vmcnt(21)
	v_lshlrev_b32_e32 v50, 16, v200
	v_and_b32_e32 v51, 0xffff0000, v200
	v_pk_fma_f32 v[22:23], v[2:3], v[50:51], v[22:23] op_sel_hi:[0,1,1]
	s_waitcnt vmcnt(20)
	v_lshlrev_b32_e32 v50, 16, v208
	v_and_b32_e32 v51, 0xffff0000, v208
	v_pk_fma_f32 v[24:25], v[2:3], v[50:51], v[24:25] op_sel_hi:[0,1,1]
	s_waitcnt vmcnt(19)
	v_lshlrev_b32_e32 v50, 16, v213
	v_and_b32_e32 v51, 0xffff0000, v213
	v_pk_fma_f32 v[26:27], v[2:3], v[50:51], v[26:27] op_sel_hi:[0,1,1]
	s_waitcnt vmcnt(18)
	v_lshlrev_b32_e32 v50, 16, v217
	v_and_b32_e32 v51, 0xffff0000, v217
	v_pk_fma_f32 v[28:29], v[2:3], v[50:51], v[28:29] op_sel_hi:[0,1,1]
	s_waitcnt vmcnt(17)
	v_lshlrev_b32_e32 v50, 16, v221
	v_and_b32_e32 v51, 0xffff0000, v221
	v_pk_fma_f32 v[30:31], v[2:3], v[50:51], v[30:31] op_sel_hi:[0,1,1]
	s_waitcnt vmcnt(16)
	v_lshlrev_b32_e32 v50, 16, v225
	v_and_b32_e32 v51, 0xffff0000, v225
	v_pk_fma_f32 v[32:33], v[2:3], v[50:51], v[32:33] op_sel_hi:[0,1,1]
	s_cbranch_scc1 .LBB0_843
	ds_write2st64_b64 v92, v[18:19], v[20:21] offset0:8 offset1:9
	ds_write2st64_b64 v92, v[22:23], v[24:25] offset0:10 offset1:11
	ds_write2st64_b64 v92, v[26:27], v[28:29] offset0:12 offset1:13
	ds_write2st64_b64 v92, v[30:31], v[32:33] offset0:14 offset1:15
	s_waitcnt lgkmcnt(0)
	s_barrier
	ds_read2st64_b64 v[236:239], v92 offset1:1
	s_cmp_gt_i32 s42, 4
	s_cselect_b64 s[50:51], -1, 0
	s_max_i32 s10, s16, 8
	s_min_i32 s23, s16, 0x78
	s_waitcnt lgkmcnt(0)
	v_pk_add_f32 v[50:51], v[236:237], 0 op_sel_hi:[1,0]
	s_sub_i32 s10, s23, s10
	v_pk_add_f32 v[50:51], v[50:51], v[238:239]
	ds_read2st64_b64 v[236:239], v92 offset0:2 offset1:3
	s_add_i32 s10, s10, 16
	v_cvt_f32_i32_e32 v242, s10
	v_cndmask_b32_e64 v2, 0, 1.0, s[50:51]
	s_waitcnt lgkmcnt(0)
	v_pk_add_f32 v[50:51], v[50:51], v[236:237]
	s_nop 0
	v_pk_add_f32 v[50:51], v[50:51], v[238:239]
	ds_read2st64_b64 v[236:239], v92 offset0:4 offset1:5
	s_waitcnt lgkmcnt(0)
	v_pk_add_f32 v[50:51], v[50:51], v[236:237]
	s_nop 0
	v_pk_add_f32 v[50:51], v[50:51], v[238:239]
	ds_read2st64_b64 v[236:239], v92 offset0:6 offset1:7
	s_waitcnt lgkmcnt(0)
	v_pk_add_f32 v[50:51], v[50:51], v[236:237]
	s_nop 0
	v_pk_add_f32 v[50:51], v[50:51], v[238:239]
	ds_read2st64_b64 v[236:239], v92 offset0:8 offset1:9
	s_waitcnt lgkmcnt(0)
	v_pk_add_f32 v[50:51], v[50:51], v[236:237]
	s_nop 0
	v_pk_add_f32 v[50:51], v[50:51], v[238:239]
	ds_read2st64_b64 v[236:239], v92 offset0:10 offset1:11
	s_waitcnt lgkmcnt(0)
	v_pk_add_f32 v[50:51], v[50:51], v[236:237]
	s_nop 0
	v_pk_add_f32 v[50:51], v[50:51], v[238:239]
	ds_read2st64_b64 v[236:239], v92 offset0:12 offset1:13
	s_waitcnt lgkmcnt(0)
	v_pk_add_f32 v[50:51], v[50:51], v[236:237]
	s_nop 0
	v_pk_add_f32 v[50:51], v[50:51], v[238:239]
	ds_read2st64_b64 v[236:239], v92 offset0:14 offset1:15
	s_waitcnt lgkmcnt(0)
	v_pk_add_f32 v[50:51], v[50:51], v[236:237]
	s_nop 0
	v_pk_add_f32 v[240:241], v[50:51], v[238:239]
	v_div_scale_f32 v50, s[50:51], v242, v242, 1.0
	v_rcp_f32_e32 v51, v50
	s_lshl_b64 s[50:51], s[16:17], 20
	v_fma_f32 v236, -v50, v51, 1.0
	v_fmac_f32_e32 v51, v236, v51
	v_div_scale_f32 v236, vcc, 1.0, v242, 1.0
	v_mul_f32_e32 v237, v236, v51
	v_fma_f32 v238, -v50, v237, v236
	v_fmac_f32_e32 v237, v238, v51
	v_fma_f32 v50, -v50, v237, v236
	v_div_fmas_f32 v50, v50, v51, v237
	v_div_fixup_f32 v242, v50, v242, 1.0
	v_mul_f32_e32 v50, v74, v242
	v_lshlrev_b32_e32 v51, 16, v111
	v_and_b32_e32 v236, 0xffff0000, v111
	v_fma_f32 v51, v50, v240, -v51
	v_fma_f32 v50, v50, v241, -v236
	v_cvt_pk_bf16_f32 v236, v51, v50
	v_lshl_add_u64 v[50:51], v[14:15], 0, s[50:51]
	global_store_dword v[50:51], v236, off
	ds_read2st64_b64 v[236:239], v92 offset1:16
	s_waitcnt lgkmcnt(0)
	v_pk_add_f32 v[236:237], v[238:239], v[236:237] neg_lo:[0,1] neg_hi:[0,1]
	s_nop 0
	v_pk_add_f32 v[240:241], v[240:241], v[236:237]
	v_mul_f32_e32 v236, v75, v242
	v_lshlrev_b32_e32 v237, 16, v117
	v_and_b32_e32 v238, 0xffff0000, v117
	v_fma_f32 v237, v236, v240, -v237
	v_fma_f32 v236, v236, v241, -v238
	v_cvt_pk_bf16_f32 v238, v237, v236
	v_add_co_u32_e32 v236, vcc, s54, v50
	s_nop 1
	v_addc_co_u32_e32 v237, vcc, 0, v51, vcc
	global_store_dword v[236:237], v238, off
	ds_read2st64_b64 v[236:239], v92 offset0:1 offset1:17
	s_waitcnt lgkmcnt(0)
; #define GAS __attribute__((address_space(1)))
; __device__ __forceinline__ unsigned cvt_pk_bf16(float lo, float hi) { unsigned r; asm volatile("v_cvt_pk_bf16_f32 %0, %1, %2" : "=v"(r) : "v"(lo), "v"(hi)); return r; }
; __device__ __forceinline__ float bf_lo(unsigned w) { return __uint_as_float(w << 16); }
; __device__ __forceinline__ float bf_hi(unsigned w) { return __uint_as_float(w & 0xffff0000u); }
; template <int W>
; __device__ __forceinline__ void pool_item(const Ctx& F, const bf16* Ub, bf16* Db, int r0, int nr) {
;     ...
;                     for (int j = 0; j < 8; ++j) {
;                         const float ic = icr * icc[j]; const unsigned m = ring[(u + NS - HW + 1) % NS][j];
;                         *(GAS unsigned*)(Db + ((size_t)r * 64 + c0 + j) * EI) = cvt_pk_bf16(h.x * ic - bf_lo(m), h.y * ic - bf_hi(m));
;                         h += row[(c0 + j + HW) * 64] - row[(c0 + j - HW) * 64];
;                     }
; #pragma unroll
;                     for (int j = 0; j < 8; ++j) { const unsigned l = ring[(u + NS - W + 1) % NS][j]; Vv[j].x -= ml * bf_lo(l); Vv[j].y -= ml * bf_hi(l); }
	v_pk_add_f32 v[236:237], v[238:239], v[236:237] neg_lo:[0,1] neg_hi:[0,1]
	s_nop 0
	v_pk_add_f32 v[240:241], v[240:241], v[236:237]
	v_mul_f32_e32 v236, v76, v242
	v_lshlrev_b32_e32 v237, 16, v123
	v_and_b32_e32 v238, 0xffff0000, v123
	v_fma_f32 v237, v236, v240, -v237
	v_fma_f32 v236, v236, v241, -v238
	v_cvt_pk_bf16_f32 v238, v237, v236
	v_add_co_u32_e32 v236, vcc, s55, v50
	s_nop 1
	v_addc_co_u32_e32 v237, vcc, 0, v51, vcc
	global_store_dword v[236:237], v238, off
	ds_read2st64_b64 v[236:239], v92 offset0:2 offset1:18
	s_waitcnt lgkmcnt(0)
	v_pk_add_f32 v[236:237], v[238:239], v[236:237] neg_lo:[0,1] neg_hi:[0,1]
	s_nop 0
	v_pk_add_f32 v[240:241], v[240:241], v[236:237]
	v_mul_f32_e32 v236, v77, v242
	v_lshlrev_b32_e32 v237, 16, v130
	v_and_b32_e32 v238, 0xffff0000, v130
	v_fma_f32 v237, v236, v240, -v237
	v_fma_f32 v236, v236, v241, -v238
	v_cvt_pk_bf16_f32 v238, v237, v236
	v_add_co_u32_e32 v236, vcc, s56, v50
	s_nop 1
	v_addc_co_u32_e32 v237, vcc, 0, v51, vcc
	global_store_dword v[236:237], v238, off
	ds_read2st64_b64 v[236:239], v92 offset0:3 offset1:19
	s_waitcnt lgkmcnt(0)
	v_pk_add_f32 v[236:237], v[238:239], v[236:237] neg_lo:[0,1] neg_hi:[0,1]
	s_nop 0
	v_pk_add_f32 v[240:241], v[240:241], v[236:237]
	v_mul_f32_e32 v236, v78, v242
	v_lshlrev_b32_e32 v237, 16, v137
	v_and_b32_e32 v238, 0xffff0000, v137
	v_fma_f32 v237, v236, v240, -v237
	v_fma_f32 v236, v236, v241, -v238
	v_cvt_pk_bf16_f32 v238, v237, v236
	v_add_co_u32_e32 v236, vcc, s57, v50
	s_nop 1
	v_addc_co_u32_e32 v237, vcc, 0, v51, vcc
	global_store_dword v[236:237], v238, off
	ds_read2st64_b64 v[236:239], v92 offset0:4 offset1:20
	s_waitcnt lgkmcnt(0)
	v_pk_add_f32 v[236:237], v[238:239], v[236:237] neg_lo:[0,1] neg_hi:[0,1]
	s_nop 0
	v_pk_add_f32 v[240:241], v[240:241], v[236:237]
	v_mul_f32_e32 v236, v79, v242
	v_lshlrev_b32_e32 v237, 16, v146
	v_and_b32_e32 v238, 0xffff0000, v146
	v_fma_f32 v237, v236, v240, -v237
	v_fma_f32 v236, v236, v241, -v238
	v_cvt_pk_bf16_f32 v238, v237, v236
	v_add_co_u32_e32 v236, vcc, s58, v50
	s_nop 1
	v_addc_co_u32_e32 v237, vcc, 0, v51, vcc
	global_store_dword v[236:237], v238, off
	ds_read2st64_b64 v[236:239], v92 offset0:5 offset1:21
	s_waitcnt lgkmcnt(0)
	v_pk_add_f32 v[236:237], v[238:239], v[236:237] neg_lo:[0,1] neg_hi:[0,1]
	s_nop 0
	v_pk_add_f32 v[240:241], v[240:241], v[236:237]
	v_mul_f32_e32 v236, v80, v242
	v_lshlrev_b32_e32 v237, 16, v155
	v_and_b32_e32 v238, 0xffff0000, v155
	v_fma_f32 v237, v236, v240, -v237
	v_fma_f32 v236, v236, v241, -v238
	v_cvt_pk_bf16_f32 v238, v237, v236
	v_add_co_u32_e32 v236, vcc, s59, v50
	s_nop 1
	v_addc_co_u32_e32 v237, vcc, 0, v51, vcc
	global_store_dword v[236:237], v238, off
	ds_read2st64_b64 v[236:239], v92 offset0:6 offset1:22
	v_add_co_u32_e32 v50, vcc, s60, v50
	s_waitcnt lgkmcnt(0)
	v_pk_add_f32 v[236:237], v[238:239], v[236:237] neg_lo:[0,1] neg_hi:[0,1]
	s_nop 0
	v_pk_add_f32 v[236:237], v[240:241], v[236:237]
	v_mul_f32_e32 v238, v81, v242
	v_lshlrev_b32_e32 v239, 16, v188
	v_fma_f32 v236, v238, v236, -v239
	v_and_b32_e32 v239, 0xffff0000, v188
	v_addc_co_u32_e32 v51, vcc, 0, v51, vcc
	v_fma_f32 v237, v238, v237, -v239
	v_cvt_pk_bf16_f32 v236, v236, v237
	global_store_dword v[50:51], v236, off
	v_lshlrev_b32_e32 v50, 16, v163
	v_and_b32_e32 v51, 0xffff0000, v163
	v_pk_fma_f32 v[18:19], v[2:3], v[50:51], v[18:19] op_sel_hi:[0,1,1] neg_lo:[1,0,0] neg_hi:[1,0,0]
	v_lshlrev_b32_e32 v50, 16, v168
	v_and_b32_e32 v51, 0xffff0000, v168
	v_pk_fma_f32 v[20:21], v[2:3], v[50:51], v[20:21] op_sel_hi:[0,1,1] neg_lo:[1,0,0] neg_hi:[1,0,0]
	v_lshlrev_b32_e32 v50, 16, v178
	v_and_b32_e32 v51, 0xffff0000, v178
	v_pk_fma_f32 v[22:23], v[2:3], v[50:51], v[22:23] op_sel_hi:[0,1,1] neg_lo:[1,0,0] neg_hi:[1,0,0]
	v_lshlrev_b32_e32 v50, 16, v190
	v_and_b32_e32 v51, 0xffff0000, v190
	v_pk_fma_f32 v[24:25], v[2:3], v[50:51], v[24:25] op_sel_hi:[0,1,1] neg_lo:[1,0,0] neg_hi:[1,0,0]
	v_lshlrev_b32_e32 v50, 16, v198
	v_and_b32_e32 v51, 0xffff0000, v198
	v_pk_fma_f32 v[26:27], v[2:3], v[50:51], v[26:27] op_sel_hi:[0,1,1] neg_lo:[1,0,0] neg_hi:[1,0,0]
	v_lshlrev_b32_e32 v50, 16, v205
	v_and_b32_e32 v51, 0xffff0000, v205
	v_pk_fma_f32 v[28:29], v[2:3], v[50:51], v[28:29] op_sel_hi:[0,1,1] neg_lo:[1,0,0] neg_hi:[1,0,0]
	v_lshlrev_b32_e32 v50, 16, v211
	v_and_b32_e32 v51, 0xffff0000, v211
	v_pk_fma_f32 v[30:31], v[2:3], v[50:51], v[30:31] op_sel_hi:[0,1,1] neg_lo:[1,0,0] neg_hi:[1,0,0]
	v_lshlrev_b32_e32 v50, 16, v222
	v_and_b32_e32 v51, 0xffff0000, v222
	v_pk_fma_f32 v[32:33], v[2:3], v[50:51], v[32:33] op_sel_hi:[0,1,1] neg_lo:[1,0,0] neg_hi:[1,0,0]
; #define GAS __attribute__((address_space(1)))
; #define LAS __attribute__((address_space(3)))
; __device__ __forceinline__ unsigned cvt_pk_bf16(float lo, float hi) { unsigned r; asm volatile("v_cvt_pk_bf16_f32 %0, %1, %2" : "=v"(r) : "v"(lo), "v"(hi)); return r; }
; __device__ __forceinline__ float bf_lo(unsigned w) { return __uint_as_float(w << 16); }
; __device__ __forceinline__ float bf_hi(unsigned w) { return __uint_as_float(w & 0xffff0000u); }
; template <int W>
; __device__ __forceinline__ void pool_item(const Ctx& F, const bf16* Ub, bf16* Db, int r0, int nr) {
;     ...
;         for (int u = 0; u < NS; ++u) {
;             const int r = base + u;
;             if (r < re) {
;                 POOL_LOAD((u + 2) % NS, r + 2);
;                 const int e = r + HW - 1;
;                 const float me = (e >= 0 && e < 128) ? 1.0f : 0.0f, ml = (r >= r0 && r - HW >= 0) ? 1.0f : 0.0f;
; #pragma unroll
;                 for (int j = 0; j < 8; ++j) { Vv[j].x += me * bf_lo(ring[u][j]); Vv[j].y += me * bf_hi(ring[u][j]); }
;                 if (r >= r0) {
;                     LAS f32x2* row = buf + ((r & 1) * 80 + 8) * 64 + lane;
; #pragma unroll
;                     for (int j = 0; j < 8; ++j) row[(c0 + j) * 64] = Vv[j];
;                     asm volatile("s_waitcnt lgkmcnt(0)" ::: "memory"); __builtin_amdgcn_s_barrier(); asm volatile("" ::: "memory");
;                     const int rlo = r - HW > 0 ? r - HW : 0, rhi = r + HW < 128 ? r + HW : 128; const float icr = 1.0f / (float)(rhi - rlo);
;                     f32x2 h = (f32x2){0.f, 0.f};
; #pragma unroll
;                     for (int c = -HW; c < HW; ++c) h += row[(c0 + c) * 64];
; #pragma unroll
;                     for (int j = 0; j < 8; ++j) {
;                         const float ic = icr * icc[j]; const unsigned m = ring[(u + NS - HW + 1) % NS][j];
;                         *(GAS unsigned*)(Db + ((size_t)r * 64 + c0 + j) * EI) = cvt_pk_bf16(h.x * ic - bf_lo(m), h.y * ic - bf_hi(m));
;                         h += row[(c0 + j + HW) * 64] - row[(c0 + j - HW) * 64];
;                     }
; #pragma unroll
;                     for (int j = 0; j < 8; ++j) { const unsigned l = ring[(u + NS - W + 1) % NS][j]; Vv[j].x -= ml * bf_lo(l); Vv[j].y -= ml * bf_hi(l); }
;                 }
.LBB0_843:
	s_add_i32 s16, s42, 4
	s_cmp_ge_i32 s16, s46
	s_cbranch_scc1 .LBB0_846
	v_med3_i32 v2, s16, -9, v93
	v_add_u32_e32 v2, 9, v2
	v_lshlrev_b64 v[50:51], 20, v[2:3]
	v_lshl_add_u64 v[50:51], v[12:13], 0, v[50:51]
	v_add_co_u32_e32 v236, vcc, 0x4000, v50
	global_load_dword v163, v[50:51], off
	s_nop 0
	v_addc_co_u32_e32 v237, vcc, 0, v51, vcc
	global_load_dword v168, v[236:237], off
	v_add_co_u32_e32 v236, vcc, 0x8000, v50
	s_add_i32 s10, s42, 11
	s_nop 0
	v_addc_co_u32_e32 v237, vcc, 0, v51, vcc
	global_load_dword v178, v[236:237], off
	v_add_co_u32_e32 v236, vcc, 0xc000, v50
	s_cmpk_lt_u32 s10, 0x80
	s_nop 0
	v_addc_co_u32_e32 v237, vcc, 0, v51, vcc
	global_load_dword v190, v[236:237], off
	v_add_co_u32_e32 v236, vcc, 0x10000, v50
	s_cselect_b64 s[50:51], -1, 0
	s_nop 0
	v_addc_co_u32_e32 v237, vcc, 0, v51, vcc
	global_load_dword v198, v[236:237], off
	v_add_co_u32_e32 v236, vcc, 0x14000, v50
	v_cndmask_b32_e64 v2, 0, 1.0, s[50:51]
	s_nop 0
	v_addc_co_u32_e32 v237, vcc, 0, v51, vcc
	global_load_dword v205, v[236:237], off
	v_add_co_u32_e32 v236, vcc, 0x18000, v50
	s_cmp_lt_i32 s16, s62
	s_nop 0
	v_addc_co_u32_e32 v237, vcc, 0, v51, vcc
	v_add_co_u32_e32 v50, vcc, 0x1c000, v50
	global_load_dword v211, v[236:237], off
	s_nop 0
	v_addc_co_u32_e32 v51, vcc, 0, v51, vcc
	global_load_dword v222, v[50:51], off
	s_waitcnt vmcnt(23)
	v_lshlrev_b32_e32 v50, 16, v179
	v_and_b32_e32 v51, 0xffff0000, v179
	v_pk_fma_f32 v[18:19], v[2:3], v[50:51], v[18:19] op_sel_hi:[0,1,1]
	s_waitcnt vmcnt(22)
	v_lshlrev_b32_e32 v50, 16, v184
	v_and_b32_e32 v51, 0xffff0000, v184
	v_pk_fma_f32 v[20:21], v[2:3], v[50:51], v[20:21] op_sel_hi:[0,1,1]
	s_waitcnt vmcnt(21)
	v_lshlrev_b32_e32 v50, 16, v194
	v_and_b32_e32 v51, 0xffff0000, v194
	v_pk_fma_f32 v[22:23], v[2:3], v[50:51], v[22:23] op_sel_hi:[0,1,1]
	s_waitcnt vmcnt(20)
	v_lshlrev_b32_e32 v50, 16, v203
	v_and_b32_e32 v51, 0xffff0000, v203
	v_pk_fma_f32 v[24:25], v[2:3], v[50:51], v[24:25] op_sel_hi:[0,1,1]
	s_waitcnt vmcnt(19)
	v_lshlrev_b32_e32 v50, 16, v209
	v_and_b32_e32 v51, 0xffff0000, v209
	v_pk_fma_f32 v[26:27], v[2:3], v[50:51], v[26:27] op_sel_hi:[0,1,1]
	s_waitcnt vmcnt(18)
	v_lshlrev_b32_e32 v50, 16, v214
	v_and_b32_e32 v51, 0xffff0000, v214
	v_pk_fma_f32 v[28:29], v[2:3], v[50:51], v[28:29] op_sel_hi:[0,1,1]
	s_waitcnt vmcnt(17)
	v_lshlrev_b32_e32 v50, 16, v218
	v_and_b32_e32 v51, 0xffff0000, v218
	v_pk_fma_f32 v[30:31], v[2:3], v[50:51], v[30:31] op_sel_hi:[0,1,1]
	s_waitcnt vmcnt(16)
	v_lshlrev_b32_e32 v50, 16, v224
	v_and_b32_e32 v51, 0xffff0000, v224
	v_pk_fma_f32 v[32:33], v[2:3], v[50:51], v[32:33] op_sel_hi:[0,1,1]
	s_cbranch_scc1 .LBB0_846
	ds_write2st64_b64 v92, v[18:19], v[20:21] offset0:88 offset1:89
	ds_write2st64_b64 v92, v[22:23], v[24:25] offset0:90 offset1:91
	ds_write2st64_b64 v92, v[26:27], v[28:29] offset0:92 offset1:93
	ds_write2st64_b64 v92, v[30:31], v[32:33] offset0:94 offset1:95
	s_waitcnt lgkmcnt(0)
	s_barrier
	ds_read2st64_b64 v[236:239], v92 offset0:80 offset1:81
	s_cmp_gt_i32 s42, 3
	s_cselect_b64 s[50:51], -1, 0
	s_max_i32 s10, s16, 8
	s_min_i32 s23, s16, 0x78
	s_waitcnt lgkmcnt(0)
	v_pk_add_f32 v[50:51], v[236:237], 0 op_sel_hi:[1,0]
	s_sub_i32 s10, s23, s10
	v_pk_add_f32 v[50:51], v[50:51], v[238:239]
	ds_read2st64_b64 v[236:239], v92 offset0:82 offset1:83
	s_add_i32 s10, s10, 16
	v_cvt_f32_i32_e32 v242, s10
	v_cndmask_b32_e64 v2, 0, 1.0, s[50:51]
	s_waitcnt lgkmcnt(0)
	v_pk_add_f32 v[50:51], v[50:51], v[236:237]
	s_nop 0
	v_pk_add_f32 v[50:51], v[50:51], v[238:239]
	ds_read2st64_b64 v[236:239], v92 offset0:84 offset1:85
	s_waitcnt lgkmcnt(0)
	v_pk_add_f32 v[50:51], v[50:51], v[236:237]
	s_nop 0
	v_pk_add_f32 v[50:51], v[50:51], v[238:239]
	ds_read2st64_b64 v[236:239], v92 offset0:86 offset1:87
	s_waitcnt lgkmcnt(0)
	v_pk_add_f32 v[50:51], v[50:51], v[236:237]
	s_nop 0
	v_pk_add_f32 v[50:51], v[50:51], v[238:239]
	ds_read2st64_b64 v[236:239], v92 offset0:88 offset1:89
	s_waitcnt lgkmcnt(0)
	v_pk_add_f32 v[50:51], v[50:51], v[236:237]
	s_nop 0
	v_pk_add_f32 v[50:51], v[50:51], v[238:239]
	ds_read2st64_b64 v[236:239], v92 offset0:90 offset1:91
	s_waitcnt lgkmcnt(0)
	v_pk_add_f32 v[50:51], v[50:51], v[236:237]
	s_nop 0
	v_pk_add_f32 v[50:51], v[50:51], v[238:239]
	ds_read2st64_b64 v[236:239], v92 offset0:92 offset1:93
	s_waitcnt lgkmcnt(0)
	v_pk_add_f32 v[50:51], v[50:51], v[236:237]
	s_nop 0
	v_pk_add_f32 v[50:51], v[50:51], v[238:239]
	ds_read2st64_b64 v[236:239], v92 offset0:94 offset1:95
	s_waitcnt lgkmcnt(0)
	v_pk_add_f32 v[50:51], v[50:51], v[236:237]
	s_nop 0
	v_pk_add_f32 v[240:241], v[50:51], v[238:239]
	v_div_scale_f32 v50, s[50:51], v242, v242, 1.0
	v_rcp_f32_e32 v51, v50
	s_lshl_b64 s[50:51], s[16:17], 20
	v_fma_f32 v236, -v50, v51, 1.0
	v_fmac_f32_e32 v51, v236, v51
	v_div_scale_f32 v236, vcc, 1.0, v242, 1.0
	v_mul_f32_e32 v237, v236, v51
	v_fma_f32 v238, -v50, v237, v236
	v_fmac_f32_e32 v237, v238, v51
	v_fma_f32 v50, -v50, v237, v236
	v_div_fmas_f32 v50, v50, v51, v237
	v_div_fixup_f32 v242, v50, v242, 1.0
	v_mul_f32_e32 v50, v74, v242
	v_lshlrev_b32_e32 v51, 16, v107
	v_and_b32_e32 v236, 0xffff0000, v107
	v_fma_f32 v51, v50, v240, -v51
	v_fma_f32 v50, v50, v241, -v236
	v_cvt_pk_bf16_f32 v236, v51, v50
	v_lshl_add_u64 v[50:51], v[14:15], 0, s[50:51]
	global_store_dword v[50:51], v236, off
	ds_read2st64_b64 v[236:239], v92 offset0:80 offset1:96
	s_waitcnt lgkmcnt(0)
	v_pk_add_f32 v[236:237], v[238:239], v[236:237] neg_lo:[0,1] neg_hi:[0,1]
	s_nop 0
	v_pk_add_f32 v[240:241], v[240:241], v[236:237]
	v_mul_f32_e32 v236, v75, v242
	v_lshlrev_b32_e32 v237, 16, v112
	v_and_b32_e32 v238, 0xffff0000, v112
	v_fma_f32 v237, v236, v240, -v237
	v_fma_f32 v236, v236, v241, -v238
	v_cvt_pk_bf16_f32 v238, v237, v236
	v_add_co_u32_e32 v236, vcc, s54, v50
	s_nop 1
	v_addc_co_u32_e32 v237, vcc, 0, v51, vcc
	global_store_dword v[236:237], v238, off
	ds_read2st64_b64 v[236:239], v92 offset0:81 offset1:97
	s_waitcnt lgkmcnt(0)
; #define GAS __attribute__((address_space(1)))
; __device__ __forceinline__ unsigned cvt_pk_bf16(float lo, float hi) { unsigned r; asm volatile("v_cvt_pk_bf16_f32 %0, %1, %2" : "=v"(r) : "v"(lo), "v"(hi)); return r; }
; __device__ __forceinline__ float bf_lo(unsigned w) { return __uint_as_float(w << 16); }
; __device__ __forceinline__ float bf_hi(unsigned w) { return __uint_as_float(w & 0xffff0000u); }
; template <int W>
; __device__ __forceinline__ void pool_item(const Ctx& F, const bf16* Ub, bf16* Db, int r0, int nr) {
;     ...
;                     for (int j = 0; j < 8; ++j) {
;                         const float ic = icr * icc[j]; const unsigned m = ring[(u + NS - HW + 1) % NS][j];
;                         *(GAS unsigned*)(Db + ((size_t)r * 64 + c0 + j) * EI) = cvt_pk_bf16(h.x * ic - bf_lo(m), h.y * ic - bf_hi(m));
;                         h += row[(c0 + j + HW) * 64] - row[(c0 + j - HW) * 64];
;                     }
; #pragma unroll
;                     for (int j = 0; j < 8; ++j) { const unsigned l = ring[(u + NS - W + 1) % NS][j]; Vv[j].x -= ml * bf_lo(l); Vv[j].y -= ml * bf_hi(l); }
	v_pk_add_f32 v[236:237], v[238:239], v[236:237] neg_lo:[0,1] neg_hi:[0,1]
	s_nop 0
	v_pk_add_f32 v[240:241], v[240:241], v[236:237]
	v_mul_f32_e32 v236, v76, v242
	v_lshlrev_b32_e32 v237, 16, v118
	v_and_b32_e32 v238, 0xffff0000, v118
	v_fma_f32 v237, v236, v240, -v237
	v_fma_f32 v236, v236, v241, -v238
	v_cvt_pk_bf16_f32 v238, v237, v236
	v_add_co_u32_e32 v236, vcc, s55, v50
	s_nop 1
	v_addc_co_u32_e32 v237, vcc, 0, v51, vcc
	global_store_dword v[236:237], v238, off
	ds_read2st64_b64 v[236:239], v92 offset0:82 offset1:98
	s_waitcnt lgkmcnt(0)
	v_pk_add_f32 v[236:237], v[238:239], v[236:237] neg_lo:[0,1] neg_hi:[0,1]
	s_nop 0
	v_pk_add_f32 v[240:241], v[240:241], v[236:237]
	v_mul_f32_e32 v236, v77, v242
	v_lshlrev_b32_e32 v237, 16, v124
	v_and_b32_e32 v238, 0xffff0000, v124
	v_fma_f32 v237, v236, v240, -v237
	v_fma_f32 v236, v236, v241, -v238
	v_cvt_pk_bf16_f32 v238, v237, v236
	v_add_co_u32_e32 v236, vcc, s56, v50
	s_nop 1
	v_addc_co_u32_e32 v237, vcc, 0, v51, vcc
	global_store_dword v[236:237], v238, off
	ds_read2st64_b64 v[236:239], v92 offset0:83 offset1:99
	s_waitcnt lgkmcnt(0)
	v_pk_add_f32 v[236:237], v[238:239], v[236:237] neg_lo:[0,1] neg_hi:[0,1]
	s_nop 0
	v_pk_add_f32 v[240:241], v[240:241], v[236:237]
	v_mul_f32_e32 v236, v78, v242
	v_lshlrev_b32_e32 v237, 16, v131
	v_and_b32_e32 v238, 0xffff0000, v131
	v_fma_f32 v237, v236, v240, -v237
	v_fma_f32 v236, v236, v241, -v238
	v_cvt_pk_bf16_f32 v238, v237, v236
	v_add_co_u32_e32 v236, vcc, s57, v50
	s_nop 1
	v_addc_co_u32_e32 v237, vcc, 0, v51, vcc
	global_store_dword v[236:237], v238, off
	ds_read2st64_b64 v[236:239], v92 offset0:84 offset1:100
	s_waitcnt lgkmcnt(0)
	v_pk_add_f32 v[236:237], v[238:239], v[236:237] neg_lo:[0,1] neg_hi:[0,1]
	s_nop 0
	v_pk_add_f32 v[240:241], v[240:241], v[236:237]
	v_mul_f32_e32 v236, v79, v242
	v_lshlrev_b32_e32 v237, 16, v138
	v_and_b32_e32 v238, 0xffff0000, v138
	v_fma_f32 v237, v236, v240, -v237
	v_fma_f32 v236, v236, v241, -v238
	v_cvt_pk_bf16_f32 v238, v237, v236
	v_add_co_u32_e32 v236, vcc, s58, v50
	s_nop 1
	v_addc_co_u32_e32 v237, vcc, 0, v51, vcc
	global_store_dword v[236:237], v238, off
	ds_read2st64_b64 v[236:239], v92 offset0:85 offset1:101
	s_waitcnt lgkmcnt(0)
	v_pk_add_f32 v[236:237], v[238:239], v[236:237] neg_lo:[0,1] neg_hi:[0,1]
	s_nop 0
	v_pk_add_f32 v[240:241], v[240:241], v[236:237]
	v_mul_f32_e32 v236, v80, v242
	v_lshlrev_b32_e32 v237, 16, v147
	v_and_b32_e32 v238, 0xffff0000, v147
	v_fma_f32 v237, v236, v240, -v237
	v_fma_f32 v236, v236, v241, -v238
	v_cvt_pk_bf16_f32 v238, v237, v236
	v_add_co_u32_e32 v236, vcc, s59, v50
	s_nop 1
	v_addc_co_u32_e32 v237, vcc, 0, v51, vcc
	global_store_dword v[236:237], v238, off
	ds_read2st64_b64 v[236:239], v92 offset0:86 offset1:102
	v_add_co_u32_e32 v50, vcc, s60, v50
	s_waitcnt lgkmcnt(0)
	v_pk_add_f32 v[236:237], v[238:239], v[236:237] neg_lo:[0,1] neg_hi:[0,1]
	s_nop 0
	v_pk_add_f32 v[236:237], v[240:241], v[236:237]
	v_mul_f32_e32 v238, v81, v242
	v_lshlrev_b32_e32 v239, 16, v180
	v_fma_f32 v236, v238, v236, -v239
	v_and_b32_e32 v239, 0xffff0000, v180
	v_addc_co_u32_e32 v51, vcc, 0, v51, vcc
	v_fma_f32 v237, v238, v237, -v239
	v_cvt_pk_bf16_f32 v236, v236, v237
	global_store_dword v[50:51], v236, off
	v_lshlrev_b32_e32 v50, 16, v154
	v_and_b32_e32 v51, 0xffff0000, v154
	v_pk_fma_f32 v[18:19], v[2:3], v[50:51], v[18:19] op_sel_hi:[0,1,1] neg_lo:[1,0,0] neg_hi:[1,0,0]
	v_lshlrev_b32_e32 v50, 16, v161
	v_and_b32_e32 v51, 0xffff0000, v161
	v_pk_fma_f32 v[20:21], v[2:3], v[50:51], v[20:21] op_sel_hi:[0,1,1] neg_lo:[1,0,0] neg_hi:[1,0,0]
	v_lshlrev_b32_e32 v50, 16, v170
	v_and_b32_e32 v51, 0xffff0000, v170
	v_pk_fma_f32 v[22:23], v[2:3], v[50:51], v[22:23] op_sel_hi:[0,1,1] neg_lo:[1,0,0] neg_hi:[1,0,0]
	v_lshlrev_b32_e32 v50, 16, v182
	v_and_b32_e32 v51, 0xffff0000, v182
	v_pk_fma_f32 v[24:25], v[2:3], v[50:51], v[24:25] op_sel_hi:[0,1,1] neg_lo:[1,0,0] neg_hi:[1,0,0]
	v_lshlrev_b32_e32 v50, 16, v191
	v_and_b32_e32 v51, 0xffff0000, v191
	v_pk_fma_f32 v[26:27], v[2:3], v[50:51], v[26:27] op_sel_hi:[0,1,1] neg_lo:[1,0,0] neg_hi:[1,0,0]
	v_lshlrev_b32_e32 v50, 16, v199
	v_and_b32_e32 v51, 0xffff0000, v199
	v_pk_fma_f32 v[28:29], v[2:3], v[50:51], v[28:29] op_sel_hi:[0,1,1] neg_lo:[1,0,0] neg_hi:[1,0,0]
	v_lshlrev_b32_e32 v50, 16, v206
	v_and_b32_e32 v51, 0xffff0000, v206
	v_pk_fma_f32 v[30:31], v[2:3], v[50:51], v[30:31] op_sel_hi:[0,1,1] neg_lo:[1,0,0] neg_hi:[1,0,0]
	v_lshlrev_b32_e32 v50, 16, v220
	v_and_b32_e32 v51, 0xffff0000, v220
	v_pk_fma_f32 v[32:33], v[2:3], v[50:51], v[32:33] op_sel_hi:[0,1,1] neg_lo:[1,0,0] neg_hi:[1,0,0]
; #define GAS __attribute__((address_space(1)))
; #define LAS __attribute__((address_space(3)))
; __device__ __forceinline__ unsigned cvt_pk_bf16(float lo, float hi) { unsigned r; asm volatile("v_cvt_pk_bf16_f32 %0, %1, %2" : "=v"(r) : "v"(lo), "v"(hi)); return r; }
; __device__ __forceinline__ float bf_lo(unsigned w) { return __uint_as_float(w << 16); }
; __device__ __forceinline__ float bf_hi(unsigned w) { return __uint_as_float(w & 0xffff0000u); }
; template <int W>
; __device__ __forceinline__ void pool_item(const Ctx& F, const bf16* Ub, bf16* Db, int r0, int nr) {
;     ...
;         for (int u = 0; u < NS; ++u) {
;             const int r = base + u;
;             if (r < re) {
;                 POOL_LOAD((u + 2) % NS, r + 2);
;                 const int e = r + HW - 1;
;                 const float me = (e >= 0 && e < 128) ? 1.0f : 0.0f, ml = (r >= r0 && r - HW >= 0) ? 1.0f : 0.0f;
; #pragma unroll
;                 for (int j = 0; j < 8; ++j) { Vv[j].x += me * bf_lo(ring[u][j]); Vv[j].y += me * bf_hi(ring[u][j]); }
;                 if (r >= r0) {
;                     LAS f32x2* row = buf + ((r & 1) * 80 + 8) * 64 + lane;
; #pragma unroll
;                     for (int j = 0; j < 8; ++j) row[(c0 + j) * 64] = Vv[j];
;                     asm volatile("s_waitcnt lgkmcnt(0)" ::: "memory"); __builtin_amdgcn_s_barrier(); asm volatile("" ::: "memory");
;                     const int rlo = r - HW > 0 ? r - HW : 0, rhi = r + HW < 128 ? r + HW : 128; const float icr = 1.0f / (float)(rhi - rlo);
;                     f32x2 h = (f32x2){0.f, 0.f};
; #pragma unroll
;                     for (int c = -HW; c < HW; ++c) h += row[(c0 + c) * 64];
; #pragma unroll
;                     for (int j = 0; j < 8; ++j) {
;                         const float ic = icr * icc[j]; const unsigned m = ring[(u + NS - HW + 1) % NS][j];
;                         *(GAS unsigned*)(Db + ((size_t)r * 64 + c0 + j) * EI) = cvt_pk_bf16(h.x * ic - bf_lo(m), h.y * ic - bf_hi(m));
;                         h += row[(c0 + j + HW) * 64] - row[(c0 + j - HW) * 64];
;                     }
; #pragma unroll
;                     for (int j = 0; j < 8; ++j) { const unsigned l = ring[(u + NS - W + 1) % NS][j]; Vv[j].x -= ml * bf_lo(l); Vv[j].y -= ml * bf_hi(l); }
;                 }
.LBB0_846:
	s_add_i32 s16, s42, 5
	s_cmp_ge_i32 s16, s46
	s_cbranch_scc1 .LBB0_849
	v_med3_i32 v2, s16, -9, v93
	v_add_u32_e32 v2, 9, v2
	v_lshlrev_b64 v[50:51], 20, v[2:3]
	v_lshl_add_u64 v[50:51], v[12:13], 0, v[50:51]
	v_add_co_u32_e32 v236, vcc, 0x4000, v50
	global_load_dword v154, v[50:51], off
	s_nop 0
	v_addc_co_u32_e32 v237, vcc, 0, v51, vcc
	global_load_dword v161, v[236:237], off
	v_add_co_u32_e32 v236, vcc, 0x8000, v50
	s_add_i32 s10, s42, 12
	s_nop 0
	v_addc_co_u32_e32 v237, vcc, 0, v51, vcc
	global_load_dword v170, v[236:237], off
	v_add_co_u32_e32 v236, vcc, 0xc000, v50
	s_cmpk_lt_u32 s10, 0x80
	s_nop 0
	v_addc_co_u32_e32 v237, vcc, 0, v51, vcc
	global_load_dword v182, v[236:237], off
	v_add_co_u32_e32 v236, vcc, 0x10000, v50
	s_cselect_b64 s[50:51], -1, 0
	s_nop 0
	v_addc_co_u32_e32 v237, vcc, 0, v51, vcc
	global_load_dword v191, v[236:237], off
	v_add_co_u32_e32 v236, vcc, 0x14000, v50
	v_cndmask_b32_e64 v2, 0, 1.0, s[50:51]
	s_nop 0
	v_addc_co_u32_e32 v237, vcc, 0, v51, vcc
	global_load_dword v199, v[236:237], off
	v_add_co_u32_e32 v236, vcc, 0x18000, v50
	s_cmp_lt_i32 s16, s62
	s_nop 0
	v_addc_co_u32_e32 v237, vcc, 0, v51, vcc
	v_add_co_u32_e32 v50, vcc, 0x1c000, v50
	global_load_dword v206, v[236:237], off
	s_nop 0
	v_addc_co_u32_e32 v51, vcc, 0, v51, vcc
	global_load_dword v220, v[50:51], off
	s_waitcnt vmcnt(23)
	v_lshlrev_b32_e32 v50, 16, v171
	v_and_b32_e32 v51, 0xffff0000, v171
	v_pk_fma_f32 v[18:19], v[2:3], v[50:51], v[18:19] op_sel_hi:[0,1,1]
	s_waitcnt vmcnt(22)
	v_lshlrev_b32_e32 v50, 16, v176
	v_and_b32_e32 v51, 0xffff0000, v176
	v_pk_fma_f32 v[20:21], v[2:3], v[50:51], v[20:21] op_sel_hi:[0,1,1]
	s_waitcnt vmcnt(21)
	v_lshlrev_b32_e32 v50, 16, v186
	v_and_b32_e32 v51, 0xffff0000, v186
	v_pk_fma_f32 v[22:23], v[2:3], v[50:51], v[22:23] op_sel_hi:[0,1,1]
	s_waitcnt vmcnt(20)
	v_lshlrev_b32_e32 v50, 16, v197
	v_and_b32_e32 v51, 0xffff0000, v197
	v_pk_fma_f32 v[24:25], v[2:3], v[50:51], v[24:25] op_sel_hi:[0,1,1]
	s_waitcnt vmcnt(19)
	v_lshlrev_b32_e32 v50, 16, v204
	v_and_b32_e32 v51, 0xffff0000, v204
	v_pk_fma_f32 v[26:27], v[2:3], v[50:51], v[26:27] op_sel_hi:[0,1,1]
	s_waitcnt vmcnt(18)
	v_lshlrev_b32_e32 v50, 16, v210
	v_and_b32_e32 v51, 0xffff0000, v210
	v_pk_fma_f32 v[28:29], v[2:3], v[50:51], v[28:29] op_sel_hi:[0,1,1]
	s_waitcnt vmcnt(17)
	v_lshlrev_b32_e32 v50, 16, v215
	v_and_b32_e32 v51, 0xffff0000, v215
	v_pk_fma_f32 v[30:31], v[2:3], v[50:51], v[30:31] op_sel_hi:[0,1,1]
	s_waitcnt vmcnt(16)
	v_lshlrev_b32_e32 v50, 16, v223
	v_and_b32_e32 v51, 0xffff0000, v223
	v_pk_fma_f32 v[32:33], v[2:3], v[50:51], v[32:33] op_sel_hi:[0,1,1]
	s_cbranch_scc1 .LBB0_849
	ds_write2st64_b64 v92, v[18:19], v[20:21] offset0:8 offset1:9
	ds_write2st64_b64 v92, v[22:23], v[24:25] offset0:10 offset1:11
	ds_write2st64_b64 v92, v[26:27], v[28:29] offset0:12 offset1:13
	ds_write2st64_b64 v92, v[30:31], v[32:33] offset0:14 offset1:15
	s_waitcnt lgkmcnt(0)
	s_barrier
	ds_read2st64_b64 v[236:239], v92 offset1:1
	s_cmp_gt_i32 s42, 2
	s_cselect_b64 s[50:51], -1, 0
	s_max_i32 s10, s16, 8
	s_min_i32 s23, s16, 0x78
	s_waitcnt lgkmcnt(0)
	v_pk_add_f32 v[50:51], v[236:237], 0 op_sel_hi:[1,0]
	s_sub_i32 s10, s23, s10
	v_pk_add_f32 v[50:51], v[50:51], v[238:239]
	ds_read2st64_b64 v[236:239], v92 offset0:2 offset1:3
	s_add_i32 s10, s10, 16
	v_cvt_f32_i32_e32 v242, s10
	v_cndmask_b32_e64 v2, 0, 1.0, s[50:51]
	s_waitcnt lgkmcnt(0)
	v_pk_add_f32 v[50:51], v[50:51], v[236:237]
	s_nop 0
	v_pk_add_f32 v[50:51], v[50:51], v[238:239]
	ds_read2st64_b64 v[236:239], v92 offset0:4 offset1:5
	s_waitcnt lgkmcnt(0)
	v_pk_add_f32 v[50:51], v[50:51], v[236:237]
	s_nop 0
	v_pk_add_f32 v[50:51], v[50:51], v[238:239]
	ds_read2st64_b64 v[236:239], v92 offset0:6 offset1:7
	s_waitcnt lgkmcnt(0)
	v_pk_add_f32 v[50:51], v[50:51], v[236:237]
	s_nop 0
	v_pk_add_f32 v[50:51], v[50:51], v[238:239]
	ds_read2st64_b64 v[236:239], v92 offset0:8 offset1:9
	s_waitcnt lgkmcnt(0)
	v_pk_add_f32 v[50:51], v[50:51], v[236:237]
	s_nop 0
	v_pk_add_f32 v[50:51], v[50:51], v[238:239]
	ds_read2st64_b64 v[236:239], v92 offset0:10 offset1:11
	s_waitcnt lgkmcnt(0)
	v_pk_add_f32 v[50:51], v[50:51], v[236:237]
	s_nop 0
	v_pk_add_f32 v[50:51], v[50:51], v[238:239]
	ds_read2st64_b64 v[236:239], v92 offset0:12 offset1:13
	s_waitcnt lgkmcnt(0)
	v_pk_add_f32 v[50:51], v[50:51], v[236:237]
	s_nop 0
	v_pk_add_f32 v[50:51], v[50:51], v[238:239]
	ds_read2st64_b64 v[236:239], v92 offset0:14 offset1:15
	s_waitcnt lgkmcnt(0)
	v_pk_add_f32 v[50:51], v[50:51], v[236:237]
	s_nop 0
	v_pk_add_f32 v[240:241], v[50:51], v[238:239]
	v_div_scale_f32 v50, s[50:51], v242, v242, 1.0
	v_rcp_f32_e32 v51, v50
	s_lshl_b64 s[50:51], s[16:17], 20
	v_fma_f32 v236, -v50, v51, 1.0
	v_fmac_f32_e32 v51, v236, v51
	v_div_scale_f32 v236, vcc, 1.0, v242, 1.0
	v_mul_f32_e32 v237, v236, v51
	v_fma_f32 v238, -v50, v237, v236
	v_fmac_f32_e32 v237, v238, v51
	v_fma_f32 v50, -v50, v237, v236
	v_div_fmas_f32 v50, v50, v51, v237
	v_div_fixup_f32 v242, v50, v242, 1.0
	v_mul_f32_e32 v50, v74, v242
	v_lshlrev_b32_e32 v51, 16, v105
	v_and_b32_e32 v236, 0xffff0000, v105
	v_fma_f32 v51, v50, v240, -v51
	v_fma_f32 v50, v50, v241, -v236
	v_cvt_pk_bf16_f32 v236, v51, v50
	v_lshl_add_u64 v[50:51], v[14:15], 0, s[50:51]
	global_store_dword v[50:51], v236, off
	ds_read2st64_b64 v[236:239], v92 offset1:16
	s_waitcnt lgkmcnt(0)
	v_pk_add_f32 v[236:237], v[238:239], v[236:237] neg_lo:[0,1] neg_hi:[0,1]
	s_nop 0
	v_pk_add_f32 v[240:241], v[240:241], v[236:237]
	v_mul_f32_e32 v236, v75, v242
	v_lshlrev_b32_e32 v237, 16, v108
	v_and_b32_e32 v238, 0xffff0000, v108
	v_fma_f32 v237, v236, v240, -v237
	v_fma_f32 v236, v236, v241, -v238
	v_cvt_pk_bf16_f32 v238, v237, v236
	v_add_co_u32_e32 v236, vcc, s54, v50
	s_nop 1
	v_addc_co_u32_e32 v237, vcc, 0, v51, vcc
	global_store_dword v[236:237], v238, off
	ds_read2st64_b64 v[236:239], v92 offset0:1 offset1:17
	s_waitcnt lgkmcnt(0)
; #define GAS __attribute__((address_space(1)))
; __device__ __forceinline__ unsigned cvt_pk_bf16(float lo, float hi) { unsigned r; asm volatile("v_cvt_pk_bf16_f32 %0, %1, %2" : "=v"(r) : "v"(lo), "v"(hi)); return r; }
; __device__ __forceinline__ float bf_lo(unsigned w) { return __uint_as_float(w << 16); }
; __device__ __forceinline__ float bf_hi(unsigned w) { return __uint_as_float(w & 0xffff0000u); }
; template <int W>
; __device__ __forceinline__ void pool_item(const Ctx& F, const bf16* Ub, bf16* Db, int r0, int nr) {
;     ...
;                     for (int j = 0; j < 8; ++j) {
;                         const float ic = icr * icc[j]; const unsigned m = ring[(u + NS - HW + 1) % NS][j];
;                         *(GAS unsigned*)(Db + ((size_t)r * 64 + c0 + j) * EI) = cvt_pk_bf16(h.x * ic - bf_lo(m), h.y * ic - bf_hi(m));
;                         h += row[(c0 + j + HW) * 64] - row[(c0 + j - HW) * 64];
;                     }
; #pragma unroll
;                     for (int j = 0; j < 8; ++j) { const unsigned l = ring[(u + NS - W + 1) % NS][j]; Vv[j].x -= ml * bf_lo(l); Vv[j].y -= ml * bf_hi(l); }
	v_pk_add_f32 v[236:237], v[238:239], v[236:237] neg_lo:[0,1] neg_hi:[0,1]
	s_nop 0
	v_pk_add_f32 v[240:241], v[240:241], v[236:237]
	v_mul_f32_e32 v236, v76, v242
	v_lshlrev_b32_e32 v237, 16, v113
	v_and_b32_e32 v238, 0xffff0000, v113
	v_fma_f32 v237, v236, v240, -v237
	v_fma_f32 v236, v236, v241, -v238
	v_cvt_pk_bf16_f32 v238, v237, v236
	v_add_co_u32_e32 v236, vcc, s55, v50
	s_nop 1
	v_addc_co_u32_e32 v237, vcc, 0, v51, vcc
	global_store_dword v[236:237], v238, off
	ds_read2st64_b64 v[236:239], v92 offset0:2 offset1:18
	s_waitcnt lgkmcnt(0)
	v_pk_add_f32 v[236:237], v[238:239], v[236:237] neg_lo:[0,1] neg_hi:[0,1]
	s_nop 0
	v_pk_add_f32 v[240:241], v[240:241], v[236:237]
	v_mul_f32_e32 v236, v77, v242
	v_lshlrev_b32_e32 v237, 16, v119
	v_and_b32_e32 v238, 0xffff0000, v119
	v_fma_f32 v237, v236, v240, -v237
	v_fma_f32 v236, v236, v241, -v238
	v_cvt_pk_bf16_f32 v238, v237, v236
	v_add_co_u32_e32 v236, vcc, s56, v50
	s_nop 1
	v_addc_co_u32_e32 v237, vcc, 0, v51, vcc
	global_store_dword v[236:237], v238, off
	ds_read2st64_b64 v[236:239], v92 offset0:3 offset1:19
	s_waitcnt lgkmcnt(0)
	v_pk_add_f32 v[236:237], v[238:239], v[236:237] neg_lo:[0,1] neg_hi:[0,1]
	s_nop 0
	v_pk_add_f32 v[240:241], v[240:241], v[236:237]
	v_mul_f32_e32 v236, v78, v242
	v_lshlrev_b32_e32 v237, 16, v125
	v_and_b32_e32 v238, 0xffff0000, v125
	v_fma_f32 v237, v236, v240, -v237
	v_fma_f32 v236, v236, v241, -v238
	v_cvt_pk_bf16_f32 v238, v237, v236
	v_add_co_u32_e32 v236, vcc, s57, v50
	s_nop 1
	v_addc_co_u32_e32 v237, vcc, 0, v51, vcc
	global_store_dword v[236:237], v238, off
	ds_read2st64_b64 v[236:239], v92 offset0:4 offset1:20
	s_waitcnt lgkmcnt(0)
	v_pk_add_f32 v[236:237], v[238:239], v[236:237] neg_lo:[0,1] neg_hi:[0,1]
	s_nop 0
	v_pk_add_f32 v[240:241], v[240:241], v[236:237]
	v_mul_f32_e32 v236, v79, v242
	v_lshlrev_b32_e32 v237, 16, v132
	v_and_b32_e32 v238, 0xffff0000, v132
	v_fma_f32 v237, v236, v240, -v237
	v_fma_f32 v236, v236, v241, -v238
	v_cvt_pk_bf16_f32 v238, v237, v236
	v_add_co_u32_e32 v236, vcc, s58, v50
	s_nop 1
	v_addc_co_u32_e32 v237, vcc, 0, v51, vcc
	global_store_dword v[236:237], v238, off
	ds_read2st64_b64 v[236:239], v92 offset0:5 offset1:21
	s_waitcnt lgkmcnt(0)
	v_pk_add_f32 v[236:237], v[238:239], v[236:237] neg_lo:[0,1] neg_hi:[0,1]
	s_nop 0
	v_pk_add_f32 v[240:241], v[240:241], v[236:237]
	v_mul_f32_e32 v236, v80, v242
	v_lshlrev_b32_e32 v237, 16, v139
	v_and_b32_e32 v238, 0xffff0000, v139
	v_fma_f32 v237, v236, v240, -v237
	v_fma_f32 v236, v236, v241, -v238
	v_cvt_pk_bf16_f32 v238, v237, v236
	v_add_co_u32_e32 v236, vcc, s59, v50
	s_nop 1
	v_addc_co_u32_e32 v237, vcc, 0, v51, vcc
	global_store_dword v[236:237], v238, off
	ds_read2st64_b64 v[236:239], v92 offset0:6 offset1:22
	v_add_co_u32_e32 v50, vcc, s60, v50
	s_waitcnt lgkmcnt(0)
	v_pk_add_f32 v[236:237], v[238:239], v[236:237] neg_lo:[0,1] neg_hi:[0,1]
	s_nop 0
	v_pk_add_f32 v[236:237], v[240:241], v[236:237]
	v_mul_f32_e32 v238, v81, v242
	v_lshlrev_b32_e32 v239, 16, v172
	v_fma_f32 v236, v238, v236, -v239
	v_and_b32_e32 v239, 0xffff0000, v172
	v_addc_co_u32_e32 v51, vcc, 0, v51, vcc
	v_fma_f32 v237, v238, v237, -v239
	v_cvt_pk_bf16_f32 v236, v236, v237
	global_store_dword v[50:51], v236, off
	v_lshlrev_b32_e32 v50, 16, v148
	v_and_b32_e32 v51, 0xffff0000, v148
	v_pk_fma_f32 v[18:19], v[2:3], v[50:51], v[18:19] op_sel_hi:[0,1,1] neg_lo:[1,0,0] neg_hi:[1,0,0]
	v_lshlrev_b32_e32 v50, 16, v157
	v_and_b32_e32 v51, 0xffff0000, v157
	v_pk_fma_f32 v[20:21], v[2:3], v[50:51], v[20:21] op_sel_hi:[0,1,1] neg_lo:[1,0,0] neg_hi:[1,0,0]
	v_lshlrev_b32_e32 v50, 16, v165
	v_and_b32_e32 v51, 0xffff0000, v165
	v_pk_fma_f32 v[22:23], v[2:3], v[50:51], v[22:23] op_sel_hi:[0,1,1] neg_lo:[1,0,0] neg_hi:[1,0,0]
	v_lshlrev_b32_e32 v50, 16, v174
	v_and_b32_e32 v51, 0xffff0000, v174
	v_pk_fma_f32 v[24:25], v[2:3], v[50:51], v[24:25] op_sel_hi:[0,1,1] neg_lo:[1,0,0] neg_hi:[1,0,0]
	v_lshlrev_b32_e32 v50, 16, v183
	v_and_b32_e32 v51, 0xffff0000, v183
	v_pk_fma_f32 v[26:27], v[2:3], v[50:51], v[26:27] op_sel_hi:[0,1,1] neg_lo:[1,0,0] neg_hi:[1,0,0]
	v_lshlrev_b32_e32 v50, 16, v193
	v_and_b32_e32 v51, 0xffff0000, v193
	v_pk_fma_f32 v[28:29], v[2:3], v[50:51], v[28:29] op_sel_hi:[0,1,1] neg_lo:[1,0,0] neg_hi:[1,0,0]
	v_lshlrev_b32_e32 v50, 16, v202
	v_and_b32_e32 v51, 0xffff0000, v202
	v_pk_fma_f32 v[30:31], v[2:3], v[50:51], v[30:31] op_sel_hi:[0,1,1] neg_lo:[1,0,0] neg_hi:[1,0,0]
	v_lshlrev_b32_e32 v50, 16, v219
	v_and_b32_e32 v51, 0xffff0000, v219
	v_pk_fma_f32 v[32:33], v[2:3], v[50:51], v[32:33] op_sel_hi:[0,1,1] neg_lo:[1,0,0] neg_hi:[1,0,0]
; #define GAS __attribute__((address_space(1)))
; #define LAS __attribute__((address_space(3)))
; __device__ __forceinline__ unsigned cvt_pk_bf16(float lo, float hi) { unsigned r; asm volatile("v_cvt_pk_bf16_f32 %0, %1, %2" : "=v"(r) : "v"(lo), "v"(hi)); return r; }
; __device__ __forceinline__ float bf_lo(unsigned w) { return __uint_as_float(w << 16); }
; __device__ __forceinline__ float bf_hi(unsigned w) { return __uint_as_float(w & 0xffff0000u); }
; template <int W>
; __device__ __forceinline__ void pool_item(const Ctx& F, const bf16* Ub, bf16* Db, int r0, int nr) {
;     ...
;         for (int u = 0; u < NS; ++u) {
;             const int r = base + u;
;             if (r < re) {
;                 POOL_LOAD((u + 2) % NS, r + 2);
;                 const int e = r + HW - 1;
;                 const float me = (e >= 0 && e < 128) ? 1.0f : 0.0f, ml = (r >= r0 && r - HW >= 0) ? 1.0f : 0.0f;
; #pragma unroll
;                 for (int j = 0; j < 8; ++j) { Vv[j].x += me * bf_lo(ring[u][j]); Vv[j].y += me * bf_hi(ring[u][j]); }
;                 if (r >= r0) {
;                     LAS f32x2* row = buf + ((r & 1) * 80 + 8) * 64 + lane;
; #pragma unroll
;                     for (int j = 0; j < 8; ++j) row[(c0 + j) * 64] = Vv[j];
;                     asm volatile("s_waitcnt lgkmcnt(0)" ::: "memory"); __builtin_amdgcn_s_barrier(); asm volatile("" ::: "memory");
;                     const int rlo = r - HW > 0 ? r - HW : 0, rhi = r + HW < 128 ? r + HW : 128; const float icr = 1.0f / (float)(rhi - rlo);
;                     f32x2 h = (f32x2){0.f, 0.f};
; #pragma unroll
;                     for (int c = -HW; c < HW; ++c) h += row[(c0 + c) * 64];
; #pragma unroll
;                     for (int j = 0; j < 8; ++j) {
;                         const float ic = icr * icc[j]; const unsigned m = ring[(u + NS - HW + 1) % NS][j];
;                         *(GAS unsigned*)(Db + ((size_t)r * 64 + c0 + j) * EI) = cvt_pk_bf16(h.x * ic - bf_lo(m), h.y * ic - bf_hi(m));
;                         h += row[(c0 + j + HW) * 64] - row[(c0 + j - HW) * 64];
;                     }
; #pragma unroll
;                     for (int j = 0; j < 8; ++j) { const unsigned l = ring[(u + NS - W + 1) % NS][j]; Vv[j].x -= ml * bf_lo(l); Vv[j].y -= ml * bf_hi(l); }
;                 }
.LBB0_849:
	s_add_i32 s16, s42, 6
	s_cmp_ge_i32 s16, s46
	s_cbranch_scc1 .LBB0_852
	s_min_i32 s50, s16, 0x76
	s_ashr_i32 s51, s50, 31
	s_lshl_b64 s[50:51], s[50:51], 20
	v_lshl_add_u64 v[50:51], v[12:13], 0, s[50:51]
	v_add_co_u32_e32 v236, vcc, 0x900000, v50
	s_add_i32 s10, s42, 13
	s_nop 0
	v_addc_co_u32_e32 v237, vcc, 0, v51, vcc
	global_load_dword v148, v[236:237], off
	v_add_co_u32_e32 v236, vcc, 0x904000, v50
	s_cmpk_lt_u32 s10, 0x80
	s_nop 0
	v_addc_co_u32_e32 v237, vcc, 0, v51, vcc
	global_load_dword v157, v[236:237], off
	v_add_co_u32_e32 v236, vcc, 0x908000, v50
	s_cselect_b64 s[50:51], -1, 0
	s_nop 0
	v_addc_co_u32_e32 v237, vcc, 0, v51, vcc
	global_load_dword v165, v[236:237], off
	v_add_co_u32_e32 v236, vcc, 0x90c000, v50
	v_cndmask_b32_e64 v2, 0, 1.0, s[50:51]
	s_nop 0
	v_addc_co_u32_e32 v237, vcc, 0, v51, vcc
	global_load_dword v174, v[236:237], off
	v_add_co_u32_e32 v236, vcc, 0x910000, v50
	s_cmp_lt_i32 s16, s62
	s_nop 0
	v_addc_co_u32_e32 v237, vcc, 0, v51, vcc
	global_load_dword v183, v[236:237], off
	v_add_co_u32_e32 v236, vcc, 0x914000, v50
	s_nop 1
	v_addc_co_u32_e32 v237, vcc, 0, v51, vcc
	global_load_dword v193, v[236:237], off
	v_add_co_u32_e32 v236, vcc, 0x918000, v50
	s_nop 1
	v_addc_co_u32_e32 v237, vcc, 0, v51, vcc
	v_add_co_u32_e32 v50, vcc, 0x91c000, v50
	global_load_dword v202, v[236:237], off
	s_nop 0
	v_addc_co_u32_e32 v51, vcc, 0, v51, vcc
	global_load_dword v219, v[50:51], off
	s_waitcnt vmcnt(23)
	v_lshlrev_b32_e32 v50, 16, v163
	v_and_b32_e32 v51, 0xffff0000, v163
	v_pk_fma_f32 v[18:19], v[2:3], v[50:51], v[18:19] op_sel_hi:[0,1,1]
	s_waitcnt vmcnt(22)
	v_lshlrev_b32_e32 v50, 16, v168
	v_and_b32_e32 v51, 0xffff0000, v168
	v_pk_fma_f32 v[20:21], v[2:3], v[50:51], v[20:21] op_sel_hi:[0,1,1]
	s_waitcnt vmcnt(21)
	v_lshlrev_b32_e32 v50, 16, v178
	v_and_b32_e32 v51, 0xffff0000, v178
	v_pk_fma_f32 v[22:23], v[2:3], v[50:51], v[22:23] op_sel_hi:[0,1,1]
	s_waitcnt vmcnt(20)
	v_lshlrev_b32_e32 v50, 16, v190
	v_and_b32_e32 v51, 0xffff0000, v190
	v_pk_fma_f32 v[24:25], v[2:3], v[50:51], v[24:25] op_sel_hi:[0,1,1]
	s_waitcnt vmcnt(19)
	v_lshlrev_b32_e32 v50, 16, v198
	v_and_b32_e32 v51, 0xffff0000, v198
	v_pk_fma_f32 v[26:27], v[2:3], v[50:51], v[26:27] op_sel_hi:[0,1,1]
	s_waitcnt vmcnt(18)
	v_lshlrev_b32_e32 v50, 16, v205
	v_and_b32_e32 v51, 0xffff0000, v205
	v_pk_fma_f32 v[28:29], v[2:3], v[50:51], v[28:29] op_sel_hi:[0,1,1]
	s_waitcnt vmcnt(17)
	v_lshlrev_b32_e32 v50, 16, v211
	v_and_b32_e32 v51, 0xffff0000, v211
	v_pk_fma_f32 v[30:31], v[2:3], v[50:51], v[30:31] op_sel_hi:[0,1,1]
	s_waitcnt vmcnt(16)
	v_lshlrev_b32_e32 v50, 16, v222
	v_and_b32_e32 v51, 0xffff0000, v222
	v_pk_fma_f32 v[32:33], v[2:3], v[50:51], v[32:33] op_sel_hi:[0,1,1]
	s_cbranch_scc1 .LBB0_852
	ds_write2st64_b64 v92, v[18:19], v[20:21] offset0:88 offset1:89
	ds_write2st64_b64 v92, v[22:23], v[24:25] offset0:90 offset1:91
	ds_write2st64_b64 v92, v[26:27], v[28:29] offset0:92 offset1:93
	ds_write2st64_b64 v92, v[30:31], v[32:33] offset0:94 offset1:95
	s_waitcnt lgkmcnt(0)
	s_barrier
	ds_read2st64_b64 v[236:239], v92 offset0:80 offset1:81
	s_cmp_gt_i32 s42, 1
	s_cselect_b64 s[50:51], -1, 0
	s_max_i32 s10, s16, 8
	s_min_i32 s23, s16, 0x78
	s_waitcnt lgkmcnt(0)
	v_pk_add_f32 v[50:51], v[236:237], 0 op_sel_hi:[1,0]
	s_sub_i32 s10, s23, s10
	v_pk_add_f32 v[50:51], v[50:51], v[238:239]
	ds_read2st64_b64 v[236:239], v92 offset0:82 offset1:83
	s_add_i32 s10, s10, 16
	v_cvt_f32_i32_e32 v242, s10
	v_cndmask_b32_e64 v2, 0, 1.0, s[50:51]
	s_waitcnt lgkmcnt(0)
	v_pk_add_f32 v[50:51], v[50:51], v[236:237]
	s_nop 0
	v_pk_add_f32 v[50:51], v[50:51], v[238:239]
	ds_read2st64_b64 v[236:239], v92 offset0:84 offset1:85
	s_waitcnt lgkmcnt(0)
	v_pk_add_f32 v[50:51], v[50:51], v[236:237]
	s_nop 0
	v_pk_add_f32 v[50:51], v[50:51], v[238:239]
	ds_read2st64_b64 v[236:239], v92 offset0:86 offset1:87
	s_waitcnt lgkmcnt(0)
	v_pk_add_f32 v[50:51], v[50:51], v[236:237]
	s_nop 0
	v_pk_add_f32 v[50:51], v[50:51], v[238:239]
	ds_read2st64_b64 v[236:239], v92 offset0:88 offset1:89
	s_waitcnt lgkmcnt(0)
	v_pk_add_f32 v[50:51], v[50:51], v[236:237]
	s_nop 0
	v_pk_add_f32 v[50:51], v[50:51], v[238:239]
	ds_read2st64_b64 v[236:239], v92 offset0:90 offset1:91
	s_waitcnt lgkmcnt(0)
	v_pk_add_f32 v[50:51], v[50:51], v[236:237]
	s_nop 0
	v_pk_add_f32 v[50:51], v[50:51], v[238:239]
	ds_read2st64_b64 v[236:239], v92 offset0:92 offset1:93
	s_waitcnt lgkmcnt(0)
	v_pk_add_f32 v[50:51], v[50:51], v[236:237]
	s_nop 0
	v_pk_add_f32 v[50:51], v[50:51], v[238:239]
	ds_read2st64_b64 v[236:239], v92 offset0:94 offset1:95
	s_waitcnt lgkmcnt(0)
	v_pk_add_f32 v[50:51], v[50:51], v[236:237]
	s_nop 0
	v_pk_add_f32 v[240:241], v[50:51], v[238:239]
	v_div_scale_f32 v50, s[50:51], v242, v242, 1.0
	v_rcp_f32_e32 v51, v50
	s_lshl_b64 s[50:51], s[16:17], 20
	v_fma_f32 v236, -v50, v51, 1.0
	v_fmac_f32_e32 v51, v236, v51
	v_div_scale_f32 v236, vcc, 1.0, v242, 1.0
	v_mul_f32_e32 v237, v236, v51
	v_fma_f32 v238, -v50, v237, v236
	v_fmac_f32_e32 v237, v238, v51
	v_fma_f32 v50, -v50, v237, v236
	v_div_fmas_f32 v50, v50, v51, v237
	v_div_fixup_f32 v242, v50, v242, 1.0
	v_mul_f32_e32 v50, v74, v242
	v_lshlrev_b32_e32 v51, 16, v101
	v_and_b32_e32 v236, 0xffff0000, v101
	v_fma_f32 v51, v50, v240, -v51
	v_fma_f32 v50, v50, v241, -v236
	v_cvt_pk_bf16_f32 v236, v51, v50
	v_lshl_add_u64 v[50:51], v[14:15], 0, s[50:51]
	global_store_dword v[50:51], v236, off
	ds_read2st64_b64 v[236:239], v92 offset0:80 offset1:96
	s_waitcnt lgkmcnt(0)
; #define GAS __attribute__((address_space(1)))
; __device__ __forceinline__ unsigned cvt_pk_bf16(float lo, float hi) { unsigned r; asm volatile("v_cvt_pk_bf16_f32 %0, %1, %2" : "=v"(r) : "v"(lo), "v"(hi)); return r; }
; __device__ __forceinline__ float bf_lo(unsigned w) { return __uint_as_float(w << 16); }
; __device__ __forceinline__ float bf_hi(unsigned w) { return __uint_as_float(w & 0xffff0000u); }
; template <int W>
; __device__ __forceinline__ void pool_item(const Ctx& F, const bf16* Ub, bf16* Db, int r0, int nr) {
;     ...
;                     for (int j = 0; j < 8; ++j) {
;                         const float ic = icr * icc[j]; const unsigned m = ring[(u + NS - HW + 1) % NS][j];
;                         *(GAS unsigned*)(Db + ((size_t)r * 64 + c0 + j) * EI) = cvt_pk_bf16(h.x * ic - bf_lo(m), h.y * ic - bf_hi(m));
;                         h += row[(c0 + j + HW) * 64] - row[(c0 + j - HW) * 64];
;                     }
; #pragma unroll
;                     for (int j = 0; j < 8; ++j) { const unsigned l = ring[(u + NS - W + 1) % NS][j]; Vv[j].x -= ml * bf_lo(l); Vv[j].y -= ml * bf_hi(l); }
	v_pk_add_f32 v[236:237], v[238:239], v[236:237] neg_lo:[0,1] neg_hi:[0,1]
	s_nop 0
	v_pk_add_f32 v[240:241], v[240:241], v[236:237]
	v_mul_f32_e32 v236, v75, v242
	v_lshlrev_b32_e32 v237, 16, v103
	v_and_b32_e32 v238, 0xffff0000, v103
	v_fma_f32 v237, v236, v240, -v237
	v_fma_f32 v236, v236, v241, -v238
	v_cvt_pk_bf16_f32 v238, v237, v236
	v_add_co_u32_e32 v236, vcc, s54, v50
	s_nop 1
	v_addc_co_u32_e32 v237, vcc, 0, v51, vcc
	global_store_dword v[236:237], v238, off
	ds_read2st64_b64 v[236:239], v92 offset0:81 offset1:97
	s_waitcnt lgkmcnt(0)
	v_pk_add_f32 v[236:237], v[238:239], v[236:237] neg_lo:[0,1] neg_hi:[0,1]
	s_nop 0
	v_pk_add_f32 v[240:241], v[240:241], v[236:237]
	v_mul_f32_e32 v236, v76, v242
	v_lshlrev_b32_e32 v237, 16, v106
	v_and_b32_e32 v238, 0xffff0000, v106
	v_fma_f32 v237, v236, v240, -v237
	v_fma_f32 v236, v236, v241, -v238
	v_cvt_pk_bf16_f32 v238, v237, v236
	v_add_co_u32_e32 v236, vcc, s55, v50
	s_nop 1
	v_addc_co_u32_e32 v237, vcc, 0, v51, vcc
	global_store_dword v[236:237], v238, off
	ds_read2st64_b64 v[236:239], v92 offset0:82 offset1:98
	s_waitcnt lgkmcnt(0)
	v_pk_add_f32 v[236:237], v[238:239], v[236:237] neg_lo:[0,1] neg_hi:[0,1]
	s_nop 0
	v_pk_add_f32 v[240:241], v[240:241], v[236:237]
	v_mul_f32_e32 v236, v77, v242
	v_lshlrev_b32_e32 v237, 16, v110
	v_and_b32_e32 v238, 0xffff0000, v110
	v_fma_f32 v237, v236, v240, -v237
	v_fma_f32 v236, v236, v241, -v238
	v_cvt_pk_bf16_f32 v238, v237, v236
	v_add_co_u32_e32 v236, vcc, s56, v50
	s_nop 1
	v_addc_co_u32_e32 v237, vcc, 0, v51, vcc
	global_store_dword v[236:237], v238, off
	ds_read2st64_b64 v[236:239], v92 offset0:83 offset1:99
	s_waitcnt lgkmcnt(0)
	v_pk_add_f32 v[236:237], v[238:239], v[236:237] neg_lo:[0,1] neg_hi:[0,1]
	s_nop 0
	v_pk_add_f32 v[240:241], v[240:241], v[236:237]
	v_mul_f32_e32 v236, v78, v242
	v_lshlrev_b32_e32 v237, 16, v115
	v_and_b32_e32 v238, 0xffff0000, v115
	v_fma_f32 v237, v236, v240, -v237
	v_fma_f32 v236, v236, v241, -v238
	v_cvt_pk_bf16_f32 v238, v237, v236
	v_add_co_u32_e32 v236, vcc, s57, v50
	s_nop 1
	v_addc_co_u32_e32 v237, vcc, 0, v51, vcc
	global_store_dword v[236:237], v238, off
	ds_read2st64_b64 v[236:239], v92 offset0:84 offset1:100
	s_waitcnt lgkmcnt(0)
	v_pk_add_f32 v[236:237], v[238:239], v[236:237] neg_lo:[0,1] neg_hi:[0,1]
	s_nop 0
	v_pk_add_f32 v[240:241], v[240:241], v[236:237]
	v_mul_f32_e32 v236, v79, v242
	v_lshlrev_b32_e32 v237, 16, v120
	v_and_b32_e32 v238, 0xffff0000, v120
	v_fma_f32 v237, v236, v240, -v237
	v_fma_f32 v236, v236, v241, -v238
	v_cvt_pk_bf16_f32 v238, v237, v236
	v_add_co_u32_e32 v236, vcc, s58, v50
	s_nop 1
	v_addc_co_u32_e32 v237, vcc, 0, v51, vcc
	global_store_dword v[236:237], v238, off
	ds_read2st64_b64 v[236:239], v92 offset0:85 offset1:101
	s_waitcnt lgkmcnt(0)
	v_pk_add_f32 v[236:237], v[238:239], v[236:237] neg_lo:[0,1] neg_hi:[0,1]
	s_nop 0
	v_pk_add_f32 v[240:241], v[240:241], v[236:237]
	v_mul_f32_e32 v236, v80, v242
	v_lshlrev_b32_e32 v237, 16, v127
	v_and_b32_e32 v238, 0xffff0000, v127
	v_fma_f32 v237, v236, v240, -v237
	v_fma_f32 v236, v236, v241, -v238
	v_cvt_pk_bf16_f32 v238, v237, v236
	v_add_co_u32_e32 v236, vcc, s59, v50
	s_nop 1
	v_addc_co_u32_e32 v237, vcc, 0, v51, vcc
	global_store_dword v[236:237], v238, off
	ds_read2st64_b64 v[236:239], v92 offset0:86 offset1:102
	v_add_co_u32_e32 v50, vcc, s60, v50
	s_waitcnt lgkmcnt(0)
	v_pk_add_f32 v[236:237], v[238:239], v[236:237] neg_lo:[0,1] neg_hi:[0,1]
	s_nop 0
	v_pk_add_f32 v[236:237], v[240:241], v[236:237]
	v_mul_f32_e32 v238, v81, v242
	v_lshlrev_b32_e32 v239, 16, v156
	v_fma_f32 v236, v238, v236, -v239
	v_and_b32_e32 v239, 0xffff0000, v156
	v_addc_co_u32_e32 v51, vcc, 0, v51, vcc
	v_fma_f32 v237, v238, v237, -v239
	v_cvt_pk_bf16_f32 v236, v236, v237
	global_store_dword v[50:51], v236, off
	v_lshlrev_b32_e32 v50, 16, v140
	v_and_b32_e32 v51, 0xffff0000, v140
	v_pk_fma_f32 v[18:19], v[2:3], v[50:51], v[18:19] op_sel_hi:[0,1,1] neg_lo:[1,0,0] neg_hi:[1,0,0]
	v_lshlrev_b32_e32 v50, 16, v149
	v_and_b32_e32 v51, 0xffff0000, v149
	v_pk_fma_f32 v[20:21], v[2:3], v[50:51], v[20:21] op_sel_hi:[0,1,1] neg_lo:[1,0,0] neg_hi:[1,0,0]
	v_lshlrev_b32_e32 v50, 16, v158
	v_and_b32_e32 v51, 0xffff0000, v158
	v_pk_fma_f32 v[22:23], v[2:3], v[50:51], v[22:23] op_sel_hi:[0,1,1] neg_lo:[1,0,0] neg_hi:[1,0,0]
	v_lshlrev_b32_e32 v50, 16, v166
	v_and_b32_e32 v51, 0xffff0000, v166
	v_pk_fma_f32 v[24:25], v[2:3], v[50:51], v[24:25] op_sel_hi:[0,1,1] neg_lo:[1,0,0] neg_hi:[1,0,0]
	v_lshlrev_b32_e32 v50, 16, v175
	v_and_b32_e32 v51, 0xffff0000, v175
	v_pk_fma_f32 v[26:27], v[2:3], v[50:51], v[26:27] op_sel_hi:[0,1,1] neg_lo:[1,0,0] neg_hi:[1,0,0]
	v_lshlrev_b32_e32 v50, 16, v185
	v_and_b32_e32 v51, 0xffff0000, v185
	v_pk_fma_f32 v[28:29], v[2:3], v[50:51], v[28:29] op_sel_hi:[0,1,1] neg_lo:[1,0,0] neg_hi:[1,0,0]
	v_lshlrev_b32_e32 v50, 16, v196
	v_and_b32_e32 v51, 0xffff0000, v196
	v_pk_fma_f32 v[30:31], v[2:3], v[50:51], v[30:31] op_sel_hi:[0,1,1] neg_lo:[1,0,0] neg_hi:[1,0,0]
	v_lshlrev_b32_e32 v50, 16, v216
	v_and_b32_e32 v51, 0xffff0000, v216
	v_pk_fma_f32 v[32:33], v[2:3], v[50:51], v[32:33] op_sel_hi:[0,1,1] neg_lo:[1,0,0] neg_hi:[1,0,0]
; #define GAS __attribute__((address_space(1)))
; #define LAS __attribute__((address_space(3)))
; __device__ __forceinline__ unsigned cvt_pk_bf16(float lo, float hi) { unsigned r; asm volatile("v_cvt_pk_bf16_f32 %0, %1, %2" : "=v"(r) : "v"(lo), "v"(hi)); return r; }
; __device__ __forceinline__ float bf_lo(unsigned w) { return __uint_as_float(w << 16); }
; __device__ __forceinline__ float bf_hi(unsigned w) { return __uint_as_float(w & 0xffff0000u); }
; template <int W>
; __device__ __forceinline__ void pool_item(const Ctx& F, const bf16* Ub, bf16* Db, int r0, int nr) {
;     ...
;         for (int u = 0; u < NS; ++u) {
;             const int r = base + u;
;             if (r < re) {
;                 POOL_LOAD((u + 2) % NS, r + 2);
;                 const int e = r + HW - 1;
;                 const float me = (e >= 0 && e < 128) ? 1.0f : 0.0f, ml = (r >= r0 && r - HW >= 0) ? 1.0f : 0.0f;
; #pragma unroll
;                 for (int j = 0; j < 8; ++j) { Vv[j].x += me * bf_lo(ring[u][j]); Vv[j].y += me * bf_hi(ring[u][j]); }
;                 if (r >= r0) {
;                     LAS f32x2* row = buf + ((r & 1) * 80 + 8) * 64 + lane;
; #pragma unroll
;                     for (int j = 0; j < 8; ++j) row[(c0 + j) * 64] = Vv[j];
;                     asm volatile("s_waitcnt lgkmcnt(0)" ::: "memory"); __builtin_amdgcn_s_barrier(); asm volatile("" ::: "memory");
;                     const int rlo = r - HW > 0 ? r - HW : 0, rhi = r + HW < 128 ? r + HW : 128; const float icr = 1.0f / (float)(rhi - rlo);
;                     f32x2 h = (f32x2){0.f, 0.f};
; #pragma unroll
;                     for (int c = -HW; c < HW; ++c) h += row[(c0 + c) * 64];
; #pragma unroll
;                     for (int j = 0; j < 8; ++j) {
;                         const float ic = icr * icc[j]; const unsigned m = ring[(u + NS - HW + 1) % NS][j];
;                         *(GAS unsigned*)(Db + ((size_t)r * 64 + c0 + j) * EI) = cvt_pk_bf16(h.x * ic - bf_lo(m), h.y * ic - bf_hi(m));
;                         h += row[(c0 + j + HW) * 64] - row[(c0 + j - HW) * 64];
;                     }
; #pragma unroll
;                     for (int j = 0; j < 8; ++j) { const unsigned l = ring[(u + NS - W + 1) % NS][j]; Vv[j].x -= ml * bf_lo(l); Vv[j].y -= ml * bf_hi(l); }
;                 }
.LBB0_852:
	s_cmp_ge_i32 s44, s46
	s_cbranch_scc1 .LBB0_855
	s_min_i32 s50, s44, 0x76
	s_ashr_i32 s51, s50, 31
	s_lshl_b64 s[50:51], s[50:51], 20
	v_lshl_add_u64 v[50:51], v[12:13], 0, s[50:51]
	v_add_co_u32_e32 v236, vcc, 0x900000, v50
	s_add_i32 s10, s42, 14
	s_nop 0
	v_addc_co_u32_e32 v237, vcc, 0, v51, vcc
	global_load_dword v140, v[236:237], off
	v_add_co_u32_e32 v236, vcc, 0x904000, v50
	s_cmpk_lt_u32 s10, 0x80
	s_nop 0
	v_addc_co_u32_e32 v237, vcc, 0, v51, vcc
	global_load_dword v149, v[236:237], off
	v_add_co_u32_e32 v236, vcc, 0x908000, v50
	s_cselect_b64 s[50:51], -1, 0
	s_nop 0
	v_addc_co_u32_e32 v237, vcc, 0, v51, vcc
	global_load_dword v158, v[236:237], off
	v_add_co_u32_e32 v236, vcc, 0x90c000, v50
	v_cndmask_b32_e64 v2, 0, 1.0, s[50:51]
	s_nop 0
	v_addc_co_u32_e32 v237, vcc, 0, v51, vcc
	global_load_dword v166, v[236:237], off
	v_add_co_u32_e32 v236, vcc, 0x910000, v50
	s_cmp_lt_i32 s44, s62
	s_nop 0
	v_addc_co_u32_e32 v237, vcc, 0, v51, vcc
	global_load_dword v175, v[236:237], off
	v_add_co_u32_e32 v236, vcc, 0x914000, v50
	s_nop 1
	v_addc_co_u32_e32 v237, vcc, 0, v51, vcc
	global_load_dword v185, v[236:237], off
	v_add_co_u32_e32 v236, vcc, 0x918000, v50
	s_nop 1
	v_addc_co_u32_e32 v237, vcc, 0, v51, vcc
	v_add_co_u32_e32 v50, vcc, 0x91c000, v50
	global_load_dword v196, v[236:237], off
	s_nop 0
	v_addc_co_u32_e32 v51, vcc, 0, v51, vcc
	global_load_dword v216, v[50:51], off
	s_waitcnt vmcnt(23)
	v_lshlrev_b32_e32 v50, 16, v154
	v_and_b32_e32 v51, 0xffff0000, v154
	v_pk_fma_f32 v[18:19], v[2:3], v[50:51], v[18:19] op_sel_hi:[0,1,1]
	s_waitcnt vmcnt(22)
	v_lshlrev_b32_e32 v50, 16, v161
	v_and_b32_e32 v51, 0xffff0000, v161
	v_pk_fma_f32 v[20:21], v[2:3], v[50:51], v[20:21] op_sel_hi:[0,1,1]
	s_waitcnt vmcnt(21)
	v_lshlrev_b32_e32 v50, 16, v170
	v_and_b32_e32 v51, 0xffff0000, v170
	v_pk_fma_f32 v[22:23], v[2:3], v[50:51], v[22:23] op_sel_hi:[0,1,1]
	s_waitcnt vmcnt(20)
	v_lshlrev_b32_e32 v50, 16, v182
	v_and_b32_e32 v51, 0xffff0000, v182
	v_pk_fma_f32 v[24:25], v[2:3], v[50:51], v[24:25] op_sel_hi:[0,1,1]
	s_waitcnt vmcnt(19)
	v_lshlrev_b32_e32 v50, 16, v191
	v_and_b32_e32 v51, 0xffff0000, v191
	v_pk_fma_f32 v[26:27], v[2:3], v[50:51], v[26:27] op_sel_hi:[0,1,1]
	s_waitcnt vmcnt(18)
	v_lshlrev_b32_e32 v50, 16, v199
	v_and_b32_e32 v51, 0xffff0000, v199
	v_pk_fma_f32 v[28:29], v[2:3], v[50:51], v[28:29] op_sel_hi:[0,1,1]
	s_waitcnt vmcnt(17)
	v_lshlrev_b32_e32 v50, 16, v206
	v_and_b32_e32 v51, 0xffff0000, v206
	v_pk_fma_f32 v[30:31], v[2:3], v[50:51], v[30:31] op_sel_hi:[0,1,1]
	s_waitcnt vmcnt(16)
	v_lshlrev_b32_e32 v50, 16, v220
	v_and_b32_e32 v51, 0xffff0000, v220
	v_pk_fma_f32 v[32:33], v[2:3], v[50:51], v[32:33] op_sel_hi:[0,1,1]
	s_cbranch_scc1 .LBB0_855
	ds_write2st64_b64 v92, v[18:19], v[20:21] offset0:8 offset1:9
	ds_write2st64_b64 v92, v[22:23], v[24:25] offset0:10 offset1:11
	ds_write2st64_b64 v92, v[26:27], v[28:29] offset0:12 offset1:13
	ds_write2st64_b64 v92, v[30:31], v[32:33] offset0:14 offset1:15
	s_waitcnt lgkmcnt(0)
	s_barrier
	ds_read2st64_b64 v[236:239], v92 offset1:1
	s_cmp_gt_i32 s42, 0
	s_cselect_b64 s[50:51], -1, 0
	s_max_i32 s10, s44, 8
	s_min_i32 s16, s44, 0x78
	s_waitcnt lgkmcnt(0)
	v_pk_add_f32 v[50:51], v[236:237], 0 op_sel_hi:[1,0]
	s_sub_i32 s10, s16, s10
	v_pk_add_f32 v[50:51], v[50:51], v[238:239]
	ds_read2st64_b64 v[236:239], v92 offset0:2 offset1:3
	s_add_i32 s10, s10, 16
	v_cvt_f32_i32_e32 v240, s10
	v_cndmask_b32_e64 v2, 0, 1.0, s[50:51]
	s_mov_b32 s45, s17
	s_waitcnt lgkmcnt(0)
	v_pk_add_f32 v[50:51], v[50:51], v[236:237]
	s_lshl_b64 s[44:45], s[44:45], 20
	v_pk_add_f32 v[50:51], v[50:51], v[238:239]
	ds_read2st64_b64 v[236:239], v92 offset0:4 offset1:5
	s_waitcnt lgkmcnt(0)
	v_pk_add_f32 v[50:51], v[50:51], v[236:237]
	s_nop 0
	v_pk_add_f32 v[50:51], v[50:51], v[238:239]
	ds_read2st64_b64 v[236:239], v92 offset0:6 offset1:7
	s_waitcnt lgkmcnt(0)
	v_pk_add_f32 v[50:51], v[50:51], v[236:237]
	s_nop 0
	v_pk_add_f32 v[50:51], v[50:51], v[238:239]
	ds_read2st64_b64 v[236:239], v92 offset0:8 offset1:9
	s_waitcnt lgkmcnt(0)
	v_pk_add_f32 v[50:51], v[50:51], v[236:237]
	s_nop 0
	v_pk_add_f32 v[50:51], v[50:51], v[238:239]
	ds_read2st64_b64 v[236:239], v92 offset0:10 offset1:11
	s_waitcnt lgkmcnt(0)
	v_pk_add_f32 v[50:51], v[50:51], v[236:237]
	s_nop 0
	v_pk_add_f32 v[50:51], v[50:51], v[238:239]
	ds_read2st64_b64 v[236:239], v92 offset0:12 offset1:13
	s_waitcnt lgkmcnt(0)
	v_pk_add_f32 v[50:51], v[50:51], v[236:237]
	s_nop 0
	v_pk_add_f32 v[50:51], v[50:51], v[238:239]
	ds_read2st64_b64 v[236:239], v92 offset0:14 offset1:15
	s_waitcnt lgkmcnt(0)
	v_pk_add_f32 v[50:51], v[50:51], v[236:237]
	v_div_scale_f32 v236, s[50:51], v240, v240, 1.0
	v_rcp_f32_e32 v237, v236
	v_pk_add_f32 v[50:51], v[50:51], v[238:239]
	v_fma_f32 v238, -v236, v237, 1.0
	v_fmac_f32_e32 v237, v238, v237
	v_div_scale_f32 v238, vcc, 1.0, v240, 1.0
	v_mul_f32_e32 v239, v238, v237
	v_fma_f32 v241, -v236, v239, v238
	v_fmac_f32_e32 v239, v241, v237
	v_fma_f32 v236, -v236, v239, v238
	v_div_fmas_f32 v236, v236, v237, v239
	v_div_fixup_f32 v242, v236, v240, 1.0
	v_mul_f32_e32 v236, v74, v242
	v_fma_f32 v237, v236, v50, -v34
	v_fma_f32 v236, v236, v51, -v35
	v_cvt_pk_bf16_f32 v236, v237, v236
	v_lshl_add_u64 v[240:241], v[14:15], 0, s[44:45]
	global_store_dword v[240:241], v236, off
	ds_read2st64_b64 v[236:239], v92 offset1:16
	s_waitcnt lgkmcnt(0)
	v_pk_add_f32 v[236:237], v[238:239], v[236:237] neg_lo:[0,1] neg_hi:[0,1]
	s_nop 0
	v_pk_add_f32 v[50:51], v[50:51], v[236:237]
	v_mul_f32_e32 v236, v75, v242
	v_fma_f32 v237, v236, v50, -v36
	v_fma_f32 v236, v236, v51, -v37
	v_cvt_pk_bf16_f32 v238, v237, v236
	v_add_co_u32_e32 v236, vcc, s54, v240
	s_nop 1
	v_addc_co_u32_e32 v237, vcc, 0, v241, vcc
	global_store_dword v[236:237], v238, off
	ds_read2st64_b64 v[236:239], v92 offset0:1 offset1:17
	s_waitcnt lgkmcnt(0)
; #define GAS __attribute__((address_space(1)))
; #define LAS __attribute__((address_space(3)))
; __device__ __forceinline__ unsigned cvt_pk_bf16(float lo, float hi) { unsigned r; asm volatile("v_cvt_pk_bf16_f32 %0, %1, %2" : "=v"(r) : "v"(lo), "v"(hi)); return r; }
; __device__ __forceinline__ float bf_lo(unsigned w) { return __uint_as_float(w << 16); }
; __device__ __forceinline__ float bf_hi(unsigned w) { return __uint_as_float(w & 0xffff0000u); }
; template <int W>
; __device__ __forceinline__ void pool_item(const Ctx& F, const bf16* Ub, bf16* Db, int r0, int nr) {
;     ...
;         for (int u = 0; u < NS; ++u) {
;             const int r = base + u;
;             if (r < re) {
;                 POOL_LOAD((u + 2) % NS, r + 2);
;                 const int e = r + HW - 1;
;                 const float me = (e >= 0 && e < 128) ? 1.0f : 0.0f, ml = (r >= r0 && r - HW >= 0) ? 1.0f : 0.0f;
; #pragma unroll
;                 for (int j = 0; j < 8; ++j) { Vv[j].x += me * bf_lo(ring[u][j]); Vv[j].y += me * bf_hi(ring[u][j]); }
;                 if (r >= r0) {
;                     LAS f32x2* row = buf + ((r & 1) * 80 + 8) * 64 + lane;
; #pragma unroll
;                     for (int j = 0; j < 8; ++j) row[(c0 + j) * 64] = Vv[j];
;                     asm volatile("s_waitcnt lgkmcnt(0)" ::: "memory"); __builtin_amdgcn_s_barrier(); asm volatile("" ::: "memory");
;                     const int rlo = r - HW > 0 ? r - HW : 0, rhi = r + HW < 128 ? r + HW : 128; const float icr = 1.0f / (float)(rhi - rlo);
;                     f32x2 h = (f32x2){0.f, 0.f};
; #pragma unroll
;                     for (int c = -HW; c < HW; ++c) h += row[(c0 + c) * 64];
; #pragma unroll
;                     for (int j = 0; j < 8; ++j) {
;                         const float ic = icr * icc[j]; const unsigned m = ring[(u + NS - HW + 1) % NS][j];
;                         *(GAS unsigned*)(Db + ((size_t)r * 64 + c0 + j) * EI) = cvt_pk_bf16(h.x * ic - bf_lo(m), h.y * ic - bf_hi(m));
;                         h += row[(c0 + j + HW) * 64] - row[(c0 + j - HW) * 64];
;                     }
; #pragma unroll
;                     for (int j = 0; j < 8; ++j) { const unsigned l = ring[(u + NS - W + 1) % NS][j]; Vv[j].x -= ml * bf_lo(l); Vv[j].y -= ml * bf_hi(l); }
;                 }
	v_pk_add_f32 v[236:237], v[238:239], v[236:237] neg_lo:[0,1] neg_hi:[0,1]
	s_nop 0
	v_pk_add_f32 v[50:51], v[50:51], v[236:237]
	v_mul_f32_e32 v236, v76, v242
	v_fma_f32 v237, v236, v50, -v38
	v_fma_f32 v236, v236, v51, -v39
	v_cvt_pk_bf16_f32 v238, v237, v236
	v_add_co_u32_e32 v236, vcc, s55, v240
	s_nop 1
	v_addc_co_u32_e32 v237, vcc, 0, v241, vcc
	global_store_dword v[236:237], v238, off
	ds_read2st64_b64 v[236:239], v92 offset0:2 offset1:18
	s_waitcnt lgkmcnt(0)
	v_pk_add_f32 v[236:237], v[238:239], v[236:237] neg_lo:[0,1] neg_hi:[0,1]
	s_nop 0
	v_pk_add_f32 v[50:51], v[50:51], v[236:237]
	v_mul_f32_e32 v236, v77, v242
	v_fma_f32 v237, v236, v50, -v40
	v_fma_f32 v236, v236, v51, -v41
	v_cvt_pk_bf16_f32 v238, v237, v236
	v_add_co_u32_e32 v236, vcc, s56, v240
	s_nop 1
	v_addc_co_u32_e32 v237, vcc, 0, v241, vcc
	global_store_dword v[236:237], v238, off
	ds_read2st64_b64 v[236:239], v92 offset0:3 offset1:19
	s_waitcnt lgkmcnt(0)
	v_pk_add_f32 v[236:237], v[238:239], v[236:237] neg_lo:[0,1] neg_hi:[0,1]
	s_nop 0
	v_pk_add_f32 v[50:51], v[50:51], v[236:237]
	v_mul_f32_e32 v236, v78, v242
	v_fma_f32 v237, v236, v50, -v42
	v_fma_f32 v236, v236, v51, -v43
	v_cvt_pk_bf16_f32 v238, v237, v236
	v_add_co_u32_e32 v236, vcc, s57, v240
	s_nop 1
	v_addc_co_u32_e32 v237, vcc, 0, v241, vcc
	global_store_dword v[236:237], v238, off
	ds_read2st64_b64 v[236:239], v92 offset0:4 offset1:20
	s_waitcnt lgkmcnt(0)
	v_pk_add_f32 v[236:237], v[238:239], v[236:237] neg_lo:[0,1] neg_hi:[0,1]
	s_nop 0
	v_pk_add_f32 v[50:51], v[50:51], v[236:237]
	v_mul_f32_e32 v236, v79, v242
	v_fma_f32 v237, v236, v50, -v44
	v_fma_f32 v236, v236, v51, -v45
	v_cvt_pk_bf16_f32 v238, v237, v236
	v_add_co_u32_e32 v236, vcc, s58, v240
	s_nop 1
	v_addc_co_u32_e32 v237, vcc, 0, v241, vcc
	global_store_dword v[236:237], v238, off
	ds_read2st64_b64 v[236:239], v92 offset0:5 offset1:21
	s_waitcnt lgkmcnt(0)
	v_pk_add_f32 v[236:237], v[238:239], v[236:237] neg_lo:[0,1] neg_hi:[0,1]
	s_nop 0
	v_pk_add_f32 v[50:51], v[50:51], v[236:237]
	v_mul_f32_e32 v236, v80, v242
	v_fma_f32 v237, v236, v50, -v46
	v_fma_f32 v236, v236, v51, -v47
	v_cvt_pk_bf16_f32 v238, v237, v236
	v_add_co_u32_e32 v236, vcc, s59, v240
	s_nop 1
	v_addc_co_u32_e32 v237, vcc, 0, v241, vcc
	global_store_dword v[236:237], v238, off
	ds_read2st64_b64 v[236:239], v92 offset0:6 offset1:22
	s_waitcnt lgkmcnt(0)
	v_pk_add_f32 v[236:237], v[238:239], v[236:237] neg_lo:[0,1] neg_hi:[0,1]
	s_nop 0
	v_pk_add_f32 v[50:51], v[50:51], v[236:237]
	v_mul_f32_e32 v236, v81, v242
	v_fma_f32 v50, v236, v50, -v48
	v_fma_f32 v51, v236, v51, -v49
	v_cvt_pk_bf16_f32 v236, v50, v51
	v_add_co_u32_e32 v50, vcc, s60, v240
	s_nop 1
	v_addc_co_u32_e32 v51, vcc, 0, v241, vcc
	global_store_dword v[50:51], v236, off
	v_lshlrev_b32_e32 v50, 16, v133
	v_and_b32_e32 v51, 0xffff0000, v133
	v_pk_fma_f32 v[18:19], v[2:3], v[50:51], v[18:19] op_sel_hi:[0,1,1] neg_lo:[1,0,0] neg_hi:[1,0,0]
	v_lshlrev_b32_e32 v50, 16, v142
	v_and_b32_e32 v51, 0xffff0000, v142
	v_pk_fma_f32 v[20:21], v[2:3], v[50:51], v[20:21] op_sel_hi:[0,1,1] neg_lo:[1,0,0] neg_hi:[1,0,0]
	v_lshlrev_b32_e32 v50, 16, v150
	v_and_b32_e32 v51, 0xffff0000, v150
	v_pk_fma_f32 v[22:23], v[2:3], v[50:51], v[22:23] op_sel_hi:[0,1,1] neg_lo:[1,0,0] neg_hi:[1,0,0]
	v_lshlrev_b32_e32 v50, 16, v159
	v_and_b32_e32 v51, 0xffff0000, v159
	v_pk_fma_f32 v[24:25], v[2:3], v[50:51], v[24:25] op_sel_hi:[0,1,1] neg_lo:[1,0,0] neg_hi:[1,0,0]
	v_lshlrev_b32_e32 v50, 16, v167
	v_and_b32_e32 v51, 0xffff0000, v167
	v_pk_fma_f32 v[26:27], v[2:3], v[50:51], v[26:27] op_sel_hi:[0,1,1] neg_lo:[1,0,0] neg_hi:[1,0,0]
	v_lshlrev_b32_e32 v50, 16, v177
	v_and_b32_e32 v51, 0xffff0000, v177
	v_pk_fma_f32 v[28:29], v[2:3], v[50:51], v[28:29] op_sel_hi:[0,1,1] neg_lo:[1,0,0] neg_hi:[1,0,0]
	v_lshlrev_b32_e32 v50, 16, v189
	v_and_b32_e32 v51, 0xffff0000, v189
	v_pk_fma_f32 v[30:31], v[2:3], v[50:51], v[30:31] op_sel_hi:[0,1,1] neg_lo:[1,0,0] neg_hi:[1,0,0]
	v_lshlrev_b32_e32 v50, 16, v212
	v_and_b32_e32 v51, 0xffff0000, v212
	v_pk_fma_f32 v[32:33], v[2:3], v[50:51], v[32:33] op_sel_hi:[0,1,1] neg_lo:[1,0,0] neg_hi:[1,0,0]
.LBB0_855:
	s_add_i32 s16, s42, 8
	s_cmp_ge_i32 s16, s46
	s_cbranch_scc1 .LBB0_858
	s_min_i32 s44, s16, 0x76
	s_ashr_i32 s45, s44, 31
	s_lshl_b64 s[44:45], s[44:45], 20
	v_lshl_add_u64 v[50:51], v[12:13], 0, s[44:45]
	v_add_co_u32_e32 v236, vcc, 0x900000, v50
	s_add_i32 s10, s42, 15
	s_nop 0
	v_addc_co_u32_e32 v237, vcc, 0, v51, vcc
	global_load_dword v133, v[236:237], off
	v_add_co_u32_e32 v236, vcc, 0x904000, v50
	s_cmpk_lt_u32 s10, 0x80
	s_nop 0
	v_addc_co_u32_e32 v237, vcc, 0, v51, vcc
	global_load_dword v142, v[236:237], off
	v_add_co_u32_e32 v236, vcc, 0x908000, v50
	s_cselect_b64 s[44:45], -1, 0
	s_nop 0
	v_addc_co_u32_e32 v237, vcc, 0, v51, vcc
	global_load_dword v150, v[236:237], off
	v_add_co_u32_e32 v236, vcc, 0x90c000, v50
	v_cndmask_b32_e64 v2, 0, 1.0, s[44:45]
	s_nop 0
	v_addc_co_u32_e32 v237, vcc, 0, v51, vcc
	global_load_dword v159, v[236:237], off
	v_add_co_u32_e32 v236, vcc, 0x910000, v50
	s_cmp_lt_i32 s16, s62
	s_nop 0
	v_addc_co_u32_e32 v237, vcc, 0, v51, vcc
	global_load_dword v167, v[236:237], off
	v_add_co_u32_e32 v236, vcc, 0x914000, v50
	s_nop 1
	v_addc_co_u32_e32 v237, vcc, 0, v51, vcc
	global_load_dword v177, v[236:237], off
	v_add_co_u32_e32 v236, vcc, 0x918000, v50
	s_nop 1
	v_addc_co_u32_e32 v237, vcc, 0, v51, vcc
	v_add_co_u32_e32 v50, vcc, 0x91c000, v50
	global_load_dword v189, v[236:237], off
	s_nop 0
	v_addc_co_u32_e32 v51, vcc, 0, v51, vcc
	global_load_dword v212, v[50:51], off
	s_waitcnt vmcnt(23)
	v_lshlrev_b32_e32 v50, 16, v148
	v_and_b32_e32 v51, 0xffff0000, v148
	v_pk_fma_f32 v[18:19], v[2:3], v[50:51], v[18:19] op_sel_hi:[0,1,1]
	s_waitcnt vmcnt(22)
	v_lshlrev_b32_e32 v50, 16, v157
	v_and_b32_e32 v51, 0xffff0000, v157
	v_pk_fma_f32 v[20:21], v[2:3], v[50:51], v[20:21] op_sel_hi:[0,1,1]
	s_waitcnt vmcnt(21)
	v_lshlrev_b32_e32 v50, 16, v165
	v_and_b32_e32 v51, 0xffff0000, v165
	v_pk_fma_f32 v[22:23], v[2:3], v[50:51], v[22:23] op_sel_hi:[0,1,1]
	s_waitcnt vmcnt(20)
	v_lshlrev_b32_e32 v50, 16, v174
	v_and_b32_e32 v51, 0xffff0000, v174
	v_pk_fma_f32 v[24:25], v[2:3], v[50:51], v[24:25] op_sel_hi:[0,1,1]
	s_waitcnt vmcnt(19)
	v_lshlrev_b32_e32 v50, 16, v183
	v_and_b32_e32 v51, 0xffff0000, v183
	v_pk_fma_f32 v[26:27], v[2:3], v[50:51], v[26:27] op_sel_hi:[0,1,1]
	s_waitcnt vmcnt(18)
	v_lshlrev_b32_e32 v50, 16, v193
	v_and_b32_e32 v51, 0xffff0000, v193
	v_pk_fma_f32 v[28:29], v[2:3], v[50:51], v[28:29] op_sel_hi:[0,1,1]
	s_waitcnt vmcnt(17)
	v_lshlrev_b32_e32 v50, 16, v202
	v_and_b32_e32 v51, 0xffff0000, v202
	v_pk_fma_f32 v[30:31], v[2:3], v[50:51], v[30:31] op_sel_hi:[0,1,1]
	s_waitcnt vmcnt(16)
	v_lshlrev_b32_e32 v50, 16, v219
	v_and_b32_e32 v51, 0xffff0000, v219
	v_pk_fma_f32 v[32:33], v[2:3], v[50:51], v[32:33] op_sel_hi:[0,1,1]
	s_cbranch_scc1 .LBB0_858
; #define GAS __attribute__((address_space(1)))
; #define LAS __attribute__((address_space(3)))
; __device__ __forceinline__ unsigned cvt_pk_bf16(float lo, float hi) { unsigned r; asm volatile("v_cvt_pk_bf16_f32 %0, %1, %2" : "=v"(r) : "v"(lo), "v"(hi)); return r; }
; __device__ __forceinline__ float bf_lo(unsigned w) { return __uint_as_float(w << 16); }
; __device__ __forceinline__ float bf_hi(unsigned w) { return __uint_as_float(w & 0xffff0000u); }
; template <int W>
; __device__ __forceinline__ void pool_item(const Ctx& F, const bf16* Ub, bf16* Db, int r0, int nr) {
;     ...
;                 if (r >= r0) {
;                     LAS f32x2* row = buf + ((r & 1) * 80 + 8) * 64 + lane;
; #pragma unroll
;                     for (int j = 0; j < 8; ++j) row[(c0 + j) * 64] = Vv[j];
;                     asm volatile("s_waitcnt lgkmcnt(0)" ::: "memory"); __builtin_amdgcn_s_barrier(); asm volatile("" ::: "memory");
;                     const int rlo = r - HW > 0 ? r - HW : 0, rhi = r + HW < 128 ? r + HW : 128; const float icr = 1.0f / (float)(rhi - rlo);
;                     f32x2 h = (f32x2){0.f, 0.f};
; #pragma unroll
;                     for (int c = -HW; c < HW; ++c) h += row[(c0 + c) * 64];
; #pragma unroll
;                     for (int j = 0; j < 8; ++j) {
;                         const float ic = icr * icc[j]; const unsigned m = ring[(u + NS - HW + 1) % NS][j];
;                         *(GAS unsigned*)(Db + ((size_t)r * 64 + c0 + j) * EI) = cvt_pk_bf16(h.x * ic - bf_lo(m), h.y * ic - bf_hi(m));
;                         h += row[(c0 + j + HW) * 64] - row[(c0 + j - HW) * 64];
	ds_write2st64_b64 v92, v[18:19], v[20:21] offset0:88 offset1:89
	ds_write2st64_b64 v92, v[22:23], v[24:25] offset0:90 offset1:91
	ds_write2st64_b64 v92, v[26:27], v[28:29] offset0:92 offset1:93
	ds_write2st64_b64 v92, v[30:31], v[32:33] offset0:94 offset1:95
	s_waitcnt lgkmcnt(0)
	s_barrier
	ds_read2st64_b64 v[236:239], v92 offset0:80 offset1:81
	s_cmp_gt_i32 s42, -1
	s_cselect_b64 s[44:45], -1, 0
	s_max_i32 s10, s16, 8
	s_min_i32 s23, s16, 0x78
	s_waitcnt lgkmcnt(0)
	v_pk_add_f32 v[50:51], v[236:237], 0 op_sel_hi:[1,0]
	s_sub_i32 s10, s23, s10
	v_pk_add_f32 v[50:51], v[50:51], v[238:239]
	ds_read2st64_b64 v[236:239], v92 offset0:82 offset1:83
	s_add_i32 s10, s10, 16
	v_cvt_f32_i32_e32 v242, s10
	v_cndmask_b32_e64 v2, 0, 1.0, s[44:45]
	s_waitcnt lgkmcnt(0)
	v_pk_add_f32 v[50:51], v[50:51], v[236:237]
	s_nop 0
	v_pk_add_f32 v[50:51], v[50:51], v[238:239]
	ds_read2st64_b64 v[236:239], v92 offset0:84 offset1:85
	s_waitcnt lgkmcnt(0)
	v_pk_add_f32 v[50:51], v[50:51], v[236:237]
	s_nop 0
	v_pk_add_f32 v[50:51], v[50:51], v[238:239]
	ds_read2st64_b64 v[236:239], v92 offset0:86 offset1:87
	s_waitcnt lgkmcnt(0)
	v_pk_add_f32 v[50:51], v[50:51], v[236:237]
	s_nop 0
	v_pk_add_f32 v[50:51], v[50:51], v[238:239]
	ds_read2st64_b64 v[236:239], v92 offset0:88 offset1:89
	s_waitcnt lgkmcnt(0)
	v_pk_add_f32 v[50:51], v[50:51], v[236:237]
	s_nop 0
	v_pk_add_f32 v[50:51], v[50:51], v[238:239]
	ds_read2st64_b64 v[236:239], v92 offset0:90 offset1:91
	s_waitcnt lgkmcnt(0)
	v_pk_add_f32 v[50:51], v[50:51], v[236:237]
	s_nop 0
	v_pk_add_f32 v[50:51], v[50:51], v[238:239]
	ds_read2st64_b64 v[236:239], v92 offset0:92 offset1:93
	s_waitcnt lgkmcnt(0)
	v_pk_add_f32 v[50:51], v[50:51], v[236:237]
	s_nop 0
	v_pk_add_f32 v[50:51], v[50:51], v[238:239]
	ds_read2st64_b64 v[236:239], v92 offset0:94 offset1:95
	s_waitcnt lgkmcnt(0)
	v_pk_add_f32 v[50:51], v[50:51], v[236:237]
	s_nop 0
	v_pk_add_f32 v[240:241], v[50:51], v[238:239]
	v_div_scale_f32 v50, s[44:45], v242, v242, 1.0
	v_rcp_f32_e32 v51, v50
	s_lshl_b64 s[44:45], s[16:17], 20
	v_fma_f32 v236, -v50, v51, 1.0
	v_fmac_f32_e32 v51, v236, v51
	v_div_scale_f32 v236, vcc, 1.0, v242, 1.0
	v_mul_f32_e32 v237, v236, v51
	v_fma_f32 v238, -v50, v237, v236
	v_fmac_f32_e32 v237, v238, v51
	v_fma_f32 v50, -v50, v237, v236
	v_div_fmas_f32 v50, v50, v51, v237
	v_div_fixup_f32 v242, v50, v242, 1.0
	v_mul_f32_e32 v50, v74, v242
	v_lshlrev_b32_e32 v51, 16, v97
	v_and_b32_e32 v236, 0xffff0000, v97
	v_fma_f32 v51, v50, v240, -v51
	v_fma_f32 v50, v50, v241, -v236
	v_cvt_pk_bf16_f32 v236, v51, v50
	v_lshl_add_u64 v[50:51], v[14:15], 0, s[44:45]
	global_store_dword v[50:51], v236, off
	ds_read2st64_b64 v[236:239], v92 offset0:80 offset1:96
	s_waitcnt lgkmcnt(0)
	v_pk_add_f32 v[236:237], v[238:239], v[236:237] neg_lo:[0,1] neg_hi:[0,1]
	s_nop 0
	v_pk_add_f32 v[240:241], v[240:241], v[236:237]
	v_mul_f32_e32 v236, v75, v242
	v_lshlrev_b32_e32 v237, 16, v98
	v_and_b32_e32 v238, 0xffff0000, v98
	v_fma_f32 v237, v236, v240, -v237
	v_fma_f32 v236, v236, v241, -v238
	v_cvt_pk_bf16_f32 v238, v237, v236
	v_add_co_u32_e32 v236, vcc, s54, v50
	s_nop 1
	v_addc_co_u32_e32 v237, vcc, 0, v51, vcc
	global_store_dword v[236:237], v238, off
	ds_read2st64_b64 v[236:239], v92 offset0:81 offset1:97
	s_waitcnt lgkmcnt(0)
	v_pk_add_f32 v[236:237], v[238:239], v[236:237] neg_lo:[0,1] neg_hi:[0,1]
	s_nop 0
	v_pk_add_f32 v[240:241], v[240:241], v[236:237]
	v_mul_f32_e32 v236, v76, v242
	v_lshlrev_b32_e32 v237, 16, v99
	v_and_b32_e32 v238, 0xffff0000, v99
	v_fma_f32 v237, v236, v240, -v237
	v_fma_f32 v236, v236, v241, -v238
	v_cvt_pk_bf16_f32 v238, v237, v236
	v_add_co_u32_e32 v236, vcc, s55, v50
	s_nop 1
	v_addc_co_u32_e32 v237, vcc, 0, v51, vcc
	global_store_dword v[236:237], v238, off
	ds_read2st64_b64 v[236:239], v92 offset0:82 offset1:98
	s_waitcnt lgkmcnt(0)
	v_pk_add_f32 v[236:237], v[238:239], v[236:237] neg_lo:[0,1] neg_hi:[0,1]
	s_nop 0
	v_pk_add_f32 v[240:241], v[240:241], v[236:237]
	v_mul_f32_e32 v236, v77, v242
	v_lshlrev_b32_e32 v237, 16, v100
	v_and_b32_e32 v238, 0xffff0000, v100
	v_fma_f32 v237, v236, v240, -v237
	v_fma_f32 v236, v236, v241, -v238
	v_cvt_pk_bf16_f32 v238, v237, v236
	v_add_co_u32_e32 v236, vcc, s56, v50
	s_nop 1
	v_addc_co_u32_e32 v237, vcc, 0, v51, vcc
	global_store_dword v[236:237], v238, off
	ds_read2st64_b64 v[236:239], v92 offset0:83 offset1:99
	s_waitcnt lgkmcnt(0)
	v_pk_add_f32 v[236:237], v[238:239], v[236:237] neg_lo:[0,1] neg_hi:[0,1]
	s_nop 0
	v_pk_add_f32 v[240:241], v[240:241], v[236:237]
	v_mul_f32_e32 v236, v78, v242
	v_lshlrev_b32_e32 v237, 16, v104
	v_and_b32_e32 v238, 0xffff0000, v104
	v_fma_f32 v237, v236, v240, -v237
	v_fma_f32 v236, v236, v241, -v238
	v_cvt_pk_bf16_f32 v238, v237, v236
	v_add_co_u32_e32 v236, vcc, s57, v50
	s_nop 1
	v_addc_co_u32_e32 v237, vcc, 0, v51, vcc
	global_store_dword v[236:237], v238, off
	ds_read2st64_b64 v[236:239], v92 offset0:84 offset1:100
	s_waitcnt lgkmcnt(0)
	v_pk_add_f32 v[236:237], v[238:239], v[236:237] neg_lo:[0,1] neg_hi:[0,1]
	s_nop 0
	v_pk_add_f32 v[240:241], v[240:241], v[236:237]
	v_mul_f32_e32 v236, v79, v242
	v_lshlrev_b32_e32 v237, 16, v109
	v_and_b32_e32 v238, 0xffff0000, v109
	v_fma_f32 v237, v236, v240, -v237
	v_fma_f32 v236, v236, v241, -v238
	v_cvt_pk_bf16_f32 v238, v237, v236
	v_add_co_u32_e32 v236, vcc, s58, v50
	s_nop 1
	v_addc_co_u32_e32 v237, vcc, 0, v51, vcc
	global_store_dword v[236:237], v238, off
	ds_read2st64_b64 v[236:239], v92 offset0:85 offset1:101
	s_waitcnt lgkmcnt(0)
; #define GAS __attribute__((address_space(1)))
; #define LAS __attribute__((address_space(3)))
; __device__ __forceinline__ unsigned cvt_pk_bf16(float lo, float hi) { unsigned r; asm volatile("v_cvt_pk_bf16_f32 %0, %1, %2" : "=v"(r) : "v"(lo), "v"(hi)); return r; }
; __device__ __forceinline__ float bf_lo(unsigned w) { return __uint_as_float(w << 16); }
; __device__ __forceinline__ float bf_hi(unsigned w) { return __uint_as_float(w & 0xffff0000u); }
; template <int W>
; __device__ __forceinline__ void pool_item(const Ctx& F, const bf16* Ub, bf16* Db, int r0, int nr) {
;     ...
;         for (int u = 0; u < NS; ++u) {
;             const int r = base + u;
;             if (r < re) {
;                 POOL_LOAD((u + 2) % NS, r + 2);
;                 const int e = r + HW - 1;
;                 const float me = (e >= 0 && e < 128) ? 1.0f : 0.0f, ml = (r >= r0 && r - HW >= 0) ? 1.0f : 0.0f;
; #pragma unroll
;                 for (int j = 0; j < 8; ++j) { Vv[j].x += me * bf_lo(ring[u][j]); Vv[j].y += me * bf_hi(ring[u][j]); }
;                 if (r >= r0) {
;                     LAS f32x2* row = buf + ((r & 1) * 80 + 8) * 64 + lane;
; #pragma unroll
;                     for (int j = 0; j < 8; ++j) row[(c0 + j) * 64] = Vv[j];
;                     asm volatile("s_waitcnt lgkmcnt(0)" ::: "memory"); __builtin_amdgcn_s_barrier(); asm volatile("" ::: "memory");
;                     const int rlo = r - HW > 0 ? r - HW : 0, rhi = r + HW < 128 ? r + HW : 128; const float icr = 1.0f / (float)(rhi - rlo);
;                     f32x2 h = (f32x2){0.f, 0.f};
; #pragma unroll
;                     for (int c = -HW; c < HW; ++c) h += row[(c0 + c) * 64];
; #pragma unroll
;                     for (int j = 0; j < 8; ++j) {
;                         const float ic = icr * icc[j]; const unsigned m = ring[(u + NS - HW + 1) % NS][j];
;                         *(GAS unsigned*)(Db + ((size_t)r * 64 + c0 + j) * EI) = cvt_pk_bf16(h.x * ic - bf_lo(m), h.y * ic - bf_hi(m));
;                         h += row[(c0 + j + HW) * 64] - row[(c0 + j - HW) * 64];
;                     }
; #pragma unroll
;                     for (int j = 0; j < 8; ++j) { const unsigned l = ring[(u + NS - W + 1) % NS][j]; Vv[j].x -= ml * bf_lo(l); Vv[j].y -= ml * bf_hi(l); }
;                 }
	v_pk_add_f32 v[236:237], v[238:239], v[236:237] neg_lo:[0,1] neg_hi:[0,1]
	s_nop 0
	v_pk_add_f32 v[240:241], v[240:241], v[236:237]
	v_mul_f32_e32 v236, v80, v242
	v_lshlrev_b32_e32 v237, 16, v114
	v_and_b32_e32 v238, 0xffff0000, v114
	v_fma_f32 v237, v236, v240, -v237
	v_fma_f32 v236, v236, v241, -v238
	v_cvt_pk_bf16_f32 v238, v237, v236
	v_add_co_u32_e32 v236, vcc, s59, v50
	s_nop 1
	v_addc_co_u32_e32 v237, vcc, 0, v51, vcc
	global_store_dword v[236:237], v238, off
	ds_read2st64_b64 v[236:239], v92 offset0:86 offset1:102
	v_add_co_u32_e32 v50, vcc, s60, v50
	s_waitcnt lgkmcnt(0)
	v_pk_add_f32 v[236:237], v[238:239], v[236:237] neg_lo:[0,1] neg_hi:[0,1]
	s_nop 0
	v_pk_add_f32 v[236:237], v[240:241], v[236:237]
	v_mul_f32_e32 v238, v81, v242
	v_lshlrev_b32_e32 v239, 16, v141
	v_fma_f32 v236, v238, v236, -v239
	v_and_b32_e32 v239, 0xffff0000, v141
	v_addc_co_u32_e32 v51, vcc, 0, v51, vcc
	v_fma_f32 v237, v238, v237, -v239
	v_cvt_pk_bf16_f32 v236, v236, v237
	global_store_dword v[50:51], v236, off
	v_lshlrev_b32_e32 v50, 16, v126
	v_and_b32_e32 v51, 0xffff0000, v126
	v_pk_fma_f32 v[18:19], v[2:3], v[50:51], v[18:19] op_sel_hi:[0,1,1] neg_lo:[1,0,0] neg_hi:[1,0,0]
	v_lshlrev_b32_e32 v50, 16, v134
	v_and_b32_e32 v51, 0xffff0000, v134
	v_pk_fma_f32 v[20:21], v[2:3], v[50:51], v[20:21] op_sel_hi:[0,1,1] neg_lo:[1,0,0] neg_hi:[1,0,0]
	v_lshlrev_b32_e32 v50, 16, v143
	v_and_b32_e32 v51, 0xffff0000, v143
	v_pk_fma_f32 v[22:23], v[2:3], v[50:51], v[22:23] op_sel_hi:[0,1,1] neg_lo:[1,0,0] neg_hi:[1,0,0]
	v_lshlrev_b32_e32 v50, 16, v151
	v_and_b32_e32 v51, 0xffff0000, v151
	v_pk_fma_f32 v[24:25], v[2:3], v[50:51], v[24:25] op_sel_hi:[0,1,1] neg_lo:[1,0,0] neg_hi:[1,0,0]
	v_lshlrev_b32_e32 v50, 16, v160
	v_and_b32_e32 v51, 0xffff0000, v160
	v_pk_fma_f32 v[26:27], v[2:3], v[50:51], v[26:27] op_sel_hi:[0,1,1] neg_lo:[1,0,0] neg_hi:[1,0,0]
	v_lshlrev_b32_e32 v50, 16, v169
	v_and_b32_e32 v51, 0xffff0000, v169
	v_pk_fma_f32 v[28:29], v[2:3], v[50:51], v[28:29] op_sel_hi:[0,1,1] neg_lo:[1,0,0] neg_hi:[1,0,0]
	v_lshlrev_b32_e32 v50, 16, v181
	v_and_b32_e32 v51, 0xffff0000, v181
	v_pk_fma_f32 v[30:31], v[2:3], v[50:51], v[30:31] op_sel_hi:[0,1,1] neg_lo:[1,0,0] neg_hi:[1,0,0]
	v_lshlrev_b32_e32 v50, 16, v207
	v_and_b32_e32 v51, 0xffff0000, v207
	v_pk_fma_f32 v[32:33], v[2:3], v[50:51], v[32:33] op_sel_hi:[0,1,1] neg_lo:[1,0,0] neg_hi:[1,0,0]
.LBB0_858:
	s_add_i32 s16, s42, 9
	s_cmp_ge_i32 s16, s46
	s_cbranch_scc1 .LBB0_861
	s_min_i32 s44, s16, 0x76
	s_ashr_i32 s45, s44, 31
	s_lshl_b64 s[44:45], s[44:45], 20
	v_lshl_add_u64 v[50:51], v[12:13], 0, s[44:45]
	v_add_co_u32_e32 v236, vcc, 0x900000, v50
	s_add_i32 s10, s42, 16
	s_nop 0
	v_addc_co_u32_e32 v237, vcc, 0, v51, vcc
	global_load_dword v126, v[236:237], off
	v_add_co_u32_e32 v236, vcc, 0x904000, v50
	s_cmpk_lt_u32 s10, 0x80
	s_nop 0
	v_addc_co_u32_e32 v237, vcc, 0, v51, vcc
	global_load_dword v134, v[236:237], off
	v_add_co_u32_e32 v236, vcc, 0x908000, v50
	s_cselect_b64 s[44:45], -1, 0
	s_nop 0
	v_addc_co_u32_e32 v237, vcc, 0, v51, vcc
	global_load_dword v143, v[236:237], off
	v_add_co_u32_e32 v236, vcc, 0x90c000, v50
	v_cndmask_b32_e64 v2, 0, 1.0, s[44:45]
	s_nop 0
	v_addc_co_u32_e32 v237, vcc, 0, v51, vcc
	global_load_dword v151, v[236:237], off
	v_add_co_u32_e32 v236, vcc, 0x910000, v50
	s_cmp_lt_i32 s16, s62
	s_nop 0
	v_addc_co_u32_e32 v237, vcc, 0, v51, vcc
	global_load_dword v160, v[236:237], off
	v_add_co_u32_e32 v236, vcc, 0x914000, v50
	s_nop 1
	v_addc_co_u32_e32 v237, vcc, 0, v51, vcc
	global_load_dword v169, v[236:237], off
	v_add_co_u32_e32 v236, vcc, 0x918000, v50
	s_nop 1
	v_addc_co_u32_e32 v237, vcc, 0, v51, vcc
	v_add_co_u32_e32 v50, vcc, 0x91c000, v50
	global_load_dword v181, v[236:237], off
	s_nop 0
	v_addc_co_u32_e32 v51, vcc, 0, v51, vcc
	global_load_dword v207, v[50:51], off
	s_waitcnt vmcnt(23)
	v_lshlrev_b32_e32 v50, 16, v140
	v_and_b32_e32 v51, 0xffff0000, v140
	v_pk_fma_f32 v[18:19], v[2:3], v[50:51], v[18:19] op_sel_hi:[0,1,1]
	s_waitcnt vmcnt(22)
	v_lshlrev_b32_e32 v50, 16, v149
	v_and_b32_e32 v51, 0xffff0000, v149
	v_pk_fma_f32 v[20:21], v[2:3], v[50:51], v[20:21] op_sel_hi:[0,1,1]
	s_waitcnt vmcnt(21)
	v_lshlrev_b32_e32 v50, 16, v158
	v_and_b32_e32 v51, 0xffff0000, v158
	v_pk_fma_f32 v[22:23], v[2:3], v[50:51], v[22:23] op_sel_hi:[0,1,1]
	s_waitcnt vmcnt(20)
	v_lshlrev_b32_e32 v50, 16, v166
	v_and_b32_e32 v51, 0xffff0000, v166
	v_pk_fma_f32 v[24:25], v[2:3], v[50:51], v[24:25] op_sel_hi:[0,1,1]
	s_waitcnt vmcnt(19)
	v_lshlrev_b32_e32 v50, 16, v175
	v_and_b32_e32 v51, 0xffff0000, v175
	v_pk_fma_f32 v[26:27], v[2:3], v[50:51], v[26:27] op_sel_hi:[0,1,1]
	s_waitcnt vmcnt(18)
	v_lshlrev_b32_e32 v50, 16, v185
	v_and_b32_e32 v51, 0xffff0000, v185
	v_pk_fma_f32 v[28:29], v[2:3], v[50:51], v[28:29] op_sel_hi:[0,1,1]
	s_waitcnt vmcnt(17)
	v_lshlrev_b32_e32 v50, 16, v196
	v_and_b32_e32 v51, 0xffff0000, v196
	v_pk_fma_f32 v[30:31], v[2:3], v[50:51], v[30:31] op_sel_hi:[0,1,1]
	s_waitcnt vmcnt(16)
	v_lshlrev_b32_e32 v50, 16, v216
	v_and_b32_e32 v51, 0xffff0000, v216
	v_pk_fma_f32 v[32:33], v[2:3], v[50:51], v[32:33] op_sel_hi:[0,1,1]
	s_cbranch_scc1 .LBB0_861
	ds_write2st64_b64 v92, v[18:19], v[20:21] offset0:8 offset1:9
	ds_write2st64_b64 v92, v[22:23], v[24:25] offset0:10 offset1:11
	ds_write2st64_b64 v92, v[26:27], v[28:29] offset0:12 offset1:13
	ds_write2st64_b64 v92, v[30:31], v[32:33] offset0:14 offset1:15
	s_waitcnt lgkmcnt(0)
	s_barrier
; #define GAS __attribute__((address_space(1)))
; __device__ __forceinline__ unsigned cvt_pk_bf16(float lo, float hi) { unsigned r; asm volatile("v_cvt_pk_bf16_f32 %0, %1, %2" : "=v"(r) : "v"(lo), "v"(hi)); return r; }
; __device__ __forceinline__ float bf_lo(unsigned w) { return __uint_as_float(w << 16); }
; __device__ __forceinline__ float bf_hi(unsigned w) { return __uint_as_float(w & 0xffff0000u); }
; template <int W>
; __device__ __forceinline__ void pool_item(const Ctx& F, const bf16* Ub, bf16* Db, int r0, int nr) {
;     ...
;                     const int rlo = r - HW > 0 ? r - HW : 0, rhi = r + HW < 128 ? r + HW : 128; const float icr = 1.0f / (float)(rhi - rlo);
;                     f32x2 h = (f32x2){0.f, 0.f};
; #pragma unroll
;                     for (int c = -HW; c < HW; ++c) h += row[(c0 + c) * 64];
; #pragma unroll
;                     for (int j = 0; j < 8; ++j) {
;                         const float ic = icr * icc[j]; const unsigned m = ring[(u + NS - HW + 1) % NS][j];
;                         *(GAS unsigned*)(Db + ((size_t)r * 64 + c0 + j) * EI) = cvt_pk_bf16(h.x * ic - bf_lo(m), h.y * ic - bf_hi(m));
;                         h += row[(c0 + j + HW) * 64] - row[(c0 + j - HW) * 64];
	ds_read2st64_b64 v[236:239], v92 offset1:1
	s_cmp_gt_i32 s42, -2
	s_cselect_b64 s[44:45], -1, 0
	s_max_i32 s10, s16, 8
	s_min_i32 s23, s16, 0x78
	s_waitcnt lgkmcnt(0)
	v_pk_add_f32 v[50:51], v[236:237], 0 op_sel_hi:[1,0]
	s_sub_i32 s10, s23, s10
	v_pk_add_f32 v[50:51], v[50:51], v[238:239]
	ds_read2st64_b64 v[236:239], v92 offset0:2 offset1:3
	s_add_i32 s10, s10, 16
	v_cvt_f32_i32_e32 v242, s10
	v_cndmask_b32_e64 v2, 0, 1.0, s[44:45]
	s_waitcnt lgkmcnt(0)
	v_pk_add_f32 v[50:51], v[50:51], v[236:237]
	s_nop 0
	v_pk_add_f32 v[50:51], v[50:51], v[238:239]
	ds_read2st64_b64 v[236:239], v92 offset0:4 offset1:5
	s_waitcnt lgkmcnt(0)
	v_pk_add_f32 v[50:51], v[50:51], v[236:237]
	s_nop 0
	v_pk_add_f32 v[50:51], v[50:51], v[238:239]
	ds_read2st64_b64 v[236:239], v92 offset0:6 offset1:7
	s_waitcnt lgkmcnt(0)
	v_pk_add_f32 v[50:51], v[50:51], v[236:237]
	s_nop 0
	v_pk_add_f32 v[50:51], v[50:51], v[238:239]
	ds_read2st64_b64 v[236:239], v92 offset0:8 offset1:9
	s_waitcnt lgkmcnt(0)
	v_pk_add_f32 v[50:51], v[50:51], v[236:237]
	s_nop 0
	v_pk_add_f32 v[50:51], v[50:51], v[238:239]
	ds_read2st64_b64 v[236:239], v92 offset0:10 offset1:11
	s_waitcnt lgkmcnt(0)
	v_pk_add_f32 v[50:51], v[50:51], v[236:237]
	s_nop 0
	v_pk_add_f32 v[50:51], v[50:51], v[238:239]
	ds_read2st64_b64 v[236:239], v92 offset0:12 offset1:13
	s_waitcnt lgkmcnt(0)
	v_pk_add_f32 v[50:51], v[50:51], v[236:237]
	s_nop 0
	v_pk_add_f32 v[50:51], v[50:51], v[238:239]
	ds_read2st64_b64 v[236:239], v92 offset0:14 offset1:15
	s_waitcnt lgkmcnt(0)
	v_pk_add_f32 v[50:51], v[50:51], v[236:237]
	s_nop 0
	v_pk_add_f32 v[240:241], v[50:51], v[238:239]
	v_div_scale_f32 v50, s[44:45], v242, v242, 1.0
	v_rcp_f32_e32 v51, v50
	s_lshl_b64 s[44:45], s[16:17], 20
	v_fma_f32 v236, -v50, v51, 1.0
	v_fmac_f32_e32 v51, v236, v51
	v_div_scale_f32 v236, vcc, 1.0, v242, 1.0
	v_mul_f32_e32 v237, v236, v51
	v_fma_f32 v238, -v50, v237, v236
	v_fmac_f32_e32 v237, v238, v51
	v_fma_f32 v50, -v50, v237, v236
	v_div_fmas_f32 v50, v50, v51, v237
	v_div_fixup_f32 v242, v50, v242, 1.0
	v_mul_f32_e32 v50, v74, v242
	v_lshlrev_b32_e32 v51, 16, v233
	v_and_b32_e32 v236, 0xffff0000, v233
	v_fma_f32 v51, v50, v240, -v51
	v_fma_f32 v50, v50, v241, -v236
	v_cvt_pk_bf16_f32 v236, v51, v50
	v_lshl_add_u64 v[50:51], v[14:15], 0, s[44:45]
	global_store_dword v[50:51], v236, off
	ds_read2st64_b64 v[236:239], v92 offset1:16
	s_waitcnt lgkmcnt(0)
	v_pk_add_f32 v[236:237], v[238:239], v[236:237] neg_lo:[0,1] neg_hi:[0,1]
	s_nop 0
	v_pk_add_f32 v[240:241], v[240:241], v[236:237]
	v_mul_f32_e32 v236, v75, v242
	v_lshlrev_b32_e32 v237, 16, v232
	v_and_b32_e32 v238, 0xffff0000, v232
	v_fma_f32 v237, v236, v240, -v237
	v_fma_f32 v236, v236, v241, -v238
	v_cvt_pk_bf16_f32 v238, v237, v236
	v_add_co_u32_e32 v236, vcc, s54, v50
	s_nop 1
	v_addc_co_u32_e32 v237, vcc, 0, v51, vcc
	global_store_dword v[236:237], v238, off
	ds_read2st64_b64 v[236:239], v92 offset0:1 offset1:17
	s_waitcnt lgkmcnt(0)
	v_pk_add_f32 v[236:237], v[238:239], v[236:237] neg_lo:[0,1] neg_hi:[0,1]
	s_nop 0
	v_pk_add_f32 v[240:241], v[240:241], v[236:237]
	v_mul_f32_e32 v236, v76, v242
	v_lshlrev_b32_e32 v237, 16, v231
	v_and_b32_e32 v238, 0xffff0000, v231
	v_fma_f32 v237, v236, v240, -v237
	v_fma_f32 v236, v236, v241, -v238
	v_cvt_pk_bf16_f32 v238, v237, v236
	v_add_co_u32_e32 v236, vcc, s55, v50
	s_nop 1
	v_addc_co_u32_e32 v237, vcc, 0, v51, vcc
	global_store_dword v[236:237], v238, off
	ds_read2st64_b64 v[236:239], v92 offset0:2 offset1:18
	s_waitcnt lgkmcnt(0)
	v_pk_add_f32 v[236:237], v[238:239], v[236:237] neg_lo:[0,1] neg_hi:[0,1]
	s_nop 0
	v_pk_add_f32 v[240:241], v[240:241], v[236:237]
	v_mul_f32_e32 v236, v77, v242
	v_lshlrev_b32_e32 v237, 16, v230
	v_and_b32_e32 v238, 0xffff0000, v230
	v_fma_f32 v237, v236, v240, -v237
	v_fma_f32 v236, v236, v241, -v238
	v_cvt_pk_bf16_f32 v238, v237, v236
	v_add_co_u32_e32 v236, vcc, s56, v50
	s_nop 1
	v_addc_co_u32_e32 v237, vcc, 0, v51, vcc
	global_store_dword v[236:237], v238, off
	ds_read2st64_b64 v[236:239], v92 offset0:3 offset1:19
	s_waitcnt lgkmcnt(0)
	v_pk_add_f32 v[236:237], v[238:239], v[236:237] neg_lo:[0,1] neg_hi:[0,1]
	s_nop 0
	v_pk_add_f32 v[240:241], v[240:241], v[236:237]
	v_mul_f32_e32 v236, v78, v242
	v_lshlrev_b32_e32 v237, 16, v229
	v_and_b32_e32 v238, 0xffff0000, v229
	v_fma_f32 v237, v236, v240, -v237
	v_fma_f32 v236, v236, v241, -v238
	v_cvt_pk_bf16_f32 v238, v237, v236
	v_add_co_u32_e32 v236, vcc, s57, v50
	s_nop 1
	v_addc_co_u32_e32 v237, vcc, 0, v51, vcc
	global_store_dword v[236:237], v238, off
	ds_read2st64_b64 v[236:239], v92 offset0:4 offset1:20
	s_waitcnt lgkmcnt(0)
	v_pk_add_f32 v[236:237], v[238:239], v[236:237] neg_lo:[0,1] neg_hi:[0,1]
	s_nop 0
	v_pk_add_f32 v[240:241], v[240:241], v[236:237]
	v_mul_f32_e32 v236, v79, v242
	v_lshlrev_b32_e32 v237, 16, v228
	v_and_b32_e32 v238, 0xffff0000, v228
	v_fma_f32 v237, v236, v240, -v237
	v_fma_f32 v236, v236, v241, -v238
	v_cvt_pk_bf16_f32 v238, v237, v236
	v_add_co_u32_e32 v236, vcc, s58, v50
	s_nop 1
	v_addc_co_u32_e32 v237, vcc, 0, v51, vcc
	global_store_dword v[236:237], v238, off
	ds_read2st64_b64 v[236:239], v92 offset0:5 offset1:21
	s_waitcnt lgkmcnt(0)
	v_pk_add_f32 v[236:237], v[238:239], v[236:237] neg_lo:[0,1] neg_hi:[0,1]
	s_nop 0
	v_pk_add_f32 v[240:241], v[240:241], v[236:237]
	v_mul_f32_e32 v236, v80, v242
	v_lshlrev_b32_e32 v237, 16, v227
	v_and_b32_e32 v238, 0xffff0000, v227
	v_fma_f32 v237, v236, v240, -v237
	v_fma_f32 v236, v236, v241, -v238
	v_cvt_pk_bf16_f32 v238, v237, v236
	v_add_co_u32_e32 v236, vcc, s59, v50
	s_nop 1
	v_addc_co_u32_e32 v237, vcc, 0, v51, vcc
	global_store_dword v[236:237], v238, off
	ds_read2st64_b64 v[236:239], v92 offset0:6 offset1:22
	v_add_co_u32_e32 v50, vcc, s60, v50
	s_waitcnt lgkmcnt(0)
; #define GAS __attribute__((address_space(1)))
; #define LAS __attribute__((address_space(3)))
; __device__ __forceinline__ unsigned cvt_pk_bf16(float lo, float hi) { unsigned r; asm volatile("v_cvt_pk_bf16_f32 %0, %1, %2" : "=v"(r) : "v"(lo), "v"(hi)); return r; }
; __device__ __forceinline__ float bf_lo(unsigned w) { return __uint_as_float(w << 16); }
; template <int W>
; __device__ __forceinline__ void pool_item(const Ctx& F, const bf16* Ub, bf16* Db, int r0, int nr) {
;     ...
;     POOL_LOAD(0, rs); POOL_LOAD(1, rs + 1);
;     __syncthreads();
;     for (int base = rs; base < re; base += NS) {
; #pragma unroll
;         for (int u = 0; u < NS; ++u) {
;             const int r = base + u;
;             if (r < re) {
;                 POOL_LOAD((u + 2) % NS, r + 2);
;                 const int e = r + HW - 1;
;                 const float me = (e >= 0 && e < 128) ? 1.0f : 0.0f, ml = (r >= r0 && r - HW >= 0) ? 1.0f : 0.0f;
; #pragma unroll
;                 for (int j = 0; j < 8; ++j) { Vv[j].x += me * bf_lo(ring[u][j]); Vv[j].y += me * bf_hi(ring[u][j]); }
;                 if (r >= r0) {
;                     LAS f32x2* row = buf + ((r & 1) * 80 + 8) * 64 + lane;
; #pragma unroll
;                     for (int j = 0; j < 8; ++j) row[(c0 + j) * 64] = Vv[j];
;                     asm volatile("s_waitcnt lgkmcnt(0)" ::: "memory"); __builtin_amdgcn_s_barrier(); asm volatile("" ::: "memory");
;                     const int rlo = r - HW > 0 ? r - HW : 0, rhi = r + HW < 128 ? r + HW : 128; const float icr = 1.0f / (float)(rhi - rlo);
;                     f32x2 h = (f32x2){0.f, 0.f};
; #pragma unroll
;                     for (int c = -HW; c < HW; ++c) h += row[(c0 + c) * 64];
; #pragma unroll
;                     for (int j = 0; j < 8; ++j) {
;                         const float ic = icr * icc[j]; const unsigned m = ring[(u + NS - HW + 1) % NS][j];
;                         *(GAS unsigned*)(Db + ((size_t)r * 64 + c0 + j) * EI) = cvt_pk_bf16(h.x * ic - bf_lo(m), h.y * ic - bf_hi(m));
;                         h += row[(c0 + j + HW) * 64] - row[(c0 + j - HW) * 64];
;                     }
; #pragma unroll
;                     for (int j = 0; j < 8; ++j) { const unsigned l = ring[(u + NS - W + 1) % NS][j]; Vv[j].x -= ml * bf_lo(l); Vv[j].y -= ml * bf_hi(l); }
;                 }
	v_pk_add_f32 v[236:237], v[238:239], v[236:237] neg_lo:[0,1] neg_hi:[0,1]
	s_nop 0
	v_pk_add_f32 v[236:237], v[240:241], v[236:237]
	v_mul_f32_e32 v238, v81, v242
	v_lshlrev_b32_e32 v239, 16, v226
	v_fma_f32 v236, v238, v236, -v239
	v_and_b32_e32 v239, 0xffff0000, v226
	v_addc_co_u32_e32 v51, vcc, 0, v51, vcc
	v_fma_f32 v237, v238, v237, -v239
	v_cvt_pk_bf16_f32 v236, v236, v237
	global_store_dword v[50:51], v236, off
	v_lshlrev_b32_e32 v50, 16, v121
	v_and_b32_e32 v51, 0xffff0000, v121
	v_pk_fma_f32 v[18:19], v[2:3], v[50:51], v[18:19] op_sel_hi:[0,1,1] neg_lo:[1,0,0] neg_hi:[1,0,0]
	v_lshlrev_b32_e32 v50, 16, v128
	v_and_b32_e32 v51, 0xffff0000, v128
	v_pk_fma_f32 v[20:21], v[2:3], v[50:51], v[20:21] op_sel_hi:[0,1,1] neg_lo:[1,0,0] neg_hi:[1,0,0]
	v_lshlrev_b32_e32 v50, 16, v135
	v_and_b32_e32 v51, 0xffff0000, v135
	v_pk_fma_f32 v[22:23], v[2:3], v[50:51], v[22:23] op_sel_hi:[0,1,1] neg_lo:[1,0,0] neg_hi:[1,0,0]
	v_lshlrev_b32_e32 v50, 16, v144
	v_and_b32_e32 v51, 0xffff0000, v144
	v_pk_fma_f32 v[24:25], v[2:3], v[50:51], v[24:25] op_sel_hi:[0,1,1] neg_lo:[1,0,0] neg_hi:[1,0,0]
	v_lshlrev_b32_e32 v50, 16, v152
	v_and_b32_e32 v51, 0xffff0000, v152
	v_pk_fma_f32 v[26:27], v[2:3], v[50:51], v[26:27] op_sel_hi:[0,1,1] neg_lo:[1,0,0] neg_hi:[1,0,0]
	v_lshlrev_b32_e32 v50, 16, v162
	v_and_b32_e32 v51, 0xffff0000, v162
	v_pk_fma_f32 v[28:29], v[2:3], v[50:51], v[28:29] op_sel_hi:[0,1,1] neg_lo:[1,0,0] neg_hi:[1,0,0]
	v_lshlrev_b32_e32 v50, 16, v173
	v_and_b32_e32 v51, 0xffff0000, v173
	v_pk_fma_f32 v[30:31], v[2:3], v[50:51], v[30:31] op_sel_hi:[0,1,1] neg_lo:[1,0,0] neg_hi:[1,0,0]
	v_lshlrev_b32_e32 v50, 16, v201
	v_and_b32_e32 v51, 0xffff0000, v201
	v_pk_fma_f32 v[32:33], v[2:3], v[50:51], v[32:33] op_sel_hi:[0,1,1] neg_lo:[1,0,0] neg_hi:[1,0,0]
.LBB0_861:
	s_add_i32 s16, s42, 10
	s_cmp_ge_i32 s16, s46
	s_cbranch_scc1 .LBB0_864
	s_min_i32 s44, s16, 0x76
	s_ashr_i32 s45, s44, 31
	s_lshl_b64 s[44:45], s[44:45], 20
	v_lshl_add_u64 v[50:51], v[12:13], 0, s[44:45]
	v_add_co_u32_e32 v236, vcc, 0x900000, v50
	s_add_i32 s10, s42, 17
	s_nop 0
	v_addc_co_u32_e32 v237, vcc, 0, v51, vcc
	global_load_dword v121, v[236:237], off
	v_add_co_u32_e32 v236, vcc, 0x904000, v50
	s_cmpk_lt_u32 s10, 0x80
	s_nop 0
	v_addc_co_u32_e32 v237, vcc, 0, v51, vcc
	global_load_dword v128, v[236:237], off
	v_add_co_u32_e32 v236, vcc, 0x908000, v50
	s_cselect_b64 s[44:45], -1, 0
	s_nop 0
	v_addc_co_u32_e32 v237, vcc, 0, v51, vcc
	global_load_dword v135, v[236:237], off
	v_add_co_u32_e32 v236, vcc, 0x90c000, v50
	v_cndmask_b32_e64 v2, 0, 1.0, s[44:45]
	s_nop 0
	v_addc_co_u32_e32 v237, vcc, 0, v51, vcc
	global_load_dword v144, v[236:237], off
	v_add_co_u32_e32 v236, vcc, 0x910000, v50
	s_cmp_lt_i32 s16, s62
	s_nop 0
	v_addc_co_u32_e32 v237, vcc, 0, v51, vcc
	global_load_dword v152, v[236:237], off
	v_add_co_u32_e32 v236, vcc, 0x914000, v50
	s_nop 1
	v_addc_co_u32_e32 v237, vcc, 0, v51, vcc
	global_load_dword v162, v[236:237], off
	v_add_co_u32_e32 v236, vcc, 0x918000, v50
	s_nop 1
	v_addc_co_u32_e32 v237, vcc, 0, v51, vcc
	v_add_co_u32_e32 v50, vcc, 0x91c000, v50
	global_load_dword v173, v[236:237], off
	s_nop 0
	v_addc_co_u32_e32 v51, vcc, 0, v51, vcc
	global_load_dword v201, v[50:51], off
	s_waitcnt vmcnt(23)
	v_lshlrev_b32_e32 v50, 16, v133
	v_and_b32_e32 v51, 0xffff0000, v133
	v_pk_fma_f32 v[18:19], v[2:3], v[50:51], v[18:19] op_sel_hi:[0,1,1]
	s_waitcnt vmcnt(22)
	v_lshlrev_b32_e32 v50, 16, v142
	v_and_b32_e32 v51, 0xffff0000, v142
	v_pk_fma_f32 v[20:21], v[2:3], v[50:51], v[20:21] op_sel_hi:[0,1,1]
	s_waitcnt vmcnt(21)
	v_lshlrev_b32_e32 v50, 16, v150
	v_and_b32_e32 v51, 0xffff0000, v150
	v_pk_fma_f32 v[22:23], v[2:3], v[50:51], v[22:23] op_sel_hi:[0,1,1]
	s_waitcnt vmcnt(20)
	v_lshlrev_b32_e32 v50, 16, v159
	v_and_b32_e32 v51, 0xffff0000, v159
	v_pk_fma_f32 v[24:25], v[2:3], v[50:51], v[24:25] op_sel_hi:[0,1,1]
	s_waitcnt vmcnt(19)
	v_lshlrev_b32_e32 v50, 16, v167
	v_and_b32_e32 v51, 0xffff0000, v167
	v_pk_fma_f32 v[26:27], v[2:3], v[50:51], v[26:27] op_sel_hi:[0,1,1]
	s_waitcnt vmcnt(18)
	v_lshlrev_b32_e32 v50, 16, v177
	v_and_b32_e32 v51, 0xffff0000, v177
	v_pk_fma_f32 v[28:29], v[2:3], v[50:51], v[28:29] op_sel_hi:[0,1,1]
	s_waitcnt vmcnt(17)
	v_lshlrev_b32_e32 v50, 16, v189
	v_and_b32_e32 v51, 0xffff0000, v189
	v_pk_fma_f32 v[30:31], v[2:3], v[50:51], v[30:31] op_sel_hi:[0,1,1]
	s_waitcnt vmcnt(16)
	v_lshlrev_b32_e32 v50, 16, v212
	v_and_b32_e32 v51, 0xffff0000, v212
	v_pk_fma_f32 v[32:33], v[2:3], v[50:51], v[32:33] op_sel_hi:[0,1,1]
	s_cbranch_scc1 .LBB0_864
	ds_write2st64_b64 v92, v[18:19], v[20:21] offset0:88 offset1:89
	ds_write2st64_b64 v92, v[22:23], v[24:25] offset0:90 offset1:91
	ds_write2st64_b64 v92, v[26:27], v[28:29] offset0:92 offset1:93
	ds_write2st64_b64 v92, v[30:31], v[32:33] offset0:94 offset1:95
	s_waitcnt lgkmcnt(0)
	s_barrier
; #define GAS __attribute__((address_space(1)))
; #define LAS __attribute__((address_space(3)))
; __device__ __forceinline__ unsigned cvt_pk_bf16(float lo, float hi) { unsigned r; asm volatile("v_cvt_pk_bf16_f32 %0, %1, %2" : "=v"(r) : "v"(lo), "v"(hi)); return r; }
; __device__ __forceinline__ float bf_lo(unsigned w) { return __uint_as_float(w << 16); }
; __device__ __forceinline__ float bf_hi(unsigned w) { return __uint_as_float(w & 0xffff0000u); }
; template <int W>
; __device__ __forceinline__ void pool_item(const Ctx& F, const bf16* Ub, bf16* Db, int r0, int nr) {
;     ...
;                 if (r >= r0) {
;                     LAS f32x2* row = buf + ((r & 1) * 80 + 8) * 64 + lane;
; #pragma unroll
;                     for (int j = 0; j < 8; ++j) row[(c0 + j) * 64] = Vv[j];
;                     asm volatile("s_waitcnt lgkmcnt(0)" ::: "memory"); __builtin_amdgcn_s_barrier(); asm volatile("" ::: "memory");
;                     const int rlo = r - HW > 0 ? r - HW : 0, rhi = r + HW < 128 ? r + HW : 128; const float icr = 1.0f / (float)(rhi - rlo);
;                     f32x2 h = (f32x2){0.f, 0.f};
; #pragma unroll
;                     for (int c = -HW; c < HW; ++c) h += row[(c0 + c) * 64];
; #pragma unroll
;                     for (int j = 0; j < 8; ++j) {
;                         const float ic = icr * icc[j]; const unsigned m = ring[(u + NS - HW + 1) % NS][j];
;                         *(GAS unsigned*)(Db + ((size_t)r * 64 + c0 + j) * EI) = cvt_pk_bf16(h.x * ic - bf_lo(m), h.y * ic - bf_hi(m));
;                         h += row[(c0 + j + HW) * 64] - row[(c0 + j - HW) * 64];
;                     }
	ds_read2st64_b64 v[236:239], v92 offset0:80 offset1:81
	s_cmp_gt_i32 s42, -3
	s_cselect_b64 s[44:45], -1, 0
	s_max_i32 s10, s16, 8
	s_min_i32 s23, s16, 0x78
	s_waitcnt lgkmcnt(0)
	v_pk_add_f32 v[50:51], v[236:237], 0 op_sel_hi:[1,0]
	s_sub_i32 s10, s23, s10
	v_pk_add_f32 v[50:51], v[50:51], v[238:239]
	ds_read2st64_b64 v[236:239], v92 offset0:82 offset1:83
	s_add_i32 s10, s10, 16
	v_cvt_f32_i32_e32 v242, s10
	v_cndmask_b32_e64 v2, 0, 1.0, s[44:45]
	s_waitcnt lgkmcnt(0)
	v_pk_add_f32 v[50:51], v[50:51], v[236:237]
	s_nop 0
	v_pk_add_f32 v[50:51], v[50:51], v[238:239]
	ds_read2st64_b64 v[236:239], v92 offset0:84 offset1:85
	s_waitcnt lgkmcnt(0)
	v_pk_add_f32 v[50:51], v[50:51], v[236:237]
	s_nop 0
	v_pk_add_f32 v[50:51], v[50:51], v[238:239]
	ds_read2st64_b64 v[236:239], v92 offset0:86 offset1:87
	s_waitcnt lgkmcnt(0)
	v_pk_add_f32 v[50:51], v[50:51], v[236:237]
	s_nop 0
	v_pk_add_f32 v[50:51], v[50:51], v[238:239]
	ds_read2st64_b64 v[236:239], v92 offset0:88 offset1:89
	s_waitcnt lgkmcnt(0)
	v_pk_add_f32 v[50:51], v[50:51], v[236:237]
	s_nop 0
	v_pk_add_f32 v[50:51], v[50:51], v[238:239]
	ds_read2st64_b64 v[236:239], v92 offset0:90 offset1:91
	s_waitcnt lgkmcnt(0)
	v_pk_add_f32 v[50:51], v[50:51], v[236:237]
	s_nop 0
	v_pk_add_f32 v[50:51], v[50:51], v[238:239]
	ds_read2st64_b64 v[236:239], v92 offset0:92 offset1:93
	s_waitcnt lgkmcnt(0)
	v_pk_add_f32 v[50:51], v[50:51], v[236:237]
	s_nop 0
	v_pk_add_f32 v[50:51], v[50:51], v[238:239]
	ds_read2st64_b64 v[236:239], v92 offset0:94 offset1:95
	s_waitcnt lgkmcnt(0)
	v_pk_add_f32 v[50:51], v[50:51], v[236:237]
	s_nop 0
	v_pk_add_f32 v[240:241], v[50:51], v[238:239]
	v_div_scale_f32 v50, s[44:45], v242, v242, 1.0
	v_rcp_f32_e32 v51, v50
	s_lshl_b64 s[44:45], s[16:17], 20
	v_fma_f32 v236, -v50, v51, 1.0
	v_fmac_f32_e32 v51, v236, v51
	v_div_scale_f32 v236, vcc, 1.0, v242, 1.0
	v_mul_f32_e32 v237, v236, v51
	v_fma_f32 v238, -v50, v237, v236
	v_fmac_f32_e32 v237, v238, v51
	v_fma_f32 v50, -v50, v237, v236
	v_div_fmas_f32 v50, v50, v51, v237
	v_div_fixup_f32 v242, v50, v242, 1.0
	v_mul_f32_e32 v50, v74, v242
	v_lshlrev_b32_e32 v51, 16, v187
	v_and_b32_e32 v236, 0xffff0000, v187
	v_fma_f32 v51, v50, v240, -v51
	v_fma_f32 v50, v50, v241, -v236
	v_cvt_pk_bf16_f32 v236, v51, v50
	v_lshl_add_u64 v[50:51], v[14:15], 0, s[44:45]
	global_store_dword v[50:51], v236, off
	ds_read2st64_b64 v[236:239], v92 offset0:80 offset1:96
	s_waitcnt lgkmcnt(0)
	v_pk_add_f32 v[236:237], v[238:239], v[236:237] neg_lo:[0,1] neg_hi:[0,1]
	s_nop 0
	v_pk_add_f32 v[240:241], v[240:241], v[236:237]
	v_mul_f32_e32 v236, v75, v242
	v_lshlrev_b32_e32 v237, 16, v192
	v_and_b32_e32 v238, 0xffff0000, v192
	v_fma_f32 v237, v236, v240, -v237
	v_fma_f32 v236, v236, v241, -v238
	v_cvt_pk_bf16_f32 v238, v237, v236
	v_add_co_u32_e32 v236, vcc, s54, v50
	s_nop 1
	v_addc_co_u32_e32 v237, vcc, 0, v51, vcc
	global_store_dword v[236:237], v238, off
	ds_read2st64_b64 v[236:239], v92 offset0:81 offset1:97
	s_waitcnt lgkmcnt(0)
	v_pk_add_f32 v[236:237], v[238:239], v[236:237] neg_lo:[0,1] neg_hi:[0,1]
	s_nop 0
	v_pk_add_f32 v[240:241], v[240:241], v[236:237]
	v_mul_f32_e32 v236, v76, v242
	v_lshlrev_b32_e32 v237, 16, v200
	v_and_b32_e32 v238, 0xffff0000, v200
	v_fma_f32 v237, v236, v240, -v237
	v_fma_f32 v236, v236, v241, -v238
	v_cvt_pk_bf16_f32 v238, v237, v236
	v_add_co_u32_e32 v236, vcc, s55, v50
	s_nop 1
	v_addc_co_u32_e32 v237, vcc, 0, v51, vcc
	global_store_dword v[236:237], v238, off
	ds_read2st64_b64 v[236:239], v92 offset0:82 offset1:98
	s_waitcnt lgkmcnt(0)
	v_pk_add_f32 v[236:237], v[238:239], v[236:237] neg_lo:[0,1] neg_hi:[0,1]
	s_nop 0
	v_pk_add_f32 v[240:241], v[240:241], v[236:237]
	v_mul_f32_e32 v236, v77, v242
	v_lshlrev_b32_e32 v237, 16, v208
	v_and_b32_e32 v238, 0xffff0000, v208
	v_fma_f32 v237, v236, v240, -v237
	v_fma_f32 v236, v236, v241, -v238
	v_cvt_pk_bf16_f32 v238, v237, v236
	v_add_co_u32_e32 v236, vcc, s56, v50
	s_nop 1
	v_addc_co_u32_e32 v237, vcc, 0, v51, vcc
	global_store_dword v[236:237], v238, off
	ds_read2st64_b64 v[236:239], v92 offset0:83 offset1:99
	s_waitcnt lgkmcnt(0)
	v_pk_add_f32 v[236:237], v[238:239], v[236:237] neg_lo:[0,1] neg_hi:[0,1]
	s_nop 0
	v_pk_add_f32 v[240:241], v[240:241], v[236:237]
	v_mul_f32_e32 v236, v78, v242
	v_lshlrev_b32_e32 v237, 16, v213
	v_and_b32_e32 v238, 0xffff0000, v213
	v_fma_f32 v237, v236, v240, -v237
	v_fma_f32 v236, v236, v241, -v238
	v_cvt_pk_bf16_f32 v238, v237, v236
	v_add_co_u32_e32 v236, vcc, s57, v50
	s_nop 1
	v_addc_co_u32_e32 v237, vcc, 0, v51, vcc
	global_store_dword v[236:237], v238, off
	ds_read2st64_b64 v[236:239], v92 offset0:84 offset1:100
	s_waitcnt lgkmcnt(0)
	v_pk_add_f32 v[236:237], v[238:239], v[236:237] neg_lo:[0,1] neg_hi:[0,1]
	s_nop 0
	v_pk_add_f32 v[240:241], v[240:241], v[236:237]
	v_mul_f32_e32 v236, v79, v242
	v_lshlrev_b32_e32 v237, 16, v217
	v_and_b32_e32 v238, 0xffff0000, v217
	v_fma_f32 v237, v236, v240, -v237
	v_fma_f32 v236, v236, v241, -v238
	v_cvt_pk_bf16_f32 v238, v237, v236
	v_add_co_u32_e32 v236, vcc, s58, v50
	s_nop 1
	v_addc_co_u32_e32 v237, vcc, 0, v51, vcc
	global_store_dword v[236:237], v238, off
	ds_read2st64_b64 v[236:239], v92 offset0:85 offset1:101
	s_waitcnt lgkmcnt(0)
	v_pk_add_f32 v[236:237], v[238:239], v[236:237] neg_lo:[0,1] neg_hi:[0,1]
	s_nop 0
	v_pk_add_f32 v[240:241], v[240:241], v[236:237]
	v_mul_f32_e32 v236, v80, v242
	v_lshlrev_b32_e32 v237, 16, v221
	v_and_b32_e32 v238, 0xffff0000, v221
	v_fma_f32 v237, v236, v240, -v237
	v_fma_f32 v236, v236, v241, -v238
	v_cvt_pk_bf16_f32 v238, v237, v236
	v_add_co_u32_e32 v236, vcc, s59, v50
	s_nop 1
	v_addc_co_u32_e32 v237, vcc, 0, v51, vcc
	global_store_dword v[236:237], v238, off
	ds_read2st64_b64 v[236:239], v92 offset0:86 offset1:102
	v_add_co_u32_e32 v50, vcc, s60, v50
	s_waitcnt lgkmcnt(0)
; #define GAS __attribute__((address_space(1)))
; #define LAS __attribute__((address_space(3)))
; __device__ __forceinline__ unsigned cvt_pk_bf16(float lo, float hi) { unsigned r; asm volatile("v_cvt_pk_bf16_f32 %0, %1, %2" : "=v"(r) : "v"(lo), "v"(hi)); return r; }
; __device__ __forceinline__ float bf_lo(unsigned w) { return __uint_as_float(w << 16); }
; template <int W>
; __device__ __forceinline__ void pool_item(const Ctx& F, const bf16* Ub, bf16* Db, int r0, int nr) {
;     ...
;     POOL_LOAD(0, rs); POOL_LOAD(1, rs + 1);
;     __syncthreads();
;     for (int base = rs; base < re; base += NS) {
; #pragma unroll
;         for (int u = 0; u < NS; ++u) {
;             const int r = base + u;
;             if (r < re) {
;                 POOL_LOAD((u + 2) % NS, r + 2);
;                 const int e = r + HW - 1;
;                 const float me = (e >= 0 && e < 128) ? 1.0f : 0.0f, ml = (r >= r0 && r - HW >= 0) ? 1.0f : 0.0f;
; #pragma unroll
;                 for (int j = 0; j < 8; ++j) { Vv[j].x += me * bf_lo(ring[u][j]); Vv[j].y += me * bf_hi(ring[u][j]); }
;                 if (r >= r0) {
;                     LAS f32x2* row = buf + ((r & 1) * 80 + 8) * 64 + lane;
; #pragma unroll
;                     for (int j = 0; j < 8; ++j) row[(c0 + j) * 64] = Vv[j];
;                     asm volatile("s_waitcnt lgkmcnt(0)" ::: "memory"); __builtin_amdgcn_s_barrier(); asm volatile("" ::: "memory");
;                     const int rlo = r - HW > 0 ? r - HW : 0, rhi = r + HW < 128 ? r + HW : 128; const float icr = 1.0f / (float)(rhi - rlo);
;                     f32x2 h = (f32x2){0.f, 0.f};
; #pragma unroll
;                     for (int c = -HW; c < HW; ++c) h += row[(c0 + c) * 64];
; #pragma unroll
;                     for (int j = 0; j < 8; ++j) {
;                         const float ic = icr * icc[j]; const unsigned m = ring[(u + NS - HW + 1) % NS][j];
;                         *(GAS unsigned*)(Db + ((size_t)r * 64 + c0 + j) * EI) = cvt_pk_bf16(h.x * ic - bf_lo(m), h.y * ic - bf_hi(m));
;                         h += row[(c0 + j + HW) * 64] - row[(c0 + j - HW) * 64];
;                     }
; #pragma unroll
;                     for (int j = 0; j < 8; ++j) { const unsigned l = ring[(u + NS - W + 1) % NS][j]; Vv[j].x -= ml * bf_lo(l); Vv[j].y -= ml * bf_hi(l); }
;                 }
	v_pk_add_f32 v[236:237], v[238:239], v[236:237] neg_lo:[0,1] neg_hi:[0,1]
	s_nop 0
	v_pk_add_f32 v[236:237], v[240:241], v[236:237]
	v_mul_f32_e32 v238, v81, v242
	v_lshlrev_b32_e32 v239, 16, v225
	v_fma_f32 v236, v238, v236, -v239
	v_and_b32_e32 v239, 0xffff0000, v225
	v_addc_co_u32_e32 v51, vcc, 0, v51, vcc
	v_fma_f32 v237, v238, v237, -v239
	v_cvt_pk_bf16_f32 v236, v236, v237
	global_store_dword v[50:51], v236, off
	v_lshlrev_b32_e32 v50, 16, v116
	v_and_b32_e32 v51, 0xffff0000, v116
	v_pk_fma_f32 v[18:19], v[2:3], v[50:51], v[18:19] op_sel_hi:[0,1,1] neg_lo:[1,0,0] neg_hi:[1,0,0]
	v_lshlrev_b32_e32 v50, 16, v122
	v_and_b32_e32 v51, 0xffff0000, v122
	v_pk_fma_f32 v[20:21], v[2:3], v[50:51], v[20:21] op_sel_hi:[0,1,1] neg_lo:[1,0,0] neg_hi:[1,0,0]
	v_lshlrev_b32_e32 v50, 16, v129
	v_and_b32_e32 v51, 0xffff0000, v129
	v_pk_fma_f32 v[22:23], v[2:3], v[50:51], v[22:23] op_sel_hi:[0,1,1] neg_lo:[1,0,0] neg_hi:[1,0,0]
	v_lshlrev_b32_e32 v50, 16, v136
	v_and_b32_e32 v51, 0xffff0000, v136
	v_pk_fma_f32 v[24:25], v[2:3], v[50:51], v[24:25] op_sel_hi:[0,1,1] neg_lo:[1,0,0] neg_hi:[1,0,0]
	v_lshlrev_b32_e32 v50, 16, v145
	v_and_b32_e32 v51, 0xffff0000, v145
	v_pk_fma_f32 v[26:27], v[2:3], v[50:51], v[26:27] op_sel_hi:[0,1,1] neg_lo:[1,0,0] neg_hi:[1,0,0]
	v_lshlrev_b32_e32 v50, 16, v153
	v_and_b32_e32 v51, 0xffff0000, v153
	v_pk_fma_f32 v[28:29], v[2:3], v[50:51], v[28:29] op_sel_hi:[0,1,1] neg_lo:[1,0,0] neg_hi:[1,0,0]
	v_lshlrev_b32_e32 v50, 16, v164
	v_and_b32_e32 v51, 0xffff0000, v164
	v_pk_fma_f32 v[30:31], v[2:3], v[50:51], v[30:31] op_sel_hi:[0,1,1] neg_lo:[1,0,0] neg_hi:[1,0,0]
	v_lshlrev_b32_e32 v50, 16, v195
	v_and_b32_e32 v51, 0xffff0000, v195
	v_pk_fma_f32 v[32:33], v[2:3], v[50:51], v[32:33] op_sel_hi:[0,1,1] neg_lo:[1,0,0] neg_hi:[1,0,0]
.LBB0_864:
	s_add_i32 s16, s42, 11
	s_cmp_ge_i32 s16, s46
	s_cbranch_scc1 .LBB0_867
	s_min_i32 s44, s16, 0x76
	s_ashr_i32 s45, s44, 31
	s_lshl_b64 s[44:45], s[44:45], 20
	v_lshl_add_u64 v[50:51], v[12:13], 0, s[44:45]
	v_add_co_u32_e32 v236, vcc, 0x900000, v50
	s_add_i32 s10, s42, 18
	s_nop 0
	v_addc_co_u32_e32 v237, vcc, 0, v51, vcc
	global_load_dword v116, v[236:237], off
	v_add_co_u32_e32 v236, vcc, 0x904000, v50
	s_cmpk_lt_u32 s10, 0x80
	s_nop 0
	v_addc_co_u32_e32 v237, vcc, 0, v51, vcc
	global_load_dword v122, v[236:237], off
	v_add_co_u32_e32 v236, vcc, 0x908000, v50
	s_cselect_b64 s[44:45], -1, 0
	s_nop 0
	v_addc_co_u32_e32 v237, vcc, 0, v51, vcc
	global_load_dword v129, v[236:237], off
	v_add_co_u32_e32 v236, vcc, 0x90c000, v50
	v_cndmask_b32_e64 v2, 0, 1.0, s[44:45]
	s_nop 0
	v_addc_co_u32_e32 v237, vcc, 0, v51, vcc
	global_load_dword v136, v[236:237], off
	v_add_co_u32_e32 v236, vcc, 0x910000, v50
	s_cmp_lt_i32 s16, s62
	s_nop 0
	v_addc_co_u32_e32 v237, vcc, 0, v51, vcc
	global_load_dword v145, v[236:237], off
	v_add_co_u32_e32 v236, vcc, 0x914000, v50
	s_nop 1
	v_addc_co_u32_e32 v237, vcc, 0, v51, vcc
	global_load_dword v153, v[236:237], off
	v_add_co_u32_e32 v236, vcc, 0x918000, v50
	s_nop 1
	v_addc_co_u32_e32 v237, vcc, 0, v51, vcc
	v_add_co_u32_e32 v50, vcc, 0x91c000, v50
	global_load_dword v164, v[236:237], off
	s_nop 0
	v_addc_co_u32_e32 v51, vcc, 0, v51, vcc
	global_load_dword v195, v[50:51], off
	s_waitcnt vmcnt(23)
	v_lshlrev_b32_e32 v50, 16, v126
	v_and_b32_e32 v51, 0xffff0000, v126
	v_pk_fma_f32 v[18:19], v[2:3], v[50:51], v[18:19] op_sel_hi:[0,1,1]
	s_waitcnt vmcnt(22)
	v_lshlrev_b32_e32 v50, 16, v134
	v_and_b32_e32 v51, 0xffff0000, v134
	v_pk_fma_f32 v[20:21], v[2:3], v[50:51], v[20:21] op_sel_hi:[0,1,1]
	s_waitcnt vmcnt(21)
	v_lshlrev_b32_e32 v50, 16, v143
	v_and_b32_e32 v51, 0xffff0000, v143
	v_pk_fma_f32 v[22:23], v[2:3], v[50:51], v[22:23] op_sel_hi:[0,1,1]
	s_waitcnt vmcnt(20)
	v_lshlrev_b32_e32 v50, 16, v151
	v_and_b32_e32 v51, 0xffff0000, v151
	v_pk_fma_f32 v[24:25], v[2:3], v[50:51], v[24:25] op_sel_hi:[0,1,1]
	s_waitcnt vmcnt(19)
	v_lshlrev_b32_e32 v50, 16, v160
	v_and_b32_e32 v51, 0xffff0000, v160
	v_pk_fma_f32 v[26:27], v[2:3], v[50:51], v[26:27] op_sel_hi:[0,1,1]
	s_waitcnt vmcnt(18)
	v_lshlrev_b32_e32 v50, 16, v169
	v_and_b32_e32 v51, 0xffff0000, v169
	v_pk_fma_f32 v[28:29], v[2:3], v[50:51], v[28:29] op_sel_hi:[0,1,1]
	s_waitcnt vmcnt(17)
	v_lshlrev_b32_e32 v50, 16, v181
	v_and_b32_e32 v51, 0xffff0000, v181
	v_pk_fma_f32 v[30:31], v[2:3], v[50:51], v[30:31] op_sel_hi:[0,1,1]
	s_waitcnt vmcnt(16)
	v_lshlrev_b32_e32 v50, 16, v207
	v_and_b32_e32 v51, 0xffff0000, v207
	v_pk_fma_f32 v[32:33], v[2:3], v[50:51], v[32:33] op_sel_hi:[0,1,1]
	s_cbranch_scc1 .LBB0_867
	ds_write2st64_b64 v92, v[18:19], v[20:21] offset0:8 offset1:9
	ds_write2st64_b64 v92, v[22:23], v[24:25] offset0:10 offset1:11
	ds_write2st64_b64 v92, v[26:27], v[28:29] offset0:12 offset1:13
	ds_write2st64_b64 v92, v[30:31], v[32:33] offset0:14 offset1:15
	s_waitcnt lgkmcnt(0)
	s_barrier
; #define GAS __attribute__((address_space(1)))
; #define LAS __attribute__((address_space(3)))
; __device__ __forceinline__ unsigned cvt_pk_bf16(float lo, float hi) { unsigned r; asm volatile("v_cvt_pk_bf16_f32 %0, %1, %2" : "=v"(r) : "v"(lo), "v"(hi)); return r; }
; __device__ __forceinline__ float bf_lo(unsigned w) { return __uint_as_float(w << 16); }
; __device__ __forceinline__ float bf_hi(unsigned w) { return __uint_as_float(w & 0xffff0000u); }
; template <int W>
; __device__ __forceinline__ void pool_item(const Ctx& F, const bf16* Ub, bf16* Db, int r0, int nr) {
;     ...
;                 if (r >= r0) {
;                     LAS f32x2* row = buf + ((r & 1) * 80 + 8) * 64 + lane;
; #pragma unroll
;                     for (int j = 0; j < 8; ++j) row[(c0 + j) * 64] = Vv[j];
;                     asm volatile("s_waitcnt lgkmcnt(0)" ::: "memory"); __builtin_amdgcn_s_barrier(); asm volatile("" ::: "memory");
;                     const int rlo = r - HW > 0 ? r - HW : 0, rhi = r + HW < 128 ? r + HW : 128; const float icr = 1.0f / (float)(rhi - rlo);
;                     f32x2 h = (f32x2){0.f, 0.f};
; #pragma unroll
;                     for (int c = -HW; c < HW; ++c) h += row[(c0 + c) * 64];
; #pragma unroll
;                     for (int j = 0; j < 8; ++j) {
;                         const float ic = icr * icc[j]; const unsigned m = ring[(u + NS - HW + 1) % NS][j];
;                         *(GAS unsigned*)(Db + ((size_t)r * 64 + c0 + j) * EI) = cvt_pk_bf16(h.x * ic - bf_lo(m), h.y * ic - bf_hi(m));
;                         h += row[(c0 + j + HW) * 64] - row[(c0 + j - HW) * 64];
;                     }
	ds_read2st64_b64 v[236:239], v92 offset1:1
	s_cmp_gt_i32 s42, -4
	s_cselect_b64 s[44:45], -1, 0
	s_max_i32 s10, s16, 8
	s_min_i32 s23, s16, 0x78
	s_waitcnt lgkmcnt(0)
	v_pk_add_f32 v[50:51], v[236:237], 0 op_sel_hi:[1,0]
	s_sub_i32 s10, s23, s10
	v_pk_add_f32 v[50:51], v[50:51], v[238:239]
	ds_read2st64_b64 v[236:239], v92 offset0:2 offset1:3
	s_add_i32 s10, s10, 16
	v_cvt_f32_i32_e32 v242, s10
	v_cndmask_b32_e64 v2, 0, 1.0, s[44:45]
	s_waitcnt lgkmcnt(0)
	v_pk_add_f32 v[50:51], v[50:51], v[236:237]
	s_nop 0
	v_pk_add_f32 v[50:51], v[50:51], v[238:239]
	ds_read2st64_b64 v[236:239], v92 offset0:4 offset1:5
	s_waitcnt lgkmcnt(0)
	v_pk_add_f32 v[50:51], v[50:51], v[236:237]
	s_nop 0
	v_pk_add_f32 v[50:51], v[50:51], v[238:239]
	ds_read2st64_b64 v[236:239], v92 offset0:6 offset1:7
	s_waitcnt lgkmcnt(0)
	v_pk_add_f32 v[50:51], v[50:51], v[236:237]
	s_nop 0
	v_pk_add_f32 v[50:51], v[50:51], v[238:239]
	ds_read2st64_b64 v[236:239], v92 offset0:8 offset1:9
	s_waitcnt lgkmcnt(0)
	v_pk_add_f32 v[50:51], v[50:51], v[236:237]
	s_nop 0
	v_pk_add_f32 v[50:51], v[50:51], v[238:239]
	ds_read2st64_b64 v[236:239], v92 offset0:10 offset1:11
	s_waitcnt lgkmcnt(0)
	v_pk_add_f32 v[50:51], v[50:51], v[236:237]
	s_nop 0
	v_pk_add_f32 v[50:51], v[50:51], v[238:239]
	ds_read2st64_b64 v[236:239], v92 offset0:12 offset1:13
	s_waitcnt lgkmcnt(0)
	v_pk_add_f32 v[50:51], v[50:51], v[236:237]
	s_nop 0
	v_pk_add_f32 v[50:51], v[50:51], v[238:239]
	ds_read2st64_b64 v[236:239], v92 offset0:14 offset1:15
	s_waitcnt lgkmcnt(0)
	v_pk_add_f32 v[50:51], v[50:51], v[236:237]
	s_nop 0
	v_pk_add_f32 v[240:241], v[50:51], v[238:239]
	v_div_scale_f32 v50, s[44:45], v242, v242, 1.0
	v_rcp_f32_e32 v51, v50
	s_lshl_b64 s[44:45], s[16:17], 20
	v_fma_f32 v236, -v50, v51, 1.0
	v_fmac_f32_e32 v51, v236, v51
	v_div_scale_f32 v236, vcc, 1.0, v242, 1.0
	v_mul_f32_e32 v237, v236, v51
	v_fma_f32 v238, -v50, v237, v236
	v_fmac_f32_e32 v237, v238, v51
	v_fma_f32 v50, -v50, v237, v236
	v_div_fmas_f32 v50, v50, v51, v237
	v_div_fixup_f32 v242, v50, v242, 1.0
	v_mul_f32_e32 v50, v74, v242
	v_lshlrev_b32_e32 v51, 16, v179
	v_and_b32_e32 v236, 0xffff0000, v179
	v_fma_f32 v51, v50, v240, -v51
	v_fma_f32 v50, v50, v241, -v236
	v_cvt_pk_bf16_f32 v236, v51, v50
	v_lshl_add_u64 v[50:51], v[14:15], 0, s[44:45]
	global_store_dword v[50:51], v236, off
	ds_read2st64_b64 v[236:239], v92 offset1:16
	s_waitcnt lgkmcnt(0)
	v_pk_add_f32 v[236:237], v[238:239], v[236:237] neg_lo:[0,1] neg_hi:[0,1]
	s_nop 0
	v_pk_add_f32 v[240:241], v[240:241], v[236:237]
	v_mul_f32_e32 v236, v75, v242
	v_lshlrev_b32_e32 v237, 16, v184
	v_and_b32_e32 v238, 0xffff0000, v184
	v_fma_f32 v237, v236, v240, -v237
	v_fma_f32 v236, v236, v241, -v238
	v_cvt_pk_bf16_f32 v238, v237, v236
	v_add_co_u32_e32 v236, vcc, s54, v50
	s_nop 1
	v_addc_co_u32_e32 v237, vcc, 0, v51, vcc
	global_store_dword v[236:237], v238, off
	ds_read2st64_b64 v[236:239], v92 offset0:1 offset1:17
	s_waitcnt lgkmcnt(0)
	v_pk_add_f32 v[236:237], v[238:239], v[236:237] neg_lo:[0,1] neg_hi:[0,1]
	s_nop 0
	v_pk_add_f32 v[240:241], v[240:241], v[236:237]
	v_mul_f32_e32 v236, v76, v242
	v_lshlrev_b32_e32 v237, 16, v194
	v_and_b32_e32 v238, 0xffff0000, v194
	v_fma_f32 v237, v236, v240, -v237
	v_fma_f32 v236, v236, v241, -v238
	v_cvt_pk_bf16_f32 v238, v237, v236
	v_add_co_u32_e32 v236, vcc, s55, v50
	s_nop 1
	v_addc_co_u32_e32 v237, vcc, 0, v51, vcc
	global_store_dword v[236:237], v238, off
	ds_read2st64_b64 v[236:239], v92 offset0:2 offset1:18
	s_waitcnt lgkmcnt(0)
	v_pk_add_f32 v[236:237], v[238:239], v[236:237] neg_lo:[0,1] neg_hi:[0,1]
	s_nop 0
	v_pk_add_f32 v[240:241], v[240:241], v[236:237]
	v_mul_f32_e32 v236, v77, v242
	v_lshlrev_b32_e32 v237, 16, v203
	v_and_b32_e32 v238, 0xffff0000, v203
	v_fma_f32 v237, v236, v240, -v237
	v_fma_f32 v236, v236, v241, -v238
	v_cvt_pk_bf16_f32 v238, v237, v236
	v_add_co_u32_e32 v236, vcc, s56, v50
	s_nop 1
	v_addc_co_u32_e32 v237, vcc, 0, v51, vcc
	global_store_dword v[236:237], v238, off
	ds_read2st64_b64 v[236:239], v92 offset0:3 offset1:19
	s_waitcnt lgkmcnt(0)
	v_pk_add_f32 v[236:237], v[238:239], v[236:237] neg_lo:[0,1] neg_hi:[0,1]
	s_nop 0
	v_pk_add_f32 v[240:241], v[240:241], v[236:237]
	v_mul_f32_e32 v236, v78, v242
	v_lshlrev_b32_e32 v237, 16, v209
	v_and_b32_e32 v238, 0xffff0000, v209
	v_fma_f32 v237, v236, v240, -v237
	v_fma_f32 v236, v236, v241, -v238
	v_cvt_pk_bf16_f32 v238, v237, v236
	v_add_co_u32_e32 v236, vcc, s57, v50
	s_nop 1
	v_addc_co_u32_e32 v237, vcc, 0, v51, vcc
	global_store_dword v[236:237], v238, off
	ds_read2st64_b64 v[236:239], v92 offset0:4 offset1:20
	s_waitcnt lgkmcnt(0)
	v_pk_add_f32 v[236:237], v[238:239], v[236:237] neg_lo:[0,1] neg_hi:[0,1]
	s_nop 0
	v_pk_add_f32 v[240:241], v[240:241], v[236:237]
	v_mul_f32_e32 v236, v79, v242
	v_lshlrev_b32_e32 v237, 16, v214
	v_and_b32_e32 v238, 0xffff0000, v214
	v_fma_f32 v237, v236, v240, -v237
	v_fma_f32 v236, v236, v241, -v238
	v_cvt_pk_bf16_f32 v238, v237, v236
	v_add_co_u32_e32 v236, vcc, s58, v50
	s_nop 1
	v_addc_co_u32_e32 v237, vcc, 0, v51, vcc
	global_store_dword v[236:237], v238, off
	ds_read2st64_b64 v[236:239], v92 offset0:5 offset1:21
	s_waitcnt lgkmcnt(0)
	v_pk_add_f32 v[236:237], v[238:239], v[236:237] neg_lo:[0,1] neg_hi:[0,1]
	s_nop 0
	v_pk_add_f32 v[240:241], v[240:241], v[236:237]
	v_mul_f32_e32 v236, v80, v242
	v_lshlrev_b32_e32 v237, 16, v218
	v_and_b32_e32 v238, 0xffff0000, v218
	v_fma_f32 v237, v236, v240, -v237
	v_fma_f32 v236, v236, v241, -v238
	v_cvt_pk_bf16_f32 v238, v237, v236
	v_add_co_u32_e32 v236, vcc, s59, v50
	s_nop 1
	v_addc_co_u32_e32 v237, vcc, 0, v51, vcc
	global_store_dword v[236:237], v238, off
	ds_read2st64_b64 v[236:239], v92 offset0:6 offset1:22
	v_add_co_u32_e32 v50, vcc, s60, v50
	s_waitcnt lgkmcnt(0)
; #define GAS __attribute__((address_space(1)))
; #define LAS __attribute__((address_space(3)))
; __device__ __forceinline__ unsigned cvt_pk_bf16(float lo, float hi) { unsigned r; asm volatile("v_cvt_pk_bf16_f32 %0, %1, %2" : "=v"(r) : "v"(lo), "v"(hi)); return r; }
; __device__ __forceinline__ float bf_lo(unsigned w) { return __uint_as_float(w << 16); }
; template <int W>
; __device__ __forceinline__ void pool_item(const Ctx& F, const bf16* Ub, bf16* Db, int r0, int nr) {
;     ...
;     POOL_LOAD(0, rs); POOL_LOAD(1, rs + 1);
;     __syncthreads();
;     for (int base = rs; base < re; base += NS) {
; #pragma unroll
;         for (int u = 0; u < NS; ++u) {
;             const int r = base + u;
;             if (r < re) {
;                 POOL_LOAD((u + 2) % NS, r + 2);
;                 const int e = r + HW - 1;
;                 const float me = (e >= 0 && e < 128) ? 1.0f : 0.0f, ml = (r >= r0 && r - HW >= 0) ? 1.0f : 0.0f;
; #pragma unroll
;                 for (int j = 0; j < 8; ++j) { Vv[j].x += me * bf_lo(ring[u][j]); Vv[j].y += me * bf_hi(ring[u][j]); }
;                 if (r >= r0) {
;                     LAS f32x2* row = buf + ((r & 1) * 80 + 8) * 64 + lane;
; #pragma unroll
;                     for (int j = 0; j < 8; ++j) row[(c0 + j) * 64] = Vv[j];
;                     asm volatile("s_waitcnt lgkmcnt(0)" ::: "memory"); __builtin_amdgcn_s_barrier(); asm volatile("" ::: "memory");
;                     const int rlo = r - HW > 0 ? r - HW : 0, rhi = r + HW < 128 ? r + HW : 128; const float icr = 1.0f / (float)(rhi - rlo);
;                     f32x2 h = (f32x2){0.f, 0.f};
; #pragma unroll
;                     for (int c = -HW; c < HW; ++c) h += row[(c0 + c) * 64];
; #pragma unroll
;                     for (int j = 0; j < 8; ++j) {
;                         const float ic = icr * icc[j]; const unsigned m = ring[(u + NS - HW + 1) % NS][j];
;                         *(GAS unsigned*)(Db + ((size_t)r * 64 + c0 + j) * EI) = cvt_pk_bf16(h.x * ic - bf_lo(m), h.y * ic - bf_hi(m));
;                         h += row[(c0 + j + HW) * 64] - row[(c0 + j - HW) * 64];
;                     }
; #pragma unroll
;                     for (int j = 0; j < 8; ++j) { const unsigned l = ring[(u + NS - W + 1) % NS][j]; Vv[j].x -= ml * bf_lo(l); Vv[j].y -= ml * bf_hi(l); }
;                 }
	v_pk_add_f32 v[236:237], v[238:239], v[236:237] neg_lo:[0,1] neg_hi:[0,1]
	s_nop 0
	v_pk_add_f32 v[236:237], v[240:241], v[236:237]
	v_mul_f32_e32 v238, v81, v242
	v_lshlrev_b32_e32 v239, 16, v224
	v_fma_f32 v236, v238, v236, -v239
	v_and_b32_e32 v239, 0xffff0000, v224
	v_addc_co_u32_e32 v51, vcc, 0, v51, vcc
	v_fma_f32 v237, v238, v237, -v239
	v_cvt_pk_bf16_f32 v236, v236, v237
	global_store_dword v[50:51], v236, off
	v_lshlrev_b32_e32 v50, 16, v111
	v_and_b32_e32 v51, 0xffff0000, v111
	v_pk_fma_f32 v[18:19], v[2:3], v[50:51], v[18:19] op_sel_hi:[0,1,1] neg_lo:[1,0,0] neg_hi:[1,0,0]
	v_lshlrev_b32_e32 v50, 16, v117
	v_and_b32_e32 v51, 0xffff0000, v117
	v_pk_fma_f32 v[20:21], v[2:3], v[50:51], v[20:21] op_sel_hi:[0,1,1] neg_lo:[1,0,0] neg_hi:[1,0,0]
	v_lshlrev_b32_e32 v50, 16, v123
	v_and_b32_e32 v51, 0xffff0000, v123
	v_pk_fma_f32 v[22:23], v[2:3], v[50:51], v[22:23] op_sel_hi:[0,1,1] neg_lo:[1,0,0] neg_hi:[1,0,0]
	v_lshlrev_b32_e32 v50, 16, v130
	v_and_b32_e32 v51, 0xffff0000, v130
	v_pk_fma_f32 v[24:25], v[2:3], v[50:51], v[24:25] op_sel_hi:[0,1,1] neg_lo:[1,0,0] neg_hi:[1,0,0]
	v_lshlrev_b32_e32 v50, 16, v137
	v_and_b32_e32 v51, 0xffff0000, v137
	v_pk_fma_f32 v[26:27], v[2:3], v[50:51], v[26:27] op_sel_hi:[0,1,1] neg_lo:[1,0,0] neg_hi:[1,0,0]
	v_lshlrev_b32_e32 v50, 16, v146
	v_and_b32_e32 v51, 0xffff0000, v146
	v_pk_fma_f32 v[28:29], v[2:3], v[50:51], v[28:29] op_sel_hi:[0,1,1] neg_lo:[1,0,0] neg_hi:[1,0,0]
	v_lshlrev_b32_e32 v50, 16, v155
	v_and_b32_e32 v51, 0xffff0000, v155
	v_pk_fma_f32 v[30:31], v[2:3], v[50:51], v[30:31] op_sel_hi:[0,1,1] neg_lo:[1,0,0] neg_hi:[1,0,0]
	v_lshlrev_b32_e32 v50, 16, v188
	v_and_b32_e32 v51, 0xffff0000, v188
	v_pk_fma_f32 v[32:33], v[2:3], v[50:51], v[32:33] op_sel_hi:[0,1,1] neg_lo:[1,0,0] neg_hi:[1,0,0]
.LBB0_867:
	s_add_i32 s16, s42, 12
	s_cmp_ge_i32 s16, s46
	s_cbranch_scc1 .LBB0_870
	s_min_i32 s44, s16, 0x76
	s_ashr_i32 s45, s44, 31
	s_lshl_b64 s[44:45], s[44:45], 20
	v_lshl_add_u64 v[50:51], v[12:13], 0, s[44:45]
	v_add_co_u32_e32 v236, vcc, 0x900000, v50
	s_add_i32 s10, s42, 19
	s_nop 0
	v_addc_co_u32_e32 v237, vcc, 0, v51, vcc
	global_load_dword v111, v[236:237], off
	v_add_co_u32_e32 v236, vcc, 0x904000, v50
	s_cmpk_lt_u32 s10, 0x80
	s_nop 0
	v_addc_co_u32_e32 v237, vcc, 0, v51, vcc
	global_load_dword v117, v[236:237], off
	v_add_co_u32_e32 v236, vcc, 0x908000, v50
	s_cselect_b64 s[44:45], -1, 0
	s_nop 0
	v_addc_co_u32_e32 v237, vcc, 0, v51, vcc
	global_load_dword v123, v[236:237], off
	v_add_co_u32_e32 v236, vcc, 0x90c000, v50
	v_cndmask_b32_e64 v2, 0, 1.0, s[44:45]
	s_nop 0
	v_addc_co_u32_e32 v237, vcc, 0, v51, vcc
	global_load_dword v130, v[236:237], off
	v_add_co_u32_e32 v236, vcc, 0x910000, v50
	s_cmp_lt_i32 s16, s62
	s_nop 0
	v_addc_co_u32_e32 v237, vcc, 0, v51, vcc
	global_load_dword v137, v[236:237], off
	v_add_co_u32_e32 v236, vcc, 0x914000, v50
	s_nop 1
	v_addc_co_u32_e32 v237, vcc, 0, v51, vcc
	global_load_dword v146, v[236:237], off
	v_add_co_u32_e32 v236, vcc, 0x918000, v50
	s_nop 1
	v_addc_co_u32_e32 v237, vcc, 0, v51, vcc
	v_add_co_u32_e32 v50, vcc, 0x91c000, v50
	global_load_dword v155, v[236:237], off
	s_nop 0
	v_addc_co_u32_e32 v51, vcc, 0, v51, vcc
	global_load_dword v188, v[50:51], off
	s_waitcnt vmcnt(23)
	v_lshlrev_b32_e32 v50, 16, v121
	v_and_b32_e32 v51, 0xffff0000, v121
	v_pk_fma_f32 v[18:19], v[2:3], v[50:51], v[18:19] op_sel_hi:[0,1,1]
	s_waitcnt vmcnt(22)
	v_lshlrev_b32_e32 v50, 16, v128
	v_and_b32_e32 v51, 0xffff0000, v128
	v_pk_fma_f32 v[20:21], v[2:3], v[50:51], v[20:21] op_sel_hi:[0,1,1]
	s_waitcnt vmcnt(21)
	v_lshlrev_b32_e32 v50, 16, v135
	v_and_b32_e32 v51, 0xffff0000, v135
	v_pk_fma_f32 v[22:23], v[2:3], v[50:51], v[22:23] op_sel_hi:[0,1,1]
	s_waitcnt vmcnt(20)
	v_lshlrev_b32_e32 v50, 16, v144
	v_and_b32_e32 v51, 0xffff0000, v144
	v_pk_fma_f32 v[24:25], v[2:3], v[50:51], v[24:25] op_sel_hi:[0,1,1]
	s_waitcnt vmcnt(19)
	v_lshlrev_b32_e32 v50, 16, v152
	v_and_b32_e32 v51, 0xffff0000, v152
	v_pk_fma_f32 v[26:27], v[2:3], v[50:51], v[26:27] op_sel_hi:[0,1,1]
	s_waitcnt vmcnt(18)
	v_lshlrev_b32_e32 v50, 16, v162
	v_and_b32_e32 v51, 0xffff0000, v162
	v_pk_fma_f32 v[28:29], v[2:3], v[50:51], v[28:29] op_sel_hi:[0,1,1]
	s_waitcnt vmcnt(17)
	v_lshlrev_b32_e32 v50, 16, v173
	v_and_b32_e32 v51, 0xffff0000, v173
	v_pk_fma_f32 v[30:31], v[2:3], v[50:51], v[30:31] op_sel_hi:[0,1,1]
	s_waitcnt vmcnt(16)
	v_lshlrev_b32_e32 v50, 16, v201
	v_and_b32_e32 v51, 0xffff0000, v201
	v_pk_fma_f32 v[32:33], v[2:3], v[50:51], v[32:33] op_sel_hi:[0,1,1]
	s_cbranch_scc1 .LBB0_870
	ds_write2st64_b64 v92, v[18:19], v[20:21] offset0:88 offset1:89
	ds_write2st64_b64 v92, v[22:23], v[24:25] offset0:90 offset1:91
	ds_write2st64_b64 v92, v[26:27], v[28:29] offset0:92 offset1:93
	ds_write2st64_b64 v92, v[30:31], v[32:33] offset0:94 offset1:95
	s_waitcnt lgkmcnt(0)
	s_barrier
; #define GAS __attribute__((address_space(1)))
; #define LAS __attribute__((address_space(3)))
; __device__ __forceinline__ unsigned cvt_pk_bf16(float lo, float hi) { unsigned r; asm volatile("v_cvt_pk_bf16_f32 %0, %1, %2" : "=v"(r) : "v"(lo), "v"(hi)); return r; }
; __device__ __forceinline__ float bf_lo(unsigned w) { return __uint_as_float(w << 16); }
; __device__ __forceinline__ float bf_hi(unsigned w) { return __uint_as_float(w & 0xffff0000u); }
; template <int W>
; __device__ __forceinline__ void pool_item(const Ctx& F, const bf16* Ub, bf16* Db, int r0, int nr) {
;     ...
;                 if (r >= r0) {
;                     LAS f32x2* row = buf + ((r & 1) * 80 + 8) * 64 + lane;
; #pragma unroll
;                     for (int j = 0; j < 8; ++j) row[(c0 + j) * 64] = Vv[j];
;                     asm volatile("s_waitcnt lgkmcnt(0)" ::: "memory"); __builtin_amdgcn_s_barrier(); asm volatile("" ::: "memory");
;                     const int rlo = r - HW > 0 ? r - HW : 0, rhi = r + HW < 128 ? r + HW : 128; const float icr = 1.0f / (float)(rhi - rlo);
;                     f32x2 h = (f32x2){0.f, 0.f};
; #pragma unroll
;                     for (int c = -HW; c < HW; ++c) h += row[(c0 + c) * 64];
; #pragma unroll
;                     for (int j = 0; j < 8; ++j) {
;                         const float ic = icr * icc[j]; const unsigned m = ring[(u + NS - HW + 1) % NS][j];
;                         *(GAS unsigned*)(Db + ((size_t)r * 64 + c0 + j) * EI) = cvt_pk_bf16(h.x * ic - bf_lo(m), h.y * ic - bf_hi(m));
;                         h += row[(c0 + j + HW) * 64] - row[(c0 + j - HW) * 64];
;                     }
	ds_read2st64_b64 v[236:239], v92 offset0:80 offset1:81
	s_cmp_gt_i32 s42, -5
	s_cselect_b64 s[44:45], -1, 0
	s_max_i32 s10, s16, 8
	s_min_i32 s23, s16, 0x78
	s_waitcnt lgkmcnt(0)
	v_pk_add_f32 v[50:51], v[236:237], 0 op_sel_hi:[1,0]
	s_sub_i32 s10, s23, s10
	v_pk_add_f32 v[50:51], v[50:51], v[238:239]
	ds_read2st64_b64 v[236:239], v92 offset0:82 offset1:83
	s_add_i32 s10, s10, 16
	v_cvt_f32_i32_e32 v242, s10
	v_cndmask_b32_e64 v2, 0, 1.0, s[44:45]
	s_waitcnt lgkmcnt(0)
	v_pk_add_f32 v[50:51], v[50:51], v[236:237]
	s_nop 0
	v_pk_add_f32 v[50:51], v[50:51], v[238:239]
	ds_read2st64_b64 v[236:239], v92 offset0:84 offset1:85
	s_waitcnt lgkmcnt(0)
	v_pk_add_f32 v[50:51], v[50:51], v[236:237]
	s_nop 0
	v_pk_add_f32 v[50:51], v[50:51], v[238:239]
	ds_read2st64_b64 v[236:239], v92 offset0:86 offset1:87
	s_waitcnt lgkmcnt(0)
	v_pk_add_f32 v[50:51], v[50:51], v[236:237]
	s_nop 0
	v_pk_add_f32 v[50:51], v[50:51], v[238:239]
	ds_read2st64_b64 v[236:239], v92 offset0:88 offset1:89
	s_waitcnt lgkmcnt(0)
	v_pk_add_f32 v[50:51], v[50:51], v[236:237]
	s_nop 0
	v_pk_add_f32 v[50:51], v[50:51], v[238:239]
	ds_read2st64_b64 v[236:239], v92 offset0:90 offset1:91
	s_waitcnt lgkmcnt(0)
	v_pk_add_f32 v[50:51], v[50:51], v[236:237]
	s_nop 0
	v_pk_add_f32 v[50:51], v[50:51], v[238:239]
	ds_read2st64_b64 v[236:239], v92 offset0:92 offset1:93
	s_waitcnt lgkmcnt(0)
	v_pk_add_f32 v[50:51], v[50:51], v[236:237]
	s_nop 0
	v_pk_add_f32 v[50:51], v[50:51], v[238:239]
	ds_read2st64_b64 v[236:239], v92 offset0:94 offset1:95
	s_waitcnt lgkmcnt(0)
	v_pk_add_f32 v[50:51], v[50:51], v[236:237]
	s_nop 0
	v_pk_add_f32 v[240:241], v[50:51], v[238:239]
	v_div_scale_f32 v50, s[44:45], v242, v242, 1.0
	v_rcp_f32_e32 v51, v50
	s_lshl_b64 s[44:45], s[16:17], 20
	v_fma_f32 v236, -v50, v51, 1.0
	v_fmac_f32_e32 v51, v236, v51
	v_div_scale_f32 v236, vcc, 1.0, v242, 1.0
	v_mul_f32_e32 v237, v236, v51
	v_fma_f32 v238, -v50, v237, v236
	v_fmac_f32_e32 v237, v238, v51
	v_fma_f32 v50, -v50, v237, v236
	v_div_fmas_f32 v50, v50, v51, v237
	v_div_fixup_f32 v242, v50, v242, 1.0
	v_mul_f32_e32 v50, v74, v242
	v_lshlrev_b32_e32 v51, 16, v171
	v_and_b32_e32 v236, 0xffff0000, v171
	v_fma_f32 v51, v50, v240, -v51
	v_fma_f32 v50, v50, v241, -v236
	v_cvt_pk_bf16_f32 v236, v51, v50
	v_lshl_add_u64 v[50:51], v[14:15], 0, s[44:45]
	global_store_dword v[50:51], v236, off
	ds_read2st64_b64 v[236:239], v92 offset0:80 offset1:96
	s_waitcnt lgkmcnt(0)
	v_pk_add_f32 v[236:237], v[238:239], v[236:237] neg_lo:[0,1] neg_hi:[0,1]
	s_nop 0
	v_pk_add_f32 v[240:241], v[240:241], v[236:237]
	v_mul_f32_e32 v236, v75, v242
	v_lshlrev_b32_e32 v237, 16, v176
	v_and_b32_e32 v238, 0xffff0000, v176
	v_fma_f32 v237, v236, v240, -v237
	v_fma_f32 v236, v236, v241, -v238
	v_cvt_pk_bf16_f32 v238, v237, v236
	v_add_co_u32_e32 v236, vcc, s54, v50
	s_nop 1
	v_addc_co_u32_e32 v237, vcc, 0, v51, vcc
	global_store_dword v[236:237], v238, off
	ds_read2st64_b64 v[236:239], v92 offset0:81 offset1:97
	s_waitcnt lgkmcnt(0)
	v_pk_add_f32 v[236:237], v[238:239], v[236:237] neg_lo:[0,1] neg_hi:[0,1]
	s_nop 0
	v_pk_add_f32 v[240:241], v[240:241], v[236:237]
	v_mul_f32_e32 v236, v76, v242
	v_lshlrev_b32_e32 v237, 16, v186
	v_and_b32_e32 v238, 0xffff0000, v186
	v_fma_f32 v237, v236, v240, -v237
	v_fma_f32 v236, v236, v241, -v238
	v_cvt_pk_bf16_f32 v238, v237, v236
	v_add_co_u32_e32 v236, vcc, s55, v50
	s_nop 1
	v_addc_co_u32_e32 v237, vcc, 0, v51, vcc
	global_store_dword v[236:237], v238, off
	ds_read2st64_b64 v[236:239], v92 offset0:82 offset1:98
	s_waitcnt lgkmcnt(0)
	v_pk_add_f32 v[236:237], v[238:239], v[236:237] neg_lo:[0,1] neg_hi:[0,1]
	s_nop 0
	v_pk_add_f32 v[240:241], v[240:241], v[236:237]
	v_mul_f32_e32 v236, v77, v242
	v_lshlrev_b32_e32 v237, 16, v197
	v_and_b32_e32 v238, 0xffff0000, v197
	v_fma_f32 v237, v236, v240, -v237
	v_fma_f32 v236, v236, v241, -v238
	v_cvt_pk_bf16_f32 v238, v237, v236
	v_add_co_u32_e32 v236, vcc, s56, v50
	s_nop 1
	v_addc_co_u32_e32 v237, vcc, 0, v51, vcc
	global_store_dword v[236:237], v238, off
	ds_read2st64_b64 v[236:239], v92 offset0:83 offset1:99
	s_waitcnt lgkmcnt(0)
	v_pk_add_f32 v[236:237], v[238:239], v[236:237] neg_lo:[0,1] neg_hi:[0,1]
	s_nop 0
	v_pk_add_f32 v[240:241], v[240:241], v[236:237]
	v_mul_f32_e32 v236, v78, v242
	v_lshlrev_b32_e32 v237, 16, v204
	v_and_b32_e32 v238, 0xffff0000, v204
	v_fma_f32 v237, v236, v240, -v237
	v_fma_f32 v236, v236, v241, -v238
	v_cvt_pk_bf16_f32 v238, v237, v236
	v_add_co_u32_e32 v236, vcc, s57, v50
	s_nop 1
	v_addc_co_u32_e32 v237, vcc, 0, v51, vcc
	global_store_dword v[236:237], v238, off
	ds_read2st64_b64 v[236:239], v92 offset0:84 offset1:100
	s_waitcnt lgkmcnt(0)
	v_pk_add_f32 v[236:237], v[238:239], v[236:237] neg_lo:[0,1] neg_hi:[0,1]
	s_nop 0
	v_pk_add_f32 v[240:241], v[240:241], v[236:237]
	v_mul_f32_e32 v236, v79, v242
	v_lshlrev_b32_e32 v237, 16, v210
	v_and_b32_e32 v238, 0xffff0000, v210
	v_fma_f32 v237, v236, v240, -v237
	v_fma_f32 v236, v236, v241, -v238
	v_cvt_pk_bf16_f32 v238, v237, v236
	v_add_co_u32_e32 v236, vcc, s58, v50
	s_nop 1
	v_addc_co_u32_e32 v237, vcc, 0, v51, vcc
	global_store_dword v[236:237], v238, off
	ds_read2st64_b64 v[236:239], v92 offset0:85 offset1:101
	s_waitcnt lgkmcnt(0)
	v_pk_add_f32 v[236:237], v[238:239], v[236:237] neg_lo:[0,1] neg_hi:[0,1]
	s_nop 0
	v_pk_add_f32 v[240:241], v[240:241], v[236:237]
	v_mul_f32_e32 v236, v80, v242
	v_lshlrev_b32_e32 v237, 16, v215
	v_and_b32_e32 v238, 0xffff0000, v215
	v_fma_f32 v237, v236, v240, -v237
	v_fma_f32 v236, v236, v241, -v238
	v_cvt_pk_bf16_f32 v238, v237, v236
	v_add_co_u32_e32 v236, vcc, s59, v50
	s_nop 1
	v_addc_co_u32_e32 v237, vcc, 0, v51, vcc
	global_store_dword v[236:237], v238, off
	ds_read2st64_b64 v[236:239], v92 offset0:86 offset1:102
	v_add_co_u32_e32 v50, vcc, s60, v50
	s_waitcnt lgkmcnt(0)
; #define GAS __attribute__((address_space(1)))
; #define LAS __attribute__((address_space(3)))
; __device__ __forceinline__ unsigned cvt_pk_bf16(float lo, float hi) { unsigned r; asm volatile("v_cvt_pk_bf16_f32 %0, %1, %2" : "=v"(r) : "v"(lo), "v"(hi)); return r; }
; __device__ __forceinline__ float bf_lo(unsigned w) { return __uint_as_float(w << 16); }
; template <int W>
; __device__ __forceinline__ void pool_item(const Ctx& F, const bf16* Ub, bf16* Db, int r0, int nr) {
;     ...
;     POOL_LOAD(0, rs); POOL_LOAD(1, rs + 1);
;     __syncthreads();
;     for (int base = rs; base < re; base += NS) {
; #pragma unroll
;         for (int u = 0; u < NS; ++u) {
;             const int r = base + u;
;             if (r < re) {
;                 POOL_LOAD((u + 2) % NS, r + 2);
;                 const int e = r + HW - 1;
;                 const float me = (e >= 0 && e < 128) ? 1.0f : 0.0f, ml = (r >= r0 && r - HW >= 0) ? 1.0f : 0.0f;
; #pragma unroll
;                 for (int j = 0; j < 8; ++j) { Vv[j].x += me * bf_lo(ring[u][j]); Vv[j].y += me * bf_hi(ring[u][j]); }
;                 if (r >= r0) {
;                     LAS f32x2* row = buf + ((r & 1) * 80 + 8) * 64 + lane;
; #pragma unroll
;                     for (int j = 0; j < 8; ++j) row[(c0 + j) * 64] = Vv[j];
;                     asm volatile("s_waitcnt lgkmcnt(0)" ::: "memory"); __builtin_amdgcn_s_barrier(); asm volatile("" ::: "memory");
;                     const int rlo = r - HW > 0 ? r - HW : 0, rhi = r + HW < 128 ? r + HW : 128; const float icr = 1.0f / (float)(rhi - rlo);
;                     f32x2 h = (f32x2){0.f, 0.f};
; #pragma unroll
;                     for (int c = -HW; c < HW; ++c) h += row[(c0 + c) * 64];
; #pragma unroll
;                     for (int j = 0; j < 8; ++j) {
;                         const float ic = icr * icc[j]; const unsigned m = ring[(u + NS - HW + 1) % NS][j];
;                         *(GAS unsigned*)(Db + ((size_t)r * 64 + c0 + j) * EI) = cvt_pk_bf16(h.x * ic - bf_lo(m), h.y * ic - bf_hi(m));
;                         h += row[(c0 + j + HW) * 64] - row[(c0 + j - HW) * 64];
;                     }
; #pragma unroll
;                     for (int j = 0; j < 8; ++j) { const unsigned l = ring[(u + NS - W + 1) % NS][j]; Vv[j].x -= ml * bf_lo(l); Vv[j].y -= ml * bf_hi(l); }
;                 }
	v_pk_add_f32 v[236:237], v[238:239], v[236:237] neg_lo:[0,1] neg_hi:[0,1]
	s_nop 0
	v_pk_add_f32 v[236:237], v[240:241], v[236:237]
	v_mul_f32_e32 v238, v81, v242
	v_lshlrev_b32_e32 v239, 16, v223
	v_fma_f32 v236, v238, v236, -v239
	v_and_b32_e32 v239, 0xffff0000, v223
	v_addc_co_u32_e32 v51, vcc, 0, v51, vcc
	v_fma_f32 v237, v238, v237, -v239
	v_cvt_pk_bf16_f32 v236, v236, v237
	global_store_dword v[50:51], v236, off
	v_lshlrev_b32_e32 v50, 16, v107
	v_and_b32_e32 v51, 0xffff0000, v107
	v_pk_fma_f32 v[18:19], v[2:3], v[50:51], v[18:19] op_sel_hi:[0,1,1] neg_lo:[1,0,0] neg_hi:[1,0,0]
	v_lshlrev_b32_e32 v50, 16, v112
	v_and_b32_e32 v51, 0xffff0000, v112
	v_pk_fma_f32 v[20:21], v[2:3], v[50:51], v[20:21] op_sel_hi:[0,1,1] neg_lo:[1,0,0] neg_hi:[1,0,0]
	v_lshlrev_b32_e32 v50, 16, v118
	v_and_b32_e32 v51, 0xffff0000, v118
	v_pk_fma_f32 v[22:23], v[2:3], v[50:51], v[22:23] op_sel_hi:[0,1,1] neg_lo:[1,0,0] neg_hi:[1,0,0]
	v_lshlrev_b32_e32 v50, 16, v124
	v_and_b32_e32 v51, 0xffff0000, v124
	v_pk_fma_f32 v[24:25], v[2:3], v[50:51], v[24:25] op_sel_hi:[0,1,1] neg_lo:[1,0,0] neg_hi:[1,0,0]
	v_lshlrev_b32_e32 v50, 16, v131
	v_and_b32_e32 v51, 0xffff0000, v131
	v_pk_fma_f32 v[26:27], v[2:3], v[50:51], v[26:27] op_sel_hi:[0,1,1] neg_lo:[1,0,0] neg_hi:[1,0,0]
	v_lshlrev_b32_e32 v50, 16, v138
	v_and_b32_e32 v51, 0xffff0000, v138
	v_pk_fma_f32 v[28:29], v[2:3], v[50:51], v[28:29] op_sel_hi:[0,1,1] neg_lo:[1,0,0] neg_hi:[1,0,0]
	v_lshlrev_b32_e32 v50, 16, v147
	v_and_b32_e32 v51, 0xffff0000, v147
	v_pk_fma_f32 v[30:31], v[2:3], v[50:51], v[30:31] op_sel_hi:[0,1,1] neg_lo:[1,0,0] neg_hi:[1,0,0]
	v_lshlrev_b32_e32 v50, 16, v180
	v_and_b32_e32 v51, 0xffff0000, v180
	v_pk_fma_f32 v[32:33], v[2:3], v[50:51], v[32:33] op_sel_hi:[0,1,1] neg_lo:[1,0,0] neg_hi:[1,0,0]
.LBB0_870:
	s_add_i32 s16, s42, 13
	s_cmp_ge_i32 s16, s46
	s_cbranch_scc1 .LBB0_873
	s_min_i32 s44, s16, 0x76
	s_ashr_i32 s45, s44, 31
	s_lshl_b64 s[44:45], s[44:45], 20
	v_lshl_add_u64 v[50:51], v[12:13], 0, s[44:45]
	v_add_co_u32_e32 v236, vcc, 0x900000, v50
	s_add_i32 s10, s42, 20
	s_nop 0
	v_addc_co_u32_e32 v237, vcc, 0, v51, vcc
	global_load_dword v107, v[236:237], off
	v_add_co_u32_e32 v236, vcc, 0x904000, v50
	s_cmpk_lt_u32 s10, 0x80
	s_nop 0
	v_addc_co_u32_e32 v237, vcc, 0, v51, vcc
	global_load_dword v112, v[236:237], off
	v_add_co_u32_e32 v236, vcc, 0x908000, v50
	s_cselect_b64 s[44:45], -1, 0
	s_nop 0
	v_addc_co_u32_e32 v237, vcc, 0, v51, vcc
	global_load_dword v118, v[236:237], off
	v_add_co_u32_e32 v236, vcc, 0x90c000, v50
	v_cndmask_b32_e64 v2, 0, 1.0, s[44:45]
	s_nop 0
	v_addc_co_u32_e32 v237, vcc, 0, v51, vcc
	global_load_dword v124, v[236:237], off
	v_add_co_u32_e32 v236, vcc, 0x910000, v50
	s_cmp_lt_i32 s16, s62
	s_nop 0
	v_addc_co_u32_e32 v237, vcc, 0, v51, vcc
	global_load_dword v131, v[236:237], off
	v_add_co_u32_e32 v236, vcc, 0x914000, v50
	s_nop 1
	v_addc_co_u32_e32 v237, vcc, 0, v51, vcc
	global_load_dword v138, v[236:237], off
	v_add_co_u32_e32 v236, vcc, 0x918000, v50
	s_nop 1
	v_addc_co_u32_e32 v237, vcc, 0, v51, vcc
	v_add_co_u32_e32 v50, vcc, 0x91c000, v50
	global_load_dword v147, v[236:237], off
	s_nop 0
	v_addc_co_u32_e32 v51, vcc, 0, v51, vcc
	global_load_dword v180, v[50:51], off
	s_waitcnt vmcnt(23)
	v_lshlrev_b32_e32 v50, 16, v116
	v_and_b32_e32 v51, 0xffff0000, v116
	v_pk_fma_f32 v[18:19], v[2:3], v[50:51], v[18:19] op_sel_hi:[0,1,1]
	s_waitcnt vmcnt(22)
	v_lshlrev_b32_e32 v50, 16, v122
	v_and_b32_e32 v51, 0xffff0000, v122
	v_pk_fma_f32 v[20:21], v[2:3], v[50:51], v[20:21] op_sel_hi:[0,1,1]
	s_waitcnt vmcnt(21)
	v_lshlrev_b32_e32 v50, 16, v129
	v_and_b32_e32 v51, 0xffff0000, v129
	v_pk_fma_f32 v[22:23], v[2:3], v[50:51], v[22:23] op_sel_hi:[0,1,1]
	s_waitcnt vmcnt(20)
	v_lshlrev_b32_e32 v50, 16, v136
	v_and_b32_e32 v51, 0xffff0000, v136
	v_pk_fma_f32 v[24:25], v[2:3], v[50:51], v[24:25] op_sel_hi:[0,1,1]
	s_waitcnt vmcnt(19)
	v_lshlrev_b32_e32 v50, 16, v145
	v_and_b32_e32 v51, 0xffff0000, v145
	v_pk_fma_f32 v[26:27], v[2:3], v[50:51], v[26:27] op_sel_hi:[0,1,1]
	s_waitcnt vmcnt(18)
	v_lshlrev_b32_e32 v50, 16, v153
	v_and_b32_e32 v51, 0xffff0000, v153
	v_pk_fma_f32 v[28:29], v[2:3], v[50:51], v[28:29] op_sel_hi:[0,1,1]
	s_waitcnt vmcnt(17)
	v_lshlrev_b32_e32 v50, 16, v164
	v_and_b32_e32 v51, 0xffff0000, v164
	v_pk_fma_f32 v[30:31], v[2:3], v[50:51], v[30:31] op_sel_hi:[0,1,1]
	s_waitcnt vmcnt(16)
	v_lshlrev_b32_e32 v50, 16, v195
	v_and_b32_e32 v51, 0xffff0000, v195
	v_pk_fma_f32 v[32:33], v[2:3], v[50:51], v[32:33] op_sel_hi:[0,1,1]
	s_cbranch_scc1 .LBB0_873
	ds_write2st64_b64 v92, v[18:19], v[20:21] offset0:8 offset1:9
	ds_write2st64_b64 v92, v[22:23], v[24:25] offset0:10 offset1:11
	ds_write2st64_b64 v92, v[26:27], v[28:29] offset0:12 offset1:13
	ds_write2st64_b64 v92, v[30:31], v[32:33] offset0:14 offset1:15
	s_waitcnt lgkmcnt(0)
	s_barrier
; #define GAS __attribute__((address_space(1)))
; #define LAS __attribute__((address_space(3)))
; __device__ __forceinline__ unsigned cvt_pk_bf16(float lo, float hi) { unsigned r; asm volatile("v_cvt_pk_bf16_f32 %0, %1, %2" : "=v"(r) : "v"(lo), "v"(hi)); return r; }
; __device__ __forceinline__ float bf_lo(unsigned w) { return __uint_as_float(w << 16); }
; __device__ __forceinline__ float bf_hi(unsigned w) { return __uint_as_float(w & 0xffff0000u); }
; template <int W>
; __device__ __forceinline__ void pool_item(const Ctx& F, const bf16* Ub, bf16* Db, int r0, int nr) {
;     ...
;                 if (r >= r0) {
;                     LAS f32x2* row = buf + ((r & 1) * 80 + 8) * 64 + lane;
; #pragma unroll
;                     for (int j = 0; j < 8; ++j) row[(c0 + j) * 64] = Vv[j];
;                     asm volatile("s_waitcnt lgkmcnt(0)" ::: "memory"); __builtin_amdgcn_s_barrier(); asm volatile("" ::: "memory");
;                     const int rlo = r - HW > 0 ? r - HW : 0, rhi = r + HW < 128 ? r + HW : 128; const float icr = 1.0f / (float)(rhi - rlo);
;                     f32x2 h = (f32x2){0.f, 0.f};
; #pragma unroll
;                     for (int c = -HW; c < HW; ++c) h += row[(c0 + c) * 64];
; #pragma unroll
;                     for (int j = 0; j < 8; ++j) {
;                         const float ic = icr * icc[j]; const unsigned m = ring[(u + NS - HW + 1) % NS][j];
;                         *(GAS unsigned*)(Db + ((size_t)r * 64 + c0 + j) * EI) = cvt_pk_bf16(h.x * ic - bf_lo(m), h.y * ic - bf_hi(m));
;                         h += row[(c0 + j + HW) * 64] - row[(c0 + j - HW) * 64];
;                     }
	ds_read2st64_b64 v[236:239], v92 offset1:1
	s_cmp_gt_i32 s42, -6
	s_cselect_b64 s[44:45], -1, 0
	s_max_i32 s10, s16, 8
	s_min_i32 s23, s16, 0x78
	s_waitcnt lgkmcnt(0)
	v_pk_add_f32 v[50:51], v[236:237], 0 op_sel_hi:[1,0]
	s_sub_i32 s10, s23, s10
	v_pk_add_f32 v[50:51], v[50:51], v[238:239]
	ds_read2st64_b64 v[236:239], v92 offset0:2 offset1:3
	s_add_i32 s10, s10, 16
	v_cvt_f32_i32_e32 v242, s10
	v_cndmask_b32_e64 v2, 0, 1.0, s[44:45]
	s_waitcnt lgkmcnt(0)
	v_pk_add_f32 v[50:51], v[50:51], v[236:237]
	s_nop 0
	v_pk_add_f32 v[50:51], v[50:51], v[238:239]
	ds_read2st64_b64 v[236:239], v92 offset0:4 offset1:5
	s_waitcnt lgkmcnt(0)
	v_pk_add_f32 v[50:51], v[50:51], v[236:237]
	s_nop 0
	v_pk_add_f32 v[50:51], v[50:51], v[238:239]
	ds_read2st64_b64 v[236:239], v92 offset0:6 offset1:7
	s_waitcnt lgkmcnt(0)
	v_pk_add_f32 v[50:51], v[50:51], v[236:237]
	s_nop 0
	v_pk_add_f32 v[50:51], v[50:51], v[238:239]
	ds_read2st64_b64 v[236:239], v92 offset0:8 offset1:9
	s_waitcnt lgkmcnt(0)
	v_pk_add_f32 v[50:51], v[50:51], v[236:237]
	s_nop 0
	v_pk_add_f32 v[50:51], v[50:51], v[238:239]
	ds_read2st64_b64 v[236:239], v92 offset0:10 offset1:11
	s_waitcnt lgkmcnt(0)
	v_pk_add_f32 v[50:51], v[50:51], v[236:237]
	s_nop 0
	v_pk_add_f32 v[50:51], v[50:51], v[238:239]
	ds_read2st64_b64 v[236:239], v92 offset0:12 offset1:13
	s_waitcnt lgkmcnt(0)
	v_pk_add_f32 v[50:51], v[50:51], v[236:237]
	s_nop 0
	v_pk_add_f32 v[50:51], v[50:51], v[238:239]
	ds_read2st64_b64 v[236:239], v92 offset0:14 offset1:15
	s_waitcnt lgkmcnt(0)
	v_pk_add_f32 v[50:51], v[50:51], v[236:237]
	s_nop 0
	v_pk_add_f32 v[240:241], v[50:51], v[238:239]
	v_div_scale_f32 v50, s[44:45], v242, v242, 1.0
	v_rcp_f32_e32 v51, v50
	s_lshl_b64 s[44:45], s[16:17], 20
	v_fma_f32 v236, -v50, v51, 1.0
	v_fmac_f32_e32 v51, v236, v51
	v_div_scale_f32 v236, vcc, 1.0, v242, 1.0
	v_mul_f32_e32 v237, v236, v51
	v_fma_f32 v238, -v50, v237, v236
	v_fmac_f32_e32 v237, v238, v51
	v_fma_f32 v50, -v50, v237, v236
	v_div_fmas_f32 v50, v50, v51, v237
	v_div_fixup_f32 v242, v50, v242, 1.0
	v_mul_f32_e32 v50, v74, v242
	v_lshlrev_b32_e32 v51, 16, v163
	v_and_b32_e32 v236, 0xffff0000, v163
	v_fma_f32 v51, v50, v240, -v51
	v_fma_f32 v50, v50, v241, -v236
	v_cvt_pk_bf16_f32 v236, v51, v50
	v_lshl_add_u64 v[50:51], v[14:15], 0, s[44:45]
	global_store_dword v[50:51], v236, off
	ds_read2st64_b64 v[236:239], v92 offset1:16
	s_waitcnt lgkmcnt(0)
	v_pk_add_f32 v[236:237], v[238:239], v[236:237] neg_lo:[0,1] neg_hi:[0,1]
	s_nop 0
	v_pk_add_f32 v[240:241], v[240:241], v[236:237]
	v_mul_f32_e32 v236, v75, v242
	v_lshlrev_b32_e32 v237, 16, v168
	v_and_b32_e32 v238, 0xffff0000, v168
	v_fma_f32 v237, v236, v240, -v237
	v_fma_f32 v236, v236, v241, -v238
	v_cvt_pk_bf16_f32 v238, v237, v236
	v_add_co_u32_e32 v236, vcc, s54, v50
	s_nop 1
	v_addc_co_u32_e32 v237, vcc, 0, v51, vcc
	global_store_dword v[236:237], v238, off
	ds_read2st64_b64 v[236:239], v92 offset0:1 offset1:17
	s_waitcnt lgkmcnt(0)
	v_pk_add_f32 v[236:237], v[238:239], v[236:237] neg_lo:[0,1] neg_hi:[0,1]
	s_nop 0
	v_pk_add_f32 v[240:241], v[240:241], v[236:237]
	v_mul_f32_e32 v236, v76, v242
	v_lshlrev_b32_e32 v237, 16, v178
	v_and_b32_e32 v238, 0xffff0000, v178
	v_fma_f32 v237, v236, v240, -v237
	v_fma_f32 v236, v236, v241, -v238
	v_cvt_pk_bf16_f32 v238, v237, v236
	v_add_co_u32_e32 v236, vcc, s55, v50
	s_nop 1
	v_addc_co_u32_e32 v237, vcc, 0, v51, vcc
	global_store_dword v[236:237], v238, off
	ds_read2st64_b64 v[236:239], v92 offset0:2 offset1:18
	s_waitcnt lgkmcnt(0)
	v_pk_add_f32 v[236:237], v[238:239], v[236:237] neg_lo:[0,1] neg_hi:[0,1]
	s_nop 0
	v_pk_add_f32 v[240:241], v[240:241], v[236:237]
	v_mul_f32_e32 v236, v77, v242
	v_lshlrev_b32_e32 v237, 16, v190
	v_and_b32_e32 v238, 0xffff0000, v190
	v_fma_f32 v237, v236, v240, -v237
	v_fma_f32 v236, v236, v241, -v238
	v_cvt_pk_bf16_f32 v238, v237, v236
	v_add_co_u32_e32 v236, vcc, s56, v50
	s_nop 1
	v_addc_co_u32_e32 v237, vcc, 0, v51, vcc
	global_store_dword v[236:237], v238, off
	ds_read2st64_b64 v[236:239], v92 offset0:3 offset1:19
	s_waitcnt lgkmcnt(0)
	v_pk_add_f32 v[236:237], v[238:239], v[236:237] neg_lo:[0,1] neg_hi:[0,1]
	s_nop 0
	v_pk_add_f32 v[240:241], v[240:241], v[236:237]
	v_mul_f32_e32 v236, v78, v242
	v_lshlrev_b32_e32 v237, 16, v198
	v_and_b32_e32 v238, 0xffff0000, v198
	v_fma_f32 v237, v236, v240, -v237
	v_fma_f32 v236, v236, v241, -v238
	v_cvt_pk_bf16_f32 v238, v237, v236
	v_add_co_u32_e32 v236, vcc, s57, v50
	s_nop 1
	v_addc_co_u32_e32 v237, vcc, 0, v51, vcc
	global_store_dword v[236:237], v238, off
	ds_read2st64_b64 v[236:239], v92 offset0:4 offset1:20
	s_waitcnt lgkmcnt(0)
	v_pk_add_f32 v[236:237], v[238:239], v[236:237] neg_lo:[0,1] neg_hi:[0,1]
	s_nop 0
	v_pk_add_f32 v[240:241], v[240:241], v[236:237]
	v_mul_f32_e32 v236, v79, v242
	v_lshlrev_b32_e32 v237, 16, v205
	v_and_b32_e32 v238, 0xffff0000, v205
	v_fma_f32 v237, v236, v240, -v237
	v_fma_f32 v236, v236, v241, -v238
	v_cvt_pk_bf16_f32 v238, v237, v236
	v_add_co_u32_e32 v236, vcc, s58, v50
	s_nop 1
	v_addc_co_u32_e32 v237, vcc, 0, v51, vcc
	global_store_dword v[236:237], v238, off
	ds_read2st64_b64 v[236:239], v92 offset0:5 offset1:21
	s_waitcnt lgkmcnt(0)
	v_pk_add_f32 v[236:237], v[238:239], v[236:237] neg_lo:[0,1] neg_hi:[0,1]
	s_nop 0
	v_pk_add_f32 v[240:241], v[240:241], v[236:237]
	v_mul_f32_e32 v236, v80, v242
	v_lshlrev_b32_e32 v237, 16, v211
	v_and_b32_e32 v238, 0xffff0000, v211
	v_fma_f32 v237, v236, v240, -v237
	v_fma_f32 v236, v236, v241, -v238
	v_cvt_pk_bf16_f32 v238, v237, v236
	v_add_co_u32_e32 v236, vcc, s59, v50
	s_nop 1
	v_addc_co_u32_e32 v237, vcc, 0, v51, vcc
	global_store_dword v[236:237], v238, off
	ds_read2st64_b64 v[236:239], v92 offset0:6 offset1:22
	v_add_co_u32_e32 v50, vcc, s60, v50
	s_waitcnt lgkmcnt(0)
; #define GAS __attribute__((address_space(1)))
; #define LAS __attribute__((address_space(3)))
; __device__ __forceinline__ unsigned cvt_pk_bf16(float lo, float hi) { unsigned r; asm volatile("v_cvt_pk_bf16_f32 %0, %1, %2" : "=v"(r) : "v"(lo), "v"(hi)); return r; }
; __device__ __forceinline__ float bf_lo(unsigned w) { return __uint_as_float(w << 16); }
; template <int W>
; __device__ __forceinline__ void pool_item(const Ctx& F, const bf16* Ub, bf16* Db, int r0, int nr) {
;     ...
;     POOL_LOAD(0, rs); POOL_LOAD(1, rs + 1);
;     __syncthreads();
;     for (int base = rs; base < re; base += NS) {
; #pragma unroll
;         for (int u = 0; u < NS; ++u) {
;             const int r = base + u;
;             if (r < re) {
;                 POOL_LOAD((u + 2) % NS, r + 2);
;                 const int e = r + HW - 1;
;                 const float me = (e >= 0 && e < 128) ? 1.0f : 0.0f, ml = (r >= r0 && r - HW >= 0) ? 1.0f : 0.0f;
; #pragma unroll
;                 for (int j = 0; j < 8; ++j) { Vv[j].x += me * bf_lo(ring[u][j]); Vv[j].y += me * bf_hi(ring[u][j]); }
;                 if (r >= r0) {
;                     LAS f32x2* row = buf + ((r & 1) * 80 + 8) * 64 + lane;
; #pragma unroll
;                     for (int j = 0; j < 8; ++j) row[(c0 + j) * 64] = Vv[j];
;                     asm volatile("s_waitcnt lgkmcnt(0)" ::: "memory"); __builtin_amdgcn_s_barrier(); asm volatile("" ::: "memory");
;                     const int rlo = r - HW > 0 ? r - HW : 0, rhi = r + HW < 128 ? r + HW : 128; const float icr = 1.0f / (float)(rhi - rlo);
;                     f32x2 h = (f32x2){0.f, 0.f};
; #pragma unroll
;                     for (int c = -HW; c < HW; ++c) h += row[(c0 + c) * 64];
; #pragma unroll
;                     for (int j = 0; j < 8; ++j) {
;                         const float ic = icr * icc[j]; const unsigned m = ring[(u + NS - HW + 1) % NS][j];
;                         *(GAS unsigned*)(Db + ((size_t)r * 64 + c0 + j) * EI) = cvt_pk_bf16(h.x * ic - bf_lo(m), h.y * ic - bf_hi(m));
;                         h += row[(c0 + j + HW) * 64] - row[(c0 + j - HW) * 64];
;                     }
; #pragma unroll
;                     for (int j = 0; j < 8; ++j) { const unsigned l = ring[(u + NS - W + 1) % NS][j]; Vv[j].x -= ml * bf_lo(l); Vv[j].y -= ml * bf_hi(l); }
;                 }
	v_pk_add_f32 v[236:237], v[238:239], v[236:237] neg_lo:[0,1] neg_hi:[0,1]
	s_nop 0
	v_pk_add_f32 v[236:237], v[240:241], v[236:237]
	v_mul_f32_e32 v238, v81, v242
	v_lshlrev_b32_e32 v239, 16, v222
	v_fma_f32 v236, v238, v236, -v239
	v_and_b32_e32 v239, 0xffff0000, v222
	v_addc_co_u32_e32 v51, vcc, 0, v51, vcc
	v_fma_f32 v237, v238, v237, -v239
	v_cvt_pk_bf16_f32 v236, v236, v237
	global_store_dword v[50:51], v236, off
	v_lshlrev_b32_e32 v50, 16, v105
	v_and_b32_e32 v51, 0xffff0000, v105
	v_pk_fma_f32 v[18:19], v[2:3], v[50:51], v[18:19] op_sel_hi:[0,1,1] neg_lo:[1,0,0] neg_hi:[1,0,0]
	v_lshlrev_b32_e32 v50, 16, v108
	v_and_b32_e32 v51, 0xffff0000, v108
	v_pk_fma_f32 v[20:21], v[2:3], v[50:51], v[20:21] op_sel_hi:[0,1,1] neg_lo:[1,0,0] neg_hi:[1,0,0]
	v_lshlrev_b32_e32 v50, 16, v113
	v_and_b32_e32 v51, 0xffff0000, v113
	v_pk_fma_f32 v[22:23], v[2:3], v[50:51], v[22:23] op_sel_hi:[0,1,1] neg_lo:[1,0,0] neg_hi:[1,0,0]
	v_lshlrev_b32_e32 v50, 16, v119
	v_and_b32_e32 v51, 0xffff0000, v119
	v_pk_fma_f32 v[24:25], v[2:3], v[50:51], v[24:25] op_sel_hi:[0,1,1] neg_lo:[1,0,0] neg_hi:[1,0,0]
	v_lshlrev_b32_e32 v50, 16, v125
	v_and_b32_e32 v51, 0xffff0000, v125
	v_pk_fma_f32 v[26:27], v[2:3], v[50:51], v[26:27] op_sel_hi:[0,1,1] neg_lo:[1,0,0] neg_hi:[1,0,0]
	v_lshlrev_b32_e32 v50, 16, v132
	v_and_b32_e32 v51, 0xffff0000, v132
	v_pk_fma_f32 v[28:29], v[2:3], v[50:51], v[28:29] op_sel_hi:[0,1,1] neg_lo:[1,0,0] neg_hi:[1,0,0]
	v_lshlrev_b32_e32 v50, 16, v139
	v_and_b32_e32 v51, 0xffff0000, v139
	v_pk_fma_f32 v[30:31], v[2:3], v[50:51], v[30:31] op_sel_hi:[0,1,1] neg_lo:[1,0,0] neg_hi:[1,0,0]
	v_lshlrev_b32_e32 v50, 16, v172
	v_and_b32_e32 v51, 0xffff0000, v172
	v_pk_fma_f32 v[32:33], v[2:3], v[50:51], v[32:33] op_sel_hi:[0,1,1] neg_lo:[1,0,0] neg_hi:[1,0,0]
.LBB0_873:
	s_add_i32 s16, s42, 14
	s_cmp_ge_i32 s16, s46
	s_cbranch_scc1 .LBB0_876
	s_min_i32 s44, s16, 0x76
	s_ashr_i32 s45, s44, 31
	s_lshl_b64 s[44:45], s[44:45], 20
	v_lshl_add_u64 v[50:51], v[12:13], 0, s[44:45]
	v_add_co_u32_e32 v236, vcc, 0x900000, v50
	s_add_i32 s10, s42, 21
	s_nop 0
	v_addc_co_u32_e32 v237, vcc, 0, v51, vcc
	global_load_dword v105, v[236:237], off
	v_add_co_u32_e32 v236, vcc, 0x904000, v50
	s_cmpk_lt_u32 s10, 0x80
	s_nop 0
	v_addc_co_u32_e32 v237, vcc, 0, v51, vcc
	global_load_dword v108, v[236:237], off
	v_add_co_u32_e32 v236, vcc, 0x908000, v50
	s_cselect_b64 s[44:45], -1, 0
	s_nop 0
	v_addc_co_u32_e32 v237, vcc, 0, v51, vcc
	global_load_dword v113, v[236:237], off
	v_add_co_u32_e32 v236, vcc, 0x90c000, v50
	v_cndmask_b32_e64 v2, 0, 1.0, s[44:45]
	s_nop 0
	v_addc_co_u32_e32 v237, vcc, 0, v51, vcc
	global_load_dword v119, v[236:237], off
	v_add_co_u32_e32 v236, vcc, 0x910000, v50
	s_cmp_lt_i32 s16, s62
	s_nop 0
	v_addc_co_u32_e32 v237, vcc, 0, v51, vcc
	global_load_dword v125, v[236:237], off
	v_add_co_u32_e32 v236, vcc, 0x914000, v50
	s_nop 1
	v_addc_co_u32_e32 v237, vcc, 0, v51, vcc
	global_load_dword v132, v[236:237], off
	v_add_co_u32_e32 v236, vcc, 0x918000, v50
	s_nop 1
	v_addc_co_u32_e32 v237, vcc, 0, v51, vcc
	v_add_co_u32_e32 v50, vcc, 0x91c000, v50
	global_load_dword v139, v[236:237], off
	s_nop 0
	v_addc_co_u32_e32 v51, vcc, 0, v51, vcc
	global_load_dword v172, v[50:51], off
	s_waitcnt vmcnt(23)
	v_lshlrev_b32_e32 v50, 16, v111
	v_and_b32_e32 v51, 0xffff0000, v111
	v_pk_fma_f32 v[18:19], v[2:3], v[50:51], v[18:19] op_sel_hi:[0,1,1]
	s_waitcnt vmcnt(22)
	v_lshlrev_b32_e32 v50, 16, v117
	v_and_b32_e32 v51, 0xffff0000, v117
	v_pk_fma_f32 v[20:21], v[2:3], v[50:51], v[20:21] op_sel_hi:[0,1,1]
	s_waitcnt vmcnt(21)
	v_lshlrev_b32_e32 v50, 16, v123
	v_and_b32_e32 v51, 0xffff0000, v123
	v_pk_fma_f32 v[22:23], v[2:3], v[50:51], v[22:23] op_sel_hi:[0,1,1]
	s_waitcnt vmcnt(20)
	v_lshlrev_b32_e32 v50, 16, v130
	v_and_b32_e32 v51, 0xffff0000, v130
	v_pk_fma_f32 v[24:25], v[2:3], v[50:51], v[24:25] op_sel_hi:[0,1,1]
	s_waitcnt vmcnt(19)
	v_lshlrev_b32_e32 v50, 16, v137
	v_and_b32_e32 v51, 0xffff0000, v137
	v_pk_fma_f32 v[26:27], v[2:3], v[50:51], v[26:27] op_sel_hi:[0,1,1]
	s_waitcnt vmcnt(18)
	v_lshlrev_b32_e32 v50, 16, v146
	v_and_b32_e32 v51, 0xffff0000, v146
	v_pk_fma_f32 v[28:29], v[2:3], v[50:51], v[28:29] op_sel_hi:[0,1,1]
	s_waitcnt vmcnt(17)
	v_lshlrev_b32_e32 v50, 16, v155
	v_and_b32_e32 v51, 0xffff0000, v155
	v_pk_fma_f32 v[30:31], v[2:3], v[50:51], v[30:31] op_sel_hi:[0,1,1]
	s_waitcnt vmcnt(16)
	v_lshlrev_b32_e32 v50, 16, v188
	v_and_b32_e32 v51, 0xffff0000, v188
	v_pk_fma_f32 v[32:33], v[2:3], v[50:51], v[32:33] op_sel_hi:[0,1,1]
	s_cbranch_scc1 .LBB0_876
	ds_write2st64_b64 v92, v[18:19], v[20:21] offset0:88 offset1:89
	ds_write2st64_b64 v92, v[22:23], v[24:25] offset0:90 offset1:91
	ds_write2st64_b64 v92, v[26:27], v[28:29] offset0:92 offset1:93
	ds_write2st64_b64 v92, v[30:31], v[32:33] offset0:94 offset1:95
	s_waitcnt lgkmcnt(0)
	s_barrier
; #define GAS __attribute__((address_space(1)))
; #define LAS __attribute__((address_space(3)))
; __device__ __forceinline__ unsigned cvt_pk_bf16(float lo, float hi) { unsigned r; asm volatile("v_cvt_pk_bf16_f32 %0, %1, %2" : "=v"(r) : "v"(lo), "v"(hi)); return r; }
; __device__ __forceinline__ float bf_lo(unsigned w) { return __uint_as_float(w << 16); }
; __device__ __forceinline__ float bf_hi(unsigned w) { return __uint_as_float(w & 0xffff0000u); }
; template <int W>
; __device__ __forceinline__ void pool_item(const Ctx& F, const bf16* Ub, bf16* Db, int r0, int nr) {
;     ...
;                 if (r >= r0) {
;                     LAS f32x2* row = buf + ((r & 1) * 80 + 8) * 64 + lane;
; #pragma unroll
;                     for (int j = 0; j < 8; ++j) row[(c0 + j) * 64] = Vv[j];
;                     asm volatile("s_waitcnt lgkmcnt(0)" ::: "memory"); __builtin_amdgcn_s_barrier(); asm volatile("" ::: "memory");
;                     const int rlo = r - HW > 0 ? r - HW : 0, rhi = r + HW < 128 ? r + HW : 128; const float icr = 1.0f / (float)(rhi - rlo);
;                     f32x2 h = (f32x2){0.f, 0.f};
; #pragma unroll
;                     for (int c = -HW; c < HW; ++c) h += row[(c0 + c) * 64];
; #pragma unroll
;                     for (int j = 0; j < 8; ++j) {
;                         const float ic = icr * icc[j]; const unsigned m = ring[(u + NS - HW + 1) % NS][j];
;                         *(GAS unsigned*)(Db + ((size_t)r * 64 + c0 + j) * EI) = cvt_pk_bf16(h.x * ic - bf_lo(m), h.y * ic - bf_hi(m));
;                         h += row[(c0 + j + HW) * 64] - row[(c0 + j - HW) * 64];
;                     }
	ds_read2st64_b64 v[236:239], v92 offset0:80 offset1:81
	s_cmp_gt_i32 s42, -7
	s_cselect_b64 s[44:45], -1, 0
	s_max_i32 s10, s16, 8
	s_min_i32 s23, s16, 0x78
	s_waitcnt lgkmcnt(0)
	v_pk_add_f32 v[50:51], v[236:237], 0 op_sel_hi:[1,0]
	s_sub_i32 s10, s23, s10
	v_pk_add_f32 v[50:51], v[50:51], v[238:239]
	ds_read2st64_b64 v[236:239], v92 offset0:82 offset1:83
	s_add_i32 s10, s10, 16
	v_cvt_f32_i32_e32 v242, s10
	v_cndmask_b32_e64 v2, 0, 1.0, s[44:45]
	s_waitcnt lgkmcnt(0)
	v_pk_add_f32 v[50:51], v[50:51], v[236:237]
	s_nop 0
	v_pk_add_f32 v[50:51], v[50:51], v[238:239]
	ds_read2st64_b64 v[236:239], v92 offset0:84 offset1:85
	s_waitcnt lgkmcnt(0)
	v_pk_add_f32 v[50:51], v[50:51], v[236:237]
	s_nop 0
	v_pk_add_f32 v[50:51], v[50:51], v[238:239]
	ds_read2st64_b64 v[236:239], v92 offset0:86 offset1:87
	s_waitcnt lgkmcnt(0)
	v_pk_add_f32 v[50:51], v[50:51], v[236:237]
	s_nop 0
	v_pk_add_f32 v[50:51], v[50:51], v[238:239]
	ds_read2st64_b64 v[236:239], v92 offset0:88 offset1:89
	s_waitcnt lgkmcnt(0)
	v_pk_add_f32 v[50:51], v[50:51], v[236:237]
	s_nop 0
	v_pk_add_f32 v[50:51], v[50:51], v[238:239]
	ds_read2st64_b64 v[236:239], v92 offset0:90 offset1:91
	s_waitcnt lgkmcnt(0)
	v_pk_add_f32 v[50:51], v[50:51], v[236:237]
	s_nop 0
	v_pk_add_f32 v[50:51], v[50:51], v[238:239]
	ds_read2st64_b64 v[236:239], v92 offset0:92 offset1:93
	s_waitcnt lgkmcnt(0)
	v_pk_add_f32 v[50:51], v[50:51], v[236:237]
	s_nop 0
	v_pk_add_f32 v[50:51], v[50:51], v[238:239]
	ds_read2st64_b64 v[236:239], v92 offset0:94 offset1:95
	s_waitcnt lgkmcnt(0)
	v_pk_add_f32 v[50:51], v[50:51], v[236:237]
	s_nop 0
	v_pk_add_f32 v[240:241], v[50:51], v[238:239]
	v_div_scale_f32 v50, s[44:45], v242, v242, 1.0
	v_rcp_f32_e32 v51, v50
	s_lshl_b64 s[44:45], s[16:17], 20
	v_fma_f32 v236, -v50, v51, 1.0
	v_fmac_f32_e32 v51, v236, v51
	v_div_scale_f32 v236, vcc, 1.0, v242, 1.0
	v_mul_f32_e32 v237, v236, v51
	v_fma_f32 v238, -v50, v237, v236
	v_fmac_f32_e32 v237, v238, v51
	v_fma_f32 v50, -v50, v237, v236
	v_div_fmas_f32 v50, v50, v51, v237
	v_div_fixup_f32 v242, v50, v242, 1.0
	v_mul_f32_e32 v50, v74, v242
	v_lshlrev_b32_e32 v51, 16, v154
	v_and_b32_e32 v236, 0xffff0000, v154
	v_fma_f32 v51, v50, v240, -v51
	v_fma_f32 v50, v50, v241, -v236
	v_cvt_pk_bf16_f32 v236, v51, v50
	v_lshl_add_u64 v[50:51], v[14:15], 0, s[44:45]
	global_store_dword v[50:51], v236, off
	ds_read2st64_b64 v[236:239], v92 offset0:80 offset1:96
	s_waitcnt lgkmcnt(0)
	v_pk_add_f32 v[236:237], v[238:239], v[236:237] neg_lo:[0,1] neg_hi:[0,1]
	s_nop 0
	v_pk_add_f32 v[240:241], v[240:241], v[236:237]
	v_mul_f32_e32 v236, v75, v242
	v_lshlrev_b32_e32 v237, 16, v161
	v_and_b32_e32 v238, 0xffff0000, v161
	v_fma_f32 v237, v236, v240, -v237
	v_fma_f32 v236, v236, v241, -v238
	v_cvt_pk_bf16_f32 v238, v237, v236
	v_add_co_u32_e32 v236, vcc, s54, v50
	s_nop 1
	v_addc_co_u32_e32 v237, vcc, 0, v51, vcc
	global_store_dword v[236:237], v238, off
	ds_read2st64_b64 v[236:239], v92 offset0:81 offset1:97
	s_waitcnt lgkmcnt(0)
	v_pk_add_f32 v[236:237], v[238:239], v[236:237] neg_lo:[0,1] neg_hi:[0,1]
	s_nop 0
	v_pk_add_f32 v[240:241], v[240:241], v[236:237]
	v_mul_f32_e32 v236, v76, v242
	v_lshlrev_b32_e32 v237, 16, v170
	v_and_b32_e32 v238, 0xffff0000, v170
	v_fma_f32 v237, v236, v240, -v237
	v_fma_f32 v236, v236, v241, -v238
	v_cvt_pk_bf16_f32 v238, v237, v236
	v_add_co_u32_e32 v236, vcc, s55, v50
	s_nop 1
	v_addc_co_u32_e32 v237, vcc, 0, v51, vcc
	global_store_dword v[236:237], v238, off
	ds_read2st64_b64 v[236:239], v92 offset0:82 offset1:98
	s_waitcnt lgkmcnt(0)
	v_pk_add_f32 v[236:237], v[238:239], v[236:237] neg_lo:[0,1] neg_hi:[0,1]
	s_nop 0
	v_pk_add_f32 v[240:241], v[240:241], v[236:237]
	v_mul_f32_e32 v236, v77, v242
	v_lshlrev_b32_e32 v237, 16, v182
	v_and_b32_e32 v238, 0xffff0000, v182
	v_fma_f32 v237, v236, v240, -v237
	v_fma_f32 v236, v236, v241, -v238
	v_cvt_pk_bf16_f32 v238, v237, v236
	v_add_co_u32_e32 v236, vcc, s56, v50
	s_nop 1
	v_addc_co_u32_e32 v237, vcc, 0, v51, vcc
	global_store_dword v[236:237], v238, off
	ds_read2st64_b64 v[236:239], v92 offset0:83 offset1:99
	s_waitcnt lgkmcnt(0)
	v_pk_add_f32 v[236:237], v[238:239], v[236:237] neg_lo:[0,1] neg_hi:[0,1]
	s_nop 0
	v_pk_add_f32 v[240:241], v[240:241], v[236:237]
	v_mul_f32_e32 v236, v78, v242
	v_lshlrev_b32_e32 v237, 16, v191
	v_and_b32_e32 v238, 0xffff0000, v191
	v_fma_f32 v237, v236, v240, -v237
	v_fma_f32 v236, v236, v241, -v238
	v_cvt_pk_bf16_f32 v238, v237, v236
	v_add_co_u32_e32 v236, vcc, s57, v50
	s_nop 1
	v_addc_co_u32_e32 v237, vcc, 0, v51, vcc
	global_store_dword v[236:237], v238, off
	ds_read2st64_b64 v[236:239], v92 offset0:84 offset1:100
	s_waitcnt lgkmcnt(0)
	v_pk_add_f32 v[236:237], v[238:239], v[236:237] neg_lo:[0,1] neg_hi:[0,1]
	s_nop 0
	v_pk_add_f32 v[240:241], v[240:241], v[236:237]
	v_mul_f32_e32 v236, v79, v242
	v_lshlrev_b32_e32 v237, 16, v199
	v_and_b32_e32 v238, 0xffff0000, v199
	v_fma_f32 v237, v236, v240, -v237
	v_fma_f32 v236, v236, v241, -v238
	v_cvt_pk_bf16_f32 v238, v237, v236
	v_add_co_u32_e32 v236, vcc, s58, v50
	s_nop 1
	v_addc_co_u32_e32 v237, vcc, 0, v51, vcc
	global_store_dword v[236:237], v238, off
	ds_read2st64_b64 v[236:239], v92 offset0:85 offset1:101
	s_waitcnt lgkmcnt(0)
	v_pk_add_f32 v[236:237], v[238:239], v[236:237] neg_lo:[0,1] neg_hi:[0,1]
	s_nop 0
	v_pk_add_f32 v[240:241], v[240:241], v[236:237]
	v_mul_f32_e32 v236, v80, v242
	v_lshlrev_b32_e32 v237, 16, v206
	v_and_b32_e32 v238, 0xffff0000, v206
	v_fma_f32 v237, v236, v240, -v237
	v_fma_f32 v236, v236, v241, -v238
	v_cvt_pk_bf16_f32 v238, v237, v236
	v_add_co_u32_e32 v236, vcc, s59, v50
	s_nop 1
	v_addc_co_u32_e32 v237, vcc, 0, v51, vcc
	global_store_dword v[236:237], v238, off
	ds_read2st64_b64 v[236:239], v92 offset0:86 offset1:102
	v_add_co_u32_e32 v50, vcc, s60, v50
	s_waitcnt lgkmcnt(0)
; #define GAS __attribute__((address_space(1)))
; #define LAS __attribute__((address_space(3)))
; __device__ __forceinline__ unsigned cvt_pk_bf16(float lo, float hi) { unsigned r; asm volatile("v_cvt_pk_bf16_f32 %0, %1, %2" : "=v"(r) : "v"(lo), "v"(hi)); return r; }
; __device__ __forceinline__ float bf_lo(unsigned w) { return __uint_as_float(w << 16); }
; template <int W>
; __device__ __forceinline__ void pool_item(const Ctx& F, const bf16* Ub, bf16* Db, int r0, int nr) {
;     ...
;     POOL_LOAD(0, rs); POOL_LOAD(1, rs + 1);
;     __syncthreads();
;     for (int base = rs; base < re; base += NS) {
; #pragma unroll
;         for (int u = 0; u < NS; ++u) {
;             const int r = base + u;
;             if (r < re) {
;                 POOL_LOAD((u + 2) % NS, r + 2);
;                 const int e = r + HW - 1;
;                 const float me = (e >= 0 && e < 128) ? 1.0f : 0.0f, ml = (r >= r0 && r - HW >= 0) ? 1.0f : 0.0f;
; #pragma unroll
;                 for (int j = 0; j < 8; ++j) { Vv[j].x += me * bf_lo(ring[u][j]); Vv[j].y += me * bf_hi(ring[u][j]); }
;                 if (r >= r0) {
;                     LAS f32x2* row = buf + ((r & 1) * 80 + 8) * 64 + lane;
; #pragma unroll
;                     for (int j = 0; j < 8; ++j) row[(c0 + j) * 64] = Vv[j];
;                     asm volatile("s_waitcnt lgkmcnt(0)" ::: "memory"); __builtin_amdgcn_s_barrier(); asm volatile("" ::: "memory");
;                     const int rlo = r - HW > 0 ? r - HW : 0, rhi = r + HW < 128 ? r + HW : 128; const float icr = 1.0f / (float)(rhi - rlo);
;                     f32x2 h = (f32x2){0.f, 0.f};
; #pragma unroll
;                     for (int c = -HW; c < HW; ++c) h += row[(c0 + c) * 64];
; #pragma unroll
;                     for (int j = 0; j < 8; ++j) {
;                         const float ic = icr * icc[j]; const unsigned m = ring[(u + NS - HW + 1) % NS][j];
;                         *(GAS unsigned*)(Db + ((size_t)r * 64 + c0 + j) * EI) = cvt_pk_bf16(h.x * ic - bf_lo(m), h.y * ic - bf_hi(m));
;                         h += row[(c0 + j + HW) * 64] - row[(c0 + j - HW) * 64];
;                     }
; #pragma unroll
;                     for (int j = 0; j < 8; ++j) { const unsigned l = ring[(u + NS - W + 1) % NS][j]; Vv[j].x -= ml * bf_lo(l); Vv[j].y -= ml * bf_hi(l); }
;                 }
	v_pk_add_f32 v[236:237], v[238:239], v[236:237] neg_lo:[0,1] neg_hi:[0,1]
	s_nop 0
	v_pk_add_f32 v[236:237], v[240:241], v[236:237]
	v_mul_f32_e32 v238, v81, v242
	v_lshlrev_b32_e32 v239, 16, v220
	v_fma_f32 v236, v238, v236, -v239
	v_and_b32_e32 v239, 0xffff0000, v220
	v_addc_co_u32_e32 v51, vcc, 0, v51, vcc
	v_fma_f32 v237, v238, v237, -v239
	v_cvt_pk_bf16_f32 v236, v236, v237
	global_store_dword v[50:51], v236, off
	v_lshlrev_b32_e32 v50, 16, v101
	v_and_b32_e32 v51, 0xffff0000, v101
	v_pk_fma_f32 v[18:19], v[2:3], v[50:51], v[18:19] op_sel_hi:[0,1,1] neg_lo:[1,0,0] neg_hi:[1,0,0]
	v_lshlrev_b32_e32 v50, 16, v103
	v_and_b32_e32 v51, 0xffff0000, v103
	v_pk_fma_f32 v[20:21], v[2:3], v[50:51], v[20:21] op_sel_hi:[0,1,1] neg_lo:[1,0,0] neg_hi:[1,0,0]
	v_lshlrev_b32_e32 v50, 16, v106
	v_and_b32_e32 v51, 0xffff0000, v106
	v_pk_fma_f32 v[22:23], v[2:3], v[50:51], v[22:23] op_sel_hi:[0,1,1] neg_lo:[1,0,0] neg_hi:[1,0,0]
	v_lshlrev_b32_e32 v50, 16, v110
	v_and_b32_e32 v51, 0xffff0000, v110
	v_pk_fma_f32 v[24:25], v[2:3], v[50:51], v[24:25] op_sel_hi:[0,1,1] neg_lo:[1,0,0] neg_hi:[1,0,0]
	v_lshlrev_b32_e32 v50, 16, v115
	v_and_b32_e32 v51, 0xffff0000, v115
	v_pk_fma_f32 v[26:27], v[2:3], v[50:51], v[26:27] op_sel_hi:[0,1,1] neg_lo:[1,0,0] neg_hi:[1,0,0]
	v_lshlrev_b32_e32 v50, 16, v120
	v_and_b32_e32 v51, 0xffff0000, v120
	v_pk_fma_f32 v[28:29], v[2:3], v[50:51], v[28:29] op_sel_hi:[0,1,1] neg_lo:[1,0,0] neg_hi:[1,0,0]
	v_lshlrev_b32_e32 v50, 16, v127
	v_and_b32_e32 v51, 0xffff0000, v127
	v_pk_fma_f32 v[30:31], v[2:3], v[50:51], v[30:31] op_sel_hi:[0,1,1] neg_lo:[1,0,0] neg_hi:[1,0,0]
	v_lshlrev_b32_e32 v50, 16, v156
	v_and_b32_e32 v51, 0xffff0000, v156
	v_pk_fma_f32 v[32:33], v[2:3], v[50:51], v[32:33] op_sel_hi:[0,1,1] neg_lo:[1,0,0] neg_hi:[1,0,0]
.LBB0_876:
	s_add_i32 s10, s42, 15
	s_cmp_ge_u32 s10, s46
	s_cbranch_scc1 .LBB0_879
	s_min_i32 s16, s10, 0x76
	s_add_i32 s16, s16, 9
	s_lshl_b64 s[44:45], s[16:17], 20
	v_lshl_add_u64 v[50:51], v[12:13], 0, s[44:45]
	v_add_co_u32_e32 v236, vcc, 0x4000, v50
	global_load_dword v101, v[50:51], off
	s_nop 0
	v_addc_co_u32_e32 v237, vcc, 0, v51, vcc
	global_load_dword v103, v[236:237], off
	v_add_co_u32_e32 v236, vcc, 0x8000, v50
	s_add_i32 s16, s42, 22
	s_nop 0
	v_addc_co_u32_e32 v237, vcc, 0, v51, vcc
	global_load_dword v106, v[236:237], off
	v_add_co_u32_e32 v236, vcc, 0xc000, v50
	s_cmpk_lt_u32 s16, 0x80
	s_nop 0
	v_addc_co_u32_e32 v237, vcc, 0, v51, vcc
	global_load_dword v110, v[236:237], off
	v_add_co_u32_e32 v236, vcc, 0x10000, v50
	s_cselect_b64 s[44:45], -1, 0
	s_nop 0
	v_addc_co_u32_e32 v237, vcc, 0, v51, vcc
	global_load_dword v115, v[236:237], off
	v_add_co_u32_e32 v236, vcc, 0x14000, v50
	v_cndmask_b32_e64 v2, 0, 1.0, s[44:45]
	s_nop 0
	v_addc_co_u32_e32 v237, vcc, 0, v51, vcc
	global_load_dword v120, v[236:237], off
	v_add_co_u32_e32 v236, vcc, 0x18000, v50
	s_cmp_lt_u32 s10, s62
	s_nop 0
	v_addc_co_u32_e32 v237, vcc, 0, v51, vcc
	v_add_co_u32_e32 v50, vcc, 0x1c000, v50
	global_load_dword v127, v[236:237], off
	s_nop 0
	v_addc_co_u32_e32 v51, vcc, 0, v51, vcc
	global_load_dword v156, v[50:51], off
	s_waitcnt vmcnt(23)
	v_lshlrev_b32_e32 v50, 16, v107
	v_and_b32_e32 v51, 0xffff0000, v107
	v_pk_fma_f32 v[18:19], v[2:3], v[50:51], v[18:19] op_sel_hi:[0,1,1]
	s_waitcnt vmcnt(22)
	v_lshlrev_b32_e32 v50, 16, v112
	v_and_b32_e32 v51, 0xffff0000, v112
	v_pk_fma_f32 v[20:21], v[2:3], v[50:51], v[20:21] op_sel_hi:[0,1,1]
	s_waitcnt vmcnt(21)
	v_lshlrev_b32_e32 v50, 16, v118
	v_and_b32_e32 v51, 0xffff0000, v118
	v_pk_fma_f32 v[22:23], v[2:3], v[50:51], v[22:23] op_sel_hi:[0,1,1]
	s_waitcnt vmcnt(20)
	v_lshlrev_b32_e32 v50, 16, v124
	v_and_b32_e32 v51, 0xffff0000, v124
	v_pk_fma_f32 v[24:25], v[2:3], v[50:51], v[24:25] op_sel_hi:[0,1,1]
	s_waitcnt vmcnt(19)
	v_lshlrev_b32_e32 v50, 16, v131
	v_and_b32_e32 v51, 0xffff0000, v131
	v_pk_fma_f32 v[26:27], v[2:3], v[50:51], v[26:27] op_sel_hi:[0,1,1]
	s_waitcnt vmcnt(18)
	v_lshlrev_b32_e32 v50, 16, v138
	v_and_b32_e32 v51, 0xffff0000, v138
	v_pk_fma_f32 v[28:29], v[2:3], v[50:51], v[28:29] op_sel_hi:[0,1,1]
	s_waitcnt vmcnt(17)
	v_lshlrev_b32_e32 v50, 16, v147
	v_and_b32_e32 v51, 0xffff0000, v147
	v_pk_fma_f32 v[30:31], v[2:3], v[50:51], v[30:31] op_sel_hi:[0,1,1]
	s_waitcnt vmcnt(16)
	v_lshlrev_b32_e32 v50, 16, v180
	v_and_b32_e32 v51, 0xffff0000, v180
	v_pk_fma_f32 v[32:33], v[2:3], v[50:51], v[32:33] op_sel_hi:[0,1,1]
	s_cbranch_scc1 .LBB0_879
	ds_write2st64_b64 v92, v[18:19], v[20:21] offset0:8 offset1:9
	ds_write2st64_b64 v92, v[22:23], v[24:25] offset0:10 offset1:11
	ds_write2st64_b64 v92, v[26:27], v[28:29] offset0:12 offset1:13
	ds_write2st64_b64 v92, v[30:31], v[32:33] offset0:14 offset1:15
	s_waitcnt lgkmcnt(0)
	s_barrier
; #define GAS __attribute__((address_space(1)))
; #define LAS __attribute__((address_space(3)))
; __device__ __forceinline__ unsigned cvt_pk_bf16(float lo, float hi) { unsigned r; asm volatile("v_cvt_pk_bf16_f32 %0, %1, %2" : "=v"(r) : "v"(lo), "v"(hi)); return r; }
; __device__ __forceinline__ float bf_lo(unsigned w) { return __uint_as_float(w << 16); }
; __device__ __forceinline__ float bf_hi(unsigned w) { return __uint_as_float(w & 0xffff0000u); }
; template <int W>
; __device__ __forceinline__ void pool_item(const Ctx& F, const bf16* Ub, bf16* Db, int r0, int nr) {
;     ...
;                 if (r >= r0) {
;                     LAS f32x2* row = buf + ((r & 1) * 80 + 8) * 64 + lane;
; #pragma unroll
;                     for (int j = 0; j < 8; ++j) row[(c0 + j) * 64] = Vv[j];
;                     asm volatile("s_waitcnt lgkmcnt(0)" ::: "memory"); __builtin_amdgcn_s_barrier(); asm volatile("" ::: "memory");
;                     const int rlo = r - HW > 0 ? r - HW : 0, rhi = r + HW < 128 ? r + HW : 128; const float icr = 1.0f / (float)(rhi - rlo);
;                     f32x2 h = (f32x2){0.f, 0.f};
; #pragma unroll
;                     for (int c = -HW; c < HW; ++c) h += row[(c0 + c) * 64];
; #pragma unroll
;                     for (int j = 0; j < 8; ++j) {
;                         const float ic = icr * icc[j]; const unsigned m = ring[(u + NS - HW + 1) % NS][j];
;                         *(GAS unsigned*)(Db + ((size_t)r * 64 + c0 + j) * EI) = cvt_pk_bf16(h.x * ic - bf_lo(m), h.y * ic - bf_hi(m));
;                         h += row[(c0 + j + HW) * 64] - row[(c0 + j - HW) * 64];
;                     }
; #pragma unroll
;                     for (int j = 0; j < 8; ++j) { const unsigned l = ring[(u + NS - W + 1) % NS][j]; Vv[j].x -= ml * bf_lo(l); Vv[j].y -= ml * bf_hi(l); }
;                 }
	ds_read2st64_b64 v[236:239], v92 offset1:1
	s_cmp_gt_u32 s10, 7
	s_cselect_b64 s[44:45], -1, 0
	s_max_i32 s16, s10, 8
	s_min_i32 s10, s10, 0x78
	s_waitcnt lgkmcnt(0)
	v_pk_add_f32 v[50:51], v[236:237], 0 op_sel_hi:[1,0]
	s_sub_i32 s10, s10, s16
	v_pk_add_f32 v[50:51], v[50:51], v[238:239]
	ds_read2st64_b64 v[236:239], v92 offset0:2 offset1:3
	s_add_i32 s10, s10, 16
	v_cvt_f32_i32_e32 v240, s10
	v_cndmask_b32_e64 v2, 0, 1.0, s[44:45]
	s_mov_b32 s10, 0xffdec000
	s_waitcnt lgkmcnt(0)
	v_pk_add_f32 v[50:51], v[50:51], v[236:237]
	v_pk_fma_f32 v[32:33], v[2:3], v[48:49], v[32:33] op_sel_hi:[0,1,1] neg_lo:[1,0,0] neg_hi:[1,0,0]
	v_pk_add_f32 v[50:51], v[50:51], v[238:239]
	ds_read2st64_b64 v[236:239], v92 offset0:4 offset1:5
	v_pk_fma_f32 v[30:31], v[2:3], v[46:47], v[30:31] op_sel_hi:[0,1,1] neg_lo:[1,0,0] neg_hi:[1,0,0]
	v_pk_fma_f32 v[28:29], v[2:3], v[44:45], v[28:29] op_sel_hi:[0,1,1] neg_lo:[1,0,0] neg_hi:[1,0,0]
	v_pk_fma_f32 v[26:27], v[2:3], v[42:43], v[26:27] op_sel_hi:[0,1,1] neg_lo:[1,0,0] neg_hi:[1,0,0]
	v_pk_fma_f32 v[24:25], v[2:3], v[40:41], v[24:25] op_sel_hi:[0,1,1] neg_lo:[1,0,0] neg_hi:[1,0,0]
	s_waitcnt lgkmcnt(0)
	v_pk_add_f32 v[50:51], v[50:51], v[236:237]
	v_pk_fma_f32 v[22:23], v[2:3], v[38:39], v[22:23] op_sel_hi:[0,1,1] neg_lo:[1,0,0] neg_hi:[1,0,0]
	v_pk_add_f32 v[50:51], v[50:51], v[238:239]
	ds_read2st64_b64 v[236:239], v92 offset0:6 offset1:7
	v_pk_fma_f32 v[20:21], v[2:3], v[36:37], v[20:21] op_sel_hi:[0,1,1] neg_lo:[1,0,0] neg_hi:[1,0,0]
	v_pk_fma_f32 v[18:19], v[2:3], v[34:35], v[18:19] op_sel_hi:[0,1,1] neg_lo:[1,0,0] neg_hi:[1,0,0]
	s_waitcnt lgkmcnt(0)
	v_pk_add_f32 v[50:51], v[50:51], v[236:237]
	s_nop 0
	v_pk_add_f32 v[50:51], v[50:51], v[238:239]
	ds_read2st64_b64 v[236:239], v92 offset0:8 offset1:9
	s_waitcnt lgkmcnt(0)
	v_pk_add_f32 v[50:51], v[50:51], v[236:237]
	s_nop 0
	v_pk_add_f32 v[50:51], v[50:51], v[238:239]
	ds_read2st64_b64 v[236:239], v92 offset0:10 offset1:11
	s_waitcnt lgkmcnt(0)
	v_pk_add_f32 v[50:51], v[50:51], v[236:237]
	s_nop 0
	v_pk_add_f32 v[50:51], v[50:51], v[238:239]
	ds_read2st64_b64 v[236:239], v92 offset0:12 offset1:13
	s_waitcnt lgkmcnt(0)
	v_pk_add_f32 v[50:51], v[50:51], v[236:237]
	s_nop 0
	v_pk_add_f32 v[50:51], v[50:51], v[238:239]
	ds_read2st64_b64 v[236:239], v92 offset0:14 offset1:15
	s_waitcnt lgkmcnt(0)
	v_pk_add_f32 v[50:51], v[50:51], v[236:237]
	v_div_scale_f32 v236, s[44:45], v240, v240, 1.0
	v_rcp_f32_e32 v237, v236
	v_pk_add_f32 v[50:51], v[50:51], v[238:239]
	v_fma_f32 v238, -v236, v237, 1.0
	v_fmac_f32_e32 v237, v238, v237
	v_div_scale_f32 v238, vcc, 1.0, v240, 1.0
	v_mul_f32_e32 v239, v238, v237
	v_fma_f32 v241, -v236, v239, v238
	v_fmac_f32_e32 v239, v241, v237
	v_fma_f32 v236, -v236, v239, v238
	v_div_fmas_f32 v236, v236, v237, v239
	v_div_fixup_f32 v240, v236, v240, 1.0
	v_mul_f32_e32 v236, v74, v240
	v_lshlrev_b32_e32 v237, 16, v148
	v_and_b32_e32 v238, 0xffff0000, v148
	v_fma_f32 v237, v236, v50, -v237
	v_fma_f32 v236, v236, v51, -v238
	v_cvt_pk_bf16_f32 v238, v237, v236
	v_add_co_u32_e32 v236, vcc, s63, v16
	s_nop 1
	v_addc_co_u32_e32 v237, vcc, -1, v17, vcc
	global_store_dword v[236:237], v238, off
	ds_read2st64_b64 v[236:239], v92 offset1:16
	s_waitcnt lgkmcnt(0)
	v_pk_add_f32 v[236:237], v[238:239], v[236:237] neg_lo:[0,1] neg_hi:[0,1]
	s_nop 0
	v_pk_add_f32 v[50:51], v[50:51], v[236:237]
	v_mul_f32_e32 v236, v75, v240
	v_lshlrev_b32_e32 v237, 16, v157
	v_and_b32_e32 v238, 0xffff0000, v157
	v_fma_f32 v237, v236, v50, -v237
	v_fma_f32 v236, v236, v51, -v238
	v_cvt_pk_bf16_f32 v238, v237, v236
	v_add_co_u32_e32 v236, vcc, s47, v16
	s_nop 1
	v_addc_co_u32_e32 v237, vcc, -1, v17, vcc
	global_store_dword v[236:237], v238, off
	ds_read2st64_b64 v[236:239], v92 offset0:1 offset1:17
	s_waitcnt lgkmcnt(0)
	v_pk_add_f32 v[236:237], v[238:239], v[236:237] neg_lo:[0,1] neg_hi:[0,1]
	s_nop 0
	v_pk_add_f32 v[50:51], v[50:51], v[236:237]
	v_mul_f32_e32 v236, v76, v240
	v_lshlrev_b32_e32 v237, 16, v165
	v_and_b32_e32 v238, 0xffff0000, v165
	v_fma_f32 v237, v236, v50, -v237
	v_fma_f32 v236, v236, v51, -v238
	v_cvt_pk_bf16_f32 v238, v237, v236
	v_add_co_u32_e32 v236, vcc, s10, v16
	s_nop 1
	v_addc_co_u32_e32 v237, vcc, -1, v17, vcc
	global_store_dword v[236:237], v238, off
	ds_read2st64_b64 v[236:239], v92 offset0:2 offset1:18
	s_waitcnt lgkmcnt(0)
	v_pk_add_f32 v[236:237], v[238:239], v[236:237] neg_lo:[0,1] neg_hi:[0,1]
	s_nop 0
	v_pk_add_f32 v[50:51], v[50:51], v[236:237]
	v_mul_f32_e32 v236, v77, v240
	v_lshlrev_b32_e32 v237, 16, v174
	v_and_b32_e32 v238, 0xffff0000, v174
	v_fma_f32 v237, v236, v50, -v237
	v_fma_f32 v236, v236, v51, -v238
	v_cvt_pk_bf16_f32 v238, v237, v236
	v_add_co_u32_e32 v236, vcc, s65, v16
	s_nop 1
	v_addc_co_u32_e32 v237, vcc, -1, v17, vcc
	global_store_dword v[236:237], v238, off
	ds_read2st64_b64 v[236:239], v92 offset0:3 offset1:19
	s_waitcnt lgkmcnt(0)
	v_pk_add_f32 v[236:237], v[238:239], v[236:237] neg_lo:[0,1] neg_hi:[0,1]
	s_nop 0
	v_pk_add_f32 v[50:51], v[50:51], v[236:237]
	v_mul_f32_e32 v236, v78, v240
	v_lshlrev_b32_e32 v237, 16, v183
	v_and_b32_e32 v238, 0xffff0000, v183
	v_fma_f32 v237, v236, v50, -v237
	v_fma_f32 v236, v236, v51, -v238
	v_cvt_pk_bf16_f32 v238, v237, v236
	v_add_co_u32_e32 v236, vcc, s66, v16
	s_nop 1
	v_addc_co_u32_e32 v237, vcc, -1, v17, vcc
	global_store_dword v[236:237], v238, off
	ds_read2st64_b64 v[236:239], v92 offset0:4 offset1:20
	s_waitcnt lgkmcnt(0)
	v_pk_add_f32 v[236:237], v[238:239], v[236:237] neg_lo:[0,1] neg_hi:[0,1]
	s_nop 0
	v_pk_add_f32 v[50:51], v[50:51], v[236:237]
	v_mul_f32_e32 v236, v79, v240
	v_lshlrev_b32_e32 v237, 16, v193
	v_and_b32_e32 v238, 0xffff0000, v193
	v_fma_f32 v237, v236, v50, -v237
	v_fma_f32 v236, v236, v51, -v238
	v_cvt_pk_bf16_f32 v238, v237, v236
	v_add_co_u32_e32 v236, vcc, s67, v16
	s_nop 1
	v_addc_co_u32_e32 v237, vcc, -1, v17, vcc
	global_store_dword v[236:237], v238, off
	ds_read2st64_b64 v[236:239], v92 offset0:5 offset1:21
	s_waitcnt lgkmcnt(0)
	v_pk_add_f32 v[236:237], v[238:239], v[236:237] neg_lo:[0,1] neg_hi:[0,1]
	s_nop 0
	v_pk_add_f32 v[50:51], v[50:51], v[236:237]
	v_mul_f32_e32 v236, v80, v240
	v_lshlrev_b32_e32 v237, 16, v202
	v_and_b32_e32 v238, 0xffff0000, v202
	v_fma_f32 v237, v236, v50, -v237
	v_fma_f32 v236, v236, v51, -v238
	v_cvt_pk_bf16_f32 v238, v237, v236
	v_add_co_u32_e32 v236, vcc, s70, v16
	s_nop 1
	v_addc_co_u32_e32 v237, vcc, -1, v17, vcc
	global_store_dword v[236:237], v238, off
	ds_read2st64_b64 v[236:239], v92 offset0:6 offset1:22
	s_waitcnt lgkmcnt(0)
	v_pk_add_f32 v[236:237], v[238:239], v[236:237] neg_lo:[0,1] neg_hi:[0,1]
	s_nop 0
	v_pk_add_f32 v[50:51], v[50:51], v[236:237]
	v_mul_f32_e32 v236, v81, v240
	v_lshlrev_b32_e32 v237, 16, v219
	v_fma_f32 v50, v236, v50, -v237
	v_and_b32_e32 v237, 0xffff0000, v219
	v_fma_f32 v51, v236, v51, -v237
	v_cvt_pk_bf16_f32 v236, v50, v51
	v_add_co_u32_e32 v50, vcc, s71, v16
	s_nop 1
	v_addc_co_u32_e32 v51, vcc, -1, v17, vcc
	global_store_dword v[50:51], v236, off
; #define GAS __attribute__((address_space(1)))
; #define LAS __attribute__((address_space(3)))
; __device__ __forceinline__ unsigned cvt_pk_bf16(float lo, float hi) { unsigned r; asm volatile("v_cvt_pk_bf16_f32 %0, %1, %2" : "=v"(r) : "v"(lo), "v"(hi)); return r; }
; __device__ __forceinline__ float bf_lo(unsigned w) { return __uint_as_float(w << 16); }
; __device__ __forceinline__ float bf_hi(unsigned w) { return __uint_as_float(w & 0xffff0000u); }
; template <int W>
; __device__ __forceinline__ void pool_item(const Ctx& F, const bf16* Ub, bf16* Db, int r0, int nr) {
;     ...
;     POOL_LOAD(0, rs); POOL_LOAD(1, rs + 1);
;     __syncthreads();
;     for (int base = rs; base < re; base += NS) {
; #pragma unroll
;         for (int u = 0; u < NS; ++u) {
;             const int r = base + u;
;             if (r < re) {
;                 POOL_LOAD((u + 2) % NS, r + 2);
;                 const int e = r + HW - 1;
;                 const float me = (e >= 0 && e < 128) ? 1.0f : 0.0f, ml = (r >= r0 && r - HW >= 0) ? 1.0f : 0.0f;
; #pragma unroll
;                 for (int j = 0; j < 8; ++j) { Vv[j].x += me * bf_lo(ring[u][j]); Vv[j].y += me * bf_hi(ring[u][j]); }
;                 if (r >= r0) {
;                     LAS f32x2* row = buf + ((r & 1) * 80 + 8) * 64 + lane;
; #pragma unroll
;                     for (int j = 0; j < 8; ++j) row[(c0 + j) * 64] = Vv[j];
;                     asm volatile("s_waitcnt lgkmcnt(0)" ::: "memory"); __builtin_amdgcn_s_barrier(); asm volatile("" ::: "memory");
;                     const int rlo = r - HW > 0 ? r - HW : 0, rhi = r + HW < 128 ? r + HW : 128; const float icr = 1.0f / (float)(rhi - rlo);
;                     f32x2 h = (f32x2){0.f, 0.f};
; #pragma unroll
;                     for (int c = -HW; c < HW; ++c) h += row[(c0 + c) * 64];
; #pragma unroll
;                     for (int j = 0; j < 8; ++j) {
;                         const float ic = icr * icc[j]; const unsigned m = ring[(u + NS - HW + 1) % NS][j];
;                         *(GAS unsigned*)(Db + ((size_t)r * 64 + c0 + j) * EI) = cvt_pk_bf16(h.x * ic - bf_lo(m), h.y * ic - bf_hi(m));
;                         h += row[(c0 + j + HW) * 64] - row[(c0 + j - HW) * 64];
;                     }
.LBB0_879:
	s_add_i32 s10, s42, 16
	s_cmp_ge_u32 s10, s46
	s_cbranch_scc1 .LBB0_882
	s_min_i32 s16, s10, 0x76
	s_add_i32 s16, s16, 9
	s_lshl_b64 s[44:45], s[16:17], 20
	v_lshl_add_u64 v[34:35], v[12:13], 0, s[44:45]
	v_add_co_u32_e32 v36, vcc, 0x4000, v34
	global_load_dword v53, v[34:35], off
	s_nop 0
	v_addc_co_u32_e32 v37, vcc, 0, v35, vcc
	global_load_dword v54, v[36:37], off
	v_add_co_u32_e32 v36, vcc, 0x8000, v34
	s_add_i32 s16, s42, 23
	s_nop 0
	v_addc_co_u32_e32 v37, vcc, 0, v35, vcc
	global_load_dword v55, v[36:37], off
	v_add_co_u32_e32 v36, vcc, 0xc000, v34
	s_cmpk_lt_u32 s16, 0x80
	s_nop 0
	v_addc_co_u32_e32 v37, vcc, 0, v35, vcc
	global_load_dword v56, v[36:37], off
	v_add_co_u32_e32 v36, vcc, 0x10000, v34
	s_cselect_b64 s[44:45], -1, 0
	s_nop 0
	v_addc_co_u32_e32 v37, vcc, 0, v35, vcc
	global_load_dword v57, v[36:37], off
	v_add_co_u32_e32 v36, vcc, 0x14000, v34
	v_cndmask_b32_e64 v2, 0, 1.0, s[44:45]
	s_nop 0
	v_addc_co_u32_e32 v37, vcc, 0, v35, vcc
	global_load_dword v95, v[36:37], off
	v_add_co_u32_e32 v36, vcc, 0x18000, v34
	s_cmp_lt_u32 s10, s62
	s_nop 0
	v_addc_co_u32_e32 v37, vcc, 0, v35, vcc
	v_add_co_u32_e32 v34, vcc, 0x1c000, v34
	global_load_dword v96, v[36:37], off
	s_nop 0
	v_addc_co_u32_e32 v35, vcc, 0, v35, vcc
	global_load_dword v102, v[34:35], off
	s_waitcnt vmcnt(23)
	v_lshlrev_b32_e32 v34, 16, v105
	v_and_b32_e32 v35, 0xffff0000, v105
	v_pk_fma_f32 v[18:19], v[2:3], v[34:35], v[18:19] op_sel_hi:[0,1,1]
	s_waitcnt vmcnt(22)
	v_lshlrev_b32_e32 v34, 16, v108
	v_and_b32_e32 v35, 0xffff0000, v108
	v_pk_fma_f32 v[20:21], v[2:3], v[34:35], v[20:21] op_sel_hi:[0,1,1]
	s_waitcnt vmcnt(21)
	v_lshlrev_b32_e32 v34, 16, v113
	v_and_b32_e32 v35, 0xffff0000, v113
	v_pk_fma_f32 v[22:23], v[2:3], v[34:35], v[22:23] op_sel_hi:[0,1,1]
	s_waitcnt vmcnt(20)
	v_lshlrev_b32_e32 v34, 16, v119
	v_and_b32_e32 v35, 0xffff0000, v119
	v_pk_fma_f32 v[24:25], v[2:3], v[34:35], v[24:25] op_sel_hi:[0,1,1]
	s_waitcnt vmcnt(19)
	v_lshlrev_b32_e32 v34, 16, v125
	v_and_b32_e32 v35, 0xffff0000, v125
	v_pk_fma_f32 v[26:27], v[2:3], v[34:35], v[26:27] op_sel_hi:[0,1,1]
	s_waitcnt vmcnt(18)
	v_lshlrev_b32_e32 v34, 16, v132
	v_and_b32_e32 v35, 0xffff0000, v132
	v_pk_fma_f32 v[28:29], v[2:3], v[34:35], v[28:29] op_sel_hi:[0,1,1]
	s_waitcnt vmcnt(17)
	v_lshlrev_b32_e32 v34, 16, v139
	v_and_b32_e32 v35, 0xffff0000, v139
	v_pk_fma_f32 v[30:31], v[2:3], v[34:35], v[30:31] op_sel_hi:[0,1,1]
	s_waitcnt vmcnt(16)
	v_lshlrev_b32_e32 v34, 16, v172
	v_and_b32_e32 v35, 0xffff0000, v172
	v_pk_fma_f32 v[32:33], v[2:3], v[34:35], v[32:33] op_sel_hi:[0,1,1]
	s_cbranch_scc1 .LBB0_882
	ds_write2st64_b64 v92, v[18:19], v[20:21] offset0:88 offset1:89
	ds_write2st64_b64 v92, v[22:23], v[24:25] offset0:90 offset1:91
	ds_write2st64_b64 v92, v[26:27], v[28:29] offset0:92 offset1:93
	ds_write2st64_b64 v92, v[30:31], v[32:33] offset0:94 offset1:95
	s_waitcnt lgkmcnt(0)
	s_barrier
	ds_read2st64_b64 v[34:37], v92 offset0:80 offset1:81
	s_cmp_gt_u32 s10, 7
	s_cselect_b64 s[44:45], -1, 0
	s_max_i32 s16, s10, 8
	s_min_i32 s10, s10, 0x78
	s_waitcnt lgkmcnt(0)
	v_pk_add_f32 v[34:35], v[34:35], 0 op_sel_hi:[1,0]
	s_sub_i32 s10, s10, s16
	v_pk_add_f32 v[38:39], v[34:35], v[36:37]
	ds_read2st64_b64 v[34:37], v92 offset0:82 offset1:83
	s_add_i32 s10, s10, 16
	v_cvt_f32_i32_e32 v40, s10
	v_cndmask_b32_e64 v2, 0, 1.0, s[44:45]
	s_waitcnt lgkmcnt(0)
	v_pk_add_f32 v[34:35], v[38:39], v[34:35]
	s_nop 0
	v_pk_add_f32 v[38:39], v[34:35], v[36:37]
	ds_read2st64_b64 v[34:37], v92 offset0:84 offset1:85
	s_waitcnt lgkmcnt(0)
	v_pk_add_f32 v[34:35], v[38:39], v[34:35]
	s_nop 0
	v_pk_add_f32 v[38:39], v[34:35], v[36:37]
	ds_read2st64_b64 v[34:37], v92 offset0:86 offset1:87
	s_waitcnt lgkmcnt(0)
	v_pk_add_f32 v[34:35], v[38:39], v[34:35]
	s_nop 0
	v_pk_add_f32 v[38:39], v[34:35], v[36:37]
	ds_read2st64_b64 v[34:37], v92 offset0:88 offset1:89
	s_waitcnt lgkmcnt(0)
	v_pk_add_f32 v[34:35], v[38:39], v[34:35]
	s_nop 0
	v_pk_add_f32 v[38:39], v[34:35], v[36:37]
	ds_read2st64_b64 v[34:37], v92 offset0:90 offset1:91
	s_waitcnt lgkmcnt(0)
	v_pk_add_f32 v[34:35], v[38:39], v[34:35]
	s_nop 0
	v_pk_add_f32 v[38:39], v[34:35], v[36:37]
	ds_read2st64_b64 v[34:37], v92 offset0:92 offset1:93
	s_waitcnt lgkmcnt(0)
	v_pk_add_f32 v[34:35], v[38:39], v[34:35]
	s_nop 0
	v_pk_add_f32 v[38:39], v[34:35], v[36:37]
	ds_read2st64_b64 v[34:37], v92 offset0:94 offset1:95
	s_waitcnt lgkmcnt(0)
	v_pk_add_f32 v[34:35], v[38:39], v[34:35]
	s_nop 0
	v_pk_add_f32 v[38:39], v[34:35], v[36:37]
	v_div_scale_f32 v34, s[44:45], v40, v40, 1.0
	v_rcp_f32_e32 v35, v34
	s_nop 0
	v_fma_f32 v36, -v34, v35, 1.0
	v_fmac_f32_e32 v35, v36, v35
	v_div_scale_f32 v36, vcc, 1.0, v40, 1.0
	v_mul_f32_e32 v37, v36, v35
	v_fma_f32 v41, -v34, v37, v36
	v_fmac_f32_e32 v37, v41, v35
	v_fma_f32 v34, -v34, v37, v36
	v_div_fmas_f32 v34, v34, v35, v37
	v_div_fixup_f32 v40, v34, v40, 1.0
	v_mul_f32_e32 v34, v74, v40
	v_lshlrev_b32_e32 v35, 16, v140
	v_and_b32_e32 v36, 0xffff0000, v140
	v_fma_f32 v35, v34, v38, -v35
	v_fma_f32 v34, v34, v39, -v36
	v_cvt_pk_bf16_f32 v36, v35, v34
	v_add_co_u32_e32 v34, vcc, s72, v16
	s_nop 1
	v_addc_co_u32_e32 v35, vcc, -1, v17, vcc
	global_store_dword v[34:35], v36, off
	ds_read2st64_b64 v[34:37], v92 offset0:80 offset1:96
	s_waitcnt lgkmcnt(0)
	v_pk_add_f32 v[34:35], v[36:37], v[34:35] neg_lo:[0,1] neg_hi:[0,1]
	s_nop 0
	v_pk_add_f32 v[38:39], v[38:39], v[34:35]
	v_mul_f32_e32 v34, v75, v40
	v_lshlrev_b32_e32 v35, 16, v149
	v_and_b32_e32 v36, 0xffff0000, v149
	v_fma_f32 v35, v34, v38, -v35
	v_fma_f32 v34, v34, v39, -v36
	v_cvt_pk_bf16_f32 v36, v35, v34
	v_add_co_u32_e32 v34, vcc, s73, v16
	s_nop 1
	v_addc_co_u32_e32 v35, vcc, -1, v17, vcc
	global_store_dword v[34:35], v36, off
	ds_read2st64_b64 v[34:37], v92 offset0:81 offset1:97
	s_waitcnt lgkmcnt(0)
; #define GAS __attribute__((address_space(1)))
; __device__ __forceinline__ unsigned cvt_pk_bf16(float lo, float hi) { unsigned r; asm volatile("v_cvt_pk_bf16_f32 %0, %1, %2" : "=v"(r) : "v"(lo), "v"(hi)); return r; }
; __device__ __forceinline__ float bf_lo(unsigned w) { return __uint_as_float(w << 16); }
; __device__ __forceinline__ float bf_hi(unsigned w) { return __uint_as_float(w & 0xffff0000u); }
; template <int W>
; __device__ __forceinline__ void pool_item(const Ctx& F, const bf16* Ub, bf16* Db, int r0, int nr) {
;     ...
;                     for (int j = 0; j < 8; ++j) {
;                         const float ic = icr * icc[j]; const unsigned m = ring[(u + NS - HW + 1) % NS][j];
;                         *(GAS unsigned*)(Db + ((size_t)r * 64 + c0 + j) * EI) = cvt_pk_bf16(h.x * ic - bf_lo(m), h.y * ic - bf_hi(m));
;                         h += row[(c0 + j + HW) * 64] - row[(c0 + j - HW) * 64];
;                     }
; #pragma unroll
;                     for (int j = 0; j < 8; ++j) { const unsigned l = ring[(u + NS - W + 1) % NS][j]; Vv[j].x -= ml * bf_lo(l); Vv[j].y -= ml * bf_hi(l); }
	v_pk_add_f32 v[34:35], v[36:37], v[34:35] neg_lo:[0,1] neg_hi:[0,1]
	s_nop 0
	v_pk_add_f32 v[38:39], v[38:39], v[34:35]
	v_mul_f32_e32 v34, v76, v40
	v_lshlrev_b32_e32 v35, 16, v158
	v_and_b32_e32 v36, 0xffff0000, v158
	v_fma_f32 v35, v34, v38, -v35
	v_fma_f32 v34, v34, v39, -v36
	v_cvt_pk_bf16_f32 v36, v35, v34
	v_add_co_u32_e32 v34, vcc, s74, v16
	s_nop 1
	v_addc_co_u32_e32 v35, vcc, -1, v17, vcc
	global_store_dword v[34:35], v36, off
	ds_read2st64_b64 v[34:37], v92 offset0:82 offset1:98
	s_waitcnt lgkmcnt(0)
	v_pk_add_f32 v[34:35], v[36:37], v[34:35] neg_lo:[0,1] neg_hi:[0,1]
	s_nop 0
	v_pk_add_f32 v[38:39], v[38:39], v[34:35]
	v_mul_f32_e32 v34, v77, v40
	v_lshlrev_b32_e32 v35, 16, v166
	v_and_b32_e32 v36, 0xffff0000, v166
	v_fma_f32 v35, v34, v38, -v35
	v_fma_f32 v34, v34, v39, -v36
	v_cvt_pk_bf16_f32 v36, v35, v34
	v_add_co_u32_e32 v34, vcc, s75, v16
	s_nop 1
	v_addc_co_u32_e32 v35, vcc, -1, v17, vcc
	global_store_dword v[34:35], v36, off
	ds_read2st64_b64 v[34:37], v92 offset0:83 offset1:99
	s_waitcnt lgkmcnt(0)
	v_pk_add_f32 v[34:35], v[36:37], v[34:35] neg_lo:[0,1] neg_hi:[0,1]
	s_nop 0
	v_pk_add_f32 v[38:39], v[38:39], v[34:35]
	v_mul_f32_e32 v34, v78, v40
	v_lshlrev_b32_e32 v35, 16, v175
	v_and_b32_e32 v36, 0xffff0000, v175
	v_fma_f32 v35, v34, v38, -v35
	v_fma_f32 v34, v34, v39, -v36
	v_cvt_pk_bf16_f32 v36, v35, v34
	v_add_co_u32_e32 v34, vcc, s76, v16
	s_nop 1
	v_addc_co_u32_e32 v35, vcc, -1, v17, vcc
	global_store_dword v[34:35], v36, off
	ds_read2st64_b64 v[34:37], v92 offset0:84 offset1:100
	s_waitcnt lgkmcnt(0)
	v_pk_add_f32 v[34:35], v[36:37], v[34:35] neg_lo:[0,1] neg_hi:[0,1]
	s_nop 0
	v_pk_add_f32 v[38:39], v[38:39], v[34:35]
	v_mul_f32_e32 v34, v79, v40
	v_lshlrev_b32_e32 v35, 16, v185
	v_and_b32_e32 v36, 0xffff0000, v185
	v_fma_f32 v35, v34, v38, -v35
	v_fma_f32 v34, v34, v39, -v36
	v_cvt_pk_bf16_f32 v36, v35, v34
	v_add_co_u32_e32 v34, vcc, s77, v16
	s_nop 1
	v_addc_co_u32_e32 v35, vcc, -1, v17, vcc
	global_store_dword v[34:35], v36, off
	ds_read2st64_b64 v[34:37], v92 offset0:85 offset1:101
	s_waitcnt lgkmcnt(0)
	v_pk_add_f32 v[34:35], v[36:37], v[34:35] neg_lo:[0,1] neg_hi:[0,1]
	s_nop 0
	v_pk_add_f32 v[38:39], v[38:39], v[34:35]
	v_mul_f32_e32 v34, v80, v40
	v_lshlrev_b32_e32 v35, 16, v196
	v_and_b32_e32 v36, 0xffff0000, v196
	v_fma_f32 v35, v34, v38, -v35
	v_fma_f32 v34, v34, v39, -v36
	v_cvt_pk_bf16_f32 v36, v35, v34
	v_add_co_u32_e32 v34, vcc, s78, v16
	s_nop 1
	v_addc_co_u32_e32 v35, vcc, -1, v17, vcc
	global_store_dword v[34:35], v36, off
	ds_read2st64_b64 v[34:37], v92 offset0:86 offset1:102
	s_waitcnt lgkmcnt(0)
	v_pk_add_f32 v[34:35], v[36:37], v[34:35] neg_lo:[0,1] neg_hi:[0,1]
	s_nop 0
	v_pk_add_f32 v[34:35], v[38:39], v[34:35]
	v_mul_f32_e32 v36, v81, v40
	v_lshlrev_b32_e32 v37, 16, v216
	v_fma_f32 v34, v36, v34, -v37
	v_and_b32_e32 v37, 0xffff0000, v216
	v_fma_f32 v35, v36, v35, -v37
	v_cvt_pk_bf16_f32 v36, v34, v35
	v_add_co_u32_e32 v34, vcc, s79, v16
	s_nop 1
	v_addc_co_u32_e32 v35, vcc, -1, v17, vcc
	global_store_dword v[34:35], v36, off
	v_lshlrev_b32_e32 v34, 16, v97
	v_and_b32_e32 v35, 0xffff0000, v97
	v_pk_fma_f32 v[18:19], v[2:3], v[34:35], v[18:19] op_sel_hi:[0,1,1] neg_lo:[1,0,0] neg_hi:[1,0,0]
	v_lshlrev_b32_e32 v34, 16, v98
	v_and_b32_e32 v35, 0xffff0000, v98
	v_pk_fma_f32 v[20:21], v[2:3], v[34:35], v[20:21] op_sel_hi:[0,1,1] neg_lo:[1,0,0] neg_hi:[1,0,0]
	v_lshlrev_b32_e32 v34, 16, v99
	v_and_b32_e32 v35, 0xffff0000, v99
	v_pk_fma_f32 v[22:23], v[2:3], v[34:35], v[22:23] op_sel_hi:[0,1,1] neg_lo:[1,0,0] neg_hi:[1,0,0]
	v_lshlrev_b32_e32 v34, 16, v100
	v_and_b32_e32 v35, 0xffff0000, v100
	v_pk_fma_f32 v[24:25], v[2:3], v[34:35], v[24:25] op_sel_hi:[0,1,1] neg_lo:[1,0,0] neg_hi:[1,0,0]
	v_lshlrev_b32_e32 v34, 16, v104
	v_and_b32_e32 v35, 0xffff0000, v104
	v_pk_fma_f32 v[26:27], v[2:3], v[34:35], v[26:27] op_sel_hi:[0,1,1] neg_lo:[1,0,0] neg_hi:[1,0,0]
	v_lshlrev_b32_e32 v34, 16, v109
	v_and_b32_e32 v35, 0xffff0000, v109
	v_pk_fma_f32 v[28:29], v[2:3], v[34:35], v[28:29] op_sel_hi:[0,1,1] neg_lo:[1,0,0] neg_hi:[1,0,0]
	v_lshlrev_b32_e32 v34, 16, v114
	v_and_b32_e32 v35, 0xffff0000, v114
	v_pk_fma_f32 v[30:31], v[2:3], v[34:35], v[30:31] op_sel_hi:[0,1,1] neg_lo:[1,0,0] neg_hi:[1,0,0]
	v_lshlrev_b32_e32 v34, 16, v141
	v_and_b32_e32 v35, 0xffff0000, v141
	v_pk_fma_f32 v[32:33], v[2:3], v[34:35], v[32:33] op_sel_hi:[0,1,1] neg_lo:[1,0,0] neg_hi:[1,0,0]
; #define GAS __attribute__((address_space(1)))
; #define LAS __attribute__((address_space(3)))
; __device__ __forceinline__ unsigned cvt_pk_bf16(float lo, float hi) { unsigned r; asm volatile("v_cvt_pk_bf16_f32 %0, %1, %2" : "=v"(r) : "v"(lo), "v"(hi)); return r; }
; __device__ __forceinline__ float bf_lo(unsigned w) { return __uint_as_float(w << 16); }
; __device__ __forceinline__ float bf_hi(unsigned w) { return __uint_as_float(w & 0xffff0000u); }
; template <int W>
; __device__ __forceinline__ void pool_item(const Ctx& F, const bf16* Ub, bf16* Db, int r0, int nr) {
;     ...
;     POOL_LOAD(0, rs); POOL_LOAD(1, rs + 1);
;     __syncthreads();
;     for (int base = rs; base < re; base += NS) {
; #pragma unroll
;         for (int u = 0; u < NS; ++u) {
;             const int r = base + u;
;             if (r < re) {
;                 POOL_LOAD((u + 2) % NS, r + 2);
;                 const int e = r + HW - 1;
;                 const float me = (e >= 0 && e < 128) ? 1.0f : 0.0f, ml = (r >= r0 && r - HW >= 0) ? 1.0f : 0.0f;
; #pragma unroll
;                 for (int j = 0; j < 8; ++j) { Vv[j].x += me * bf_lo(ring[u][j]); Vv[j].y += me * bf_hi(ring[u][j]); }
;                 if (r >= r0) {
;                     LAS f32x2* row = buf + ((r & 1) * 80 + 8) * 64 + lane;
; #pragma unroll
;                     for (int j = 0; j < 8; ++j) row[(c0 + j) * 64] = Vv[j];
;                     asm volatile("s_waitcnt lgkmcnt(0)" ::: "memory"); __builtin_amdgcn_s_barrier(); asm volatile("" ::: "memory");
;                     const int rlo = r - HW > 0 ? r - HW : 0, rhi = r + HW < 128 ? r + HW : 128; const float icr = 1.0f / (float)(rhi - rlo);
;                     f32x2 h = (f32x2){0.f, 0.f};
; #pragma unroll
;                     for (int c = -HW; c < HW; ++c) h += row[(c0 + c) * 64];
; #pragma unroll
;                     for (int j = 0; j < 8; ++j) {
;                         const float ic = icr * icc[j]; const unsigned m = ring[(u + NS - HW + 1) % NS][j];
;                         *(GAS unsigned*)(Db + ((size_t)r * 64 + c0 + j) * EI) = cvt_pk_bf16(h.x * ic - bf_lo(m), h.y * ic - bf_hi(m));
;                         h += row[(c0 + j + HW) * 64] - row[(c0 + j - HW) * 64];
;                     }
.LBB0_882:
	s_add_i32 s10, s42, 17
	s_cmp_ge_u32 s10, s46
	s_cbranch_scc1 .LBB0_831
	s_min_i32 s16, s10, 0x76
	s_add_i32 s16, s16, 9
	s_lshl_b64 s[44:45], s[16:17], 20
	v_lshl_add_u64 v[34:35], v[12:13], 0, s[44:45]
	v_add_co_u32_e32 v36, vcc, 0x4000, v34
	global_load_dword v97, v[34:35], off
	s_nop 0
	v_addc_co_u32_e32 v37, vcc, 0, v35, vcc
	global_load_dword v98, v[36:37], off
	v_add_co_u32_e32 v36, vcc, 0x8000, v34
	s_add_i32 s16, s42, 24
	s_nop 0
	v_addc_co_u32_e32 v37, vcc, 0, v35, vcc
	global_load_dword v99, v[36:37], off
	v_add_co_u32_e32 v36, vcc, 0xc000, v34
	s_cmpk_lt_u32 s16, 0x80
	s_nop 0
	v_addc_co_u32_e32 v37, vcc, 0, v35, vcc
	global_load_dword v100, v[36:37], off
	v_add_co_u32_e32 v36, vcc, 0x10000, v34
	s_cselect_b64 s[44:45], -1, 0
	s_nop 0
	v_addc_co_u32_e32 v37, vcc, 0, v35, vcc
	global_load_dword v104, v[36:37], off
	v_add_co_u32_e32 v36, vcc, 0x14000, v34
	v_cndmask_b32_e64 v2, 0, 1.0, s[44:45]
	s_nop 0
	v_addc_co_u32_e32 v37, vcc, 0, v35, vcc
	global_load_dword v109, v[36:37], off
	v_add_co_u32_e32 v36, vcc, 0x18000, v34
	s_cmp_lt_u32 s10, s62
	s_nop 0
	v_addc_co_u32_e32 v37, vcc, 0, v35, vcc
	v_add_co_u32_e32 v34, vcc, 0x1c000, v34
	global_load_dword v114, v[36:37], off
	s_nop 0
	v_addc_co_u32_e32 v35, vcc, 0, v35, vcc
	global_load_dword v141, v[34:35], off
	s_waitcnt vmcnt(23)
	v_lshlrev_b32_e32 v34, 16, v101
	v_and_b32_e32 v35, 0xffff0000, v101
	v_pk_fma_f32 v[18:19], v[2:3], v[34:35], v[18:19] op_sel_hi:[0,1,1]
	s_waitcnt vmcnt(22)
	v_lshlrev_b32_e32 v34, 16, v103
	v_and_b32_e32 v35, 0xffff0000, v103
	v_pk_fma_f32 v[20:21], v[2:3], v[34:35], v[20:21] op_sel_hi:[0,1,1]
	s_waitcnt vmcnt(21)
	v_lshlrev_b32_e32 v34, 16, v106
	v_and_b32_e32 v35, 0xffff0000, v106
	v_pk_fma_f32 v[22:23], v[2:3], v[34:35], v[22:23] op_sel_hi:[0,1,1]
	s_waitcnt vmcnt(20)
	v_lshlrev_b32_e32 v34, 16, v110
	v_and_b32_e32 v35, 0xffff0000, v110
	v_pk_fma_f32 v[24:25], v[2:3], v[34:35], v[24:25] op_sel_hi:[0,1,1]
	s_waitcnt vmcnt(19)
	v_lshlrev_b32_e32 v34, 16, v115
	v_and_b32_e32 v35, 0xffff0000, v115
	v_pk_fma_f32 v[26:27], v[2:3], v[34:35], v[26:27] op_sel_hi:[0,1,1]
	s_waitcnt vmcnt(18)
	v_lshlrev_b32_e32 v34, 16, v120
	v_and_b32_e32 v35, 0xffff0000, v120
	v_pk_fma_f32 v[28:29], v[2:3], v[34:35], v[28:29] op_sel_hi:[0,1,1]
	s_waitcnt vmcnt(17)
	v_lshlrev_b32_e32 v34, 16, v127
	v_and_b32_e32 v35, 0xffff0000, v127
	v_pk_fma_f32 v[30:31], v[2:3], v[34:35], v[30:31] op_sel_hi:[0,1,1]
	s_waitcnt vmcnt(16)
	v_lshlrev_b32_e32 v34, 16, v156
	v_and_b32_e32 v35, 0xffff0000, v156
	v_pk_fma_f32 v[32:33], v[2:3], v[34:35], v[32:33] op_sel_hi:[0,1,1]
	s_cbranch_scc1 .LBB0_831
	ds_write2st64_b64 v92, v[18:19], v[20:21] offset0:8 offset1:9
	ds_write2st64_b64 v92, v[22:23], v[24:25] offset0:10 offset1:11
	ds_write2st64_b64 v92, v[26:27], v[28:29] offset0:12 offset1:13
	ds_write2st64_b64 v92, v[30:31], v[32:33] offset0:14 offset1:15
	s_waitcnt lgkmcnt(0)
	s_barrier
	ds_read2st64_b64 v[34:37], v92 offset1:1
	s_cmp_gt_u32 s10, 7
	s_cselect_b64 s[44:45], -1, 0
	s_max_i32 s16, s10, 8
	s_min_i32 s10, s10, 0x78
	s_waitcnt lgkmcnt(0)
	v_pk_add_f32 v[34:35], v[34:35], 0 op_sel_hi:[1,0]
	s_sub_i32 s10, s10, s16
	v_pk_add_f32 v[38:39], v[34:35], v[36:37]
	ds_read2st64_b64 v[34:37], v92 offset0:2 offset1:3
	s_add_i32 s10, s10, 16
	v_cvt_f32_i32_e32 v40, s10
	v_cndmask_b32_e64 v2, 0, 1.0, s[44:45]
	s_waitcnt lgkmcnt(0)
	v_pk_add_f32 v[34:35], v[38:39], v[34:35]
	s_nop 0
	v_pk_add_f32 v[38:39], v[34:35], v[36:37]
	ds_read2st64_b64 v[34:37], v92 offset0:4 offset1:5
	s_waitcnt lgkmcnt(0)
	v_pk_add_f32 v[34:35], v[38:39], v[34:35]
	s_nop 0
	v_pk_add_f32 v[38:39], v[34:35], v[36:37]
	ds_read2st64_b64 v[34:37], v92 offset0:6 offset1:7
	s_waitcnt lgkmcnt(0)
	v_pk_add_f32 v[34:35], v[38:39], v[34:35]
	s_nop 0
	v_pk_add_f32 v[38:39], v[34:35], v[36:37]
	ds_read2st64_b64 v[34:37], v92 offset0:8 offset1:9
	s_waitcnt lgkmcnt(0)
	v_pk_add_f32 v[34:35], v[38:39], v[34:35]
	s_nop 0
	v_pk_add_f32 v[38:39], v[34:35], v[36:37]
	ds_read2st64_b64 v[34:37], v92 offset0:10 offset1:11
	s_waitcnt lgkmcnt(0)
	v_pk_add_f32 v[34:35], v[38:39], v[34:35]
	s_nop 0
	v_pk_add_f32 v[38:39], v[34:35], v[36:37]
	ds_read2st64_b64 v[34:37], v92 offset0:12 offset1:13
	s_waitcnt lgkmcnt(0)
	v_pk_add_f32 v[34:35], v[38:39], v[34:35]
	s_nop 0
	v_pk_add_f32 v[38:39], v[34:35], v[36:37]
	ds_read2st64_b64 v[34:37], v92 offset0:14 offset1:15
	s_waitcnt lgkmcnt(0)
	v_pk_add_f32 v[34:35], v[38:39], v[34:35]
	s_nop 0
	v_pk_add_f32 v[38:39], v[34:35], v[36:37]
	v_div_scale_f32 v34, s[44:45], v40, v40, 1.0
	v_rcp_f32_e32 v35, v34
	s_nop 0
	v_fma_f32 v36, -v34, v35, 1.0
	v_fmac_f32_e32 v35, v36, v35
	v_div_scale_f32 v36, vcc, 1.0, v40, 1.0
	v_mul_f32_e32 v37, v36, v35
	v_fma_f32 v41, -v34, v37, v36
	v_fmac_f32_e32 v37, v41, v35
	v_fma_f32 v34, -v34, v37, v36
	v_div_fmas_f32 v34, v34, v35, v37
	v_div_fixup_f32 v40, v34, v40, 1.0
	v_mul_f32_e32 v34, v74, v40
	v_lshlrev_b32_e32 v35, 16, v133
	v_and_b32_e32 v36, 0xffff0000, v133
	v_fma_f32 v35, v34, v38, -v35
	v_fma_f32 v34, v34, v39, -v36
	v_cvt_pk_bf16_f32 v36, v35, v34
	v_add_co_u32_e32 v34, vcc, s80, v16
	s_nop 1
	v_addc_co_u32_e32 v35, vcc, -1, v17, vcc
	global_store_dword v[34:35], v36, off
	ds_read2st64_b64 v[34:37], v92 offset1:16
	s_waitcnt lgkmcnt(0)
; #define GAS __attribute__((address_space(1)))
; __device__ __forceinline__ unsigned cvt_pk_bf16(float lo, float hi) { unsigned r; asm volatile("v_cvt_pk_bf16_f32 %0, %1, %2" : "=v"(r) : "v"(lo), "v"(hi)); return r; }
; __device__ __forceinline__ float bf_lo(unsigned w) { return __uint_as_float(w << 16); }
; __device__ __forceinline__ float bf_hi(unsigned w) { return __uint_as_float(w & 0xffff0000u); }
; template <int W>
; __device__ __forceinline__ void pool_item(const Ctx& F, const bf16* Ub, bf16* Db, int r0, int nr) {
;     ...
;                     for (int j = 0; j < 8; ++j) {
;                         const float ic = icr * icc[j]; const unsigned m = ring[(u + NS - HW + 1) % NS][j];
;                         *(GAS unsigned*)(Db + ((size_t)r * 64 + c0 + j) * EI) = cvt_pk_bf16(h.x * ic - bf_lo(m), h.y * ic - bf_hi(m));
;                         h += row[(c0 + j + HW) * 64] - row[(c0 + j - HW) * 64];
;                     }
; #pragma unroll
;                     for (int j = 0; j < 8; ++j) { const unsigned l = ring[(u + NS - W + 1) % NS][j]; Vv[j].x -= ml * bf_lo(l); Vv[j].y -= ml * bf_hi(l); }
	v_pk_add_f32 v[34:35], v[36:37], v[34:35] neg_lo:[0,1] neg_hi:[0,1]
	s_nop 0
	v_pk_add_f32 v[38:39], v[38:39], v[34:35]
	v_mul_f32_e32 v34, v75, v40
	v_lshlrev_b32_e32 v35, 16, v142
	v_and_b32_e32 v36, 0xffff0000, v142
	v_fma_f32 v35, v34, v38, -v35
	v_fma_f32 v34, v34, v39, -v36
	v_cvt_pk_bf16_f32 v36, v35, v34
	v_add_co_u32_e32 v34, vcc, s81, v16
	s_nop 1
	v_addc_co_u32_e32 v35, vcc, -1, v17, vcc
	global_store_dword v[34:35], v36, off
	ds_read2st64_b64 v[34:37], v92 offset0:1 offset1:17
	s_waitcnt lgkmcnt(0)
	v_pk_add_f32 v[34:35], v[36:37], v[34:35] neg_lo:[0,1] neg_hi:[0,1]
	s_nop 0
	v_pk_add_f32 v[38:39], v[38:39], v[34:35]
	v_mul_f32_e32 v34, v76, v40
	v_lshlrev_b32_e32 v35, 16, v150
	v_and_b32_e32 v36, 0xffff0000, v150
	v_fma_f32 v35, v34, v38, -v35
	v_fma_f32 v34, v34, v39, -v36
	v_cvt_pk_bf16_f32 v36, v35, v34
	v_add_co_u32_e32 v34, vcc, s82, v16
	s_nop 1
	v_addc_co_u32_e32 v35, vcc, -1, v17, vcc
	global_store_dword v[34:35], v36, off
	ds_read2st64_b64 v[34:37], v92 offset0:2 offset1:18
	s_waitcnt lgkmcnt(0)
	v_pk_add_f32 v[34:35], v[36:37], v[34:35] neg_lo:[0,1] neg_hi:[0,1]
	s_nop 0
	v_pk_add_f32 v[38:39], v[38:39], v[34:35]
	v_mul_f32_e32 v34, v77, v40
	v_lshlrev_b32_e32 v35, 16, v159
	v_and_b32_e32 v36, 0xffff0000, v159
	v_fma_f32 v35, v34, v38, -v35
	v_fma_f32 v34, v34, v39, -v36
	v_cvt_pk_bf16_f32 v36, v35, v34
	v_add_co_u32_e32 v34, vcc, s61, v16
	s_nop 1
	v_addc_co_u32_e32 v35, vcc, -1, v17, vcc
	global_store_dword v[34:35], v36, off
	ds_read2st64_b64 v[34:37], v92 offset0:3 offset1:19
	s_waitcnt lgkmcnt(0)
	v_pk_add_f32 v[34:35], v[36:37], v[34:35] neg_lo:[0,1] neg_hi:[0,1]
	s_nop 0
	v_pk_add_f32 v[38:39], v[38:39], v[34:35]
	v_mul_f32_e32 v34, v78, v40
	v_lshlrev_b32_e32 v35, 16, v167
	v_and_b32_e32 v36, 0xffff0000, v167
	v_fma_f32 v35, v34, v38, -v35
	v_fma_f32 v34, v34, v39, -v36
	v_cvt_pk_bf16_f32 v36, v35, v34
	v_add_co_u32_e32 v34, vcc, s83, v16
	s_nop 1
	v_addc_co_u32_e32 v35, vcc, -1, v17, vcc
	global_store_dword v[34:35], v36, off
	ds_read2st64_b64 v[34:37], v92 offset0:4 offset1:20
	s_waitcnt lgkmcnt(0)
	v_pk_add_f32 v[34:35], v[36:37], v[34:35] neg_lo:[0,1] neg_hi:[0,1]
	s_nop 0
	v_pk_add_f32 v[38:39], v[38:39], v[34:35]
	v_mul_f32_e32 v34, v79, v40
	v_lshlrev_b32_e32 v35, 16, v177
	v_and_b32_e32 v36, 0xffff0000, v177
	v_fma_f32 v35, v34, v38, -v35
	v_fma_f32 v34, v34, v39, -v36
	v_cvt_pk_bf16_f32 v36, v35, v34
	v_add_co_u32_e32 v34, vcc, s84, v16
	s_nop 1
	v_addc_co_u32_e32 v35, vcc, -1, v17, vcc
	global_store_dword v[34:35], v36, off
	ds_read2st64_b64 v[34:37], v92 offset0:5 offset1:21
	s_waitcnt lgkmcnt(0)
	v_pk_add_f32 v[34:35], v[36:37], v[34:35] neg_lo:[0,1] neg_hi:[0,1]
	s_nop 0
	v_pk_add_f32 v[38:39], v[38:39], v[34:35]
	v_mul_f32_e32 v34, v80, v40
	v_lshlrev_b32_e32 v35, 16, v189
	v_and_b32_e32 v36, 0xffff0000, v189
	v_fma_f32 v35, v34, v38, -v35
	v_fma_f32 v34, v34, v39, -v36
	v_cvt_pk_bf16_f32 v36, v35, v34
	v_add_co_u32_e32 v34, vcc, s85, v16
	s_nop 1
	v_addc_co_u32_e32 v35, vcc, -1, v17, vcc
	global_store_dword v[34:35], v36, off
	ds_read2st64_b64 v[34:37], v92 offset0:6 offset1:22
	s_waitcnt lgkmcnt(0)
	v_pk_add_f32 v[34:35], v[36:37], v[34:35] neg_lo:[0,1] neg_hi:[0,1]
	s_nop 0
	v_pk_add_f32 v[34:35], v[38:39], v[34:35]
	v_mul_f32_e32 v36, v81, v40
	v_lshlrev_b32_e32 v37, 16, v212
	v_fma_f32 v34, v36, v34, -v37
	v_and_b32_e32 v37, 0xffff0000, v212
	v_fma_f32 v35, v36, v35, -v37
	v_cvt_pk_bf16_f32 v34, v34, v35
	global_store_dword v[16:17], v34, off
	v_lshlrev_b32_e32 v34, 16, v233
	v_and_b32_e32 v35, 0xffff0000, v233
	v_pk_fma_f32 v[18:19], v[2:3], v[34:35], v[18:19] op_sel_hi:[0,1,1] neg_lo:[1,0,0] neg_hi:[1,0,0]
	v_lshlrev_b32_e32 v34, 16, v232
	v_and_b32_e32 v35, 0xffff0000, v232
	v_pk_fma_f32 v[20:21], v[2:3], v[34:35], v[20:21] op_sel_hi:[0,1,1] neg_lo:[1,0,0] neg_hi:[1,0,0]
	v_lshlrev_b32_e32 v34, 16, v231
	v_and_b32_e32 v35, 0xffff0000, v231
	v_pk_fma_f32 v[22:23], v[2:3], v[34:35], v[22:23] op_sel_hi:[0,1,1] neg_lo:[1,0,0] neg_hi:[1,0,0]
	v_lshlrev_b32_e32 v34, 16, v230
	v_and_b32_e32 v35, 0xffff0000, v230
	v_pk_fma_f32 v[24:25], v[2:3], v[34:35], v[24:25] op_sel_hi:[0,1,1] neg_lo:[1,0,0] neg_hi:[1,0,0]
	v_lshlrev_b32_e32 v34, 16, v229
	v_and_b32_e32 v35, 0xffff0000, v229
	v_pk_fma_f32 v[26:27], v[2:3], v[34:35], v[26:27] op_sel_hi:[0,1,1] neg_lo:[1,0,0] neg_hi:[1,0,0]
	v_lshlrev_b32_e32 v34, 16, v228
	v_and_b32_e32 v35, 0xffff0000, v228
	v_pk_fma_f32 v[28:29], v[2:3], v[34:35], v[28:29] op_sel_hi:[0,1,1] neg_lo:[1,0,0] neg_hi:[1,0,0]
	v_lshlrev_b32_e32 v34, 16, v227
	v_and_b32_e32 v35, 0xffff0000, v227
	v_pk_fma_f32 v[30:31], v[2:3], v[34:35], v[30:31] op_sel_hi:[0,1,1] neg_lo:[1,0,0] neg_hi:[1,0,0]
	v_lshlrev_b32_e32 v34, 16, v226
	v_and_b32_e32 v35, 0xffff0000, v226
	v_pk_fma_f32 v[32:33], v[2:3], v[34:35], v[32:33] op_sel_hi:[0,1,1] neg_lo:[1,0,0] neg_hi:[1,0,0]
	s_branch .LBB0_831

; #define GAS __attribute__((address_space(1)))
; #define LAS __attribute__((address_space(3)))
; __device__ __forceinline__ unsigned cvt_pk_bf16(float lo, float hi) { unsigned r; asm volatile("v_cvt_pk_bf16_f32 %0, %1, %2" : "=v"(r) : "v"(lo), "v"(hi)); return r; }
; __device__ __forceinline__ float bf_lo(unsigned w) { return __uint_as_float(w << 16); }
; __device__ __forceinline__ float bf_hi(unsigned w) { return __uint_as_float(w & 0xffff0000u); }
; template <int W>
; __device__ __forceinline__ void pool_item(const Ctx& F, const bf16* Ub, bf16* Db, int r0, int nr) {
;     ...
;     POOL_LOAD(0, rs); POOL_LOAD(1, rs + 1);
;     __syncthreads();
;     for (int base = rs; base < re; base += NS) {
; #pragma unroll
;         for (int u = 0; u < NS; ++u) {
;             const int r = base + u;
;             if (r < re) {
;                 POOL_LOAD((u + 2) % NS, r + 2);
;                 const int e = r + HW - 1;
;                 const float me = (e >= 0 && e < 128) ? 1.0f : 0.0f, ml = (r >= r0 && r - HW >= 0) ? 1.0f : 0.0f;
; #pragma unroll
;                 for (int j = 0; j < 8; ++j) { Vv[j].x += me * bf_lo(ring[u][j]); Vv[j].y += me * bf_hi(ring[u][j]); }
;                 if (r >= r0) {
;                     LAS f32x2* row = buf + ((r & 1) * 80 + 8) * 64 + lane;
; #pragma unroll
;                     for (int j = 0; j < 8; ++j) row[(c0 + j) * 64] = Vv[j];
;                     asm volatile("s_waitcnt lgkmcnt(0)" ::: "memory"); __builtin_amdgcn_s_barrier(); asm volatile("" ::: "memory");
;                     const int rlo = r - HW > 0 ? r - HW : 0, rhi = r + HW < 128 ? r + HW : 128; const float icr = 1.0f / (float)(rhi - rlo);
;                     f32x2 h = (f32x2){0.f, 0.f};
; #pragma unroll
;                     for (int c = -HW; c < HW; ++c) h += row[(c0 + c) * 64];
; #pragma unroll
;                     for (int j = 0; j < 8; ++j) {
;                         const float ic = icr * icc[j]; const unsigned m = ring[(u + NS - HW + 1) % NS][j];
;                         *(GAS unsigned*)(Db + ((size_t)r * 64 + c0 + j) * EI) = cvt_pk_bf16(h.x * ic - bf_lo(m), h.y * ic - bf_hi(m));
;                         h += row[(c0 + j + HW) * 64] - row[(c0 + j - HW) * 64];
;                     }
.LBB0_892:
	v_med3_i32 v2, s42, -5, v94
	v_add_u32_e32 v2, 5, v2
	v_lshlrev_b64 v[34:35], 20, v[2:3]
	v_lshl_add_u64 v[34:35], v[12:13], 0, v[34:35]
	v_add_co_u32_e32 v36, vcc, s54, v34
	s_add_i32 s44, s42, 3
	s_nop 0
	v_addc_co_u32_e32 v37, vcc, 0, v35, vcc
	v_add_co_u32_e32 v38, vcc, s55, v34
	s_cmpk_lt_u32 s44, 0x80
	s_nop 0
	v_addc_co_u32_e32 v39, vcc, 0, v35, vcc
	v_add_co_u32_e32 v40, vcc, s56, v34
	s_cselect_b64 s[50:51], -1, 0
	s_nop 0
	v_addc_co_u32_e32 v41, vcc, 0, v35, vcc
	v_add_co_u32_e32 v42, vcc, s57, v34
	v_cndmask_b32_e64 v2, 0, 1.0, s[50:51]
	s_nop 0
	v_addc_co_u32_e32 v43, vcc, 0, v35, vcc
	v_add_co_u32_e32 v44, vcc, s58, v34
	s_cmp_lt_i32 s42, s62
	s_nop 0
	v_addc_co_u32_e32 v45, vcc, 0, v35, vcc
	v_add_co_u32_e32 v46, vcc, s59, v34
	s_nop 1
	v_addc_co_u32_e32 v47, vcc, 0, v35, vcc
	v_add_co_u32_e32 v48, vcc, s60, v34
	s_nop 1
	v_addc_co_u32_e32 v49, vcc, 0, v35, vcc
	global_load_dword v169, v[34:35], off
	global_load_dword v168, v[36:37], off
	global_load_dword v167, v[38:39], off
	global_load_dword v166, v[40:41], off
	global_load_dword v165, v[42:43], off
	global_load_dword v164, v[44:45], off
	global_load_dword v163, v[46:47], off
	global_load_dword v162, v[48:49], off
	s_waitcnt vmcnt(23)
	v_lshlrev_b32_e32 v34, 16, v53
	v_and_b32_e32 v35, 0xffff0000, v53
	s_waitcnt vmcnt(22)
	v_lshlrev_b32_e32 v36, 16, v54
	v_and_b32_e32 v37, 0xffff0000, v54
	s_waitcnt vmcnt(21)
	v_lshlrev_b32_e32 v38, 16, v55
	v_and_b32_e32 v39, 0xffff0000, v55
	s_waitcnt vmcnt(20)
	v_lshlrev_b32_e32 v40, 16, v56
	v_and_b32_e32 v41, 0xffff0000, v56
	s_waitcnt vmcnt(19)
	v_lshlrev_b32_e32 v42, 16, v57
	v_and_b32_e32 v43, 0xffff0000, v57
	s_waitcnt vmcnt(18)
	v_lshlrev_b32_e32 v44, 16, v95
	v_and_b32_e32 v45, 0xffff0000, v95
	s_waitcnt vmcnt(17)
	v_lshlrev_b32_e32 v46, 16, v96
	v_and_b32_e32 v47, 0xffff0000, v96
	s_waitcnt vmcnt(16)
	v_lshlrev_b32_e32 v48, 16, v102
	v_and_b32_e32 v49, 0xffff0000, v102
	v_pk_fma_f32 v[18:19], v[2:3], v[34:35], v[18:19] op_sel_hi:[0,1,1]
	v_pk_fma_f32 v[20:21], v[2:3], v[36:37], v[20:21] op_sel_hi:[0,1,1]
	v_pk_fma_f32 v[22:23], v[2:3], v[38:39], v[22:23] op_sel_hi:[0,1,1]
	v_pk_fma_f32 v[24:25], v[2:3], v[40:41], v[24:25] op_sel_hi:[0,1,1]
	v_pk_fma_f32 v[26:27], v[2:3], v[42:43], v[26:27] op_sel_hi:[0,1,1]
	v_pk_fma_f32 v[28:29], v[2:3], v[44:45], v[28:29] op_sel_hi:[0,1,1]
	v_pk_fma_f32 v[30:31], v[2:3], v[46:47], v[30:31] op_sel_hi:[0,1,1]
	v_pk_fma_f32 v[32:33], v[2:3], v[48:49], v[32:33] op_sel_hi:[0,1,1]
	s_cbranch_scc1 .LBB0_894
	ds_write2st64_b64 v92, v[18:19], v[20:21] offset0:88 offset1:89
	ds_write2st64_b64 v92, v[22:23], v[24:25] offset0:90 offset1:91
	ds_write2st64_b64 v92, v[26:27], v[28:29] offset0:92 offset1:93
	ds_write2st64_b64 v92, v[30:31], v[32:33] offset0:94 offset1:95
	s_waitcnt lgkmcnt(0)
	s_barrier
	ds_read2st64_b64 v[170:173], v92 offset0:84 offset1:85
	s_cmp_gt_i32 s42, 3
	s_cselect_b64 s[50:51], -1, 0
	s_max_i32 s10, s42, 4
	s_min_i32 s16, s42, 0x7c
	s_waitcnt lgkmcnt(0)
	v_pk_add_f32 v[50:51], v[170:171], 0 op_sel_hi:[1,0]
	s_sub_i32 s10, s16, s10
	v_pk_add_f32 v[50:51], v[50:51], v[172:173]
	ds_read2st64_b64 v[170:173], v92 offset0:86 offset1:87
	s_add_i32 s10, s10, 8
	v_cvt_f32_i32_e32 v176, s10
	v_cndmask_b32_e64 v2, 0, 1.0, s[50:51]
	s_mov_b32 s43, s17
	s_waitcnt lgkmcnt(0)
	v_pk_add_f32 v[50:51], v[50:51], v[170:171]
	s_nop 0
	v_pk_add_f32 v[50:51], v[50:51], v[172:173]
	ds_read2st64_b64 v[170:173], v92 offset0:88 offset1:89
	s_waitcnt lgkmcnt(0)
	v_pk_add_f32 v[50:51], v[50:51], v[170:171]
	s_nop 0
	v_pk_add_f32 v[50:51], v[50:51], v[172:173]
	ds_read2st64_b64 v[170:173], v92 offset0:90 offset1:91
	s_waitcnt lgkmcnt(0)
	v_pk_add_f32 v[50:51], v[50:51], v[170:171]
	s_nop 0
	v_pk_add_f32 v[174:175], v[50:51], v[172:173]
	v_div_scale_f32 v50, s[50:51], v176, v176, 1.0
	v_rcp_f32_e32 v51, v50
	s_lshl_b64 s[50:51], s[42:43], 20
	v_fma_f32 v170, -v50, v51, 1.0
	v_fmac_f32_e32 v51, v170, v51
	v_div_scale_f32 v170, vcc, 1.0, v176, 1.0
	v_mul_f32_e32 v171, v170, v51
	v_fma_f32 v172, -v50, v171, v170
	v_fmac_f32_e32 v171, v172, v51
	v_fma_f32 v50, -v50, v171, v170
	v_div_fmas_f32 v50, v50, v51, v171
	v_div_fixup_f32 v176, v50, v176, 1.0
	v_mul_f32_e32 v50, v58, v176
	v_lshlrev_b32_e32 v51, 16, v107
	v_and_b32_e32 v170, 0xffff0000, v107
	v_fma_f32 v51, v50, v174, -v51
	v_fma_f32 v50, v50, v175, -v170
	v_cvt_pk_bf16_f32 v170, v51, v50
	v_lshl_add_u64 v[50:51], v[14:15], 0, s[50:51]
	global_store_dword v[50:51], v170, off
	ds_read2st64_b64 v[170:173], v92 offset0:84 offset1:92
	s_waitcnt lgkmcnt(0)
	v_pk_add_f32 v[170:171], v[172:173], v[170:171] neg_lo:[0,1] neg_hi:[0,1]
	s_nop 0
	v_pk_add_f32 v[174:175], v[174:175], v[170:171]
	v_mul_f32_e32 v170, v59, v176
	v_lshlrev_b32_e32 v171, 16, v112
	v_and_b32_e32 v172, 0xffff0000, v112
	v_fma_f32 v171, v170, v174, -v171
	v_fma_f32 v170, v170, v175, -v172
	v_cvt_pk_bf16_f32 v172, v171, v170
	v_add_co_u32_e32 v170, vcc, s54, v50
	s_nop 1
	v_addc_co_u32_e32 v171, vcc, 0, v51, vcc
	global_store_dword v[170:171], v172, off
	ds_read2st64_b64 v[170:173], v92 offset0:85 offset1:93
	s_waitcnt lgkmcnt(0)
	v_pk_add_f32 v[170:171], v[172:173], v[170:171] neg_lo:[0,1] neg_hi:[0,1]
	s_nop 0
	v_pk_add_f32 v[174:175], v[174:175], v[170:171]
	v_mul_f32_e32 v170, v60, v176
	v_lshlrev_b32_e32 v171, 16, v118
	v_and_b32_e32 v172, 0xffff0000, v118
	v_fma_f32 v171, v170, v174, -v171
	v_fma_f32 v170, v170, v175, -v172
	v_cvt_pk_bf16_f32 v172, v171, v170
	v_add_co_u32_e32 v170, vcc, s55, v50
	s_nop 1
	v_addc_co_u32_e32 v171, vcc, 0, v51, vcc
	global_store_dword v[170:171], v172, off
	ds_read2st64_b64 v[170:173], v92 offset0:86 offset1:94
	s_waitcnt lgkmcnt(0)
; #define GAS __attribute__((address_space(1)))
; __device__ __forceinline__ unsigned cvt_pk_bf16(float lo, float hi) { unsigned r; asm volatile("v_cvt_pk_bf16_f32 %0, %1, %2" : "=v"(r) : "v"(lo), "v"(hi)); return r; }
; __device__ __forceinline__ float bf_lo(unsigned w) { return __uint_as_float(w << 16); }
; __device__ __forceinline__ float bf_hi(unsigned w) { return __uint_as_float(w & 0xffff0000u); }
; #define POOL_LOAD(slot_, r_) do { int e_ = (r_) + HW - 1; e_ = e_ < 0 ? 0 : (e_ > 127 ? 127 : e_); \
;         _Pragma("unroll") for (int j = 0; j < 8; ++j) ring[slot_][j] = *(const GAS unsigned*)(Ub + ((size_t)e_ * 64 + c0 + j) * EI); } while (0)
; template <int W>
; __device__ __forceinline__ void pool_item(const Ctx& F, const bf16* Ub, bf16* Db, int r0, int nr) {
;     ...
;     POOL_LOAD(0, rs); POOL_LOAD(1, rs + 1);
;     __syncthreads();
;     for (int base = rs; base < re; base += NS) {
; #pragma unroll
;         for (int u = 0; u < NS; ++u) {
;             const int r = base + u;
;             if (r < re) {
;                 POOL_LOAD((u + 2) % NS, r + 2);
;                 const int e = r + HW - 1;
;                 const float me = (e >= 0 && e < 128) ? 1.0f : 0.0f, ml = (r >= r0 && r - HW >= 0) ? 1.0f : 0.0f;
; #pragma unroll
;                 for (int j = 0; j < 8; ++j) { Vv[j].x += me * bf_lo(ring[u][j]); Vv[j].y += me * bf_hi(ring[u][j]); }
;     ...
;                     for (int j = 0; j < 8; ++j) {
;                         const float ic = icr * icc[j]; const unsigned m = ring[(u + NS - HW + 1) % NS][j];
;                         *(GAS unsigned*)(Db + ((size_t)r * 64 + c0 + j) * EI) = cvt_pk_bf16(h.x * ic - bf_lo(m), h.y * ic - bf_hi(m));
;                         h += row[(c0 + j + HW) * 64] - row[(c0 + j - HW) * 64];
;                     }
; #pragma unroll
;                     for (int j = 0; j < 8; ++j) { const unsigned l = ring[(u + NS - W + 1) % NS][j]; Vv[j].x -= ml * bf_lo(l); Vv[j].y -= ml * bf_hi(l); }
;                 }
	v_pk_add_f32 v[170:171], v[172:173], v[170:171] neg_lo:[0,1] neg_hi:[0,1]
	s_nop 0
	v_pk_add_f32 v[174:175], v[174:175], v[170:171]
	v_mul_f32_e32 v170, v61, v176
	v_lshlrev_b32_e32 v171, 16, v124
	v_and_b32_e32 v172, 0xffff0000, v124
	v_fma_f32 v171, v170, v174, -v171
	v_fma_f32 v170, v170, v175, -v172
	v_cvt_pk_bf16_f32 v172, v171, v170
	v_add_co_u32_e32 v170, vcc, s56, v50
	s_nop 1
	v_addc_co_u32_e32 v171, vcc, 0, v51, vcc
	global_store_dword v[170:171], v172, off
	ds_read2st64_b64 v[170:173], v92 offset0:87 offset1:95
	s_waitcnt lgkmcnt(0)
	v_pk_add_f32 v[170:171], v[172:173], v[170:171] neg_lo:[0,1] neg_hi:[0,1]
	s_nop 0
	v_pk_add_f32 v[174:175], v[174:175], v[170:171]
	v_mul_f32_e32 v170, v62, v176
	v_lshlrev_b32_e32 v171, 16, v131
	v_and_b32_e32 v172, 0xffff0000, v131
	v_fma_f32 v171, v170, v174, -v171
	v_fma_f32 v170, v170, v175, -v172
	v_cvt_pk_bf16_f32 v172, v171, v170
	v_add_co_u32_e32 v170, vcc, s57, v50
	s_nop 1
	v_addc_co_u32_e32 v171, vcc, 0, v51, vcc
	global_store_dword v[170:171], v172, off
	ds_read2st64_b64 v[170:173], v92 offset0:88 offset1:96
	s_waitcnt lgkmcnt(0)
	v_pk_add_f32 v[170:171], v[172:173], v[170:171] neg_lo:[0,1] neg_hi:[0,1]
	s_nop 0
	v_pk_add_f32 v[174:175], v[174:175], v[170:171]
	v_mul_f32_e32 v170, v63, v176
	v_lshlrev_b32_e32 v171, 16, v137
	v_and_b32_e32 v172, 0xffff0000, v137
	v_fma_f32 v171, v170, v174, -v171
	v_fma_f32 v170, v170, v175, -v172
	v_cvt_pk_bf16_f32 v172, v171, v170
	v_add_co_u32_e32 v170, vcc, s58, v50
	s_nop 1
	v_addc_co_u32_e32 v171, vcc, 0, v51, vcc
	global_store_dword v[170:171], v172, off
	ds_read2st64_b64 v[170:173], v92 offset0:89 offset1:97
	s_waitcnt lgkmcnt(0)
	v_pk_add_f32 v[170:171], v[172:173], v[170:171] neg_lo:[0,1] neg_hi:[0,1]
	s_nop 0
	v_pk_add_f32 v[174:175], v[174:175], v[170:171]
	v_mul_f32_e32 v170, v64, v176
	v_lshlrev_b32_e32 v171, 16, v144
	v_and_b32_e32 v172, 0xffff0000, v144
	v_fma_f32 v171, v170, v174, -v171
	v_fma_f32 v170, v170, v175, -v172
	v_cvt_pk_bf16_f32 v172, v171, v170
	v_add_co_u32_e32 v170, vcc, s59, v50
	s_nop 1
	v_addc_co_u32_e32 v171, vcc, 0, v51, vcc
	global_store_dword v[170:171], v172, off
	ds_read2st64_b64 v[170:173], v92 offset0:90 offset1:98
	v_add_co_u32_e32 v50, vcc, s60, v50
	s_waitcnt lgkmcnt(0)
	v_pk_add_f32 v[170:171], v[172:173], v[170:171] neg_lo:[0,1] neg_hi:[0,1]
	s_nop 0
	v_pk_add_f32 v[170:171], v[174:175], v[170:171]
	v_mul_f32_e32 v172, v65, v176
	v_lshlrev_b32_e32 v173, 16, v157
	v_fma_f32 v170, v172, v170, -v173
	v_and_b32_e32 v173, 0xffff0000, v157
	v_addc_co_u32_e32 v51, vcc, 0, v51, vcc
	v_fma_f32 v171, v172, v171, -v173
	v_cvt_pk_bf16_f32 v170, v170, v171
	global_store_dword v[50:51], v170, off
	v_lshlrev_b32_e32 v50, 16, v126
	v_and_b32_e32 v51, 0xffff0000, v126
	v_pk_fma_f32 v[18:19], v[2:3], v[50:51], v[18:19] op_sel_hi:[0,1,1] neg_lo:[1,0,0] neg_hi:[1,0,0]
	v_lshlrev_b32_e32 v50, 16, v132
	v_and_b32_e32 v51, 0xffff0000, v132
	v_pk_fma_f32 v[20:21], v[2:3], v[50:51], v[20:21] op_sel_hi:[0,1,1] neg_lo:[1,0,0] neg_hi:[1,0,0]
	v_lshlrev_b32_e32 v50, 16, v138
	v_and_b32_e32 v51, 0xffff0000, v138
	v_pk_fma_f32 v[22:23], v[2:3], v[50:51], v[22:23] op_sel_hi:[0,1,1] neg_lo:[1,0,0] neg_hi:[1,0,0]
	v_lshlrev_b32_e32 v50, 16, v145
	v_and_b32_e32 v51, 0xffff0000, v145
	v_pk_fma_f32 v[24:25], v[2:3], v[50:51], v[24:25] op_sel_hi:[0,1,1] neg_lo:[1,0,0] neg_hi:[1,0,0]
	v_lshlrev_b32_e32 v50, 16, v149
	v_and_b32_e32 v51, 0xffff0000, v149
	v_pk_fma_f32 v[26:27], v[2:3], v[50:51], v[26:27] op_sel_hi:[0,1,1] neg_lo:[1,0,0] neg_hi:[1,0,0]
	v_lshlrev_b32_e32 v50, 16, v153
	v_and_b32_e32 v51, 0xffff0000, v153
	v_pk_fma_f32 v[28:29], v[2:3], v[50:51], v[28:29] op_sel_hi:[0,1,1] neg_lo:[1,0,0] neg_hi:[1,0,0]
	v_lshlrev_b32_e32 v50, 16, v156
	v_and_b32_e32 v51, 0xffff0000, v156
	v_pk_fma_f32 v[30:31], v[2:3], v[50:51], v[30:31] op_sel_hi:[0,1,1] neg_lo:[1,0,0] neg_hi:[1,0,0]
	v_lshlrev_b32_e32 v50, 16, v161
	v_and_b32_e32 v51, 0xffff0000, v161
	v_pk_fma_f32 v[32:33], v[2:3], v[50:51], v[32:33] op_sel_hi:[0,1,1] neg_lo:[1,0,0] neg_hi:[1,0,0]
.LBB0_894:
	s_add_i32 s16, s42, 1
	s_cmp_ge_i32 s16, s46
	s_cbranch_scc1 .LBB0_897
	v_med3_i32 v2, s16, -5, v94
	v_add_u32_e32 v2, 5, v2
	v_lshlrev_b64 v[50:51], 20, v[2:3]
	v_lshl_add_u64 v[50:51], v[12:13], 0, v[50:51]
	v_add_co_u32_e32 v170, vcc, 0x4000, v50
	global_load_dword v126, v[50:51], off
	s_nop 0
	v_addc_co_u32_e32 v171, vcc, 0, v51, vcc
	global_load_dword v132, v[170:171], off
	v_add_co_u32_e32 v170, vcc, 0x8000, v50
	s_add_i32 s10, s42, 4
	s_nop 0
	v_addc_co_u32_e32 v171, vcc, 0, v51, vcc
	global_load_dword v138, v[170:171], off
	v_add_co_u32_e32 v170, vcc, 0xc000, v50
	s_cmpk_lt_u32 s10, 0x80
	s_nop 0
	v_addc_co_u32_e32 v171, vcc, 0, v51, vcc
	global_load_dword v145, v[170:171], off
	v_add_co_u32_e32 v170, vcc, 0x10000, v50
	s_cselect_b64 s[50:51], -1, 0
	s_nop 0
	v_addc_co_u32_e32 v171, vcc, 0, v51, vcc
	global_load_dword v149, v[170:171], off
	v_add_co_u32_e32 v170, vcc, 0x14000, v50
	v_cndmask_b32_e64 v2, 0, 1.0, s[50:51]
	s_nop 0
	v_addc_co_u32_e32 v171, vcc, 0, v51, vcc
	global_load_dword v153, v[170:171], off
	v_add_co_u32_e32 v170, vcc, 0x18000, v50
	s_cmp_lt_i32 s16, s62
	s_nop 0
	v_addc_co_u32_e32 v171, vcc, 0, v51, vcc
	v_add_co_u32_e32 v50, vcc, 0x1c000, v50
	global_load_dword v156, v[170:171], off
	s_nop 0
	v_addc_co_u32_e32 v51, vcc, 0, v51, vcc
	global_load_dword v161, v[50:51], off
	s_waitcnt vmcnt(16)
	v_lshlrev_b32_e32 v50, 16, v97
	v_and_b32_e32 v51, 0xffff0000, v97
	v_pk_fma_f32 v[18:19], v[2:3], v[50:51], v[18:19] op_sel_hi:[0,1,1]
	v_lshlrev_b32_e32 v50, 16, v98
	v_and_b32_e32 v51, 0xffff0000, v98
	v_pk_fma_f32 v[20:21], v[2:3], v[50:51], v[20:21] op_sel_hi:[0,1,1]
	v_lshlrev_b32_e32 v50, 16, v99
	v_and_b32_e32 v51, 0xffff0000, v99
	v_pk_fma_f32 v[22:23], v[2:3], v[50:51], v[22:23] op_sel_hi:[0,1,1]
	v_lshlrev_b32_e32 v50, 16, v100
	v_and_b32_e32 v51, 0xffff0000, v100
	v_pk_fma_f32 v[24:25], v[2:3], v[50:51], v[24:25] op_sel_hi:[0,1,1]
	v_lshlrev_b32_e32 v50, 16, v104
	v_and_b32_e32 v51, 0xffff0000, v104
	v_pk_fma_f32 v[26:27], v[2:3], v[50:51], v[26:27] op_sel_hi:[0,1,1]
	v_lshlrev_b32_e32 v50, 16, v109
	v_and_b32_e32 v51, 0xffff0000, v109
	v_pk_fma_f32 v[28:29], v[2:3], v[50:51], v[28:29] op_sel_hi:[0,1,1]
	v_lshlrev_b32_e32 v50, 16, v114
	v_and_b32_e32 v51, 0xffff0000, v114
	v_pk_fma_f32 v[30:31], v[2:3], v[50:51], v[30:31] op_sel_hi:[0,1,1]
	v_lshlrev_b32_e32 v50, 16, v140
	v_and_b32_e32 v51, 0xffff0000, v140
	v_pk_fma_f32 v[32:33], v[2:3], v[50:51], v[32:33] op_sel_hi:[0,1,1]
	s_cbranch_scc1 .LBB0_897
; #define GAS __attribute__((address_space(1)))
; #define LAS __attribute__((address_space(3)))
; __device__ __forceinline__ unsigned cvt_pk_bf16(float lo, float hi) { unsigned r; asm volatile("v_cvt_pk_bf16_f32 %0, %1, %2" : "=v"(r) : "v"(lo), "v"(hi)); return r; }
; __device__ __forceinline__ float bf_lo(unsigned w) { return __uint_as_float(w << 16); }
; __device__ __forceinline__ float bf_hi(unsigned w) { return __uint_as_float(w & 0xffff0000u); }
; template <int W>
; __device__ __forceinline__ void pool_item(const Ctx& F, const bf16* Ub, bf16* Db, int r0, int nr) {
;     ...
;                 if (r >= r0) {
;                     LAS f32x2* row = buf + ((r & 1) * 80 + 8) * 64 + lane;
; #pragma unroll
;                     for (int j = 0; j < 8; ++j) row[(c0 + j) * 64] = Vv[j];
;                     asm volatile("s_waitcnt lgkmcnt(0)" ::: "memory"); __builtin_amdgcn_s_barrier(); asm volatile("" ::: "memory");
;                     const int rlo = r - HW > 0 ? r - HW : 0, rhi = r + HW < 128 ? r + HW : 128; const float icr = 1.0f / (float)(rhi - rlo);
;                     f32x2 h = (f32x2){0.f, 0.f};
; #pragma unroll
;                     for (int c = -HW; c < HW; ++c) h += row[(c0 + c) * 64];
; #pragma unroll
;                     for (int j = 0; j < 8; ++j) {
;                         const float ic = icr * icc[j]; const unsigned m = ring[(u + NS - HW + 1) % NS][j];
;                         *(GAS unsigned*)(Db + ((size_t)r * 64 + c0 + j) * EI) = cvt_pk_bf16(h.x * ic - bf_lo(m), h.y * ic - bf_hi(m));
;                         h += row[(c0 + j + HW) * 64] - row[(c0 + j - HW) * 64];
;                     }
	ds_write2st64_b64 v92, v[18:19], v[20:21] offset0:8 offset1:9
	ds_write2st64_b64 v92, v[22:23], v[24:25] offset0:10 offset1:11
	ds_write2st64_b64 v92, v[26:27], v[28:29] offset0:12 offset1:13
	ds_write2st64_b64 v92, v[30:31], v[32:33] offset0:14 offset1:15
	s_waitcnt lgkmcnt(0)
	s_barrier
	ds_read2st64_b64 v[170:173], v92 offset0:4 offset1:5
	s_cmp_gt_i32 s42, 2
	s_cselect_b64 s[50:51], -1, 0
	s_max_i32 s10, s16, 4
	s_min_i32 s23, s16, 0x7c
	s_waitcnt lgkmcnt(0)
	v_pk_add_f32 v[50:51], v[170:171], 0 op_sel_hi:[1,0]
	s_sub_i32 s10, s23, s10
	v_pk_add_f32 v[50:51], v[50:51], v[172:173]
	ds_read2st64_b64 v[170:173], v92 offset0:6 offset1:7
	s_add_i32 s10, s10, 8
	v_cvt_f32_i32_e32 v176, s10
	v_cndmask_b32_e64 v2, 0, 1.0, s[50:51]
	s_waitcnt lgkmcnt(0)
	v_pk_add_f32 v[50:51], v[50:51], v[170:171]
	s_nop 0
	v_pk_add_f32 v[50:51], v[50:51], v[172:173]
	ds_read2st64_b64 v[170:173], v92 offset0:8 offset1:9
	s_waitcnt lgkmcnt(0)
	v_pk_add_f32 v[50:51], v[50:51], v[170:171]
	s_nop 0
	v_pk_add_f32 v[50:51], v[50:51], v[172:173]
	ds_read2st64_b64 v[170:173], v92 offset0:10 offset1:11
	s_waitcnt lgkmcnt(0)
	v_pk_add_f32 v[50:51], v[50:51], v[170:171]
	s_nop 0
	v_pk_add_f32 v[174:175], v[50:51], v[172:173]
	v_div_scale_f32 v50, s[50:51], v176, v176, 1.0
	v_rcp_f32_e32 v51, v50
	s_lshl_b64 s[50:51], s[16:17], 20
	v_fma_f32 v170, -v50, v51, 1.0
	v_fmac_f32_e32 v51, v170, v51
	v_div_scale_f32 v170, vcc, 1.0, v176, 1.0
	v_mul_f32_e32 v171, v170, v51
	v_fma_f32 v172, -v50, v171, v170
	v_fmac_f32_e32 v171, v172, v51
	v_fma_f32 v50, -v50, v171, v170
	v_div_fmas_f32 v50, v50, v51, v171
	v_div_fixup_f32 v176, v50, v176, 1.0
	v_mul_f32_e32 v50, v58, v176
	v_lshlrev_b32_e32 v51, 16, v105
	v_and_b32_e32 v170, 0xffff0000, v105
	v_fma_f32 v51, v50, v174, -v51
	v_fma_f32 v50, v50, v175, -v170
	v_cvt_pk_bf16_f32 v170, v51, v50
	v_lshl_add_u64 v[50:51], v[14:15], 0, s[50:51]
	global_store_dword v[50:51], v170, off
	ds_read2st64_b64 v[170:173], v92 offset0:4 offset1:12
	s_waitcnt lgkmcnt(0)
	v_pk_add_f32 v[170:171], v[172:173], v[170:171] neg_lo:[0,1] neg_hi:[0,1]
	s_nop 0
	v_pk_add_f32 v[174:175], v[174:175], v[170:171]
	v_mul_f32_e32 v170, v59, v176
	v_lshlrev_b32_e32 v171, 16, v108
	v_and_b32_e32 v172, 0xffff0000, v108
	v_fma_f32 v171, v170, v174, -v171
	v_fma_f32 v170, v170, v175, -v172
	v_cvt_pk_bf16_f32 v172, v171, v170
	v_add_co_u32_e32 v170, vcc, s54, v50
	s_nop 1
	v_addc_co_u32_e32 v171, vcc, 0, v51, vcc
	global_store_dword v[170:171], v172, off
	ds_read2st64_b64 v[170:173], v92 offset0:5 offset1:13
	s_waitcnt lgkmcnt(0)
	v_pk_add_f32 v[170:171], v[172:173], v[170:171] neg_lo:[0,1] neg_hi:[0,1]
	s_nop 0
	v_pk_add_f32 v[174:175], v[174:175], v[170:171]
	v_mul_f32_e32 v170, v60, v176
	v_lshlrev_b32_e32 v171, 16, v113
	v_and_b32_e32 v172, 0xffff0000, v113
	v_fma_f32 v171, v170, v174, -v171
	v_fma_f32 v170, v170, v175, -v172
	v_cvt_pk_bf16_f32 v172, v171, v170
	v_add_co_u32_e32 v170, vcc, s55, v50
	s_nop 1
	v_addc_co_u32_e32 v171, vcc, 0, v51, vcc
	global_store_dword v[170:171], v172, off
	ds_read2st64_b64 v[170:173], v92 offset0:6 offset1:14
	s_waitcnt lgkmcnt(0)
	v_pk_add_f32 v[170:171], v[172:173], v[170:171] neg_lo:[0,1] neg_hi:[0,1]
	s_nop 0
	v_pk_add_f32 v[174:175], v[174:175], v[170:171]
	v_mul_f32_e32 v170, v61, v176
	v_lshlrev_b32_e32 v171, 16, v119
	v_and_b32_e32 v172, 0xffff0000, v119
	v_fma_f32 v171, v170, v174, -v171
	v_fma_f32 v170, v170, v175, -v172
	v_cvt_pk_bf16_f32 v172, v171, v170
	v_add_co_u32_e32 v170, vcc, s56, v50
	s_nop 1
	v_addc_co_u32_e32 v171, vcc, 0, v51, vcc
	global_store_dword v[170:171], v172, off
	ds_read2st64_b64 v[170:173], v92 offset0:7 offset1:15
	s_waitcnt lgkmcnt(0)
	v_pk_add_f32 v[170:171], v[172:173], v[170:171] neg_lo:[0,1] neg_hi:[0,1]
	s_nop 0
	v_pk_add_f32 v[174:175], v[174:175], v[170:171]
	v_mul_f32_e32 v170, v62, v176
	v_lshlrev_b32_e32 v171, 16, v125
	v_and_b32_e32 v172, 0xffff0000, v125
	v_fma_f32 v171, v170, v174, -v171
	v_fma_f32 v170, v170, v175, -v172
	v_cvt_pk_bf16_f32 v172, v171, v170
	v_add_co_u32_e32 v170, vcc, s57, v50
	s_nop 1
	v_addc_co_u32_e32 v171, vcc, 0, v51, vcc
	global_store_dword v[170:171], v172, off
	ds_read2st64_b64 v[170:173], v92 offset0:8 offset1:16
	s_waitcnt lgkmcnt(0)
	v_pk_add_f32 v[170:171], v[172:173], v[170:171] neg_lo:[0,1] neg_hi:[0,1]
	s_nop 0
	v_pk_add_f32 v[174:175], v[174:175], v[170:171]
	v_mul_f32_e32 v170, v63, v176
	v_lshlrev_b32_e32 v171, 16, v133
	v_and_b32_e32 v172, 0xffff0000, v133
	v_fma_f32 v171, v170, v174, -v171
	v_fma_f32 v170, v170, v175, -v172
	v_cvt_pk_bf16_f32 v172, v171, v170
	v_add_co_u32_e32 v170, vcc, s58, v50
	s_nop 1
	v_addc_co_u32_e32 v171, vcc, 0, v51, vcc
	global_store_dword v[170:171], v172, off
	ds_read2st64_b64 v[170:173], v92 offset0:9 offset1:17
	s_waitcnt lgkmcnt(0)
	v_pk_add_f32 v[170:171], v[172:173], v[170:171] neg_lo:[0,1] neg_hi:[0,1]
	s_nop 0
	v_pk_add_f32 v[174:175], v[174:175], v[170:171]
	v_mul_f32_e32 v170, v64, v176
	v_lshlrev_b32_e32 v171, 16, v139
	v_and_b32_e32 v172, 0xffff0000, v139
	v_fma_f32 v171, v170, v174, -v171
	v_fma_f32 v170, v170, v175, -v172
	v_cvt_pk_bf16_f32 v172, v171, v170
	v_add_co_u32_e32 v170, vcc, s59, v50
	s_nop 1
	v_addc_co_u32_e32 v171, vcc, 0, v51, vcc
	global_store_dword v[170:171], v172, off
	ds_read2st64_b64 v[170:173], v92 offset0:10 offset1:18
	v_add_co_u32_e32 v50, vcc, s60, v50
	s_waitcnt lgkmcnt(0)
; #define GAS __attribute__((address_space(1)))
; #define LAS __attribute__((address_space(3)))
; __device__ __forceinline__ unsigned cvt_pk_bf16(float lo, float hi) { unsigned r; asm volatile("v_cvt_pk_bf16_f32 %0, %1, %2" : "=v"(r) : "v"(lo), "v"(hi)); return r; }
; __device__ __forceinline__ float bf_lo(unsigned w) { return __uint_as_float(w << 16); }
; template <int W>
; __device__ __forceinline__ void pool_item(const Ctx& F, const bf16* Ub, bf16* Db, int r0, int nr) {
;     ...
;     POOL_LOAD(0, rs); POOL_LOAD(1, rs + 1);
;     __syncthreads();
;     for (int base = rs; base < re; base += NS) {
; #pragma unroll
;         for (int u = 0; u < NS; ++u) {
;             const int r = base + u;
;             if (r < re) {
;                 POOL_LOAD((u + 2) % NS, r + 2);
;                 const int e = r + HW - 1;
;                 const float me = (e >= 0 && e < 128) ? 1.0f : 0.0f, ml = (r >= r0 && r - HW >= 0) ? 1.0f : 0.0f;
; #pragma unroll
;                 for (int j = 0; j < 8; ++j) { Vv[j].x += me * bf_lo(ring[u][j]); Vv[j].y += me * bf_hi(ring[u][j]); }
;                 if (r >= r0) {
;                     LAS f32x2* row = buf + ((r & 1) * 80 + 8) * 64 + lane;
; #pragma unroll
;                     for (int j = 0; j < 8; ++j) row[(c0 + j) * 64] = Vv[j];
;                     asm volatile("s_waitcnt lgkmcnt(0)" ::: "memory"); __builtin_amdgcn_s_barrier(); asm volatile("" ::: "memory");
;                     const int rlo = r - HW > 0 ? r - HW : 0, rhi = r + HW < 128 ? r + HW : 128; const float icr = 1.0f / (float)(rhi - rlo);
;                     f32x2 h = (f32x2){0.f, 0.f};
; #pragma unroll
;                     for (int c = -HW; c < HW; ++c) h += row[(c0 + c) * 64];
; #pragma unroll
;                     for (int j = 0; j < 8; ++j) {
;                         const float ic = icr * icc[j]; const unsigned m = ring[(u + NS - HW + 1) % NS][j];
;                         *(GAS unsigned*)(Db + ((size_t)r * 64 + c0 + j) * EI) = cvt_pk_bf16(h.x * ic - bf_lo(m), h.y * ic - bf_hi(m));
;                         h += row[(c0 + j + HW) * 64] - row[(c0 + j - HW) * 64];
;                     }
; #pragma unroll
;                     for (int j = 0; j < 8; ++j) { const unsigned l = ring[(u + NS - W + 1) % NS][j]; Vv[j].x -= ml * bf_lo(l); Vv[j].y -= ml * bf_hi(l); }
;                 }
	v_pk_add_f32 v[170:171], v[172:173], v[170:171] neg_lo:[0,1] neg_hi:[0,1]
	s_nop 0
	v_pk_add_f32 v[170:171], v[174:175], v[170:171]
	v_mul_f32_e32 v172, v65, v176
	v_lshlrev_b32_e32 v173, 16, v154
	v_fma_f32 v170, v172, v170, -v173
	v_and_b32_e32 v173, 0xffff0000, v154
	v_addc_co_u32_e32 v51, vcc, 0, v51, vcc
	v_fma_f32 v171, v172, v171, -v173
	v_cvt_pk_bf16_f32 v170, v170, v171
	global_store_dword v[50:51], v170, off
	v_lshlrev_b32_e32 v50, 16, v121
	v_and_b32_e32 v51, 0xffff0000, v121
	v_pk_fma_f32 v[18:19], v[2:3], v[50:51], v[18:19] op_sel_hi:[0,1,1] neg_lo:[1,0,0] neg_hi:[1,0,0]
	v_lshlrev_b32_e32 v50, 16, v128
	v_and_b32_e32 v51, 0xffff0000, v128
	v_pk_fma_f32 v[20:21], v[2:3], v[50:51], v[20:21] op_sel_hi:[0,1,1] neg_lo:[1,0,0] neg_hi:[1,0,0]
	v_lshlrev_b32_e32 v50, 16, v134
	v_and_b32_e32 v51, 0xffff0000, v134
	v_pk_fma_f32 v[22:23], v[2:3], v[50:51], v[22:23] op_sel_hi:[0,1,1] neg_lo:[1,0,0] neg_hi:[1,0,0]
	v_lshlrev_b32_e32 v50, 16, v141
	v_and_b32_e32 v51, 0xffff0000, v141
	v_pk_fma_f32 v[24:25], v[2:3], v[50:51], v[24:25] op_sel_hi:[0,1,1] neg_lo:[1,0,0] neg_hi:[1,0,0]
	v_lshlrev_b32_e32 v50, 16, v146
	v_and_b32_e32 v51, 0xffff0000, v146
	v_pk_fma_f32 v[26:27], v[2:3], v[50:51], v[26:27] op_sel_hi:[0,1,1] neg_lo:[1,0,0] neg_hi:[1,0,0]
	v_lshlrev_b32_e32 v50, 16, v151
	v_and_b32_e32 v51, 0xffff0000, v151
	v_pk_fma_f32 v[28:29], v[2:3], v[50:51], v[28:29] op_sel_hi:[0,1,1] neg_lo:[1,0,0] neg_hi:[1,0,0]
	v_lshlrev_b32_e32 v50, 16, v155
	v_and_b32_e32 v51, 0xffff0000, v155
	v_pk_fma_f32 v[30:31], v[2:3], v[50:51], v[30:31] op_sel_hi:[0,1,1] neg_lo:[1,0,0] neg_hi:[1,0,0]
	v_lshlrev_b32_e32 v50, 16, v160
	v_and_b32_e32 v51, 0xffff0000, v160
	v_pk_fma_f32 v[32:33], v[2:3], v[50:51], v[32:33] op_sel_hi:[0,1,1] neg_lo:[1,0,0] neg_hi:[1,0,0]
.LBB0_897:
	s_add_i32 s16, s42, 2
	s_cmp_ge_i32 s16, s46
	s_cbranch_scc1 .LBB0_900
	s_min_i32 s50, s16, 0x7a
	s_ashr_i32 s51, s50, 31
	s_lshl_b64 s[50:51], s[50:51], 20
	v_lshl_add_u64 v[50:51], v[12:13], 0, s[50:51]
	v_add_co_u32_e32 v170, vcc, 0x500000, v50
	s_add_i32 s10, s42, 5
	s_nop 0
	v_addc_co_u32_e32 v171, vcc, 0, v51, vcc
	global_load_dword v121, v[170:171], off
	v_add_co_u32_e32 v170, vcc, 0x504000, v50
	s_cmpk_lt_u32 s10, 0x80
	s_nop 0
	v_addc_co_u32_e32 v171, vcc, 0, v51, vcc
	global_load_dword v128, v[170:171], off
	v_add_co_u32_e32 v170, vcc, 0x508000, v50
	s_cselect_b64 s[50:51], -1, 0
	s_nop 0
	v_addc_co_u32_e32 v171, vcc, 0, v51, vcc
	global_load_dword v134, v[170:171], off
	v_add_co_u32_e32 v170, vcc, 0x50c000, v50
	v_cndmask_b32_e64 v2, 0, 1.0, s[50:51]
	s_nop 0
	v_addc_co_u32_e32 v171, vcc, 0, v51, vcc
	global_load_dword v141, v[170:171], off
	v_add_co_u32_e32 v170, vcc, 0x510000, v50
	s_cmp_lt_i32 s16, s62
	s_nop 0
	v_addc_co_u32_e32 v171, vcc, 0, v51, vcc
	global_load_dword v146, v[170:171], off
	v_add_co_u32_e32 v170, vcc, 0x514000, v50
	s_nop 1
	v_addc_co_u32_e32 v171, vcc, 0, v51, vcc
	global_load_dword v151, v[170:171], off
	v_add_co_u32_e32 v170, vcc, 0x518000, v50
	s_nop 1
	v_addc_co_u32_e32 v171, vcc, 0, v51, vcc
	v_add_co_u32_e32 v50, vcc, 0x51c000, v50
	global_load_dword v155, v[170:171], off
	s_nop 0
	v_addc_co_u32_e32 v51, vcc, 0, v51, vcc
	global_load_dword v160, v[50:51], off
	s_waitcnt vmcnt(23)
	v_lshlrev_b32_e32 v50, 16, v169
	v_and_b32_e32 v51, 0xffff0000, v169
	v_pk_fma_f32 v[18:19], v[2:3], v[50:51], v[18:19] op_sel_hi:[0,1,1]
	s_waitcnt vmcnt(22)
	v_lshlrev_b32_e32 v50, 16, v168
	v_and_b32_e32 v51, 0xffff0000, v168
	v_pk_fma_f32 v[20:21], v[2:3], v[50:51], v[20:21] op_sel_hi:[0,1,1]
	s_waitcnt vmcnt(21)
	v_lshlrev_b32_e32 v50, 16, v167
	v_and_b32_e32 v51, 0xffff0000, v167
	v_pk_fma_f32 v[22:23], v[2:3], v[50:51], v[22:23] op_sel_hi:[0,1,1]
	s_waitcnt vmcnt(20)
	v_lshlrev_b32_e32 v50, 16, v166
	v_and_b32_e32 v51, 0xffff0000, v166
	v_pk_fma_f32 v[24:25], v[2:3], v[50:51], v[24:25] op_sel_hi:[0,1,1]
	s_waitcnt vmcnt(19)
	v_lshlrev_b32_e32 v50, 16, v165
	v_and_b32_e32 v51, 0xffff0000, v165
	v_pk_fma_f32 v[26:27], v[2:3], v[50:51], v[26:27] op_sel_hi:[0,1,1]
	s_waitcnt vmcnt(18)
	v_lshlrev_b32_e32 v50, 16, v164
	v_and_b32_e32 v51, 0xffff0000, v164
	v_pk_fma_f32 v[28:29], v[2:3], v[50:51], v[28:29] op_sel_hi:[0,1,1]
	s_waitcnt vmcnt(17)
	v_lshlrev_b32_e32 v50, 16, v163
	v_and_b32_e32 v51, 0xffff0000, v163
	v_pk_fma_f32 v[30:31], v[2:3], v[50:51], v[30:31] op_sel_hi:[0,1,1]
	s_waitcnt vmcnt(16)
	v_lshlrev_b32_e32 v50, 16, v162
	v_and_b32_e32 v51, 0xffff0000, v162
	v_pk_fma_f32 v[32:33], v[2:3], v[50:51], v[32:33] op_sel_hi:[0,1,1]
	s_cbranch_scc1 .LBB0_900
	ds_write2st64_b64 v92, v[18:19], v[20:21] offset0:88 offset1:89
	ds_write2st64_b64 v92, v[22:23], v[24:25] offset0:90 offset1:91
	ds_write2st64_b64 v92, v[26:27], v[28:29] offset0:92 offset1:93
	ds_write2st64_b64 v92, v[30:31], v[32:33] offset0:94 offset1:95
	s_waitcnt lgkmcnt(0)
	s_barrier
; #define GAS __attribute__((address_space(1)))
; #define LAS __attribute__((address_space(3)))
; __device__ __forceinline__ unsigned cvt_pk_bf16(float lo, float hi) { unsigned r; asm volatile("v_cvt_pk_bf16_f32 %0, %1, %2" : "=v"(r) : "v"(lo), "v"(hi)); return r; }
; __device__ __forceinline__ float bf_lo(unsigned w) { return __uint_as_float(w << 16); }
; __device__ __forceinline__ float bf_hi(unsigned w) { return __uint_as_float(w & 0xffff0000u); }
; template <int W>
; __device__ __forceinline__ void pool_item(const Ctx& F, const bf16* Ub, bf16* Db, int r0, int nr) {
;     ...
;                 if (r >= r0) {
;                     LAS f32x2* row = buf + ((r & 1) * 80 + 8) * 64 + lane;
; #pragma unroll
;                     for (int j = 0; j < 8; ++j) row[(c0 + j) * 64] = Vv[j];
;                     asm volatile("s_waitcnt lgkmcnt(0)" ::: "memory"); __builtin_amdgcn_s_barrier(); asm volatile("" ::: "memory");
;                     const int rlo = r - HW > 0 ? r - HW : 0, rhi = r + HW < 128 ? r + HW : 128; const float icr = 1.0f / (float)(rhi - rlo);
;                     f32x2 h = (f32x2){0.f, 0.f};
; #pragma unroll
;                     for (int c = -HW; c < HW; ++c) h += row[(c0 + c) * 64];
; #pragma unroll
;                     for (int j = 0; j < 8; ++j) {
;                         const float ic = icr * icc[j]; const unsigned m = ring[(u + NS - HW + 1) % NS][j];
;                         *(GAS unsigned*)(Db + ((size_t)r * 64 + c0 + j) * EI) = cvt_pk_bf16(h.x * ic - bf_lo(m), h.y * ic - bf_hi(m));
;                         h += row[(c0 + j + HW) * 64] - row[(c0 + j - HW) * 64];
;                     }
; #pragma unroll
;                     for (int j = 0; j < 8; ++j) { const unsigned l = ring[(u + NS - W + 1) % NS][j]; Vv[j].x -= ml * bf_lo(l); Vv[j].y -= ml * bf_hi(l); }
;                 }
	ds_read2st64_b64 v[170:173], v92 offset0:84 offset1:85
	s_cmp_gt_i32 s42, 1
	s_cselect_b64 s[50:51], -1, 0
	s_max_i32 s10, s16, 4
	s_min_i32 s23, s16, 0x7c
	s_waitcnt lgkmcnt(0)
	v_pk_add_f32 v[50:51], v[170:171], 0 op_sel_hi:[1,0]
	s_sub_i32 s10, s23, s10
	v_pk_add_f32 v[50:51], v[50:51], v[172:173]
	ds_read2st64_b64 v[170:173], v92 offset0:86 offset1:87
	s_add_i32 s10, s10, 8
	v_cvt_f32_i32_e32 v176, s10
	v_cndmask_b32_e64 v2, 0, 1.0, s[50:51]
	s_waitcnt lgkmcnt(0)
	v_pk_add_f32 v[50:51], v[50:51], v[170:171]
	s_nop 0
	v_pk_add_f32 v[50:51], v[50:51], v[172:173]
	ds_read2st64_b64 v[170:173], v92 offset0:88 offset1:89
	s_waitcnt lgkmcnt(0)
	v_pk_add_f32 v[50:51], v[50:51], v[170:171]
	s_nop 0
	v_pk_add_f32 v[50:51], v[50:51], v[172:173]
	ds_read2st64_b64 v[170:173], v92 offset0:90 offset1:91
	s_waitcnt lgkmcnt(0)
	v_pk_add_f32 v[50:51], v[50:51], v[170:171]
	s_nop 0
	v_pk_add_f32 v[174:175], v[50:51], v[172:173]
	v_div_scale_f32 v50, s[50:51], v176, v176, 1.0
	v_rcp_f32_e32 v51, v50
	s_lshl_b64 s[50:51], s[16:17], 20
	v_fma_f32 v170, -v50, v51, 1.0
	v_fmac_f32_e32 v51, v170, v51
	v_div_scale_f32 v170, vcc, 1.0, v176, 1.0
	v_mul_f32_e32 v171, v170, v51
	v_fma_f32 v172, -v50, v171, v170
	v_fmac_f32_e32 v171, v172, v51
	v_fma_f32 v50, -v50, v171, v170
	v_div_fmas_f32 v50, v50, v51, v171
	v_div_fixup_f32 v176, v50, v176, 1.0
	v_mul_f32_e32 v50, v58, v176
	v_lshlrev_b32_e32 v51, 16, v101
	v_and_b32_e32 v170, 0xffff0000, v101
	v_fma_f32 v51, v50, v174, -v51
	v_fma_f32 v50, v50, v175, -v170
	v_cvt_pk_bf16_f32 v170, v51, v50
	v_lshl_add_u64 v[50:51], v[14:15], 0, s[50:51]
	global_store_dword v[50:51], v170, off
	ds_read2st64_b64 v[170:173], v92 offset0:84 offset1:92
	s_waitcnt lgkmcnt(0)
	v_pk_add_f32 v[170:171], v[172:173], v[170:171] neg_lo:[0,1] neg_hi:[0,1]
	s_nop 0
	v_pk_add_f32 v[174:175], v[174:175], v[170:171]
	v_mul_f32_e32 v170, v59, v176
	v_lshlrev_b32_e32 v171, 16, v103
	v_and_b32_e32 v172, 0xffff0000, v103
	v_fma_f32 v171, v170, v174, -v171
	v_fma_f32 v170, v170, v175, -v172
	v_cvt_pk_bf16_f32 v172, v171, v170
	v_add_co_u32_e32 v170, vcc, s54, v50
	s_nop 1
	v_addc_co_u32_e32 v171, vcc, 0, v51, vcc
	global_store_dword v[170:171], v172, off
	ds_read2st64_b64 v[170:173], v92 offset0:85 offset1:93
	s_waitcnt lgkmcnt(0)
	v_pk_add_f32 v[170:171], v[172:173], v[170:171] neg_lo:[0,1] neg_hi:[0,1]
	s_nop 0
	v_pk_add_f32 v[174:175], v[174:175], v[170:171]
	v_mul_f32_e32 v170, v60, v176
	v_lshlrev_b32_e32 v171, 16, v106
	v_and_b32_e32 v172, 0xffff0000, v106
	v_fma_f32 v171, v170, v174, -v171
	v_fma_f32 v170, v170, v175, -v172
	v_cvt_pk_bf16_f32 v172, v171, v170
	v_add_co_u32_e32 v170, vcc, s55, v50
	s_nop 1
	v_addc_co_u32_e32 v171, vcc, 0, v51, vcc
	global_store_dword v[170:171], v172, off
	ds_read2st64_b64 v[170:173], v92 offset0:86 offset1:94
	s_waitcnt lgkmcnt(0)
	v_pk_add_f32 v[170:171], v[172:173], v[170:171] neg_lo:[0,1] neg_hi:[0,1]
	s_nop 0
	v_pk_add_f32 v[174:175], v[174:175], v[170:171]
	v_mul_f32_e32 v170, v61, v176
	v_lshlrev_b32_e32 v171, 16, v110
	v_and_b32_e32 v172, 0xffff0000, v110
	v_fma_f32 v171, v170, v174, -v171
	v_fma_f32 v170, v170, v175, -v172
	v_cvt_pk_bf16_f32 v172, v171, v170
	v_add_co_u32_e32 v170, vcc, s56, v50
	s_nop 1
	v_addc_co_u32_e32 v171, vcc, 0, v51, vcc
	global_store_dword v[170:171], v172, off
	ds_read2st64_b64 v[170:173], v92 offset0:87 offset1:95
	s_waitcnt lgkmcnt(0)
	v_pk_add_f32 v[170:171], v[172:173], v[170:171] neg_lo:[0,1] neg_hi:[0,1]
	s_nop 0
	v_pk_add_f32 v[174:175], v[174:175], v[170:171]
	v_mul_f32_e32 v170, v62, v176
	v_lshlrev_b32_e32 v171, 16, v115
	v_and_b32_e32 v172, 0xffff0000, v115
	v_fma_f32 v171, v170, v174, -v171
	v_fma_f32 v170, v170, v175, -v172
	v_cvt_pk_bf16_f32 v172, v171, v170
	v_add_co_u32_e32 v170, vcc, s57, v50
	s_nop 1
	v_addc_co_u32_e32 v171, vcc, 0, v51, vcc
	global_store_dword v[170:171], v172, off
	ds_read2st64_b64 v[170:173], v92 offset0:88 offset1:96
	s_waitcnt lgkmcnt(0)
	v_pk_add_f32 v[170:171], v[172:173], v[170:171] neg_lo:[0,1] neg_hi:[0,1]
	s_nop 0
	v_pk_add_f32 v[174:175], v[174:175], v[170:171]
	v_mul_f32_e32 v170, v63, v176
	v_lshlrev_b32_e32 v171, 16, v120
	v_and_b32_e32 v172, 0xffff0000, v120
	v_fma_f32 v171, v170, v174, -v171
	v_fma_f32 v170, v170, v175, -v172
	v_cvt_pk_bf16_f32 v172, v171, v170
	v_add_co_u32_e32 v170, vcc, s58, v50
	s_nop 1
	v_addc_co_u32_e32 v171, vcc, 0, v51, vcc
	global_store_dword v[170:171], v172, off
	ds_read2st64_b64 v[170:173], v92 offset0:89 offset1:97
	s_waitcnt lgkmcnt(0)
	v_pk_add_f32 v[170:171], v[172:173], v[170:171] neg_lo:[0,1] neg_hi:[0,1]
	s_nop 0
	v_pk_add_f32 v[174:175], v[174:175], v[170:171]
	v_mul_f32_e32 v170, v64, v176
	v_lshlrev_b32_e32 v171, 16, v127
	v_and_b32_e32 v172, 0xffff0000, v127
	v_fma_f32 v171, v170, v174, -v171
	v_fma_f32 v170, v170, v175, -v172
	v_cvt_pk_bf16_f32 v172, v171, v170
	v_add_co_u32_e32 v170, vcc, s59, v50
	s_nop 1
	v_addc_co_u32_e32 v171, vcc, 0, v51, vcc
	global_store_dword v[170:171], v172, off
	ds_read2st64_b64 v[170:173], v92 offset0:90 offset1:98
	v_add_co_u32_e32 v50, vcc, s60, v50
	s_waitcnt lgkmcnt(0)
	v_pk_add_f32 v[170:171], v[172:173], v[170:171] neg_lo:[0,1] neg_hi:[0,1]
	s_nop 0
	v_pk_add_f32 v[170:171], v[174:175], v[170:171]
	v_mul_f32_e32 v172, v65, v176
	v_lshlrev_b32_e32 v173, 16, v150
	v_fma_f32 v170, v172, v170, -v173
	v_and_b32_e32 v173, 0xffff0000, v150
	v_addc_co_u32_e32 v51, vcc, 0, v51, vcc
	v_fma_f32 v171, v172, v171, -v173
	v_cvt_pk_bf16_f32 v170, v170, v171
	global_store_dword v[50:51], v170, off
	v_lshlrev_b32_e32 v50, 16, v116
	v_and_b32_e32 v51, 0xffff0000, v116
	v_pk_fma_f32 v[18:19], v[2:3], v[50:51], v[18:19] op_sel_hi:[0,1,1] neg_lo:[1,0,0] neg_hi:[1,0,0]
	v_lshlrev_b32_e32 v50, 16, v122
	v_and_b32_e32 v51, 0xffff0000, v122
	v_pk_fma_f32 v[20:21], v[2:3], v[50:51], v[20:21] op_sel_hi:[0,1,1] neg_lo:[1,0,0] neg_hi:[1,0,0]
	v_lshlrev_b32_e32 v50, 16, v129
	v_and_b32_e32 v51, 0xffff0000, v129
	v_pk_fma_f32 v[22:23], v[2:3], v[50:51], v[22:23] op_sel_hi:[0,1,1] neg_lo:[1,0,0] neg_hi:[1,0,0]
	v_lshlrev_b32_e32 v50, 16, v135
	v_and_b32_e32 v51, 0xffff0000, v135
	v_pk_fma_f32 v[24:25], v[2:3], v[50:51], v[24:25] op_sel_hi:[0,1,1] neg_lo:[1,0,0] neg_hi:[1,0,0]
	v_lshlrev_b32_e32 v50, 16, v142
	v_and_b32_e32 v51, 0xffff0000, v142
	v_pk_fma_f32 v[26:27], v[2:3], v[50:51], v[26:27] op_sel_hi:[0,1,1] neg_lo:[1,0,0] neg_hi:[1,0,0]
	v_lshlrev_b32_e32 v50, 16, v147
	v_and_b32_e32 v51, 0xffff0000, v147
	v_pk_fma_f32 v[28:29], v[2:3], v[50:51], v[28:29] op_sel_hi:[0,1,1] neg_lo:[1,0,0] neg_hi:[1,0,0]
	v_lshlrev_b32_e32 v50, 16, v152
	v_and_b32_e32 v51, 0xffff0000, v152
	v_pk_fma_f32 v[30:31], v[2:3], v[50:51], v[30:31] op_sel_hi:[0,1,1] neg_lo:[1,0,0] neg_hi:[1,0,0]
	v_lshlrev_b32_e32 v50, 16, v159
	v_and_b32_e32 v51, 0xffff0000, v159
	v_pk_fma_f32 v[32:33], v[2:3], v[50:51], v[32:33] op_sel_hi:[0,1,1] neg_lo:[1,0,0] neg_hi:[1,0,0]
; #define GAS __attribute__((address_space(1)))
; #define LAS __attribute__((address_space(3)))
; __device__ __forceinline__ unsigned cvt_pk_bf16(float lo, float hi) { unsigned r; asm volatile("v_cvt_pk_bf16_f32 %0, %1, %2" : "=v"(r) : "v"(lo), "v"(hi)); return r; }
; __device__ __forceinline__ float bf_lo(unsigned w) { return __uint_as_float(w << 16); }
; __device__ __forceinline__ float bf_hi(unsigned w) { return __uint_as_float(w & 0xffff0000u); }
; template <int W>
; __device__ __forceinline__ void pool_item(const Ctx& F, const bf16* Ub, bf16* Db, int r0, int nr) {
;     ...
;     POOL_LOAD(0, rs); POOL_LOAD(1, rs + 1);
;     __syncthreads();
;     for (int base = rs; base < re; base += NS) {
; #pragma unroll
;         for (int u = 0; u < NS; ++u) {
;             const int r = base + u;
;             if (r < re) {
;                 POOL_LOAD((u + 2) % NS, r + 2);
;                 const int e = r + HW - 1;
;                 const float me = (e >= 0 && e < 128) ? 1.0f : 0.0f, ml = (r >= r0 && r - HW >= 0) ? 1.0f : 0.0f;
; #pragma unroll
;                 for (int j = 0; j < 8; ++j) { Vv[j].x += me * bf_lo(ring[u][j]); Vv[j].y += me * bf_hi(ring[u][j]); }
;                 if (r >= r0) {
;                     LAS f32x2* row = buf + ((r & 1) * 80 + 8) * 64 + lane;
; #pragma unroll
;                     for (int j = 0; j < 8; ++j) row[(c0 + j) * 64] = Vv[j];
;                     asm volatile("s_waitcnt lgkmcnt(0)" ::: "memory"); __builtin_amdgcn_s_barrier(); asm volatile("" ::: "memory");
;                     const int rlo = r - HW > 0 ? r - HW : 0, rhi = r + HW < 128 ? r + HW : 128; const float icr = 1.0f / (float)(rhi - rlo);
;                     f32x2 h = (f32x2){0.f, 0.f};
; #pragma unroll
;                     for (int c = -HW; c < HW; ++c) h += row[(c0 + c) * 64];
; #pragma unroll
;                     for (int j = 0; j < 8; ++j) {
;                         const float ic = icr * icc[j]; const unsigned m = ring[(u + NS - HW + 1) % NS][j];
;                         *(GAS unsigned*)(Db + ((size_t)r * 64 + c0 + j) * EI) = cvt_pk_bf16(h.x * ic - bf_lo(m), h.y * ic - bf_hi(m));
;                         h += row[(c0 + j + HW) * 64] - row[(c0 + j - HW) * 64];
;                     }
.LBB0_900:
	s_cmp_ge_i32 s44, s46
	s_cbranch_scc1 .LBB0_903
	s_min_i32 s50, s44, 0x7a
	s_ashr_i32 s51, s50, 31
	s_lshl_b64 s[50:51], s[50:51], 20
	v_lshl_add_u64 v[50:51], v[12:13], 0, s[50:51]
	v_add_co_u32_e32 v170, vcc, 0x500000, v50
	s_add_i32 s10, s42, 6
	s_nop 0
	v_addc_co_u32_e32 v171, vcc, 0, v51, vcc
	global_load_dword v116, v[170:171], off
	v_add_co_u32_e32 v170, vcc, 0x504000, v50
	s_cmpk_lt_u32 s10, 0x80
	s_nop 0
	v_addc_co_u32_e32 v171, vcc, 0, v51, vcc
	global_load_dword v122, v[170:171], off
	v_add_co_u32_e32 v170, vcc, 0x508000, v50
	s_cselect_b64 s[50:51], -1, 0
	s_nop 0
	v_addc_co_u32_e32 v171, vcc, 0, v51, vcc
	global_load_dword v129, v[170:171], off
	v_add_co_u32_e32 v170, vcc, 0x50c000, v50
	v_cndmask_b32_e64 v2, 0, 1.0, s[50:51]
	s_nop 0
	v_addc_co_u32_e32 v171, vcc, 0, v51, vcc
	global_load_dword v135, v[170:171], off
	v_add_co_u32_e32 v170, vcc, 0x510000, v50
	s_cmp_lt_i32 s44, s62
	s_nop 0
	v_addc_co_u32_e32 v171, vcc, 0, v51, vcc
	global_load_dword v142, v[170:171], off
	v_add_co_u32_e32 v170, vcc, 0x514000, v50
	s_nop 1
	v_addc_co_u32_e32 v171, vcc, 0, v51, vcc
	global_load_dword v147, v[170:171], off
	v_add_co_u32_e32 v170, vcc, 0x518000, v50
	s_nop 1
	v_addc_co_u32_e32 v171, vcc, 0, v51, vcc
	v_add_co_u32_e32 v50, vcc, 0x51c000, v50
	global_load_dword v152, v[170:171], off
	s_nop 0
	v_addc_co_u32_e32 v51, vcc, 0, v51, vcc
	global_load_dword v159, v[50:51], off
	s_waitcnt vmcnt(23)
	v_lshlrev_b32_e32 v50, 16, v126
	v_and_b32_e32 v51, 0xffff0000, v126
	v_pk_fma_f32 v[18:19], v[2:3], v[50:51], v[18:19] op_sel_hi:[0,1,1]
	s_waitcnt vmcnt(22)
	v_lshlrev_b32_e32 v50, 16, v132
	v_and_b32_e32 v51, 0xffff0000, v132
	v_pk_fma_f32 v[20:21], v[2:3], v[50:51], v[20:21] op_sel_hi:[0,1,1]
	s_waitcnt vmcnt(21)
	v_lshlrev_b32_e32 v50, 16, v138
	v_and_b32_e32 v51, 0xffff0000, v138
	v_pk_fma_f32 v[22:23], v[2:3], v[50:51], v[22:23] op_sel_hi:[0,1,1]
	s_waitcnt vmcnt(20)
	v_lshlrev_b32_e32 v50, 16, v145
	v_and_b32_e32 v51, 0xffff0000, v145
	v_pk_fma_f32 v[24:25], v[2:3], v[50:51], v[24:25] op_sel_hi:[0,1,1]
	s_waitcnt vmcnt(19)
	v_lshlrev_b32_e32 v50, 16, v149
	v_and_b32_e32 v51, 0xffff0000, v149
	v_pk_fma_f32 v[26:27], v[2:3], v[50:51], v[26:27] op_sel_hi:[0,1,1]
	s_waitcnt vmcnt(18)
	v_lshlrev_b32_e32 v50, 16, v153
	v_and_b32_e32 v51, 0xffff0000, v153
	v_pk_fma_f32 v[28:29], v[2:3], v[50:51], v[28:29] op_sel_hi:[0,1,1]
	s_waitcnt vmcnt(17)
	v_lshlrev_b32_e32 v50, 16, v156
	v_and_b32_e32 v51, 0xffff0000, v156
	v_pk_fma_f32 v[30:31], v[2:3], v[50:51], v[30:31] op_sel_hi:[0,1,1]
	s_waitcnt vmcnt(16)
	v_lshlrev_b32_e32 v50, 16, v161
	v_and_b32_e32 v51, 0xffff0000, v161
	v_pk_fma_f32 v[32:33], v[2:3], v[50:51], v[32:33] op_sel_hi:[0,1,1]
	s_cbranch_scc1 .LBB0_903
	ds_write2st64_b64 v92, v[18:19], v[20:21] offset0:8 offset1:9
	ds_write2st64_b64 v92, v[22:23], v[24:25] offset0:10 offset1:11
	ds_write2st64_b64 v92, v[26:27], v[28:29] offset0:12 offset1:13
	ds_write2st64_b64 v92, v[30:31], v[32:33] offset0:14 offset1:15
	s_waitcnt lgkmcnt(0)
	s_barrier
	ds_read2st64_b64 v[170:173], v92 offset0:4 offset1:5
	s_cmp_gt_i32 s42, 0
	s_cselect_b64 s[50:51], -1, 0
	s_max_i32 s10, s44, 4
	s_min_i32 s16, s44, 0x7c
	s_waitcnt lgkmcnt(0)
	v_pk_add_f32 v[50:51], v[170:171], 0 op_sel_hi:[1,0]
	s_sub_i32 s10, s16, s10
	v_pk_add_f32 v[50:51], v[50:51], v[172:173]
	ds_read2st64_b64 v[170:173], v92 offset0:6 offset1:7
	s_add_i32 s10, s10, 8
	v_cvt_f32_i32_e32 v174, s10
	v_cndmask_b32_e64 v2, 0, 1.0, s[50:51]
	s_mov_b32 s45, s17
	s_waitcnt lgkmcnt(0)
	v_pk_add_f32 v[50:51], v[50:51], v[170:171]
	s_lshl_b64 s[44:45], s[44:45], 20
	v_pk_add_f32 v[50:51], v[50:51], v[172:173]
	ds_read2st64_b64 v[170:173], v92 offset0:8 offset1:9
	s_waitcnt lgkmcnt(0)
	v_pk_add_f32 v[50:51], v[50:51], v[170:171]
	s_nop 0
	v_pk_add_f32 v[50:51], v[50:51], v[172:173]
	ds_read2st64_b64 v[170:173], v92 offset0:10 offset1:11
	s_waitcnt lgkmcnt(0)
	v_pk_add_f32 v[50:51], v[50:51], v[170:171]
	v_div_scale_f32 v170, s[50:51], v174, v174, 1.0
	v_rcp_f32_e32 v171, v170
	v_pk_add_f32 v[50:51], v[50:51], v[172:173]
	v_fma_f32 v172, -v170, v171, 1.0
	v_fmac_f32_e32 v171, v172, v171
	v_div_scale_f32 v172, vcc, 1.0, v174, 1.0
	v_mul_f32_e32 v173, v172, v171
	v_fma_f32 v175, -v170, v173, v172
	v_fmac_f32_e32 v173, v175, v171
	v_fma_f32 v170, -v170, v173, v172
	v_div_fmas_f32 v170, v170, v171, v173
	v_div_fixup_f32 v176, v170, v174, 1.0
	v_mul_f32_e32 v170, v58, v176
	v_fma_f32 v171, v170, v50, -v34
	v_fma_f32 v170, v170, v51, -v35
	v_cvt_pk_bf16_f32 v170, v171, v170
	v_lshl_add_u64 v[174:175], v[14:15], 0, s[44:45]
	global_store_dword v[174:175], v170, off
	ds_read2st64_b64 v[170:173], v92 offset0:4 offset1:12
	s_waitcnt lgkmcnt(0)
	v_pk_add_f32 v[170:171], v[172:173], v[170:171] neg_lo:[0,1] neg_hi:[0,1]
	s_nop 0
	v_pk_add_f32 v[50:51], v[50:51], v[170:171]
	v_mul_f32_e32 v170, v59, v176
	v_fma_f32 v171, v170, v50, -v36
	v_fma_f32 v170, v170, v51, -v37
	v_cvt_pk_bf16_f32 v172, v171, v170
	v_add_co_u32_e32 v170, vcc, s54, v174
	s_nop 1
	v_addc_co_u32_e32 v171, vcc, 0, v175, vcc
	global_store_dword v[170:171], v172, off
	ds_read2st64_b64 v[170:173], v92 offset0:5 offset1:13
	s_waitcnt lgkmcnt(0)
	v_pk_add_f32 v[170:171], v[172:173], v[170:171] neg_lo:[0,1] neg_hi:[0,1]
	s_nop 0
	v_pk_add_f32 v[50:51], v[50:51], v[170:171]
	v_mul_f32_e32 v170, v60, v176
	v_fma_f32 v171, v170, v50, -v38
	v_fma_f32 v170, v170, v51, -v39
	v_cvt_pk_bf16_f32 v172, v171, v170
	v_add_co_u32_e32 v170, vcc, s55, v174
	s_nop 1
	v_addc_co_u32_e32 v171, vcc, 0, v175, vcc
	global_store_dword v[170:171], v172, off
	ds_read2st64_b64 v[170:173], v92 offset0:6 offset1:14
	s_waitcnt lgkmcnt(0)
; #define GAS __attribute__((address_space(1)))
; #define LAS __attribute__((address_space(3)))
; __device__ __forceinline__ unsigned cvt_pk_bf16(float lo, float hi) { unsigned r; asm volatile("v_cvt_pk_bf16_f32 %0, %1, %2" : "=v"(r) : "v"(lo), "v"(hi)); return r; }
; __device__ __forceinline__ float bf_lo(unsigned w) { return __uint_as_float(w << 16); }
; __device__ __forceinline__ float bf_hi(unsigned w) { return __uint_as_float(w & 0xffff0000u); }
; template <int W>
; __device__ __forceinline__ void pool_item(const Ctx& F, const bf16* Ub, bf16* Db, int r0, int nr) {
;     ...
;         for (int u = 0; u < NS; ++u) {
;             const int r = base + u;
;             if (r < re) {
;                 POOL_LOAD((u + 2) % NS, r + 2);
;                 const int e = r + HW - 1;
;                 const float me = (e >= 0 && e < 128) ? 1.0f : 0.0f, ml = (r >= r0 && r - HW >= 0) ? 1.0f : 0.0f;
; #pragma unroll
;                 for (int j = 0; j < 8; ++j) { Vv[j].x += me * bf_lo(ring[u][j]); Vv[j].y += me * bf_hi(ring[u][j]); }
;                 if (r >= r0) {
;                     LAS f32x2* row = buf + ((r & 1) * 80 + 8) * 64 + lane;
; #pragma unroll
;                     for (int j = 0; j < 8; ++j) row[(c0 + j) * 64] = Vv[j];
;                     asm volatile("s_waitcnt lgkmcnt(0)" ::: "memory"); __builtin_amdgcn_s_barrier(); asm volatile("" ::: "memory");
;                     const int rlo = r - HW > 0 ? r - HW : 0, rhi = r + HW < 128 ? r + HW : 128; const float icr = 1.0f / (float)(rhi - rlo);
;                     f32x2 h = (f32x2){0.f, 0.f};
; #pragma unroll
;                     for (int c = -HW; c < HW; ++c) h += row[(c0 + c) * 64];
; #pragma unroll
;                     for (int j = 0; j < 8; ++j) {
;                         const float ic = icr * icc[j]; const unsigned m = ring[(u + NS - HW + 1) % NS][j];
;                         *(GAS unsigned*)(Db + ((size_t)r * 64 + c0 + j) * EI) = cvt_pk_bf16(h.x * ic - bf_lo(m), h.y * ic - bf_hi(m));
;                         h += row[(c0 + j + HW) * 64] - row[(c0 + j - HW) * 64];
;                     }
; #pragma unroll
;                     for (int j = 0; j < 8; ++j) { const unsigned l = ring[(u + NS - W + 1) % NS][j]; Vv[j].x -= ml * bf_lo(l); Vv[j].y -= ml * bf_hi(l); }
;                 }
	v_pk_add_f32 v[170:171], v[172:173], v[170:171] neg_lo:[0,1] neg_hi:[0,1]
	s_nop 0
	v_pk_add_f32 v[50:51], v[50:51], v[170:171]
	v_mul_f32_e32 v170, v61, v176
	v_fma_f32 v171, v170, v50, -v40
	v_fma_f32 v170, v170, v51, -v41
	v_cvt_pk_bf16_f32 v172, v171, v170
	v_add_co_u32_e32 v170, vcc, s56, v174
	s_nop 1
	v_addc_co_u32_e32 v171, vcc, 0, v175, vcc
	global_store_dword v[170:171], v172, off
	ds_read2st64_b64 v[170:173], v92 offset0:7 offset1:15
	s_waitcnt lgkmcnt(0)
	v_pk_add_f32 v[170:171], v[172:173], v[170:171] neg_lo:[0,1] neg_hi:[0,1]
	s_nop 0
	v_pk_add_f32 v[50:51], v[50:51], v[170:171]
	v_mul_f32_e32 v170, v62, v176
	v_fma_f32 v171, v170, v50, -v42
	v_fma_f32 v170, v170, v51, -v43
	v_cvt_pk_bf16_f32 v172, v171, v170
	v_add_co_u32_e32 v170, vcc, s57, v174
	s_nop 1
	v_addc_co_u32_e32 v171, vcc, 0, v175, vcc
	global_store_dword v[170:171], v172, off
	ds_read2st64_b64 v[170:173], v92 offset0:8 offset1:16
	s_waitcnt lgkmcnt(0)
	v_pk_add_f32 v[170:171], v[172:173], v[170:171] neg_lo:[0,1] neg_hi:[0,1]
	s_nop 0
	v_pk_add_f32 v[50:51], v[50:51], v[170:171]
	v_mul_f32_e32 v170, v63, v176
	v_fma_f32 v171, v170, v50, -v44
	v_fma_f32 v170, v170, v51, -v45
	v_cvt_pk_bf16_f32 v172, v171, v170
	v_add_co_u32_e32 v170, vcc, s58, v174
	s_nop 1
	v_addc_co_u32_e32 v171, vcc, 0, v175, vcc
	global_store_dword v[170:171], v172, off
	ds_read2st64_b64 v[170:173], v92 offset0:9 offset1:17
	s_waitcnt lgkmcnt(0)
	v_pk_add_f32 v[170:171], v[172:173], v[170:171] neg_lo:[0,1] neg_hi:[0,1]
	s_nop 0
	v_pk_add_f32 v[50:51], v[50:51], v[170:171]
	v_mul_f32_e32 v170, v64, v176
	v_fma_f32 v171, v170, v50, -v46
	v_fma_f32 v170, v170, v51, -v47
	v_cvt_pk_bf16_f32 v172, v171, v170
	v_add_co_u32_e32 v170, vcc, s59, v174
	s_nop 1
	v_addc_co_u32_e32 v171, vcc, 0, v175, vcc
	global_store_dword v[170:171], v172, off
	ds_read2st64_b64 v[170:173], v92 offset0:10 offset1:18
	s_waitcnt lgkmcnt(0)
	v_pk_add_f32 v[170:171], v[172:173], v[170:171] neg_lo:[0,1] neg_hi:[0,1]
	s_nop 0
	v_pk_add_f32 v[50:51], v[50:51], v[170:171]
	v_mul_f32_e32 v170, v65, v176
	v_fma_f32 v50, v170, v50, -v48
	v_fma_f32 v51, v170, v51, -v49
	v_cvt_pk_bf16_f32 v170, v50, v51
	v_add_co_u32_e32 v50, vcc, s60, v174
	s_nop 1
	v_addc_co_u32_e32 v51, vcc, 0, v175, vcc
	global_store_dword v[50:51], v170, off
	v_lshlrev_b32_e32 v50, 16, v111
	v_and_b32_e32 v51, 0xffff0000, v111
	v_pk_fma_f32 v[18:19], v[2:3], v[50:51], v[18:19] op_sel_hi:[0,1,1] neg_lo:[1,0,0] neg_hi:[1,0,0]
	v_lshlrev_b32_e32 v50, 16, v117
	v_and_b32_e32 v51, 0xffff0000, v117
	v_pk_fma_f32 v[20:21], v[2:3], v[50:51], v[20:21] op_sel_hi:[0,1,1] neg_lo:[1,0,0] neg_hi:[1,0,0]
	v_lshlrev_b32_e32 v50, 16, v123
	v_and_b32_e32 v51, 0xffff0000, v123
	v_pk_fma_f32 v[22:23], v[2:3], v[50:51], v[22:23] op_sel_hi:[0,1,1] neg_lo:[1,0,0] neg_hi:[1,0,0]
	v_lshlrev_b32_e32 v50, 16, v130
	v_and_b32_e32 v51, 0xffff0000, v130
	v_pk_fma_f32 v[24:25], v[2:3], v[50:51], v[24:25] op_sel_hi:[0,1,1] neg_lo:[1,0,0] neg_hi:[1,0,0]
	v_lshlrev_b32_e32 v50, 16, v136
	v_and_b32_e32 v51, 0xffff0000, v136
	v_pk_fma_f32 v[26:27], v[2:3], v[50:51], v[26:27] op_sel_hi:[0,1,1] neg_lo:[1,0,0] neg_hi:[1,0,0]
	v_lshlrev_b32_e32 v50, 16, v143
	v_and_b32_e32 v51, 0xffff0000, v143
	v_pk_fma_f32 v[28:29], v[2:3], v[50:51], v[28:29] op_sel_hi:[0,1,1] neg_lo:[1,0,0] neg_hi:[1,0,0]
	v_lshlrev_b32_e32 v50, 16, v148
	v_and_b32_e32 v51, 0xffff0000, v148
	v_pk_fma_f32 v[30:31], v[2:3], v[50:51], v[30:31] op_sel_hi:[0,1,1] neg_lo:[1,0,0] neg_hi:[1,0,0]
	v_lshlrev_b32_e32 v50, 16, v158
	v_and_b32_e32 v51, 0xffff0000, v158
	v_pk_fma_f32 v[32:33], v[2:3], v[50:51], v[32:33] op_sel_hi:[0,1,1] neg_lo:[1,0,0] neg_hi:[1,0,0]
.LBB0_903:
	s_add_i32 s16, s42, 4
	s_cmp_ge_i32 s16, s46
	s_cbranch_scc1 .LBB0_906
	s_min_i32 s44, s16, 0x7a
	s_ashr_i32 s45, s44, 31
	s_lshl_b64 s[44:45], s[44:45], 20
	v_lshl_add_u64 v[50:51], v[12:13], 0, s[44:45]
	v_add_co_u32_e32 v170, vcc, 0x500000, v50
	s_add_i32 s10, s42, 7
	s_nop 0
	v_addc_co_u32_e32 v171, vcc, 0, v51, vcc
	global_load_dword v111, v[170:171], off
	v_add_co_u32_e32 v170, vcc, 0x504000, v50
	s_cmpk_lt_u32 s10, 0x80
	s_nop 0
	v_addc_co_u32_e32 v171, vcc, 0, v51, vcc
	global_load_dword v117, v[170:171], off
	v_add_co_u32_e32 v170, vcc, 0x508000, v50
	s_cselect_b64 s[44:45], -1, 0
	s_nop 0
	v_addc_co_u32_e32 v171, vcc, 0, v51, vcc
	global_load_dword v123, v[170:171], off
	v_add_co_u32_e32 v170, vcc, 0x50c000, v50
	v_cndmask_b32_e64 v2, 0, 1.0, s[44:45]
	s_nop 0
	v_addc_co_u32_e32 v171, vcc, 0, v51, vcc
	global_load_dword v130, v[170:171], off
	v_add_co_u32_e32 v170, vcc, 0x510000, v50
	s_cmp_lt_i32 s16, s62
	s_nop 0
	v_addc_co_u32_e32 v171, vcc, 0, v51, vcc
	global_load_dword v136, v[170:171], off
	v_add_co_u32_e32 v170, vcc, 0x514000, v50
	s_nop 1
	v_addc_co_u32_e32 v171, vcc, 0, v51, vcc
	global_load_dword v143, v[170:171], off
	v_add_co_u32_e32 v170, vcc, 0x518000, v50
	s_nop 1
	v_addc_co_u32_e32 v171, vcc, 0, v51, vcc
	v_add_co_u32_e32 v50, vcc, 0x51c000, v50
	global_load_dword v148, v[170:171], off
	s_nop 0
	v_addc_co_u32_e32 v51, vcc, 0, v51, vcc
	global_load_dword v158, v[50:51], off
	s_waitcnt vmcnt(23)
	v_lshlrev_b32_e32 v50, 16, v121
	v_and_b32_e32 v51, 0xffff0000, v121
	v_pk_fma_f32 v[18:19], v[2:3], v[50:51], v[18:19] op_sel_hi:[0,1,1]
	s_waitcnt vmcnt(22)
	v_lshlrev_b32_e32 v50, 16, v128
	v_and_b32_e32 v51, 0xffff0000, v128
	v_pk_fma_f32 v[20:21], v[2:3], v[50:51], v[20:21] op_sel_hi:[0,1,1]
	s_waitcnt vmcnt(21)
	v_lshlrev_b32_e32 v50, 16, v134
	v_and_b32_e32 v51, 0xffff0000, v134
	v_pk_fma_f32 v[22:23], v[2:3], v[50:51], v[22:23] op_sel_hi:[0,1,1]
	s_waitcnt vmcnt(20)
	v_lshlrev_b32_e32 v50, 16, v141
	v_and_b32_e32 v51, 0xffff0000, v141
	v_pk_fma_f32 v[24:25], v[2:3], v[50:51], v[24:25] op_sel_hi:[0,1,1]
	s_waitcnt vmcnt(19)
	v_lshlrev_b32_e32 v50, 16, v146
	v_and_b32_e32 v51, 0xffff0000, v146
	v_pk_fma_f32 v[26:27], v[2:3], v[50:51], v[26:27] op_sel_hi:[0,1,1]
	s_waitcnt vmcnt(18)
	v_lshlrev_b32_e32 v50, 16, v151
	v_and_b32_e32 v51, 0xffff0000, v151
	v_pk_fma_f32 v[28:29], v[2:3], v[50:51], v[28:29] op_sel_hi:[0,1,1]
	s_waitcnt vmcnt(17)
	v_lshlrev_b32_e32 v50, 16, v155
	v_and_b32_e32 v51, 0xffff0000, v155
	v_pk_fma_f32 v[30:31], v[2:3], v[50:51], v[30:31] op_sel_hi:[0,1,1]
	s_waitcnt vmcnt(16)
	v_lshlrev_b32_e32 v50, 16, v160
	v_and_b32_e32 v51, 0xffff0000, v160
	v_pk_fma_f32 v[32:33], v[2:3], v[50:51], v[32:33] op_sel_hi:[0,1,1]
	s_cbranch_scc1 .LBB0_906
; #define GAS __attribute__((address_space(1)))
; #define LAS __attribute__((address_space(3)))
; __device__ __forceinline__ unsigned cvt_pk_bf16(float lo, float hi) { unsigned r; asm volatile("v_cvt_pk_bf16_f32 %0, %1, %2" : "=v"(r) : "v"(lo), "v"(hi)); return r; }
; __device__ __forceinline__ float bf_lo(unsigned w) { return __uint_as_float(w << 16); }
; __device__ __forceinline__ float bf_hi(unsigned w) { return __uint_as_float(w & 0xffff0000u); }
; template <int W>
; __device__ __forceinline__ void pool_item(const Ctx& F, const bf16* Ub, bf16* Db, int r0, int nr) {
;     ...
;                 if (r >= r0) {
;                     LAS f32x2* row = buf + ((r & 1) * 80 + 8) * 64 + lane;
; #pragma unroll
;                     for (int j = 0; j < 8; ++j) row[(c0 + j) * 64] = Vv[j];
;                     asm volatile("s_waitcnt lgkmcnt(0)" ::: "memory"); __builtin_amdgcn_s_barrier(); asm volatile("" ::: "memory");
;                     const int rlo = r - HW > 0 ? r - HW : 0, rhi = r + HW < 128 ? r + HW : 128; const float icr = 1.0f / (float)(rhi - rlo);
;                     f32x2 h = (f32x2){0.f, 0.f};
; #pragma unroll
;                     for (int c = -HW; c < HW; ++c) h += row[(c0 + c) * 64];
; #pragma unroll
;                     for (int j = 0; j < 8; ++j) {
;                         const float ic = icr * icc[j]; const unsigned m = ring[(u + NS - HW + 1) % NS][j];
;                         *(GAS unsigned*)(Db + ((size_t)r * 64 + c0 + j) * EI) = cvt_pk_bf16(h.x * ic - bf_lo(m), h.y * ic - bf_hi(m));
;                         h += row[(c0 + j + HW) * 64] - row[(c0 + j - HW) * 64];
	ds_write2st64_b64 v92, v[18:19], v[20:21] offset0:88 offset1:89
	ds_write2st64_b64 v92, v[22:23], v[24:25] offset0:90 offset1:91
	ds_write2st64_b64 v92, v[26:27], v[28:29] offset0:92 offset1:93
	ds_write2st64_b64 v92, v[30:31], v[32:33] offset0:94 offset1:95
	s_waitcnt lgkmcnt(0)
	s_barrier
	ds_read2st64_b64 v[170:173], v92 offset0:84 offset1:85
	s_cmp_gt_i32 s42, -1
	s_cselect_b64 s[44:45], -1, 0
	s_max_i32 s10, s16, 4
	s_min_i32 s23, s16, 0x7c
	s_waitcnt lgkmcnt(0)
	v_pk_add_f32 v[50:51], v[170:171], 0 op_sel_hi:[1,0]
	s_sub_i32 s10, s23, s10
	v_pk_add_f32 v[50:51], v[50:51], v[172:173]
	ds_read2st64_b64 v[170:173], v92 offset0:86 offset1:87
	s_add_i32 s10, s10, 8
	v_cvt_f32_i32_e32 v176, s10
	v_cndmask_b32_e64 v2, 0, 1.0, s[44:45]
	s_waitcnt lgkmcnt(0)
	v_pk_add_f32 v[50:51], v[50:51], v[170:171]
	s_nop 0
	v_pk_add_f32 v[50:51], v[50:51], v[172:173]
	ds_read2st64_b64 v[170:173], v92 offset0:88 offset1:89
	s_waitcnt lgkmcnt(0)
	v_pk_add_f32 v[50:51], v[50:51], v[170:171]
	s_nop 0
	v_pk_add_f32 v[50:51], v[50:51], v[172:173]
	ds_read2st64_b64 v[170:173], v92 offset0:90 offset1:91
	s_waitcnt lgkmcnt(0)
	v_pk_add_f32 v[50:51], v[50:51], v[170:171]
	s_nop 0
	v_pk_add_f32 v[174:175], v[50:51], v[172:173]
	v_div_scale_f32 v50, s[44:45], v176, v176, 1.0
	v_rcp_f32_e32 v51, v50
	s_lshl_b64 s[44:45], s[16:17], 20
	v_fma_f32 v170, -v50, v51, 1.0
	v_fmac_f32_e32 v51, v170, v51
	v_div_scale_f32 v170, vcc, 1.0, v176, 1.0
	v_mul_f32_e32 v171, v170, v51
	v_fma_f32 v172, -v50, v171, v170
	v_fmac_f32_e32 v171, v172, v51
	v_fma_f32 v50, -v50, v171, v170
	v_div_fmas_f32 v50, v50, v51, v171
	v_div_fixup_f32 v176, v50, v176, 1.0
	v_mul_f32_e32 v50, v58, v176
	v_lshlrev_b32_e32 v51, 16, v97
	v_and_b32_e32 v170, 0xffff0000, v97
	v_fma_f32 v51, v50, v174, -v51
	v_fma_f32 v50, v50, v175, -v170
	v_cvt_pk_bf16_f32 v170, v51, v50
	v_lshl_add_u64 v[50:51], v[14:15], 0, s[44:45]
	global_store_dword v[50:51], v170, off
	ds_read2st64_b64 v[170:173], v92 offset0:84 offset1:92
	s_waitcnt lgkmcnt(0)
	v_pk_add_f32 v[170:171], v[172:173], v[170:171] neg_lo:[0,1] neg_hi:[0,1]
	s_nop 0
	v_pk_add_f32 v[174:175], v[174:175], v[170:171]
	v_mul_f32_e32 v170, v59, v176
	v_lshlrev_b32_e32 v171, 16, v98
	v_and_b32_e32 v172, 0xffff0000, v98
	v_fma_f32 v171, v170, v174, -v171
	v_fma_f32 v170, v170, v175, -v172
	v_cvt_pk_bf16_f32 v172, v171, v170
	v_add_co_u32_e32 v170, vcc, s54, v50
	s_nop 1
	v_addc_co_u32_e32 v171, vcc, 0, v51, vcc
	global_store_dword v[170:171], v172, off
	ds_read2st64_b64 v[170:173], v92 offset0:85 offset1:93
	s_waitcnt lgkmcnt(0)
	v_pk_add_f32 v[170:171], v[172:173], v[170:171] neg_lo:[0,1] neg_hi:[0,1]
	s_nop 0
	v_pk_add_f32 v[174:175], v[174:175], v[170:171]
	v_mul_f32_e32 v170, v60, v176
	v_lshlrev_b32_e32 v171, 16, v99
	v_and_b32_e32 v172, 0xffff0000, v99
	v_fma_f32 v171, v170, v174, -v171
	v_fma_f32 v170, v170, v175, -v172
	v_cvt_pk_bf16_f32 v172, v171, v170
	v_add_co_u32_e32 v170, vcc, s55, v50
	s_nop 1
	v_addc_co_u32_e32 v171, vcc, 0, v51, vcc
	global_store_dword v[170:171], v172, off
	ds_read2st64_b64 v[170:173], v92 offset0:86 offset1:94
	s_waitcnt lgkmcnt(0)
	v_pk_add_f32 v[170:171], v[172:173], v[170:171] neg_lo:[0,1] neg_hi:[0,1]
	s_nop 0
	v_pk_add_f32 v[174:175], v[174:175], v[170:171]
	v_mul_f32_e32 v170, v61, v176
	v_lshlrev_b32_e32 v171, 16, v100
	v_and_b32_e32 v172, 0xffff0000, v100
	v_fma_f32 v171, v170, v174, -v171
	v_fma_f32 v170, v170, v175, -v172
	v_cvt_pk_bf16_f32 v172, v171, v170
	v_add_co_u32_e32 v170, vcc, s56, v50
	s_nop 1
	v_addc_co_u32_e32 v171, vcc, 0, v51, vcc
	global_store_dword v[170:171], v172, off
	ds_read2st64_b64 v[170:173], v92 offset0:87 offset1:95
	s_waitcnt lgkmcnt(0)
	v_pk_add_f32 v[170:171], v[172:173], v[170:171] neg_lo:[0,1] neg_hi:[0,1]
	s_nop 0
	v_pk_add_f32 v[174:175], v[174:175], v[170:171]
	v_mul_f32_e32 v170, v62, v176
	v_lshlrev_b32_e32 v171, 16, v104
	v_and_b32_e32 v172, 0xffff0000, v104
	v_fma_f32 v171, v170, v174, -v171
	v_fma_f32 v170, v170, v175, -v172
	v_cvt_pk_bf16_f32 v172, v171, v170
	v_add_co_u32_e32 v170, vcc, s57, v50
	s_nop 1
	v_addc_co_u32_e32 v171, vcc, 0, v51, vcc
	global_store_dword v[170:171], v172, off
	ds_read2st64_b64 v[170:173], v92 offset0:88 offset1:96
	s_waitcnt lgkmcnt(0)
	v_pk_add_f32 v[170:171], v[172:173], v[170:171] neg_lo:[0,1] neg_hi:[0,1]
	s_nop 0
	v_pk_add_f32 v[174:175], v[174:175], v[170:171]
	v_mul_f32_e32 v170, v63, v176
	v_lshlrev_b32_e32 v171, 16, v109
	v_and_b32_e32 v172, 0xffff0000, v109
	v_fma_f32 v171, v170, v174, -v171
	v_fma_f32 v170, v170, v175, -v172
	v_cvt_pk_bf16_f32 v172, v171, v170
	v_add_co_u32_e32 v170, vcc, s58, v50
	s_nop 1
	v_addc_co_u32_e32 v171, vcc, 0, v51, vcc
	global_store_dword v[170:171], v172, off
	ds_read2st64_b64 v[170:173], v92 offset0:89 offset1:97
	s_waitcnt lgkmcnt(0)
	v_pk_add_f32 v[170:171], v[172:173], v[170:171] neg_lo:[0,1] neg_hi:[0,1]
	s_nop 0
	v_pk_add_f32 v[174:175], v[174:175], v[170:171]
	v_mul_f32_e32 v170, v64, v176
	v_lshlrev_b32_e32 v171, 16, v114
	v_and_b32_e32 v172, 0xffff0000, v114
	v_fma_f32 v171, v170, v174, -v171
	v_fma_f32 v170, v170, v175, -v172
	v_cvt_pk_bf16_f32 v172, v171, v170
	v_add_co_u32_e32 v170, vcc, s59, v50
	s_nop 1
	v_addc_co_u32_e32 v171, vcc, 0, v51, vcc
	global_store_dword v[170:171], v172, off
	ds_read2st64_b64 v[170:173], v92 offset0:90 offset1:98
	v_add_co_u32_e32 v50, vcc, s60, v50
	s_waitcnt lgkmcnt(0)
; #define GAS __attribute__((address_space(1)))
; #define LAS __attribute__((address_space(3)))
; __device__ __forceinline__ unsigned cvt_pk_bf16(float lo, float hi) { unsigned r; asm volatile("v_cvt_pk_bf16_f32 %0, %1, %2" : "=v"(r) : "v"(lo), "v"(hi)); return r; }
; __device__ __forceinline__ float bf_lo(unsigned w) { return __uint_as_float(w << 16); }
; __device__ __forceinline__ float bf_hi(unsigned w) { return __uint_as_float(w & 0xffff0000u); }
; template <int W>
; __device__ __forceinline__ void pool_item(const Ctx& F, const bf16* Ub, bf16* Db, int r0, int nr) {
;     ...
;         for (int u = 0; u < NS; ++u) {
;             const int r = base + u;
;             if (r < re) {
;                 POOL_LOAD((u + 2) % NS, r + 2);
;                 const int e = r + HW - 1;
;                 const float me = (e >= 0 && e < 128) ? 1.0f : 0.0f, ml = (r >= r0 && r - HW >= 0) ? 1.0f : 0.0f;
; #pragma unroll
;                 for (int j = 0; j < 8; ++j) { Vv[j].x += me * bf_lo(ring[u][j]); Vv[j].y += me * bf_hi(ring[u][j]); }
;                 if (r >= r0) {
;                     LAS f32x2* row = buf + ((r & 1) * 80 + 8) * 64 + lane;
; #pragma unroll
;                     for (int j = 0; j < 8; ++j) row[(c0 + j) * 64] = Vv[j];
;                     asm volatile("s_waitcnt lgkmcnt(0)" ::: "memory"); __builtin_amdgcn_s_barrier(); asm volatile("" ::: "memory");
;                     const int rlo = r - HW > 0 ? r - HW : 0, rhi = r + HW < 128 ? r + HW : 128; const float icr = 1.0f / (float)(rhi - rlo);
;                     f32x2 h = (f32x2){0.f, 0.f};
; #pragma unroll
;                     for (int c = -HW; c < HW; ++c) h += row[(c0 + c) * 64];
; #pragma unroll
;                     for (int j = 0; j < 8; ++j) {
;                         const float ic = icr * icc[j]; const unsigned m = ring[(u + NS - HW + 1) % NS][j];
;                         *(GAS unsigned*)(Db + ((size_t)r * 64 + c0 + j) * EI) = cvt_pk_bf16(h.x * ic - bf_lo(m), h.y * ic - bf_hi(m));
;                         h += row[(c0 + j + HW) * 64] - row[(c0 + j - HW) * 64];
;                     }
; #pragma unroll
;                     for (int j = 0; j < 8; ++j) { const unsigned l = ring[(u + NS - W + 1) % NS][j]; Vv[j].x -= ml * bf_lo(l); Vv[j].y -= ml * bf_hi(l); }
;                 }
	v_pk_add_f32 v[170:171], v[172:173], v[170:171] neg_lo:[0,1] neg_hi:[0,1]
	s_nop 0
	v_pk_add_f32 v[170:171], v[174:175], v[170:171]
	v_mul_f32_e32 v172, v65, v176
	v_lshlrev_b32_e32 v173, 16, v140
	v_fma_f32 v170, v172, v170, -v173
	v_and_b32_e32 v173, 0xffff0000, v140
	v_addc_co_u32_e32 v51, vcc, 0, v51, vcc
	v_fma_f32 v171, v172, v171, -v173
	v_cvt_pk_bf16_f32 v170, v170, v171
	global_store_dword v[50:51], v170, off
	v_lshlrev_b32_e32 v50, 16, v107
	v_and_b32_e32 v51, 0xffff0000, v107
	v_pk_fma_f32 v[18:19], v[2:3], v[50:51], v[18:19] op_sel_hi:[0,1,1] neg_lo:[1,0,0] neg_hi:[1,0,0]
	v_lshlrev_b32_e32 v50, 16, v112
	v_and_b32_e32 v51, 0xffff0000, v112
	v_pk_fma_f32 v[20:21], v[2:3], v[50:51], v[20:21] op_sel_hi:[0,1,1] neg_lo:[1,0,0] neg_hi:[1,0,0]
	v_lshlrev_b32_e32 v50, 16, v118
	v_and_b32_e32 v51, 0xffff0000, v118
	v_pk_fma_f32 v[22:23], v[2:3], v[50:51], v[22:23] op_sel_hi:[0,1,1] neg_lo:[1,0,0] neg_hi:[1,0,0]
	v_lshlrev_b32_e32 v50, 16, v124
	v_and_b32_e32 v51, 0xffff0000, v124
	v_pk_fma_f32 v[24:25], v[2:3], v[50:51], v[24:25] op_sel_hi:[0,1,1] neg_lo:[1,0,0] neg_hi:[1,0,0]
	v_lshlrev_b32_e32 v50, 16, v131
	v_and_b32_e32 v51, 0xffff0000, v131
	v_pk_fma_f32 v[26:27], v[2:3], v[50:51], v[26:27] op_sel_hi:[0,1,1] neg_lo:[1,0,0] neg_hi:[1,0,0]
	v_lshlrev_b32_e32 v50, 16, v137
	v_and_b32_e32 v51, 0xffff0000, v137
	v_pk_fma_f32 v[28:29], v[2:3], v[50:51], v[28:29] op_sel_hi:[0,1,1] neg_lo:[1,0,0] neg_hi:[1,0,0]
	v_lshlrev_b32_e32 v50, 16, v144
	v_and_b32_e32 v51, 0xffff0000, v144
	v_pk_fma_f32 v[30:31], v[2:3], v[50:51], v[30:31] op_sel_hi:[0,1,1] neg_lo:[1,0,0] neg_hi:[1,0,0]
	v_lshlrev_b32_e32 v50, 16, v157
	v_and_b32_e32 v51, 0xffff0000, v157
	v_pk_fma_f32 v[32:33], v[2:3], v[50:51], v[32:33] op_sel_hi:[0,1,1] neg_lo:[1,0,0] neg_hi:[1,0,0]
.LBB0_906:
	s_add_i32 s16, s42, 5
	s_cmp_ge_i32 s16, s46
	s_cbranch_scc1 .LBB0_909
	s_min_i32 s44, s16, 0x7a
	s_ashr_i32 s45, s44, 31
	s_lshl_b64 s[44:45], s[44:45], 20
	v_lshl_add_u64 v[50:51], v[12:13], 0, s[44:45]
	v_add_co_u32_e32 v170, vcc, 0x500000, v50
	s_add_i32 s10, s42, 8
	s_nop 0
	v_addc_co_u32_e32 v171, vcc, 0, v51, vcc
	global_load_dword v107, v[170:171], off
	v_add_co_u32_e32 v170, vcc, 0x504000, v50
	s_cmpk_lt_u32 s10, 0x80
	s_nop 0
	v_addc_co_u32_e32 v171, vcc, 0, v51, vcc
	global_load_dword v112, v[170:171], off
	v_add_co_u32_e32 v170, vcc, 0x508000, v50
	s_cselect_b64 s[44:45], -1, 0
	s_nop 0
	v_addc_co_u32_e32 v171, vcc, 0, v51, vcc
	global_load_dword v118, v[170:171], off
	v_add_co_u32_e32 v170, vcc, 0x50c000, v50
	v_cndmask_b32_e64 v2, 0, 1.0, s[44:45]
	s_nop 0
	v_addc_co_u32_e32 v171, vcc, 0, v51, vcc
	global_load_dword v124, v[170:171], off
	v_add_co_u32_e32 v170, vcc, 0x510000, v50
	s_cmp_lt_i32 s16, s62
	s_nop 0
	v_addc_co_u32_e32 v171, vcc, 0, v51, vcc
	global_load_dword v131, v[170:171], off
	v_add_co_u32_e32 v170, vcc, 0x514000, v50
	s_nop 1
	v_addc_co_u32_e32 v171, vcc, 0, v51, vcc
	global_load_dword v137, v[170:171], off
	v_add_co_u32_e32 v170, vcc, 0x518000, v50
	s_nop 1
	v_addc_co_u32_e32 v171, vcc, 0, v51, vcc
	v_add_co_u32_e32 v50, vcc, 0x51c000, v50
	global_load_dword v144, v[170:171], off
	s_nop 0
	v_addc_co_u32_e32 v51, vcc, 0, v51, vcc
	global_load_dword v157, v[50:51], off
	s_waitcnt vmcnt(23)
	v_lshlrev_b32_e32 v50, 16, v116
	v_and_b32_e32 v51, 0xffff0000, v116
	v_pk_fma_f32 v[18:19], v[2:3], v[50:51], v[18:19] op_sel_hi:[0,1,1]
	s_waitcnt vmcnt(22)
	v_lshlrev_b32_e32 v50, 16, v122
	v_and_b32_e32 v51, 0xffff0000, v122
	v_pk_fma_f32 v[20:21], v[2:3], v[50:51], v[20:21] op_sel_hi:[0,1,1]
	s_waitcnt vmcnt(21)
	v_lshlrev_b32_e32 v50, 16, v129
	v_and_b32_e32 v51, 0xffff0000, v129
	v_pk_fma_f32 v[22:23], v[2:3], v[50:51], v[22:23] op_sel_hi:[0,1,1]
	s_waitcnt vmcnt(20)
	v_lshlrev_b32_e32 v50, 16, v135
	v_and_b32_e32 v51, 0xffff0000, v135
	v_pk_fma_f32 v[24:25], v[2:3], v[50:51], v[24:25] op_sel_hi:[0,1,1]
	s_waitcnt vmcnt(19)
	v_lshlrev_b32_e32 v50, 16, v142
	v_and_b32_e32 v51, 0xffff0000, v142
	v_pk_fma_f32 v[26:27], v[2:3], v[50:51], v[26:27] op_sel_hi:[0,1,1]
	s_waitcnt vmcnt(18)
	v_lshlrev_b32_e32 v50, 16, v147
	v_and_b32_e32 v51, 0xffff0000, v147
	v_pk_fma_f32 v[28:29], v[2:3], v[50:51], v[28:29] op_sel_hi:[0,1,1]
	s_waitcnt vmcnt(17)
	v_lshlrev_b32_e32 v50, 16, v152
	v_and_b32_e32 v51, 0xffff0000, v152
	v_pk_fma_f32 v[30:31], v[2:3], v[50:51], v[30:31] op_sel_hi:[0,1,1]
	s_waitcnt vmcnt(16)
	v_lshlrev_b32_e32 v50, 16, v159
	v_and_b32_e32 v51, 0xffff0000, v159
	v_pk_fma_f32 v[32:33], v[2:3], v[50:51], v[32:33] op_sel_hi:[0,1,1]
	s_cbranch_scc1 .LBB0_909
	ds_write2st64_b64 v92, v[18:19], v[20:21] offset0:8 offset1:9
	ds_write2st64_b64 v92, v[22:23], v[24:25] offset0:10 offset1:11
	ds_write2st64_b64 v92, v[26:27], v[28:29] offset0:12 offset1:13
	ds_write2st64_b64 v92, v[30:31], v[32:33] offset0:14 offset1:15
	s_waitcnt lgkmcnt(0)
	s_barrier
; #define GAS __attribute__((address_space(1)))
; #define LAS __attribute__((address_space(3)))
; __device__ __forceinline__ unsigned cvt_pk_bf16(float lo, float hi) { unsigned r; asm volatile("v_cvt_pk_bf16_f32 %0, %1, %2" : "=v"(r) : "v"(lo), "v"(hi)); return r; }
; __device__ __forceinline__ float bf_lo(unsigned w) { return __uint_as_float(w << 16); }
; __device__ __forceinline__ float bf_hi(unsigned w) { return __uint_as_float(w & 0xffff0000u); }
; template <int W>
; __device__ __forceinline__ void pool_item(const Ctx& F, const bf16* Ub, bf16* Db, int r0, int nr) {
;     ...
;                 if (r >= r0) {
;                     LAS f32x2* row = buf + ((r & 1) * 80 + 8) * 64 + lane;
; #pragma unroll
;                     for (int j = 0; j < 8; ++j) row[(c0 + j) * 64] = Vv[j];
;                     asm volatile("s_waitcnt lgkmcnt(0)" ::: "memory"); __builtin_amdgcn_s_barrier(); asm volatile("" ::: "memory");
;                     const int rlo = r - HW > 0 ? r - HW : 0, rhi = r + HW < 128 ? r + HW : 128; const float icr = 1.0f / (float)(rhi - rlo);
;                     f32x2 h = (f32x2){0.f, 0.f};
; #pragma unroll
;                     for (int c = -HW; c < HW; ++c) h += row[(c0 + c) * 64];
; #pragma unroll
;                     for (int j = 0; j < 8; ++j) {
;                         const float ic = icr * icc[j]; const unsigned m = ring[(u + NS - HW + 1) % NS][j];
;                         *(GAS unsigned*)(Db + ((size_t)r * 64 + c0 + j) * EI) = cvt_pk_bf16(h.x * ic - bf_lo(m), h.y * ic - bf_hi(m));
;                         h += row[(c0 + j + HW) * 64] - row[(c0 + j - HW) * 64];
;                     }
; #pragma unroll
;                     for (int j = 0; j < 8; ++j) { const unsigned l = ring[(u + NS - W + 1) % NS][j]; Vv[j].x -= ml * bf_lo(l); Vv[j].y -= ml * bf_hi(l); }
;                 }
	ds_read2st64_b64 v[170:173], v92 offset0:4 offset1:5
	s_cmp_gt_i32 s42, -2
	s_cselect_b64 s[44:45], -1, 0
	s_max_i32 s10, s16, 4
	s_min_i32 s23, s16, 0x7c
	s_waitcnt lgkmcnt(0)
	v_pk_add_f32 v[50:51], v[170:171], 0 op_sel_hi:[1,0]
	s_sub_i32 s10, s23, s10
	v_pk_add_f32 v[50:51], v[50:51], v[172:173]
	ds_read2st64_b64 v[170:173], v92 offset0:6 offset1:7
	s_add_i32 s10, s10, 8
	v_cvt_f32_i32_e32 v176, s10
	v_cndmask_b32_e64 v2, 0, 1.0, s[44:45]
	s_waitcnt lgkmcnt(0)
	v_pk_add_f32 v[50:51], v[50:51], v[170:171]
	s_nop 0
	v_pk_add_f32 v[50:51], v[50:51], v[172:173]
	ds_read2st64_b64 v[170:173], v92 offset0:8 offset1:9
	s_waitcnt lgkmcnt(0)
	v_pk_add_f32 v[50:51], v[50:51], v[170:171]
	s_nop 0
	v_pk_add_f32 v[50:51], v[50:51], v[172:173]
	ds_read2st64_b64 v[170:173], v92 offset0:10 offset1:11
	s_waitcnt lgkmcnt(0)
	v_pk_add_f32 v[50:51], v[50:51], v[170:171]
	s_nop 0
	v_pk_add_f32 v[174:175], v[50:51], v[172:173]
	v_div_scale_f32 v50, s[44:45], v176, v176, 1.0
	v_rcp_f32_e32 v51, v50
	s_lshl_b64 s[44:45], s[16:17], 20
	v_fma_f32 v170, -v50, v51, 1.0
	v_fmac_f32_e32 v51, v170, v51
	v_div_scale_f32 v170, vcc, 1.0, v176, 1.0
	v_mul_f32_e32 v171, v170, v51
	v_fma_f32 v172, -v50, v171, v170
	v_fmac_f32_e32 v171, v172, v51
	v_fma_f32 v50, -v50, v171, v170
	v_div_fmas_f32 v50, v50, v51, v171
	v_div_fixup_f32 v176, v50, v176, 1.0
	v_mul_f32_e32 v50, v58, v176
	v_lshlrev_b32_e32 v51, 16, v169
	v_and_b32_e32 v170, 0xffff0000, v169
	v_fma_f32 v51, v50, v174, -v51
	v_fma_f32 v50, v50, v175, -v170
	v_cvt_pk_bf16_f32 v170, v51, v50
	v_lshl_add_u64 v[50:51], v[14:15], 0, s[44:45]
	global_store_dword v[50:51], v170, off
	ds_read2st64_b64 v[170:173], v92 offset0:4 offset1:12
	s_waitcnt lgkmcnt(0)
	v_pk_add_f32 v[170:171], v[172:173], v[170:171] neg_lo:[0,1] neg_hi:[0,1]
	s_nop 0
	v_pk_add_f32 v[174:175], v[174:175], v[170:171]
	v_mul_f32_e32 v170, v59, v176
	v_lshlrev_b32_e32 v171, 16, v168
	v_and_b32_e32 v172, 0xffff0000, v168
	v_fma_f32 v171, v170, v174, -v171
	v_fma_f32 v170, v170, v175, -v172
	v_cvt_pk_bf16_f32 v172, v171, v170
	v_add_co_u32_e32 v170, vcc, s54, v50
	s_nop 1
	v_addc_co_u32_e32 v171, vcc, 0, v51, vcc
	global_store_dword v[170:171], v172, off
	ds_read2st64_b64 v[170:173], v92 offset0:5 offset1:13
	s_waitcnt lgkmcnt(0)
	v_pk_add_f32 v[170:171], v[172:173], v[170:171] neg_lo:[0,1] neg_hi:[0,1]
	s_nop 0
	v_pk_add_f32 v[174:175], v[174:175], v[170:171]
	v_mul_f32_e32 v170, v60, v176
	v_lshlrev_b32_e32 v171, 16, v167
	v_and_b32_e32 v172, 0xffff0000, v167
	v_fma_f32 v171, v170, v174, -v171
	v_fma_f32 v170, v170, v175, -v172
	v_cvt_pk_bf16_f32 v172, v171, v170
	v_add_co_u32_e32 v170, vcc, s55, v50
	s_nop 1
	v_addc_co_u32_e32 v171, vcc, 0, v51, vcc
	global_store_dword v[170:171], v172, off
	ds_read2st64_b64 v[170:173], v92 offset0:6 offset1:14
	s_waitcnt lgkmcnt(0)
	v_pk_add_f32 v[170:171], v[172:173], v[170:171] neg_lo:[0,1] neg_hi:[0,1]
	s_nop 0
	v_pk_add_f32 v[174:175], v[174:175], v[170:171]
	v_mul_f32_e32 v170, v61, v176
	v_lshlrev_b32_e32 v171, 16, v166
	v_and_b32_e32 v172, 0xffff0000, v166
	v_fma_f32 v171, v170, v174, -v171
	v_fma_f32 v170, v170, v175, -v172
	v_cvt_pk_bf16_f32 v172, v171, v170
	v_add_co_u32_e32 v170, vcc, s56, v50
	s_nop 1
	v_addc_co_u32_e32 v171, vcc, 0, v51, vcc
	global_store_dword v[170:171], v172, off
	ds_read2st64_b64 v[170:173], v92 offset0:7 offset1:15
	s_waitcnt lgkmcnt(0)
	v_pk_add_f32 v[170:171], v[172:173], v[170:171] neg_lo:[0,1] neg_hi:[0,1]
	s_nop 0
	v_pk_add_f32 v[174:175], v[174:175], v[170:171]
	v_mul_f32_e32 v170, v62, v176
	v_lshlrev_b32_e32 v171, 16, v165
	v_and_b32_e32 v172, 0xffff0000, v165
	v_fma_f32 v171, v170, v174, -v171
	v_fma_f32 v170, v170, v175, -v172
	v_cvt_pk_bf16_f32 v172, v171, v170
	v_add_co_u32_e32 v170, vcc, s57, v50
	s_nop 1
	v_addc_co_u32_e32 v171, vcc, 0, v51, vcc
	global_store_dword v[170:171], v172, off
	ds_read2st64_b64 v[170:173], v92 offset0:8 offset1:16
	s_waitcnt lgkmcnt(0)
	v_pk_add_f32 v[170:171], v[172:173], v[170:171] neg_lo:[0,1] neg_hi:[0,1]
	s_nop 0
	v_pk_add_f32 v[174:175], v[174:175], v[170:171]
	v_mul_f32_e32 v170, v63, v176
	v_lshlrev_b32_e32 v171, 16, v164
	v_and_b32_e32 v172, 0xffff0000, v164
	v_fma_f32 v171, v170, v174, -v171
	v_fma_f32 v170, v170, v175, -v172
	v_cvt_pk_bf16_f32 v172, v171, v170
	v_add_co_u32_e32 v170, vcc, s58, v50
	s_nop 1
	v_addc_co_u32_e32 v171, vcc, 0, v51, vcc
	global_store_dword v[170:171], v172, off
	ds_read2st64_b64 v[170:173], v92 offset0:9 offset1:17
	s_waitcnt lgkmcnt(0)
	v_pk_add_f32 v[170:171], v[172:173], v[170:171] neg_lo:[0,1] neg_hi:[0,1]
	s_nop 0
	v_pk_add_f32 v[174:175], v[174:175], v[170:171]
	v_mul_f32_e32 v170, v64, v176
	v_lshlrev_b32_e32 v171, 16, v163
	v_and_b32_e32 v172, 0xffff0000, v163
	v_fma_f32 v171, v170, v174, -v171
	v_fma_f32 v170, v170, v175, -v172
	v_cvt_pk_bf16_f32 v172, v171, v170
	v_add_co_u32_e32 v170, vcc, s59, v50
	s_nop 1
	v_addc_co_u32_e32 v171, vcc, 0, v51, vcc
	global_store_dword v[170:171], v172, off
	ds_read2st64_b64 v[170:173], v92 offset0:10 offset1:18
	v_add_co_u32_e32 v50, vcc, s60, v50
	s_waitcnt lgkmcnt(0)
	v_pk_add_f32 v[170:171], v[172:173], v[170:171] neg_lo:[0,1] neg_hi:[0,1]
	s_nop 0
	v_pk_add_f32 v[170:171], v[174:175], v[170:171]
	v_mul_f32_e32 v172, v65, v176
	v_lshlrev_b32_e32 v173, 16, v162
	v_fma_f32 v170, v172, v170, -v173
	v_and_b32_e32 v173, 0xffff0000, v162
	v_addc_co_u32_e32 v51, vcc, 0, v51, vcc
	v_fma_f32 v171, v172, v171, -v173
	v_cvt_pk_bf16_f32 v170, v170, v171
	global_store_dword v[50:51], v170, off
	v_lshlrev_b32_e32 v50, 16, v105
	v_and_b32_e32 v51, 0xffff0000, v105
	v_pk_fma_f32 v[18:19], v[2:3], v[50:51], v[18:19] op_sel_hi:[0,1,1] neg_lo:[1,0,0] neg_hi:[1,0,0]
	v_lshlrev_b32_e32 v50, 16, v108
	v_and_b32_e32 v51, 0xffff0000, v108
	v_pk_fma_f32 v[20:21], v[2:3], v[50:51], v[20:21] op_sel_hi:[0,1,1] neg_lo:[1,0,0] neg_hi:[1,0,0]
	v_lshlrev_b32_e32 v50, 16, v113
	v_and_b32_e32 v51, 0xffff0000, v113
	v_pk_fma_f32 v[22:23], v[2:3], v[50:51], v[22:23] op_sel_hi:[0,1,1] neg_lo:[1,0,0] neg_hi:[1,0,0]
	v_lshlrev_b32_e32 v50, 16, v119
	v_and_b32_e32 v51, 0xffff0000, v119
	v_pk_fma_f32 v[24:25], v[2:3], v[50:51], v[24:25] op_sel_hi:[0,1,1] neg_lo:[1,0,0] neg_hi:[1,0,0]
	v_lshlrev_b32_e32 v50, 16, v125
	v_and_b32_e32 v51, 0xffff0000, v125
	v_pk_fma_f32 v[26:27], v[2:3], v[50:51], v[26:27] op_sel_hi:[0,1,1] neg_lo:[1,0,0] neg_hi:[1,0,0]
	v_lshlrev_b32_e32 v50, 16, v133
	v_and_b32_e32 v51, 0xffff0000, v133
	v_pk_fma_f32 v[28:29], v[2:3], v[50:51], v[28:29] op_sel_hi:[0,1,1] neg_lo:[1,0,0] neg_hi:[1,0,0]
	v_lshlrev_b32_e32 v50, 16, v139
	v_and_b32_e32 v51, 0xffff0000, v139
	v_pk_fma_f32 v[30:31], v[2:3], v[50:51], v[30:31] op_sel_hi:[0,1,1] neg_lo:[1,0,0] neg_hi:[1,0,0]
	v_lshlrev_b32_e32 v50, 16, v154
	v_and_b32_e32 v51, 0xffff0000, v154
	v_pk_fma_f32 v[32:33], v[2:3], v[50:51], v[32:33] op_sel_hi:[0,1,1] neg_lo:[1,0,0] neg_hi:[1,0,0]
; #define GAS __attribute__((address_space(1)))
; #define LAS __attribute__((address_space(3)))
; __device__ __forceinline__ unsigned cvt_pk_bf16(float lo, float hi) { unsigned r; asm volatile("v_cvt_pk_bf16_f32 %0, %1, %2" : "=v"(r) : "v"(lo), "v"(hi)); return r; }
; __device__ __forceinline__ float bf_lo(unsigned w) { return __uint_as_float(w << 16); }
; __device__ __forceinline__ float bf_hi(unsigned w) { return __uint_as_float(w & 0xffff0000u); }
; template <int W>
; __device__ __forceinline__ void pool_item(const Ctx& F, const bf16* Ub, bf16* Db, int r0, int nr) {
;     ...
;         for (int u = 0; u < NS; ++u) {
;             const int r = base + u;
;             if (r < re) {
;                 POOL_LOAD((u + 2) % NS, r + 2);
;                 const int e = r + HW - 1;
;                 const float me = (e >= 0 && e < 128) ? 1.0f : 0.0f, ml = (r >= r0 && r - HW >= 0) ? 1.0f : 0.0f;
; #pragma unroll
;                 for (int j = 0; j < 8; ++j) { Vv[j].x += me * bf_lo(ring[u][j]); Vv[j].y += me * bf_hi(ring[u][j]); }
;                 if (r >= r0) {
;                     LAS f32x2* row = buf + ((r & 1) * 80 + 8) * 64 + lane;
; #pragma unroll
;                     for (int j = 0; j < 8; ++j) row[(c0 + j) * 64] = Vv[j];
;                     asm volatile("s_waitcnt lgkmcnt(0)" ::: "memory"); __builtin_amdgcn_s_barrier(); asm volatile("" ::: "memory");
;                     const int rlo = r - HW > 0 ? r - HW : 0, rhi = r + HW < 128 ? r + HW : 128; const float icr = 1.0f / (float)(rhi - rlo);
;                     f32x2 h = (f32x2){0.f, 0.f};
; #pragma unroll
;                     for (int c = -HW; c < HW; ++c) h += row[(c0 + c) * 64];
; #pragma unroll
;                     for (int j = 0; j < 8; ++j) {
;                         const float ic = icr * icc[j]; const unsigned m = ring[(u + NS - HW + 1) % NS][j];
;                         *(GAS unsigned*)(Db + ((size_t)r * 64 + c0 + j) * EI) = cvt_pk_bf16(h.x * ic - bf_lo(m), h.y * ic - bf_hi(m));
;                         h += row[(c0 + j + HW) * 64] - row[(c0 + j - HW) * 64];
;                     }
; #pragma unroll
;                     for (int j = 0; j < 8; ++j) { const unsigned l = ring[(u + NS - W + 1) % NS][j]; Vv[j].x -= ml * bf_lo(l); Vv[j].y -= ml * bf_hi(l); }
;                 }
.LBB0_909:
	s_add_i32 s16, s42, 6
	s_cmp_ge_i32 s16, s46
	s_cbranch_scc1 .LBB0_912
	s_min_i32 s44, s16, 0x7a
	s_ashr_i32 s45, s44, 31
	s_lshl_b64 s[44:45], s[44:45], 20
	v_lshl_add_u64 v[50:51], v[12:13], 0, s[44:45]
	v_add_co_u32_e32 v170, vcc, 0x500000, v50
	s_add_i32 s10, s42, 9
	s_nop 0
	v_addc_co_u32_e32 v171, vcc, 0, v51, vcc
	global_load_dword v105, v[170:171], off
	v_add_co_u32_e32 v170, vcc, 0x504000, v50
	s_cmpk_lt_u32 s10, 0x80
	s_nop 0
	v_addc_co_u32_e32 v171, vcc, 0, v51, vcc
	global_load_dword v108, v[170:171], off
	v_add_co_u32_e32 v170, vcc, 0x508000, v50
	s_cselect_b64 s[44:45], -1, 0
	s_nop 0
	v_addc_co_u32_e32 v171, vcc, 0, v51, vcc
	global_load_dword v113, v[170:171], off
	v_add_co_u32_e32 v170, vcc, 0x50c000, v50
	v_cndmask_b32_e64 v2, 0, 1.0, s[44:45]
	s_nop 0
	v_addc_co_u32_e32 v171, vcc, 0, v51, vcc
	global_load_dword v119, v[170:171], off
	v_add_co_u32_e32 v170, vcc, 0x510000, v50
	s_cmp_lt_i32 s16, s62
	s_nop 0
	v_addc_co_u32_e32 v171, vcc, 0, v51, vcc
	global_load_dword v125, v[170:171], off
	v_add_co_u32_e32 v170, vcc, 0x514000, v50
	s_nop 1
	v_addc_co_u32_e32 v171, vcc, 0, v51, vcc
	global_load_dword v133, v[170:171], off
	v_add_co_u32_e32 v170, vcc, 0x518000, v50
	s_nop 1
	v_addc_co_u32_e32 v171, vcc, 0, v51, vcc
	v_add_co_u32_e32 v50, vcc, 0x51c000, v50
	global_load_dword v139, v[170:171], off
	s_nop 0
	v_addc_co_u32_e32 v51, vcc, 0, v51, vcc
	global_load_dword v154, v[50:51], off
	s_waitcnt vmcnt(23)
	v_lshlrev_b32_e32 v50, 16, v111
	v_and_b32_e32 v51, 0xffff0000, v111
	v_pk_fma_f32 v[18:19], v[2:3], v[50:51], v[18:19] op_sel_hi:[0,1,1]
	s_waitcnt vmcnt(22)
	v_lshlrev_b32_e32 v50, 16, v117
	v_and_b32_e32 v51, 0xffff0000, v117
	v_pk_fma_f32 v[20:21], v[2:3], v[50:51], v[20:21] op_sel_hi:[0,1,1]
	s_waitcnt vmcnt(21)
	v_lshlrev_b32_e32 v50, 16, v123
	v_and_b32_e32 v51, 0xffff0000, v123
	v_pk_fma_f32 v[22:23], v[2:3], v[50:51], v[22:23] op_sel_hi:[0,1,1]
	s_waitcnt vmcnt(20)
	v_lshlrev_b32_e32 v50, 16, v130
	v_and_b32_e32 v51, 0xffff0000, v130
	v_pk_fma_f32 v[24:25], v[2:3], v[50:51], v[24:25] op_sel_hi:[0,1,1]
	s_waitcnt vmcnt(19)
	v_lshlrev_b32_e32 v50, 16, v136
	v_and_b32_e32 v51, 0xffff0000, v136
	v_pk_fma_f32 v[26:27], v[2:3], v[50:51], v[26:27] op_sel_hi:[0,1,1]
	s_waitcnt vmcnt(18)
	v_lshlrev_b32_e32 v50, 16, v143
	v_and_b32_e32 v51, 0xffff0000, v143
	v_pk_fma_f32 v[28:29], v[2:3], v[50:51], v[28:29] op_sel_hi:[0,1,1]
	s_waitcnt vmcnt(17)
	v_lshlrev_b32_e32 v50, 16, v148
	v_and_b32_e32 v51, 0xffff0000, v148
	v_pk_fma_f32 v[30:31], v[2:3], v[50:51], v[30:31] op_sel_hi:[0,1,1]
	s_waitcnt vmcnt(16)
	v_lshlrev_b32_e32 v50, 16, v158
	v_and_b32_e32 v51, 0xffff0000, v158
	v_pk_fma_f32 v[32:33], v[2:3], v[50:51], v[32:33] op_sel_hi:[0,1,1]
	s_cbranch_scc1 .LBB0_912
	ds_write2st64_b64 v92, v[18:19], v[20:21] offset0:88 offset1:89
	ds_write2st64_b64 v92, v[22:23], v[24:25] offset0:90 offset1:91
	ds_write2st64_b64 v92, v[26:27], v[28:29] offset0:92 offset1:93
	ds_write2st64_b64 v92, v[30:31], v[32:33] offset0:94 offset1:95
	s_waitcnt lgkmcnt(0)
	s_barrier
	ds_read2st64_b64 v[170:173], v92 offset0:84 offset1:85
	s_cmp_gt_i32 s42, -3
	s_cselect_b64 s[44:45], -1, 0
	s_max_i32 s10, s16, 4
	s_min_i32 s23, s16, 0x7c
	s_waitcnt lgkmcnt(0)
	v_pk_add_f32 v[50:51], v[170:171], 0 op_sel_hi:[1,0]
	s_sub_i32 s10, s23, s10
	v_pk_add_f32 v[50:51], v[50:51], v[172:173]
	ds_read2st64_b64 v[170:173], v92 offset0:86 offset1:87
	s_add_i32 s10, s10, 8
	v_cvt_f32_i32_e32 v176, s10
	v_cndmask_b32_e64 v2, 0, 1.0, s[44:45]
	s_waitcnt lgkmcnt(0)
	v_pk_add_f32 v[50:51], v[50:51], v[170:171]
	s_nop 0
	v_pk_add_f32 v[50:51], v[50:51], v[172:173]
	ds_read2st64_b64 v[170:173], v92 offset0:88 offset1:89
	s_waitcnt lgkmcnt(0)
	v_pk_add_f32 v[50:51], v[50:51], v[170:171]
	s_nop 0
	v_pk_add_f32 v[50:51], v[50:51], v[172:173]
	ds_read2st64_b64 v[170:173], v92 offset0:90 offset1:91
	s_waitcnt lgkmcnt(0)
	v_pk_add_f32 v[50:51], v[50:51], v[170:171]
	s_nop 0
	v_pk_add_f32 v[174:175], v[50:51], v[172:173]
	v_div_scale_f32 v50, s[44:45], v176, v176, 1.0
	v_rcp_f32_e32 v51, v50
	s_lshl_b64 s[44:45], s[16:17], 20
	v_fma_f32 v170, -v50, v51, 1.0
	v_fmac_f32_e32 v51, v170, v51
	v_div_scale_f32 v170, vcc, 1.0, v176, 1.0
	v_mul_f32_e32 v171, v170, v51
	v_fma_f32 v172, -v50, v171, v170
	v_fmac_f32_e32 v171, v172, v51
	v_fma_f32 v50, -v50, v171, v170
	v_div_fmas_f32 v50, v50, v51, v171
	v_div_fixup_f32 v176, v50, v176, 1.0
	v_mul_f32_e32 v50, v58, v176
	v_lshlrev_b32_e32 v51, 16, v126
	v_and_b32_e32 v170, 0xffff0000, v126
	v_fma_f32 v51, v50, v174, -v51
	v_fma_f32 v50, v50, v175, -v170
	v_cvt_pk_bf16_f32 v170, v51, v50
	v_lshl_add_u64 v[50:51], v[14:15], 0, s[44:45]
	global_store_dword v[50:51], v170, off
	ds_read2st64_b64 v[170:173], v92 offset0:84 offset1:92
	s_waitcnt lgkmcnt(0)
	v_pk_add_f32 v[170:171], v[172:173], v[170:171] neg_lo:[0,1] neg_hi:[0,1]
	s_nop 0
	v_pk_add_f32 v[174:175], v[174:175], v[170:171]
	v_mul_f32_e32 v170, v59, v176
	v_lshlrev_b32_e32 v171, 16, v132
	v_and_b32_e32 v172, 0xffff0000, v132
	v_fma_f32 v171, v170, v174, -v171
	v_fma_f32 v170, v170, v175, -v172
	v_cvt_pk_bf16_f32 v172, v171, v170
	v_add_co_u32_e32 v170, vcc, s54, v50
	s_nop 1
	v_addc_co_u32_e32 v171, vcc, 0, v51, vcc
	global_store_dword v[170:171], v172, off
	ds_read2st64_b64 v[170:173], v92 offset0:85 offset1:93
	s_waitcnt lgkmcnt(0)
	v_pk_add_f32 v[170:171], v[172:173], v[170:171] neg_lo:[0,1] neg_hi:[0,1]
	s_nop 0
	v_pk_add_f32 v[174:175], v[174:175], v[170:171]
	v_mul_f32_e32 v170, v60, v176
	v_lshlrev_b32_e32 v171, 16, v138
	v_and_b32_e32 v172, 0xffff0000, v138
	v_fma_f32 v171, v170, v174, -v171
	v_fma_f32 v170, v170, v175, -v172
	v_cvt_pk_bf16_f32 v172, v171, v170
	v_add_co_u32_e32 v170, vcc, s55, v50
	s_nop 1
	v_addc_co_u32_e32 v171, vcc, 0, v51, vcc
	global_store_dword v[170:171], v172, off
	ds_read2st64_b64 v[170:173], v92 offset0:86 offset1:94
	s_waitcnt lgkmcnt(0)
; #define GAS __attribute__((address_space(1)))
; #define LAS __attribute__((address_space(3)))
; __device__ __forceinline__ unsigned cvt_pk_bf16(float lo, float hi) { unsigned r; asm volatile("v_cvt_pk_bf16_f32 %0, %1, %2" : "=v"(r) : "v"(lo), "v"(hi)); return r; }
; __device__ __forceinline__ float bf_lo(unsigned w) { return __uint_as_float(w << 16); }
; __device__ __forceinline__ float bf_hi(unsigned w) { return __uint_as_float(w & 0xffff0000u); }
; template <int W>
; __device__ __forceinline__ void pool_item(const Ctx& F, const bf16* Ub, bf16* Db, int r0, int nr) {
;     ...
;         for (int u = 0; u < NS; ++u) {
;             const int r = base + u;
;             if (r < re) {
;                 POOL_LOAD((u + 2) % NS, r + 2);
;                 const int e = r + HW - 1;
;                 const float me = (e >= 0 && e < 128) ? 1.0f : 0.0f, ml = (r >= r0 && r - HW >= 0) ? 1.0f : 0.0f;
; #pragma unroll
;                 for (int j = 0; j < 8; ++j) { Vv[j].x += me * bf_lo(ring[u][j]); Vv[j].y += me * bf_hi(ring[u][j]); }
;                 if (r >= r0) {
;                     LAS f32x2* row = buf + ((r & 1) * 80 + 8) * 64 + lane;
; #pragma unroll
;                     for (int j = 0; j < 8; ++j) row[(c0 + j) * 64] = Vv[j];
;                     asm volatile("s_waitcnt lgkmcnt(0)" ::: "memory"); __builtin_amdgcn_s_barrier(); asm volatile("" ::: "memory");
;                     const int rlo = r - HW > 0 ? r - HW : 0, rhi = r + HW < 128 ? r + HW : 128; const float icr = 1.0f / (float)(rhi - rlo);
;                     f32x2 h = (f32x2){0.f, 0.f};
; #pragma unroll
;                     for (int c = -HW; c < HW; ++c) h += row[(c0 + c) * 64];
; #pragma unroll
;                     for (int j = 0; j < 8; ++j) {
;                         const float ic = icr * icc[j]; const unsigned m = ring[(u + NS - HW + 1) % NS][j];
;                         *(GAS unsigned*)(Db + ((size_t)r * 64 + c0 + j) * EI) = cvt_pk_bf16(h.x * ic - bf_lo(m), h.y * ic - bf_hi(m));
;                         h += row[(c0 + j + HW) * 64] - row[(c0 + j - HW) * 64];
;                     }
; #pragma unroll
;                     for (int j = 0; j < 8; ++j) { const unsigned l = ring[(u + NS - W + 1) % NS][j]; Vv[j].x -= ml * bf_lo(l); Vv[j].y -= ml * bf_hi(l); }
;                 }
	v_pk_add_f32 v[170:171], v[172:173], v[170:171] neg_lo:[0,1] neg_hi:[0,1]
	s_nop 0
	v_pk_add_f32 v[174:175], v[174:175], v[170:171]
	v_mul_f32_e32 v170, v61, v176
	v_lshlrev_b32_e32 v171, 16, v145
	v_and_b32_e32 v172, 0xffff0000, v145
	v_fma_f32 v171, v170, v174, -v171
	v_fma_f32 v170, v170, v175, -v172
	v_cvt_pk_bf16_f32 v172, v171, v170
	v_add_co_u32_e32 v170, vcc, s56, v50
	s_nop 1
	v_addc_co_u32_e32 v171, vcc, 0, v51, vcc
	global_store_dword v[170:171], v172, off
	ds_read2st64_b64 v[170:173], v92 offset0:87 offset1:95
	s_waitcnt lgkmcnt(0)
	v_pk_add_f32 v[170:171], v[172:173], v[170:171] neg_lo:[0,1] neg_hi:[0,1]
	s_nop 0
	v_pk_add_f32 v[174:175], v[174:175], v[170:171]
	v_mul_f32_e32 v170, v62, v176
	v_lshlrev_b32_e32 v171, 16, v149
	v_and_b32_e32 v172, 0xffff0000, v149
	v_fma_f32 v171, v170, v174, -v171
	v_fma_f32 v170, v170, v175, -v172
	v_cvt_pk_bf16_f32 v172, v171, v170
	v_add_co_u32_e32 v170, vcc, s57, v50
	s_nop 1
	v_addc_co_u32_e32 v171, vcc, 0, v51, vcc
	global_store_dword v[170:171], v172, off
	ds_read2st64_b64 v[170:173], v92 offset0:88 offset1:96
	s_waitcnt lgkmcnt(0)
	v_pk_add_f32 v[170:171], v[172:173], v[170:171] neg_lo:[0,1] neg_hi:[0,1]
	s_nop 0
	v_pk_add_f32 v[174:175], v[174:175], v[170:171]
	v_mul_f32_e32 v170, v63, v176
	v_lshlrev_b32_e32 v171, 16, v153
	v_and_b32_e32 v172, 0xffff0000, v153
	v_fma_f32 v171, v170, v174, -v171
	v_fma_f32 v170, v170, v175, -v172
	v_cvt_pk_bf16_f32 v172, v171, v170
	v_add_co_u32_e32 v170, vcc, s58, v50
	s_nop 1
	v_addc_co_u32_e32 v171, vcc, 0, v51, vcc
	global_store_dword v[170:171], v172, off
	ds_read2st64_b64 v[170:173], v92 offset0:89 offset1:97
	s_waitcnt lgkmcnt(0)
	v_pk_add_f32 v[170:171], v[172:173], v[170:171] neg_lo:[0,1] neg_hi:[0,1]
	s_nop 0
	v_pk_add_f32 v[174:175], v[174:175], v[170:171]
	v_mul_f32_e32 v170, v64, v176
	v_lshlrev_b32_e32 v171, 16, v156
	v_and_b32_e32 v172, 0xffff0000, v156
	v_fma_f32 v171, v170, v174, -v171
	v_fma_f32 v170, v170, v175, -v172
	v_cvt_pk_bf16_f32 v172, v171, v170
	v_add_co_u32_e32 v170, vcc, s59, v50
	s_nop 1
	v_addc_co_u32_e32 v171, vcc, 0, v51, vcc
	global_store_dword v[170:171], v172, off
	ds_read2st64_b64 v[170:173], v92 offset0:90 offset1:98
	v_add_co_u32_e32 v50, vcc, s60, v50
	s_waitcnt lgkmcnt(0)
	v_pk_add_f32 v[170:171], v[172:173], v[170:171] neg_lo:[0,1] neg_hi:[0,1]
	s_nop 0
	v_pk_add_f32 v[170:171], v[174:175], v[170:171]
	v_mul_f32_e32 v172, v65, v176
	v_lshlrev_b32_e32 v173, 16, v161
	v_fma_f32 v170, v172, v170, -v173
	v_and_b32_e32 v173, 0xffff0000, v161
	v_addc_co_u32_e32 v51, vcc, 0, v51, vcc
	v_fma_f32 v171, v172, v171, -v173
	v_cvt_pk_bf16_f32 v170, v170, v171
	global_store_dword v[50:51], v170, off
	v_lshlrev_b32_e32 v50, 16, v101
	v_and_b32_e32 v51, 0xffff0000, v101
	v_pk_fma_f32 v[18:19], v[2:3], v[50:51], v[18:19] op_sel_hi:[0,1,1] neg_lo:[1,0,0] neg_hi:[1,0,0]
	v_lshlrev_b32_e32 v50, 16, v103
	v_and_b32_e32 v51, 0xffff0000, v103
	v_pk_fma_f32 v[20:21], v[2:3], v[50:51], v[20:21] op_sel_hi:[0,1,1] neg_lo:[1,0,0] neg_hi:[1,0,0]
	v_lshlrev_b32_e32 v50, 16, v106
	v_and_b32_e32 v51, 0xffff0000, v106
	v_pk_fma_f32 v[22:23], v[2:3], v[50:51], v[22:23] op_sel_hi:[0,1,1] neg_lo:[1,0,0] neg_hi:[1,0,0]
	v_lshlrev_b32_e32 v50, 16, v110
	v_and_b32_e32 v51, 0xffff0000, v110
	v_pk_fma_f32 v[24:25], v[2:3], v[50:51], v[24:25] op_sel_hi:[0,1,1] neg_lo:[1,0,0] neg_hi:[1,0,0]
	v_lshlrev_b32_e32 v50, 16, v115
	v_and_b32_e32 v51, 0xffff0000, v115
	v_pk_fma_f32 v[26:27], v[2:3], v[50:51], v[26:27] op_sel_hi:[0,1,1] neg_lo:[1,0,0] neg_hi:[1,0,0]
	v_lshlrev_b32_e32 v50, 16, v120
	v_and_b32_e32 v51, 0xffff0000, v120
	v_pk_fma_f32 v[28:29], v[2:3], v[50:51], v[28:29] op_sel_hi:[0,1,1] neg_lo:[1,0,0] neg_hi:[1,0,0]
	v_lshlrev_b32_e32 v50, 16, v127
	v_and_b32_e32 v51, 0xffff0000, v127
	v_pk_fma_f32 v[30:31], v[2:3], v[50:51], v[30:31] op_sel_hi:[0,1,1] neg_lo:[1,0,0] neg_hi:[1,0,0]
	v_lshlrev_b32_e32 v50, 16, v150
	v_and_b32_e32 v51, 0xffff0000, v150
	v_pk_fma_f32 v[32:33], v[2:3], v[50:51], v[32:33] op_sel_hi:[0,1,1] neg_lo:[1,0,0] neg_hi:[1,0,0]
.LBB0_912:
	s_add_i32 s10, s42, 7
	s_cmp_ge_u32 s10, s46
	s_cbranch_scc1 .LBB0_915
	s_min_i32 s16, s10, 0x7a
	s_add_i32 s16, s16, 5
	s_lshl_b64 s[44:45], s[16:17], 20
	v_lshl_add_u64 v[50:51], v[12:13], 0, s[44:45]
	v_add_co_u32_e32 v170, vcc, 0x4000, v50
	global_load_dword v101, v[50:51], off
	s_nop 0
	v_addc_co_u32_e32 v171, vcc, 0, v51, vcc
	global_load_dword v103, v[170:171], off
	v_add_co_u32_e32 v170, vcc, 0x8000, v50
	s_add_i32 s16, s42, 10
	s_nop 0
	v_addc_co_u32_e32 v171, vcc, 0, v51, vcc
	global_load_dword v106, v[170:171], off
	v_add_co_u32_e32 v170, vcc, 0xc000, v50
	s_cmpk_lt_u32 s16, 0x80
	s_nop 0
	v_addc_co_u32_e32 v171, vcc, 0, v51, vcc
	global_load_dword v110, v[170:171], off
	v_add_co_u32_e32 v170, vcc, 0x10000, v50
	s_cselect_b64 s[44:45], -1, 0
	s_nop 0
	v_addc_co_u32_e32 v171, vcc, 0, v51, vcc
	global_load_dword v115, v[170:171], off
	v_add_co_u32_e32 v170, vcc, 0x14000, v50
	v_cndmask_b32_e64 v2, 0, 1.0, s[44:45]
	s_nop 0
	v_addc_co_u32_e32 v171, vcc, 0, v51, vcc
	global_load_dword v120, v[170:171], off
	v_add_co_u32_e32 v170, vcc, 0x18000, v50
	s_cmp_lt_u32 s10, s62
	s_nop 0
	v_addc_co_u32_e32 v171, vcc, 0, v51, vcc
	v_add_co_u32_e32 v50, vcc, 0x1c000, v50
	global_load_dword v127, v[170:171], off
	s_nop 0
	v_addc_co_u32_e32 v51, vcc, 0, v51, vcc
	global_load_dword v150, v[50:51], off
	s_waitcnt vmcnt(23)
	v_lshlrev_b32_e32 v50, 16, v107
	v_and_b32_e32 v51, 0xffff0000, v107
	v_pk_fma_f32 v[18:19], v[2:3], v[50:51], v[18:19] op_sel_hi:[0,1,1]
	s_waitcnt vmcnt(22)
	v_lshlrev_b32_e32 v50, 16, v112
	v_and_b32_e32 v51, 0xffff0000, v112
	v_pk_fma_f32 v[20:21], v[2:3], v[50:51], v[20:21] op_sel_hi:[0,1,1]
	s_waitcnt vmcnt(21)
	v_lshlrev_b32_e32 v50, 16, v118
	v_and_b32_e32 v51, 0xffff0000, v118
	v_pk_fma_f32 v[22:23], v[2:3], v[50:51], v[22:23] op_sel_hi:[0,1,1]
	s_waitcnt vmcnt(20)
	v_lshlrev_b32_e32 v50, 16, v124
	v_and_b32_e32 v51, 0xffff0000, v124
	v_pk_fma_f32 v[24:25], v[2:3], v[50:51], v[24:25] op_sel_hi:[0,1,1]
	s_waitcnt vmcnt(19)
	v_lshlrev_b32_e32 v50, 16, v131
	v_and_b32_e32 v51, 0xffff0000, v131
	v_pk_fma_f32 v[26:27], v[2:3], v[50:51], v[26:27] op_sel_hi:[0,1,1]
	s_waitcnt vmcnt(18)
	v_lshlrev_b32_e32 v50, 16, v137
	v_and_b32_e32 v51, 0xffff0000, v137
	v_pk_fma_f32 v[28:29], v[2:3], v[50:51], v[28:29] op_sel_hi:[0,1,1]
	s_waitcnt vmcnt(17)
	v_lshlrev_b32_e32 v50, 16, v144
	v_and_b32_e32 v51, 0xffff0000, v144
	v_pk_fma_f32 v[30:31], v[2:3], v[50:51], v[30:31] op_sel_hi:[0,1,1]
	s_waitcnt vmcnt(16)
	v_lshlrev_b32_e32 v50, 16, v157
	v_and_b32_e32 v51, 0xffff0000, v157
	v_pk_fma_f32 v[32:33], v[2:3], v[50:51], v[32:33] op_sel_hi:[0,1,1]
	s_cbranch_scc1 .LBB0_915
; #define GAS __attribute__((address_space(1)))
; #define LAS __attribute__((address_space(3)))
; __device__ __forceinline__ unsigned cvt_pk_bf16(float lo, float hi) { unsigned r; asm volatile("v_cvt_pk_bf16_f32 %0, %1, %2" : "=v"(r) : "v"(lo), "v"(hi)); return r; }
; __device__ __forceinline__ float bf_lo(unsigned w) { return __uint_as_float(w << 16); }
; __device__ __forceinline__ float bf_hi(unsigned w) { return __uint_as_float(w & 0xffff0000u); }
; template <int W>
; __device__ __forceinline__ void pool_item(const Ctx& F, const bf16* Ub, bf16* Db, int r0, int nr) {
;     ...
;                 if (r >= r0) {
;                     LAS f32x2* row = buf + ((r & 1) * 80 + 8) * 64 + lane;
; #pragma unroll
;                     for (int j = 0; j < 8; ++j) row[(c0 + j) * 64] = Vv[j];
;                     asm volatile("s_waitcnt lgkmcnt(0)" ::: "memory"); __builtin_amdgcn_s_barrier(); asm volatile("" ::: "memory");
;                     const int rlo = r - HW > 0 ? r - HW : 0, rhi = r + HW < 128 ? r + HW : 128; const float icr = 1.0f / (float)(rhi - rlo);
;                     f32x2 h = (f32x2){0.f, 0.f};
; #pragma unroll
;                     for (int c = -HW; c < HW; ++c) h += row[(c0 + c) * 64];
; #pragma unroll
;                     for (int j = 0; j < 8; ++j) {
;                         const float ic = icr * icc[j]; const unsigned m = ring[(u + NS - HW + 1) % NS][j];
;                         *(GAS unsigned*)(Db + ((size_t)r * 64 + c0 + j) * EI) = cvt_pk_bf16(h.x * ic - bf_lo(m), h.y * ic - bf_hi(m));
;                         h += row[(c0 + j + HW) * 64] - row[(c0 + j - HW) * 64];
;                     }
; #pragma unroll
;                     for (int j = 0; j < 8; ++j) { const unsigned l = ring[(u + NS - W + 1) % NS][j]; Vv[j].x -= ml * bf_lo(l); Vv[j].y -= ml * bf_hi(l); }
;                 }
	ds_write2st64_b64 v92, v[18:19], v[20:21] offset0:8 offset1:9
	ds_write2st64_b64 v92, v[22:23], v[24:25] offset0:10 offset1:11
	ds_write2st64_b64 v92, v[26:27], v[28:29] offset0:12 offset1:13
	ds_write2st64_b64 v92, v[30:31], v[32:33] offset0:14 offset1:15
	s_waitcnt lgkmcnt(0)
	s_barrier
	ds_read2st64_b64 v[170:173], v92 offset0:4 offset1:5
	s_cmp_gt_u32 s10, 3
	s_cselect_b64 s[44:45], -1, 0
	s_max_i32 s16, s10, 4
	s_min_i32 s10, s10, 0x7c
	s_waitcnt lgkmcnt(0)
	v_pk_add_f32 v[50:51], v[170:171], 0 op_sel_hi:[1,0]
	s_sub_i32 s10, s10, s16
	v_pk_add_f32 v[50:51], v[50:51], v[172:173]
	ds_read2st64_b64 v[170:173], v92 offset0:6 offset1:7
	s_add_i32 s10, s10, 8
	v_cvt_f32_i32_e32 v174, s10
	v_cndmask_b32_e64 v2, 0, 1.0, s[44:45]
	s_mov_b32 s10, 0xffdec000
	s_waitcnt lgkmcnt(0)
	v_pk_add_f32 v[50:51], v[50:51], v[170:171]
	v_pk_fma_f32 v[32:33], v[2:3], v[48:49], v[32:33] op_sel_hi:[0,1,1] neg_lo:[1,0,0] neg_hi:[1,0,0]
	v_pk_add_f32 v[50:51], v[50:51], v[172:173]
	ds_read2st64_b64 v[170:173], v92 offset0:8 offset1:9
	v_pk_fma_f32 v[30:31], v[2:3], v[46:47], v[30:31] op_sel_hi:[0,1,1] neg_lo:[1,0,0] neg_hi:[1,0,0]
	v_pk_fma_f32 v[28:29], v[2:3], v[44:45], v[28:29] op_sel_hi:[0,1,1] neg_lo:[1,0,0] neg_hi:[1,0,0]
	v_pk_fma_f32 v[26:27], v[2:3], v[42:43], v[26:27] op_sel_hi:[0,1,1] neg_lo:[1,0,0] neg_hi:[1,0,0]
	v_pk_fma_f32 v[24:25], v[2:3], v[40:41], v[24:25] op_sel_hi:[0,1,1] neg_lo:[1,0,0] neg_hi:[1,0,0]
	s_waitcnt lgkmcnt(0)
	v_pk_add_f32 v[50:51], v[50:51], v[170:171]
	v_pk_fma_f32 v[22:23], v[2:3], v[38:39], v[22:23] op_sel_hi:[0,1,1] neg_lo:[1,0,0] neg_hi:[1,0,0]
	v_pk_add_f32 v[50:51], v[50:51], v[172:173]
	ds_read2st64_b64 v[170:173], v92 offset0:10 offset1:11
	v_pk_fma_f32 v[20:21], v[2:3], v[36:37], v[20:21] op_sel_hi:[0,1,1] neg_lo:[1,0,0] neg_hi:[1,0,0]
	v_pk_fma_f32 v[18:19], v[2:3], v[34:35], v[18:19] op_sel_hi:[0,1,1] neg_lo:[1,0,0] neg_hi:[1,0,0]
	s_waitcnt lgkmcnt(0)
	v_pk_add_f32 v[50:51], v[50:51], v[170:171]
	v_div_scale_f32 v170, s[44:45], v174, v174, 1.0
	v_rcp_f32_e32 v171, v170
	v_pk_add_f32 v[50:51], v[50:51], v[172:173]
	v_fma_f32 v172, -v170, v171, 1.0
	v_fmac_f32_e32 v171, v172, v171
	v_div_scale_f32 v172, vcc, 1.0, v174, 1.0
	v_mul_f32_e32 v173, v172, v171
	v_fma_f32 v175, -v170, v173, v172
	v_fmac_f32_e32 v173, v175, v171
	v_fma_f32 v170, -v170, v173, v172
	v_div_fmas_f32 v170, v170, v171, v173
	v_div_fixup_f32 v174, v170, v174, 1.0
	v_mul_f32_e32 v170, v58, v174
	v_lshlrev_b32_e32 v171, 16, v121
	v_and_b32_e32 v172, 0xffff0000, v121
	v_fma_f32 v171, v170, v50, -v171
	v_fma_f32 v170, v170, v51, -v172
	v_cvt_pk_bf16_f32 v172, v171, v170
	v_add_co_u32_e32 v170, vcc, s63, v16
	s_nop 1
	v_addc_co_u32_e32 v171, vcc, -1, v17, vcc
	global_store_dword v[170:171], v172, off
	ds_read2st64_b64 v[170:173], v92 offset0:4 offset1:12
	s_waitcnt lgkmcnt(0)
	v_pk_add_f32 v[170:171], v[172:173], v[170:171] neg_lo:[0,1] neg_hi:[0,1]
	s_nop 0
	v_pk_add_f32 v[50:51], v[50:51], v[170:171]
	v_mul_f32_e32 v170, v59, v174
	v_lshlrev_b32_e32 v171, 16, v128
	v_and_b32_e32 v172, 0xffff0000, v128
	v_fma_f32 v171, v170, v50, -v171
	v_fma_f32 v170, v170, v51, -v172
	v_cvt_pk_bf16_f32 v172, v171, v170
	v_add_co_u32_e32 v170, vcc, s47, v16
	s_nop 1
	v_addc_co_u32_e32 v171, vcc, -1, v17, vcc
	global_store_dword v[170:171], v172, off
	ds_read2st64_b64 v[170:173], v92 offset0:5 offset1:13
	s_waitcnt lgkmcnt(0)
	v_pk_add_f32 v[170:171], v[172:173], v[170:171] neg_lo:[0,1] neg_hi:[0,1]
	s_nop 0
	v_pk_add_f32 v[50:51], v[50:51], v[170:171]
	v_mul_f32_e32 v170, v60, v174
	v_lshlrev_b32_e32 v171, 16, v134
	v_and_b32_e32 v172, 0xffff0000, v134
	v_fma_f32 v171, v170, v50, -v171
	v_fma_f32 v170, v170, v51, -v172
	v_cvt_pk_bf16_f32 v172, v171, v170
	v_add_co_u32_e32 v170, vcc, s10, v16
	s_nop 1
	v_addc_co_u32_e32 v171, vcc, -1, v17, vcc
	global_store_dword v[170:171], v172, off
	ds_read2st64_b64 v[170:173], v92 offset0:6 offset1:14
	s_waitcnt lgkmcnt(0)
	v_pk_add_f32 v[170:171], v[172:173], v[170:171] neg_lo:[0,1] neg_hi:[0,1]
	s_nop 0
	v_pk_add_f32 v[50:51], v[50:51], v[170:171]
	v_mul_f32_e32 v170, v61, v174
	v_lshlrev_b32_e32 v171, 16, v141
	v_and_b32_e32 v172, 0xffff0000, v141
	v_fma_f32 v171, v170, v50, -v171
	v_fma_f32 v170, v170, v51, -v172
	v_cvt_pk_bf16_f32 v172, v171, v170
	v_add_co_u32_e32 v170, vcc, s65, v16
	s_nop 1
	v_addc_co_u32_e32 v171, vcc, -1, v17, vcc
	global_store_dword v[170:171], v172, off
	ds_read2st64_b64 v[170:173], v92 offset0:7 offset1:15
	s_waitcnt lgkmcnt(0)
	v_pk_add_f32 v[170:171], v[172:173], v[170:171] neg_lo:[0,1] neg_hi:[0,1]
	s_nop 0
	v_pk_add_f32 v[50:51], v[50:51], v[170:171]
	v_mul_f32_e32 v170, v62, v174
	v_lshlrev_b32_e32 v171, 16, v146
	v_and_b32_e32 v172, 0xffff0000, v146
	v_fma_f32 v171, v170, v50, -v171
	v_fma_f32 v170, v170, v51, -v172
	v_cvt_pk_bf16_f32 v172, v171, v170
	v_add_co_u32_e32 v170, vcc, s66, v16
	s_nop 1
	v_addc_co_u32_e32 v171, vcc, -1, v17, vcc
	global_store_dword v[170:171], v172, off
	ds_read2st64_b64 v[170:173], v92 offset0:8 offset1:16
	s_waitcnt lgkmcnt(0)
	v_pk_add_f32 v[170:171], v[172:173], v[170:171] neg_lo:[0,1] neg_hi:[0,1]
	s_nop 0
	v_pk_add_f32 v[50:51], v[50:51], v[170:171]
	v_mul_f32_e32 v170, v63, v174
	v_lshlrev_b32_e32 v171, 16, v151
	v_and_b32_e32 v172, 0xffff0000, v151
	v_fma_f32 v171, v170, v50, -v171
	v_fma_f32 v170, v170, v51, -v172
	v_cvt_pk_bf16_f32 v172, v171, v170
	v_add_co_u32_e32 v170, vcc, s67, v16
	s_nop 1
	v_addc_co_u32_e32 v171, vcc, -1, v17, vcc
	global_store_dword v[170:171], v172, off
	ds_read2st64_b64 v[170:173], v92 offset0:9 offset1:17
	s_waitcnt lgkmcnt(0)
	v_pk_add_f32 v[170:171], v[172:173], v[170:171] neg_lo:[0,1] neg_hi:[0,1]
	s_nop 0
	v_pk_add_f32 v[50:51], v[50:51], v[170:171]
	v_mul_f32_e32 v170, v64, v174
	v_lshlrev_b32_e32 v171, 16, v155
	v_and_b32_e32 v172, 0xffff0000, v155
	v_fma_f32 v171, v170, v50, -v171
	v_fma_f32 v170, v170, v51, -v172
	v_cvt_pk_bf16_f32 v172, v171, v170
	v_add_co_u32_e32 v170, vcc, s70, v16
	s_nop 1
	v_addc_co_u32_e32 v171, vcc, -1, v17, vcc
	global_store_dword v[170:171], v172, off
	ds_read2st64_b64 v[170:173], v92 offset0:10 offset1:18
	s_waitcnt lgkmcnt(0)
	v_pk_add_f32 v[170:171], v[172:173], v[170:171] neg_lo:[0,1] neg_hi:[0,1]
	s_nop 0
	v_pk_add_f32 v[50:51], v[50:51], v[170:171]
	v_mul_f32_e32 v170, v65, v174
	v_lshlrev_b32_e32 v171, 16, v160
	v_fma_f32 v50, v170, v50, -v171
	v_and_b32_e32 v171, 0xffff0000, v160
	v_fma_f32 v51, v170, v51, -v171
	v_cvt_pk_bf16_f32 v170, v50, v51
	v_add_co_u32_e32 v50, vcc, s71, v16
	s_nop 1
	v_addc_co_u32_e32 v51, vcc, -1, v17, vcc
	global_store_dword v[50:51], v170, off
; #define GAS __attribute__((address_space(1)))
; #define LAS __attribute__((address_space(3)))
; __device__ __forceinline__ unsigned cvt_pk_bf16(float lo, float hi) { unsigned r; asm volatile("v_cvt_pk_bf16_f32 %0, %1, %2" : "=v"(r) : "v"(lo), "v"(hi)); return r; }
; __device__ __forceinline__ float bf_lo(unsigned w) { return __uint_as_float(w << 16); }
; __device__ __forceinline__ float bf_hi(unsigned w) { return __uint_as_float(w & 0xffff0000u); }
; template <int W>
; __device__ __forceinline__ void pool_item(const Ctx& F, const bf16* Ub, bf16* Db, int r0, int nr) {
;     ...
;         for (int u = 0; u < NS; ++u) {
;             const int r = base + u;
;             if (r < re) {
;                 POOL_LOAD((u + 2) % NS, r + 2);
;                 const int e = r + HW - 1;
;                 const float me = (e >= 0 && e < 128) ? 1.0f : 0.0f, ml = (r >= r0 && r - HW >= 0) ? 1.0f : 0.0f;
; #pragma unroll
;                 for (int j = 0; j < 8; ++j) { Vv[j].x += me * bf_lo(ring[u][j]); Vv[j].y += me * bf_hi(ring[u][j]); }
;                 if (r >= r0) {
;                     LAS f32x2* row = buf + ((r & 1) * 80 + 8) * 64 + lane;
; #pragma unroll
;                     for (int j = 0; j < 8; ++j) row[(c0 + j) * 64] = Vv[j];
;                     asm volatile("s_waitcnt lgkmcnt(0)" ::: "memory"); __builtin_amdgcn_s_barrier(); asm volatile("" ::: "memory");
;                     const int rlo = r - HW > 0 ? r - HW : 0, rhi = r + HW < 128 ? r + HW : 128; const float icr = 1.0f / (float)(rhi - rlo);
;                     f32x2 h = (f32x2){0.f, 0.f};
; #pragma unroll
;                     for (int c = -HW; c < HW; ++c) h += row[(c0 + c) * 64];
; #pragma unroll
;                     for (int j = 0; j < 8; ++j) {
;                         const float ic = icr * icc[j]; const unsigned m = ring[(u + NS - HW + 1) % NS][j];
;                         *(GAS unsigned*)(Db + ((size_t)r * 64 + c0 + j) * EI) = cvt_pk_bf16(h.x * ic - bf_lo(m), h.y * ic - bf_hi(m));
;                         h += row[(c0 + j + HW) * 64] - row[(c0 + j - HW) * 64];
;                     }
; #pragma unroll
;                     for (int j = 0; j < 8; ++j) { const unsigned l = ring[(u + NS - W + 1) % NS][j]; Vv[j].x -= ml * bf_lo(l); Vv[j].y -= ml * bf_hi(l); }
;                 }
.LBB0_915:
	s_add_i32 s10, s42, 8
	s_cmp_ge_u32 s10, s46
	s_cbranch_scc1 .LBB0_918
	s_min_i32 s16, s10, 0x7a
	s_add_i32 s16, s16, 5
	s_lshl_b64 s[44:45], s[16:17], 20
	v_lshl_add_u64 v[34:35], v[12:13], 0, s[44:45]
	v_add_co_u32_e32 v36, vcc, 0x4000, v34
	global_load_dword v53, v[34:35], off
	s_nop 0
	v_addc_co_u32_e32 v37, vcc, 0, v35, vcc
	global_load_dword v54, v[36:37], off
	v_add_co_u32_e32 v36, vcc, 0x8000, v34
	s_add_i32 s16, s42, 11
	s_nop 0
	v_addc_co_u32_e32 v37, vcc, 0, v35, vcc
	global_load_dword v55, v[36:37], off
	v_add_co_u32_e32 v36, vcc, 0xc000, v34
	s_cmpk_lt_u32 s16, 0x80
	s_nop 0
	v_addc_co_u32_e32 v37, vcc, 0, v35, vcc
	global_load_dword v56, v[36:37], off
	v_add_co_u32_e32 v36, vcc, 0x10000, v34
	s_cselect_b64 s[44:45], -1, 0
	s_nop 0
	v_addc_co_u32_e32 v37, vcc, 0, v35, vcc
	global_load_dword v57, v[36:37], off
	v_add_co_u32_e32 v36, vcc, 0x14000, v34
	v_cndmask_b32_e64 v2, 0, 1.0, s[44:45]
	s_nop 0
	v_addc_co_u32_e32 v37, vcc, 0, v35, vcc
	global_load_dword v95, v[36:37], off
	v_add_co_u32_e32 v36, vcc, 0x18000, v34
	s_cmp_lt_u32 s10, s62
	s_nop 0
	v_addc_co_u32_e32 v37, vcc, 0, v35, vcc
	v_add_co_u32_e32 v34, vcc, 0x1c000, v34
	global_load_dword v96, v[36:37], off
	s_nop 0
	v_addc_co_u32_e32 v35, vcc, 0, v35, vcc
	global_load_dword v102, v[34:35], off
	s_waitcnt vmcnt(23)
	v_lshlrev_b32_e32 v34, 16, v105
	v_and_b32_e32 v35, 0xffff0000, v105
	v_pk_fma_f32 v[18:19], v[2:3], v[34:35], v[18:19] op_sel_hi:[0,1,1]
	s_waitcnt vmcnt(22)
	v_lshlrev_b32_e32 v34, 16, v108
	v_and_b32_e32 v35, 0xffff0000, v108
	v_pk_fma_f32 v[20:21], v[2:3], v[34:35], v[20:21] op_sel_hi:[0,1,1]
	s_waitcnt vmcnt(21)
	v_lshlrev_b32_e32 v34, 16, v113
	v_and_b32_e32 v35, 0xffff0000, v113
	v_pk_fma_f32 v[22:23], v[2:3], v[34:35], v[22:23] op_sel_hi:[0,1,1]
	s_waitcnt vmcnt(20)
	v_lshlrev_b32_e32 v34, 16, v119
	v_and_b32_e32 v35, 0xffff0000, v119
	v_pk_fma_f32 v[24:25], v[2:3], v[34:35], v[24:25] op_sel_hi:[0,1,1]
	s_waitcnt vmcnt(19)
	v_lshlrev_b32_e32 v34, 16, v125
	v_and_b32_e32 v35, 0xffff0000, v125
	v_pk_fma_f32 v[26:27], v[2:3], v[34:35], v[26:27] op_sel_hi:[0,1,1]
	s_waitcnt vmcnt(18)
	v_lshlrev_b32_e32 v34, 16, v133
	v_and_b32_e32 v35, 0xffff0000, v133
	v_pk_fma_f32 v[28:29], v[2:3], v[34:35], v[28:29] op_sel_hi:[0,1,1]
	s_waitcnt vmcnt(17)
	v_lshlrev_b32_e32 v34, 16, v139
	v_and_b32_e32 v35, 0xffff0000, v139
	v_pk_fma_f32 v[30:31], v[2:3], v[34:35], v[30:31] op_sel_hi:[0,1,1]
	s_waitcnt vmcnt(16)
	v_lshlrev_b32_e32 v34, 16, v154
	v_and_b32_e32 v35, 0xffff0000, v154
	v_pk_fma_f32 v[32:33], v[2:3], v[34:35], v[32:33] op_sel_hi:[0,1,1]
	s_cbranch_scc1 .LBB0_918
	ds_write2st64_b64 v92, v[18:19], v[20:21] offset0:88 offset1:89
	ds_write2st64_b64 v92, v[22:23], v[24:25] offset0:90 offset1:91
	ds_write2st64_b64 v92, v[26:27], v[28:29] offset0:92 offset1:93
	ds_write2st64_b64 v92, v[30:31], v[32:33] offset0:94 offset1:95
	s_waitcnt lgkmcnt(0)
	s_barrier
	ds_read2st64_b64 v[34:37], v92 offset0:84 offset1:85
	s_cmp_gt_u32 s10, 3
	s_cselect_b64 s[44:45], -1, 0
	s_max_i32 s16, s10, 4
	s_min_i32 s10, s10, 0x7c
	s_waitcnt lgkmcnt(0)
	v_pk_add_f32 v[34:35], v[34:35], 0 op_sel_hi:[1,0]
	s_sub_i32 s10, s10, s16
	v_pk_add_f32 v[38:39], v[34:35], v[36:37]
	ds_read2st64_b64 v[34:37], v92 offset0:86 offset1:87
	s_add_i32 s10, s10, 8
	v_cvt_f32_i32_e32 v40, s10
	v_cndmask_b32_e64 v2, 0, 1.0, s[44:45]
	s_waitcnt lgkmcnt(0)
	v_pk_add_f32 v[34:35], v[38:39], v[34:35]
	s_nop 0
	v_pk_add_f32 v[38:39], v[34:35], v[36:37]
	ds_read2st64_b64 v[34:37], v92 offset0:88 offset1:89
	s_waitcnt lgkmcnt(0)
	v_pk_add_f32 v[34:35], v[38:39], v[34:35]
	s_nop 0
	v_pk_add_f32 v[38:39], v[34:35], v[36:37]
	ds_read2st64_b64 v[34:37], v92 offset0:90 offset1:91
	s_waitcnt lgkmcnt(0)
	v_pk_add_f32 v[34:35], v[38:39], v[34:35]
	s_nop 0
	v_pk_add_f32 v[38:39], v[34:35], v[36:37]
	v_div_scale_f32 v34, s[44:45], v40, v40, 1.0
	v_rcp_f32_e32 v35, v34
	s_nop 0
	v_fma_f32 v36, -v34, v35, 1.0
	v_fmac_f32_e32 v35, v36, v35
	v_div_scale_f32 v36, vcc, 1.0, v40, 1.0
	v_mul_f32_e32 v37, v36, v35
	v_fma_f32 v41, -v34, v37, v36
	v_fmac_f32_e32 v37, v41, v35
	v_fma_f32 v34, -v34, v37, v36
	v_div_fmas_f32 v34, v34, v35, v37
	v_div_fixup_f32 v40, v34, v40, 1.0
	v_mul_f32_e32 v34, v58, v40
	v_lshlrev_b32_e32 v35, 16, v116
	v_and_b32_e32 v36, 0xffff0000, v116
	v_fma_f32 v35, v34, v38, -v35
	v_fma_f32 v34, v34, v39, -v36
	v_cvt_pk_bf16_f32 v36, v35, v34
	v_add_co_u32_e32 v34, vcc, s72, v16
	s_nop 1
	v_addc_co_u32_e32 v35, vcc, -1, v17, vcc
	global_store_dword v[34:35], v36, off
	ds_read2st64_b64 v[34:37], v92 offset0:84 offset1:92
	s_waitcnt lgkmcnt(0)
	v_pk_add_f32 v[34:35], v[36:37], v[34:35] neg_lo:[0,1] neg_hi:[0,1]
	s_nop 0
	v_pk_add_f32 v[38:39], v[38:39], v[34:35]
	v_mul_f32_e32 v34, v59, v40
	v_lshlrev_b32_e32 v35, 16, v122
	v_and_b32_e32 v36, 0xffff0000, v122
	v_fma_f32 v35, v34, v38, -v35
	v_fma_f32 v34, v34, v39, -v36
	v_cvt_pk_bf16_f32 v36, v35, v34
	v_add_co_u32_e32 v34, vcc, s73, v16
	s_nop 1
	v_addc_co_u32_e32 v35, vcc, -1, v17, vcc
	global_store_dword v[34:35], v36, off
	ds_read2st64_b64 v[34:37], v92 offset0:85 offset1:93
	s_waitcnt lgkmcnt(0)
	v_pk_add_f32 v[34:35], v[36:37], v[34:35] neg_lo:[0,1] neg_hi:[0,1]
	s_nop 0
	v_pk_add_f32 v[38:39], v[38:39], v[34:35]
	v_mul_f32_e32 v34, v60, v40
	v_lshlrev_b32_e32 v35, 16, v129
	v_and_b32_e32 v36, 0xffff0000, v129
	v_fma_f32 v35, v34, v38, -v35
	v_fma_f32 v34, v34, v39, -v36
	v_cvt_pk_bf16_f32 v36, v35, v34
	v_add_co_u32_e32 v34, vcc, s74, v16
	s_nop 1
	v_addc_co_u32_e32 v35, vcc, -1, v17, vcc
	global_store_dword v[34:35], v36, off
	ds_read2st64_b64 v[34:37], v92 offset0:86 offset1:94
	s_waitcnt lgkmcnt(0)
; #define GAS __attribute__((address_space(1)))
; #define LAS __attribute__((address_space(3)))
; __device__ __forceinline__ unsigned cvt_pk_bf16(float lo, float hi) { unsigned r; asm volatile("v_cvt_pk_bf16_f32 %0, %1, %2" : "=v"(r) : "v"(lo), "v"(hi)); return r; }
; __device__ __forceinline__ float bf_lo(unsigned w) { return __uint_as_float(w << 16); }
; __device__ __forceinline__ float bf_hi(unsigned w) { return __uint_as_float(w & 0xffff0000u); }
; template <int W>
; __device__ __forceinline__ void pool_item(const Ctx& F, const bf16* Ub, bf16* Db, int r0, int nr) {
;     ...
;         for (int u = 0; u < NS; ++u) {
;             const int r = base + u;
;             if (r < re) {
;                 POOL_LOAD((u + 2) % NS, r + 2);
;                 const int e = r + HW - 1;
;                 const float me = (e >= 0 && e < 128) ? 1.0f : 0.0f, ml = (r >= r0 && r - HW >= 0) ? 1.0f : 0.0f;
; #pragma unroll
;                 for (int j = 0; j < 8; ++j) { Vv[j].x += me * bf_lo(ring[u][j]); Vv[j].y += me * bf_hi(ring[u][j]); }
;                 if (r >= r0) {
;                     LAS f32x2* row = buf + ((r & 1) * 80 + 8) * 64 + lane;
; #pragma unroll
;                     for (int j = 0; j < 8; ++j) row[(c0 + j) * 64] = Vv[j];
;                     asm volatile("s_waitcnt lgkmcnt(0)" ::: "memory"); __builtin_amdgcn_s_barrier(); asm volatile("" ::: "memory");
;                     const int rlo = r - HW > 0 ? r - HW : 0, rhi = r + HW < 128 ? r + HW : 128; const float icr = 1.0f / (float)(rhi - rlo);
;                     f32x2 h = (f32x2){0.f, 0.f};
; #pragma unroll
;                     for (int c = -HW; c < HW; ++c) h += row[(c0 + c) * 64];
; #pragma unroll
;                     for (int j = 0; j < 8; ++j) {
;                         const float ic = icr * icc[j]; const unsigned m = ring[(u + NS - HW + 1) % NS][j];
;                         *(GAS unsigned*)(Db + ((size_t)r * 64 + c0 + j) * EI) = cvt_pk_bf16(h.x * ic - bf_lo(m), h.y * ic - bf_hi(m));
;                         h += row[(c0 + j + HW) * 64] - row[(c0 + j - HW) * 64];
;                     }
; #pragma unroll
;                     for (int j = 0; j < 8; ++j) { const unsigned l = ring[(u + NS - W + 1) % NS][j]; Vv[j].x -= ml * bf_lo(l); Vv[j].y -= ml * bf_hi(l); }
;                 }
	v_pk_add_f32 v[34:35], v[36:37], v[34:35] neg_lo:[0,1] neg_hi:[0,1]
	s_nop 0
	v_pk_add_f32 v[38:39], v[38:39], v[34:35]
	v_mul_f32_e32 v34, v61, v40
	v_lshlrev_b32_e32 v35, 16, v135
	v_and_b32_e32 v36, 0xffff0000, v135
	v_fma_f32 v35, v34, v38, -v35
	v_fma_f32 v34, v34, v39, -v36
	v_cvt_pk_bf16_f32 v36, v35, v34
	v_add_co_u32_e32 v34, vcc, s75, v16
	s_nop 1
	v_addc_co_u32_e32 v35, vcc, -1, v17, vcc
	global_store_dword v[34:35], v36, off
	ds_read2st64_b64 v[34:37], v92 offset0:87 offset1:95
	s_waitcnt lgkmcnt(0)
	v_pk_add_f32 v[34:35], v[36:37], v[34:35] neg_lo:[0,1] neg_hi:[0,1]
	s_nop 0
	v_pk_add_f32 v[38:39], v[38:39], v[34:35]
	v_mul_f32_e32 v34, v62, v40
	v_lshlrev_b32_e32 v35, 16, v142
	v_and_b32_e32 v36, 0xffff0000, v142
	v_fma_f32 v35, v34, v38, -v35
	v_fma_f32 v34, v34, v39, -v36
	v_cvt_pk_bf16_f32 v36, v35, v34
	v_add_co_u32_e32 v34, vcc, s76, v16
	s_nop 1
	v_addc_co_u32_e32 v35, vcc, -1, v17, vcc
	global_store_dword v[34:35], v36, off
	ds_read2st64_b64 v[34:37], v92 offset0:88 offset1:96
	s_waitcnt lgkmcnt(0)
	v_pk_add_f32 v[34:35], v[36:37], v[34:35] neg_lo:[0,1] neg_hi:[0,1]
	s_nop 0
	v_pk_add_f32 v[38:39], v[38:39], v[34:35]
	v_mul_f32_e32 v34, v63, v40
	v_lshlrev_b32_e32 v35, 16, v147
	v_and_b32_e32 v36, 0xffff0000, v147
	v_fma_f32 v35, v34, v38, -v35
	v_fma_f32 v34, v34, v39, -v36
	v_cvt_pk_bf16_f32 v36, v35, v34
	v_add_co_u32_e32 v34, vcc, s77, v16
	s_nop 1
	v_addc_co_u32_e32 v35, vcc, -1, v17, vcc
	global_store_dword v[34:35], v36, off
	ds_read2st64_b64 v[34:37], v92 offset0:89 offset1:97
	s_waitcnt lgkmcnt(0)
	v_pk_add_f32 v[34:35], v[36:37], v[34:35] neg_lo:[0,1] neg_hi:[0,1]
	s_nop 0
	v_pk_add_f32 v[38:39], v[38:39], v[34:35]
	v_mul_f32_e32 v34, v64, v40
	v_lshlrev_b32_e32 v35, 16, v152
	v_and_b32_e32 v36, 0xffff0000, v152
	v_fma_f32 v35, v34, v38, -v35
	v_fma_f32 v34, v34, v39, -v36
	v_cvt_pk_bf16_f32 v36, v35, v34
	v_add_co_u32_e32 v34, vcc, s78, v16
	s_nop 1
	v_addc_co_u32_e32 v35, vcc, -1, v17, vcc
	global_store_dword v[34:35], v36, off
	ds_read2st64_b64 v[34:37], v92 offset0:90 offset1:98
	s_waitcnt lgkmcnt(0)
	v_pk_add_f32 v[34:35], v[36:37], v[34:35] neg_lo:[0,1] neg_hi:[0,1]
	s_nop 0
	v_pk_add_f32 v[34:35], v[38:39], v[34:35]
	v_mul_f32_e32 v36, v65, v40
	v_lshlrev_b32_e32 v37, 16, v159
	v_fma_f32 v34, v36, v34, -v37
	v_and_b32_e32 v37, 0xffff0000, v159
	v_fma_f32 v35, v36, v35, -v37
	v_cvt_pk_bf16_f32 v36, v34, v35
	v_add_co_u32_e32 v34, vcc, s79, v16
	s_nop 1
	v_addc_co_u32_e32 v35, vcc, -1, v17, vcc
	global_store_dword v[34:35], v36, off
	v_lshlrev_b32_e32 v34, 16, v97
	v_and_b32_e32 v35, 0xffff0000, v97
	v_pk_fma_f32 v[18:19], v[2:3], v[34:35], v[18:19] op_sel_hi:[0,1,1] neg_lo:[1,0,0] neg_hi:[1,0,0]
	v_lshlrev_b32_e32 v34, 16, v98
	v_and_b32_e32 v35, 0xffff0000, v98
	v_pk_fma_f32 v[20:21], v[2:3], v[34:35], v[20:21] op_sel_hi:[0,1,1] neg_lo:[1,0,0] neg_hi:[1,0,0]
	v_lshlrev_b32_e32 v34, 16, v99
	v_and_b32_e32 v35, 0xffff0000, v99
	v_pk_fma_f32 v[22:23], v[2:3], v[34:35], v[22:23] op_sel_hi:[0,1,1] neg_lo:[1,0,0] neg_hi:[1,0,0]
	v_lshlrev_b32_e32 v34, 16, v100
	v_and_b32_e32 v35, 0xffff0000, v100
	v_pk_fma_f32 v[24:25], v[2:3], v[34:35], v[24:25] op_sel_hi:[0,1,1] neg_lo:[1,0,0] neg_hi:[1,0,0]
	v_lshlrev_b32_e32 v34, 16, v104
	v_and_b32_e32 v35, 0xffff0000, v104
	v_pk_fma_f32 v[26:27], v[2:3], v[34:35], v[26:27] op_sel_hi:[0,1,1] neg_lo:[1,0,0] neg_hi:[1,0,0]
	v_lshlrev_b32_e32 v34, 16, v109
	v_and_b32_e32 v35, 0xffff0000, v109
	v_pk_fma_f32 v[28:29], v[2:3], v[34:35], v[28:29] op_sel_hi:[0,1,1] neg_lo:[1,0,0] neg_hi:[1,0,0]
	v_lshlrev_b32_e32 v34, 16, v114
	v_and_b32_e32 v35, 0xffff0000, v114
	v_pk_fma_f32 v[30:31], v[2:3], v[34:35], v[30:31] op_sel_hi:[0,1,1] neg_lo:[1,0,0] neg_hi:[1,0,0]
	v_lshlrev_b32_e32 v34, 16, v140
	v_and_b32_e32 v35, 0xffff0000, v140
	v_pk_fma_f32 v[32:33], v[2:3], v[34:35], v[32:33] op_sel_hi:[0,1,1] neg_lo:[1,0,0] neg_hi:[1,0,0]
.LBB0_918:
	s_add_i32 s10, s42, 9
	s_cmp_ge_u32 s10, s46
	s_cbranch_scc1 .LBB0_891
	s_min_i32 s16, s10, 0x7a
	s_add_i32 s16, s16, 5
	s_lshl_b64 s[44:45], s[16:17], 20
	v_lshl_add_u64 v[34:35], v[12:13], 0, s[44:45]
	v_add_co_u32_e32 v36, vcc, 0x4000, v34
	global_load_dword v97, v[34:35], off
	s_nop 0
	v_addc_co_u32_e32 v37, vcc, 0, v35, vcc
	global_load_dword v98, v[36:37], off
	v_add_co_u32_e32 v36, vcc, 0x8000, v34
	s_add_i32 s16, s42, 12
	s_nop 0
	v_addc_co_u32_e32 v37, vcc, 0, v35, vcc
	global_load_dword v99, v[36:37], off
	v_add_co_u32_e32 v36, vcc, 0xc000, v34
	s_cmpk_lt_u32 s16, 0x80
	s_nop 0
	v_addc_co_u32_e32 v37, vcc, 0, v35, vcc
	global_load_dword v100, v[36:37], off
	v_add_co_u32_e32 v36, vcc, 0x10000, v34
	s_cselect_b64 s[44:45], -1, 0
	s_nop 0
	v_addc_co_u32_e32 v37, vcc, 0, v35, vcc
	global_load_dword v104, v[36:37], off
	v_add_co_u32_e32 v36, vcc, 0x14000, v34
	v_cndmask_b32_e64 v2, 0, 1.0, s[44:45]
	s_nop 0
	v_addc_co_u32_e32 v37, vcc, 0, v35, vcc
	global_load_dword v109, v[36:37], off
	v_add_co_u32_e32 v36, vcc, 0x18000, v34
	s_cmp_lt_u32 s10, s62
	s_nop 0
	v_addc_co_u32_e32 v37, vcc, 0, v35, vcc
	v_add_co_u32_e32 v34, vcc, 0x1c000, v34
	global_load_dword v114, v[36:37], off
	s_nop 0
	v_addc_co_u32_e32 v35, vcc, 0, v35, vcc
	global_load_dword v140, v[34:35], off
	s_waitcnt vmcnt(23)
	v_lshlrev_b32_e32 v34, 16, v101
	v_and_b32_e32 v35, 0xffff0000, v101
	v_pk_fma_f32 v[18:19], v[2:3], v[34:35], v[18:19] op_sel_hi:[0,1,1]
	s_waitcnt vmcnt(22)
	v_lshlrev_b32_e32 v34, 16, v103
	v_and_b32_e32 v35, 0xffff0000, v103
	v_pk_fma_f32 v[20:21], v[2:3], v[34:35], v[20:21] op_sel_hi:[0,1,1]
	s_waitcnt vmcnt(21)
	v_lshlrev_b32_e32 v34, 16, v106
	v_and_b32_e32 v35, 0xffff0000, v106
	v_pk_fma_f32 v[22:23], v[2:3], v[34:35], v[22:23] op_sel_hi:[0,1,1]
	s_waitcnt vmcnt(20)
	v_lshlrev_b32_e32 v34, 16, v110
	v_and_b32_e32 v35, 0xffff0000, v110
	v_pk_fma_f32 v[24:25], v[2:3], v[34:35], v[24:25] op_sel_hi:[0,1,1]
	s_waitcnt vmcnt(19)
	v_lshlrev_b32_e32 v34, 16, v115
	v_and_b32_e32 v35, 0xffff0000, v115
	v_pk_fma_f32 v[26:27], v[2:3], v[34:35], v[26:27] op_sel_hi:[0,1,1]
	s_waitcnt vmcnt(18)
	v_lshlrev_b32_e32 v34, 16, v120
	v_and_b32_e32 v35, 0xffff0000, v120
	v_pk_fma_f32 v[28:29], v[2:3], v[34:35], v[28:29] op_sel_hi:[0,1,1]
	s_waitcnt vmcnt(17)
	v_lshlrev_b32_e32 v34, 16, v127
	v_and_b32_e32 v35, 0xffff0000, v127
	v_pk_fma_f32 v[30:31], v[2:3], v[34:35], v[30:31] op_sel_hi:[0,1,1]
	s_waitcnt vmcnt(16)
	v_lshlrev_b32_e32 v34, 16, v150
	v_and_b32_e32 v35, 0xffff0000, v150
	v_pk_fma_f32 v[32:33], v[2:3], v[34:35], v[32:33] op_sel_hi:[0,1,1]
	s_cbranch_scc1 .LBB0_891
; #define GAS __attribute__((address_space(1)))
; #define LAS __attribute__((address_space(3)))
; __device__ __forceinline__ unsigned cvt_pk_bf16(float lo, float hi) { unsigned r; asm volatile("v_cvt_pk_bf16_f32 %0, %1, %2" : "=v"(r) : "v"(lo), "v"(hi)); return r; }
; __device__ __forceinline__ float bf_lo(unsigned w) { return __uint_as_float(w << 16); }
; __device__ __forceinline__ float bf_hi(unsigned w) { return __uint_as_float(w & 0xffff0000u); }
; template <int W>
; __device__ __forceinline__ void pool_item(const Ctx& F, const bf16* Ub, bf16* Db, int r0, int nr) {
;     ...
;                 if (r >= r0) {
;                     LAS f32x2* row = buf + ((r & 1) * 80 + 8) * 64 + lane;
; #pragma unroll
;                     for (int j = 0; j < 8; ++j) row[(c0 + j) * 64] = Vv[j];
;                     asm volatile("s_waitcnt lgkmcnt(0)" ::: "memory"); __builtin_amdgcn_s_barrier(); asm volatile("" ::: "memory");
;                     const int rlo = r - HW > 0 ? r - HW : 0, rhi = r + HW < 128 ? r + HW : 128; const float icr = 1.0f / (float)(rhi - rlo);
;                     f32x2 h = (f32x2){0.f, 0.f};
; #pragma unroll
;                     for (int c = -HW; c < HW; ++c) h += row[(c0 + c) * 64];
; #pragma unroll
;                     for (int j = 0; j < 8; ++j) {
;                         const float ic = icr * icc[j]; const unsigned m = ring[(u + NS - HW + 1) % NS][j];
;                         *(GAS unsigned*)(Db + ((size_t)r * 64 + c0 + j) * EI) = cvt_pk_bf16(h.x * ic - bf_lo(m), h.y * ic - bf_hi(m));
;                         h += row[(c0 + j + HW) * 64] - row[(c0 + j - HW) * 64];
;                     }
; #pragma unroll
;                     for (int j = 0; j < 8; ++j) { const unsigned l = ring[(u + NS - W + 1) % NS][j]; Vv[j].x -= ml * bf_lo(l); Vv[j].y -= ml * bf_hi(l); }
;                 }
	ds_write2st64_b64 v92, v[18:19], v[20:21] offset0:8 offset1:9
	ds_write2st64_b64 v92, v[22:23], v[24:25] offset0:10 offset1:11
	ds_write2st64_b64 v92, v[26:27], v[28:29] offset0:12 offset1:13
	ds_write2st64_b64 v92, v[30:31], v[32:33] offset0:14 offset1:15
	s_waitcnt lgkmcnt(0)
	s_barrier
	ds_read2st64_b64 v[34:37], v92 offset0:4 offset1:5
	s_cmp_gt_u32 s10, 3
	s_cselect_b64 s[44:45], -1, 0
	s_max_i32 s16, s10, 4
	s_min_i32 s10, s10, 0x7c
	s_waitcnt lgkmcnt(0)
	v_pk_add_f32 v[34:35], v[34:35], 0 op_sel_hi:[1,0]
	s_sub_i32 s10, s10, s16
	v_pk_add_f32 v[38:39], v[34:35], v[36:37]
	ds_read2st64_b64 v[34:37], v92 offset0:6 offset1:7
	s_add_i32 s10, s10, 8
	v_cvt_f32_i32_e32 v40, s10
	v_cndmask_b32_e64 v2, 0, 1.0, s[44:45]
	s_waitcnt lgkmcnt(0)
	v_pk_add_f32 v[34:35], v[38:39], v[34:35]
	s_nop 0
	v_pk_add_f32 v[38:39], v[34:35], v[36:37]
	ds_read2st64_b64 v[34:37], v92 offset0:8 offset1:9
	s_waitcnt lgkmcnt(0)
	v_pk_add_f32 v[34:35], v[38:39], v[34:35]
	s_nop 0
	v_pk_add_f32 v[38:39], v[34:35], v[36:37]
	ds_read2st64_b64 v[34:37], v92 offset0:10 offset1:11
	s_waitcnt lgkmcnt(0)
	v_pk_add_f32 v[34:35], v[38:39], v[34:35]
	s_nop 0
	v_pk_add_f32 v[38:39], v[34:35], v[36:37]
	v_div_scale_f32 v34, s[44:45], v40, v40, 1.0
	v_rcp_f32_e32 v35, v34
	s_nop 0
	v_fma_f32 v36, -v34, v35, 1.0
	v_fmac_f32_e32 v35, v36, v35
	v_div_scale_f32 v36, vcc, 1.0, v40, 1.0
	v_mul_f32_e32 v37, v36, v35
	v_fma_f32 v41, -v34, v37, v36
	v_fmac_f32_e32 v37, v41, v35
	v_fma_f32 v34, -v34, v37, v36
	v_div_fmas_f32 v34, v34, v35, v37
	v_div_fixup_f32 v40, v34, v40, 1.0
	v_mul_f32_e32 v34, v58, v40
	v_lshlrev_b32_e32 v35, 16, v111
	v_and_b32_e32 v36, 0xffff0000, v111
	v_fma_f32 v35, v34, v38, -v35
	v_fma_f32 v34, v34, v39, -v36
	v_cvt_pk_bf16_f32 v36, v35, v34
	v_add_co_u32_e32 v34, vcc, s80, v16
	s_nop 1
	v_addc_co_u32_e32 v35, vcc, -1, v17, vcc
	global_store_dword v[34:35], v36, off
	ds_read2st64_b64 v[34:37], v92 offset0:4 offset1:12
	s_waitcnt lgkmcnt(0)
	v_pk_add_f32 v[34:35], v[36:37], v[34:35] neg_lo:[0,1] neg_hi:[0,1]
	s_nop 0
	v_pk_add_f32 v[38:39], v[38:39], v[34:35]
	v_mul_f32_e32 v34, v59, v40
	v_lshlrev_b32_e32 v35, 16, v117
	v_and_b32_e32 v36, 0xffff0000, v117
	v_fma_f32 v35, v34, v38, -v35
	v_fma_f32 v34, v34, v39, -v36
	v_cvt_pk_bf16_f32 v36, v35, v34
	v_add_co_u32_e32 v34, vcc, s81, v16
	s_nop 1
	v_addc_co_u32_e32 v35, vcc, -1, v17, vcc
	global_store_dword v[34:35], v36, off
	ds_read2st64_b64 v[34:37], v92 offset0:5 offset1:13
	s_waitcnt lgkmcnt(0)
	v_pk_add_f32 v[34:35], v[36:37], v[34:35] neg_lo:[0,1] neg_hi:[0,1]
	s_nop 0
	v_pk_add_f32 v[38:39], v[38:39], v[34:35]
	v_mul_f32_e32 v34, v60, v40
	v_lshlrev_b32_e32 v35, 16, v123
	v_and_b32_e32 v36, 0xffff0000, v123
	v_fma_f32 v35, v34, v38, -v35
	v_fma_f32 v34, v34, v39, -v36
	v_cvt_pk_bf16_f32 v36, v35, v34
	v_add_co_u32_e32 v34, vcc, s82, v16
	s_nop 1
	v_addc_co_u32_e32 v35, vcc, -1, v17, vcc
	global_store_dword v[34:35], v36, off
	ds_read2st64_b64 v[34:37], v92 offset0:6 offset1:14
	s_waitcnt lgkmcnt(0)
	v_pk_add_f32 v[34:35], v[36:37], v[34:35] neg_lo:[0,1] neg_hi:[0,1]
	s_nop 0
	v_pk_add_f32 v[38:39], v[38:39], v[34:35]
	v_mul_f32_e32 v34, v61, v40
	v_lshlrev_b32_e32 v35, 16, v130
	v_and_b32_e32 v36, 0xffff0000, v130
	v_fma_f32 v35, v34, v38, -v35
	v_fma_f32 v34, v34, v39, -v36
	v_cvt_pk_bf16_f32 v36, v35, v34
	v_add_co_u32_e32 v34, vcc, s61, v16
	s_nop 1
	v_addc_co_u32_e32 v35, vcc, -1, v17, vcc
	global_store_dword v[34:35], v36, off
	ds_read2st64_b64 v[34:37], v92 offset0:7 offset1:15
	s_waitcnt lgkmcnt(0)
	v_pk_add_f32 v[34:35], v[36:37], v[34:35] neg_lo:[0,1] neg_hi:[0,1]
	s_nop 0
	v_pk_add_f32 v[38:39], v[38:39], v[34:35]
	v_mul_f32_e32 v34, v62, v40
	v_lshlrev_b32_e32 v35, 16, v136
	v_and_b32_e32 v36, 0xffff0000, v136
	v_fma_f32 v35, v34, v38, -v35
	v_fma_f32 v34, v34, v39, -v36
	v_cvt_pk_bf16_f32 v36, v35, v34
	v_add_co_u32_e32 v34, vcc, s83, v16
	s_nop 1
	v_addc_co_u32_e32 v35, vcc, -1, v17, vcc
	global_store_dword v[34:35], v36, off
	ds_read2st64_b64 v[34:37], v92 offset0:8 offset1:16
	s_waitcnt lgkmcnt(0)
	v_pk_add_f32 v[34:35], v[36:37], v[34:35] neg_lo:[0,1] neg_hi:[0,1]
	s_nop 0
	v_pk_add_f32 v[38:39], v[38:39], v[34:35]
	v_mul_f32_e32 v34, v63, v40
	v_lshlrev_b32_e32 v35, 16, v143
	v_and_b32_e32 v36, 0xffff0000, v143
	v_fma_f32 v35, v34, v38, -v35
	v_fma_f32 v34, v34, v39, -v36
	v_cvt_pk_bf16_f32 v36, v35, v34
	v_add_co_u32_e32 v34, vcc, s84, v16
	s_nop 1
	v_addc_co_u32_e32 v35, vcc, -1, v17, vcc
	global_store_dword v[34:35], v36, off
	ds_read2st64_b64 v[34:37], v92 offset0:9 offset1:17
	s_waitcnt lgkmcnt(0)
	v_pk_add_f32 v[34:35], v[36:37], v[34:35] neg_lo:[0,1] neg_hi:[0,1]
	s_nop 0
	v_pk_add_f32 v[38:39], v[38:39], v[34:35]
	v_mul_f32_e32 v34, v64, v40
	v_lshlrev_b32_e32 v35, 16, v148
	v_and_b32_e32 v36, 0xffff0000, v148
	v_fma_f32 v35, v34, v38, -v35
	v_fma_f32 v34, v34, v39, -v36
	v_cvt_pk_bf16_f32 v36, v35, v34
	v_add_co_u32_e32 v34, vcc, s85, v16
	s_nop 1
	v_addc_co_u32_e32 v35, vcc, -1, v17, vcc
	global_store_dword v[34:35], v36, off
	ds_read2st64_b64 v[34:37], v92 offset0:10 offset1:18
	s_waitcnt lgkmcnt(0)
	v_pk_add_f32 v[34:35], v[36:37], v[34:35] neg_lo:[0,1] neg_hi:[0,1]
	s_nop 0
	v_pk_add_f32 v[34:35], v[38:39], v[34:35]
	v_mul_f32_e32 v36, v65, v40
	v_lshlrev_b32_e32 v37, 16, v158
	v_fma_f32 v34, v36, v34, -v37
	v_and_b32_e32 v37, 0xffff0000, v158
	v_fma_f32 v35, v36, v35, -v37
	v_cvt_pk_bf16_f32 v34, v34, v35
	global_store_dword v[16:17], v34, off
	v_lshlrev_b32_e32 v34, 16, v169
	v_and_b32_e32 v35, 0xffff0000, v169
	v_pk_fma_f32 v[18:19], v[2:3], v[34:35], v[18:19] op_sel_hi:[0,1,1] neg_lo:[1,0,0] neg_hi:[1,0,0]
	v_lshlrev_b32_e32 v34, 16, v168
	v_and_b32_e32 v35, 0xffff0000, v168
	v_pk_fma_f32 v[20:21], v[2:3], v[34:35], v[20:21] op_sel_hi:[0,1,1] neg_lo:[1,0,0] neg_hi:[1,0,0]
	v_lshlrev_b32_e32 v34, 16, v167
	v_and_b32_e32 v35, 0xffff0000, v167
	v_pk_fma_f32 v[22:23], v[2:3], v[34:35], v[22:23] op_sel_hi:[0,1,1] neg_lo:[1,0,0] neg_hi:[1,0,0]
	v_lshlrev_b32_e32 v34, 16, v166
	v_and_b32_e32 v35, 0xffff0000, v166
	v_pk_fma_f32 v[24:25], v[2:3], v[34:35], v[24:25] op_sel_hi:[0,1,1] neg_lo:[1,0,0] neg_hi:[1,0,0]
	v_lshlrev_b32_e32 v34, 16, v165
	v_and_b32_e32 v35, 0xffff0000, v165
	v_pk_fma_f32 v[26:27], v[2:3], v[34:35], v[26:27] op_sel_hi:[0,1,1] neg_lo:[1,0,0] neg_hi:[1,0,0]
	v_lshlrev_b32_e32 v34, 16, v164
	v_and_b32_e32 v35, 0xffff0000, v164
	v_pk_fma_f32 v[28:29], v[2:3], v[34:35], v[28:29] op_sel_hi:[0,1,1] neg_lo:[1,0,0] neg_hi:[1,0,0]
	v_lshlrev_b32_e32 v34, 16, v163
	v_and_b32_e32 v35, 0xffff0000, v163
	v_pk_fma_f32 v[30:31], v[2:3], v[34:35], v[30:31] op_sel_hi:[0,1,1] neg_lo:[1,0,0] neg_hi:[1,0,0]
	v_lshlrev_b32_e32 v34, 16, v162
	v_and_b32_e32 v35, 0xffff0000, v162
	v_pk_fma_f32 v[32:33], v[2:3], v[34:35], v[32:33] op_sel_hi:[0,1,1] neg_lo:[1,0,0] neg_hi:[1,0,0]
	s_branch .LBB0_891

; __device__ __forceinline__ float bf_lo(unsigned w) { return __uint_as_float(w << 16); }
; __device__ __forceinline__ float bf_hi(unsigned w) { return __uint_as_float(w & 0xffff0000u); }
; #define POOL_LOAD(slot_, r_) do { int e_ = (r_) + HW - 1; e_ = e_ < 0 ? 0 : (e_ > 127 ? 127 : e_); \
;         _Pragma("unroll") for (int j = 0; j < 8; ++j) ring[slot_][j] = *(const GAS unsigned*)(Ub + ((size_t)e_ * 64 + c0 + j) * EI); } while (0)
; template <int W>
; __device__ __forceinline__ void pool_item(const Ctx& F, const bf16* Ub, bf16* Db, int r0, int nr) {
;     ...
;     POOL_LOAD(0, rs); POOL_LOAD(1, rs + 1);
;     __syncthreads();
;     for (int base = rs; base < re; base += NS) {
; #pragma unroll
;         for (int u = 0; u < NS; ++u) {
;             const int r = base + u;
;             if (r < re) {
;                 POOL_LOAD((u + 2) % NS, r + 2);
;                 const int e = r + HW - 1;
;                 const float me = (e >= 0 && e < 128) ? 1.0f : 0.0f, ml = (r >= r0 && r - HW >= 0) ? 1.0f : 0.0f;
; #pragma unroll
;                 for (int j = 0; j < 8; ++j) { Vv[j].x += me * bf_lo(ring[u][j]); Vv[j].y += me * bf_hi(ring[u][j]); }
.LBB0_929:
	s_min_i32 s46, s42, 0x7c
	s_ashr_i32 s47, s46, 31
	s_lshl_b64 s[46:47], s[46:47], 20
	v_lshl_add_u64 v[32:33], v[12:13], 0, s[46:47]
	s_mov_b32 s16, 0x300000
	v_add_co_u32_e32 v34, vcc, s16, v32
	s_mov_b32 s16, 0x304000
	s_nop 0
	v_addc_co_u32_e32 v35, vcc, 0, v33, vcc
	v_add_co_u32_e32 v36, vcc, s16, v32
	s_mov_b32 s16, 0x308000
	s_nop 0
	v_addc_co_u32_e32 v37, vcc, 0, v33, vcc
	v_add_co_u32_e32 v38, vcc, s16, v32
	s_mov_b32 s16, 0x30c000
	s_nop 0
	v_addc_co_u32_e32 v39, vcc, 0, v33, vcc
	v_add_co_u32_e32 v40, vcc, s16, v32
	s_mov_b32 s16, 0x310000
	s_nop 0
	v_addc_co_u32_e32 v41, vcc, 0, v33, vcc
	v_add_co_u32_e32 v42, vcc, s16, v32
	s_mov_b32 s16, 0x314000
	s_nop 0
	v_addc_co_u32_e32 v43, vcc, 0, v33, vcc
	v_add_co_u32_e32 v44, vcc, s16, v32
	s_mov_b32 s16, 0x318000
	s_nop 0
	v_addc_co_u32_e32 v45, vcc, 0, v33, vcc
	v_add_co_u32_e32 v46, vcc, s16, v32
	s_mov_b32 s16, 0x31c000
	s_nop 0
	v_addc_co_u32_e32 v47, vcc, 0, v33, vcc
	v_add_co_u32_e32 v32, vcc, s16, v32
	s_add_i32 s16, s42, 1
	s_nop 0
	v_addc_co_u32_e32 v33, vcc, 0, v33, vcc
	global_load_dword v135, v[34:35], off
	global_load_dword v134, v[36:37], off
	global_load_dword v133, v[38:39], off
	global_load_dword v132, v[40:41], off
	global_load_dword v131, v[42:43], off
	global_load_dword v130, v[44:45], off
	global_load_dword v129, v[46:47], off
	global_load_dword v128, v[32:33], off
	s_cmpk_lt_u32 s16, 0x80
	s_cselect_b64 s[46:47], -1, 0
	v_cndmask_b32_e64 v2, 0, 1.0, s[46:47]
	s_waitcnt vmcnt(23)
	v_lshlrev_b32_e32 v32, 16, v50
	v_and_b32_e32 v33, 0xffff0000, v50
	s_waitcnt vmcnt(22)
	v_lshlrev_b32_e32 v34, 16, v51
	v_and_b32_e32 v35, 0xffff0000, v51
	s_waitcnt vmcnt(21)
	v_lshlrev_b32_e32 v36, 16, v53
	v_and_b32_e32 v37, 0xffff0000, v53
	s_waitcnt vmcnt(20)
	v_lshlrev_b32_e32 v38, 16, v54
	v_and_b32_e32 v39, 0xffff0000, v54
	s_waitcnt vmcnt(19)
	v_lshlrev_b32_e32 v40, 16, v55
	v_and_b32_e32 v41, 0xffff0000, v55
	s_waitcnt vmcnt(18)
	v_lshlrev_b32_e32 v42, 16, v56
	v_and_b32_e32 v43, 0xffff0000, v56
	s_waitcnt vmcnt(17)
	v_lshlrev_b32_e32 v44, 16, v57
	v_and_b32_e32 v45, 0xffff0000, v57
	s_waitcnt vmcnt(16)
	v_lshlrev_b32_e32 v46, 16, v100
	v_and_b32_e32 v47, 0xffff0000, v100
	s_cmp_lt_i32 s42, s62
	v_pk_fma_f32 v[16:17], v[2:3], v[32:33], v[16:17] op_sel_hi:[0,1,1]
	v_pk_fma_f32 v[18:19], v[2:3], v[34:35], v[18:19] op_sel_hi:[0,1,1]
	v_pk_fma_f32 v[20:21], v[2:3], v[36:37], v[20:21] op_sel_hi:[0,1,1]
	v_pk_fma_f32 v[22:23], v[2:3], v[38:39], v[22:23] op_sel_hi:[0,1,1]
	v_pk_fma_f32 v[24:25], v[2:3], v[40:41], v[24:25] op_sel_hi:[0,1,1]
	v_pk_fma_f32 v[26:27], v[2:3], v[42:43], v[26:27] op_sel_hi:[0,1,1]
	v_pk_fma_f32 v[28:29], v[2:3], v[44:45], v[28:29] op_sel_hi:[0,1,1]
	v_pk_fma_f32 v[30:31], v[2:3], v[46:47], v[30:31] op_sel_hi:[0,1,1]
	s_cbranch_scc1 .LBB0_932
	ds_write2st64_b64 v92, v[16:17], v[18:19] offset0:88 offset1:89
	ds_write2st64_b64 v92, v[20:21], v[22:23] offset0:90 offset1:91
	ds_write2st64_b64 v92, v[24:25], v[26:27] offset0:92 offset1:93
	ds_write2st64_b64 v92, v[28:29], v[30:31] offset0:94 offset1:95
	s_waitcnt lgkmcnt(0)
	s_barrier
; #define GAS __attribute__((address_space(1)))
; #define LAS __attribute__((address_space(3)))
; __device__ __forceinline__ unsigned cvt_pk_bf16(float lo, float hi) { unsigned r; asm volatile("v_cvt_pk_bf16_f32 %0, %1, %2" : "=v"(r) : "v"(lo), "v"(hi)); return r; }
; __device__ __forceinline__ float bf_lo(unsigned w) { return __uint_as_float(w << 16); }
; __device__ __forceinline__ float bf_hi(unsigned w) { return __uint_as_float(w & 0xffff0000u); }
; template <int W>
; __device__ __forceinline__ void pool_item(const Ctx& F, const bf16* Ub, bf16* Db, int r0, int nr) {
;     ...
;                 if (r >= r0) {
;                     LAS f32x2* row = buf + ((r & 1) * 80 + 8) * 64 + lane;
; #pragma unroll
;                     for (int j = 0; j < 8; ++j) row[(c0 + j) * 64] = Vv[j];
;                     asm volatile("s_waitcnt lgkmcnt(0)" ::: "memory"); __builtin_amdgcn_s_barrier(); asm volatile("" ::: "memory");
;                     const int rlo = r - HW > 0 ? r - HW : 0, rhi = r + HW < 128 ? r + HW : 128; const float icr = 1.0f / (float)(rhi - rlo);
;                     f32x2 h = (f32x2){0.f, 0.f};
; #pragma unroll
;                     for (int c = -HW; c < HW; ++c) h += row[(c0 + c) * 64];
; #pragma unroll
;                     for (int j = 0; j < 8; ++j) {
;                         const float ic = icr * icc[j]; const unsigned m = ring[(u + NS - HW + 1) % NS][j];
;                         *(GAS unsigned*)(Db + ((size_t)r * 64 + c0 + j) * EI) = cvt_pk_bf16(h.x * ic - bf_lo(m), h.y * ic - bf_hi(m));
;                         h += row[(c0 + j + HW) * 64] - row[(c0 + j - HW) * 64];
;                     }
; #pragma unroll
;                     for (int j = 0; j < 8; ++j) { const unsigned l = ring[(u + NS - W + 1) % NS][j]; Vv[j].x -= ml * bf_lo(l); Vv[j].y -= ml * bf_hi(l); }
;                 }
	ds_read2st64_b64 v[136:139], v92 offset0:86 offset1:87
	s_cmp_gt_i32 s42, 1
	s_cselect_b64 s[46:47], -1, 0
	v_cndmask_b32_e64 v2, 0, 1.0, s[46:47]
	s_max_i32 s43, s42, 2
	s_min_i32 s46, s42, 0x7e
	s_waitcnt lgkmcnt(0)
	v_pk_add_f32 v[48:49], v[136:137], 0 op_sel_hi:[1,0]
	s_sub_i32 s43, s46, s43
	v_pk_add_f32 v[48:49], v[48:49], v[138:139]
	ds_read2st64_b64 v[136:139], v92 offset0:88 offset1:89
	s_add_i32 s43, s43, 4
	v_cvt_f32_i32_e32 v142, s43
	s_mov_b32 s43, s17
	s_waitcnt lgkmcnt(0)
	v_pk_add_f32 v[48:49], v[48:49], v[136:137]
	s_nop 0
	v_pk_add_f32 v[140:141], v[48:49], v[138:139]
	v_div_scale_f32 v48, s[46:47], v142, v142, 1.0
	v_rcp_f32_e32 v49, v48
	s_lshl_b64 s[46:47], s[42:43], 20
	v_fma_f32 v136, -v48, v49, 1.0
	v_fmac_f32_e32 v49, v136, v49
	v_div_scale_f32 v136, vcc, 1.0, v142, 1.0
	v_mul_f32_e32 v137, v136, v49
	v_fma_f32 v138, -v48, v137, v136
	v_fmac_f32_e32 v137, v138, v49
	v_fma_f32 v48, -v48, v137, v136
	v_div_fmas_f32 v48, v48, v49, v137
	v_div_fixup_f32 v142, v48, v142, 1.0
	v_mul_f32_e32 v48, v66, v142
	v_lshlrev_b32_e32 v49, 16, v99
	v_and_b32_e32 v136, 0xffff0000, v99
	v_fma_f32 v49, v48, v140, -v49
	v_fma_f32 v48, v48, v141, -v136
	v_cvt_pk_bf16_f32 v136, v49, v48
	v_lshl_add_u64 v[48:49], v[10:11], 0, s[46:47]
	global_store_dword v[48:49], v136, off
	ds_read2st64_b64 v[136:139], v92 offset0:86 offset1:90
	s_waitcnt lgkmcnt(0)
	v_pk_add_f32 v[136:137], v[138:139], v[136:137] neg_lo:[0,1] neg_hi:[0,1]
	s_nop 0
	v_pk_add_f32 v[140:141], v[140:141], v[136:137]
	v_mul_f32_e32 v136, v67, v142
	v_lshlrev_b32_e32 v137, 16, v101
	v_and_b32_e32 v138, 0xffff0000, v101
	v_fma_f32 v137, v136, v140, -v137
	v_fma_f32 v136, v136, v141, -v138
	v_cvt_pk_bf16_f32 v138, v137, v136
	v_add_co_u32_e32 v136, vcc, s54, v48
	s_nop 1
	v_addc_co_u32_e32 v137, vcc, 0, v49, vcc
	global_store_dword v[136:137], v138, off
	ds_read2st64_b64 v[136:139], v92 offset0:87 offset1:91
	s_waitcnt lgkmcnt(0)
	v_pk_add_f32 v[136:137], v[138:139], v[136:137] neg_lo:[0,1] neg_hi:[0,1]
	s_nop 0
	v_pk_add_f32 v[140:141], v[140:141], v[136:137]
	v_mul_f32_e32 v136, v68, v142
	v_lshlrev_b32_e32 v137, 16, v104
	v_and_b32_e32 v138, 0xffff0000, v104
	v_fma_f32 v137, v136, v140, -v137
	v_fma_f32 v136, v136, v141, -v138
	v_cvt_pk_bf16_f32 v138, v137, v136
	v_add_co_u32_e32 v136, vcc, s55, v48
	s_nop 1
	v_addc_co_u32_e32 v137, vcc, 0, v49, vcc
	global_store_dword v[136:137], v138, off
	ds_read2st64_b64 v[136:139], v92 offset0:88 offset1:92
	s_waitcnt lgkmcnt(0)
	v_pk_add_f32 v[136:137], v[138:139], v[136:137] neg_lo:[0,1] neg_hi:[0,1]
	s_nop 0
	v_pk_add_f32 v[140:141], v[140:141], v[136:137]
	v_mul_f32_e32 v136, v69, v142
	v_lshlrev_b32_e32 v137, 16, v108
	v_and_b32_e32 v138, 0xffff0000, v108
	v_fma_f32 v137, v136, v140, -v137
	v_fma_f32 v136, v136, v141, -v138
	v_cvt_pk_bf16_f32 v138, v137, v136
	v_add_co_u32_e32 v136, vcc, s56, v48
	s_nop 1
	v_addc_co_u32_e32 v137, vcc, 0, v49, vcc
	global_store_dword v[136:137], v138, off
	ds_read2st64_b64 v[136:139], v92 offset0:89 offset1:93
	s_waitcnt lgkmcnt(0)
	v_pk_add_f32 v[136:137], v[138:139], v[136:137] neg_lo:[0,1] neg_hi:[0,1]
	s_nop 0
	v_pk_add_f32 v[140:141], v[140:141], v[136:137]
	v_mul_f32_e32 v136, v70, v142
	v_lshlrev_b32_e32 v137, 16, v112
	v_and_b32_e32 v138, 0xffff0000, v112
	v_fma_f32 v137, v136, v140, -v137
	v_fma_f32 v136, v136, v141, -v138
	v_cvt_pk_bf16_f32 v138, v137, v136
	v_add_co_u32_e32 v136, vcc, s57, v48
	s_nop 1
	v_addc_co_u32_e32 v137, vcc, 0, v49, vcc
	global_store_dword v[136:137], v138, off
	ds_read2st64_b64 v[136:139], v92 offset0:90 offset1:94
	s_waitcnt lgkmcnt(0)
	v_pk_add_f32 v[136:137], v[138:139], v[136:137] neg_lo:[0,1] neg_hi:[0,1]
	s_nop 0
	v_pk_add_f32 v[140:141], v[140:141], v[136:137]
	v_mul_f32_e32 v136, v71, v142
	v_lshlrev_b32_e32 v137, 16, v115
	v_and_b32_e32 v138, 0xffff0000, v115
	v_fma_f32 v137, v136, v140, -v137
	v_fma_f32 v136, v136, v141, -v138
	v_cvt_pk_bf16_f32 v138, v137, v136
	v_add_co_u32_e32 v136, vcc, s58, v48
	s_nop 1
	v_addc_co_u32_e32 v137, vcc, 0, v49, vcc
	global_store_dword v[136:137], v138, off
	ds_read2st64_b64 v[136:139], v92 offset0:91 offset1:95
	s_waitcnt lgkmcnt(0)
	v_pk_add_f32 v[136:137], v[138:139], v[136:137] neg_lo:[0,1] neg_hi:[0,1]
	s_nop 0
	v_pk_add_f32 v[140:141], v[140:141], v[136:137]
	v_mul_f32_e32 v136, v72, v142
	v_lshlrev_b32_e32 v137, 16, v118
	v_and_b32_e32 v138, 0xffff0000, v118
	v_fma_f32 v137, v136, v140, -v137
	v_fma_f32 v136, v136, v141, -v138
	v_cvt_pk_bf16_f32 v138, v137, v136
	v_add_co_u32_e32 v136, vcc, s59, v48
	s_nop 1
	v_addc_co_u32_e32 v137, vcc, 0, v49, vcc
	global_store_dword v[136:137], v138, off
	ds_read2st64_b64 v[136:139], v92 offset0:92 offset1:96
	v_add_co_u32_e32 v48, vcc, s60, v48
	s_waitcnt lgkmcnt(0)
	v_pk_add_f32 v[136:137], v[138:139], v[136:137] neg_lo:[0,1] neg_hi:[0,1]
	s_nop 0
	v_pk_add_f32 v[136:137], v[140:141], v[136:137]
	v_mul_f32_e32 v138, v73, v142
	v_lshlrev_b32_e32 v139, 16, v125
	v_fma_f32 v136, v138, v136, -v139
	v_and_b32_e32 v139, 0xffff0000, v125
	v_addc_co_u32_e32 v49, vcc, 0, v49, vcc
	v_fma_f32 v137, v138, v137, -v139
	v_cvt_pk_bf16_f32 v136, v136, v137
	global_store_dword v[48:49], v136, off
	v_lshlrev_b32_e32 v48, 16, v106
	v_and_b32_e32 v49, 0xffff0000, v106
	v_pk_fma_f32 v[16:17], v[2:3], v[48:49], v[16:17] op_sel_hi:[0,1,1] neg_lo:[1,0,0] neg_hi:[1,0,0]
	v_lshlrev_b32_e32 v48, 16, v109
	v_and_b32_e32 v49, 0xffff0000, v109
	v_pk_fma_f32 v[18:19], v[2:3], v[48:49], v[18:19] op_sel_hi:[0,1,1] neg_lo:[1,0,0] neg_hi:[1,0,0]
	v_lshlrev_b32_e32 v48, 16, v113
	v_and_b32_e32 v49, 0xffff0000, v113
	v_pk_fma_f32 v[20:21], v[2:3], v[48:49], v[20:21] op_sel_hi:[0,1,1] neg_lo:[1,0,0] neg_hi:[1,0,0]
	v_lshlrev_b32_e32 v48, 16, v116
	v_and_b32_e32 v49, 0xffff0000, v116
	v_pk_fma_f32 v[22:23], v[2:3], v[48:49], v[22:23] op_sel_hi:[0,1,1] neg_lo:[1,0,0] neg_hi:[1,0,0]
	v_lshlrev_b32_e32 v48, 16, v119
	v_and_b32_e32 v49, 0xffff0000, v119
	v_pk_fma_f32 v[24:25], v[2:3], v[48:49], v[24:25] op_sel_hi:[0,1,1] neg_lo:[1,0,0] neg_hi:[1,0,0]
	v_lshlrev_b32_e32 v48, 16, v121
	v_and_b32_e32 v49, 0xffff0000, v121
	v_pk_fma_f32 v[26:27], v[2:3], v[48:49], v[26:27] op_sel_hi:[0,1,1] neg_lo:[1,0,0] neg_hi:[1,0,0]
	v_lshlrev_b32_e32 v48, 16, v124
	v_and_b32_e32 v49, 0xffff0000, v124
	v_pk_fma_f32 v[28:29], v[2:3], v[48:49], v[28:29] op_sel_hi:[0,1,1] neg_lo:[1,0,0] neg_hi:[1,0,0]
	v_lshlrev_b32_e32 v48, 16, v127
	v_and_b32_e32 v49, 0xffff0000, v127
	v_pk_fma_f32 v[30:31], v[2:3], v[48:49], v[30:31] op_sel_hi:[0,1,1] neg_lo:[1,0,0] neg_hi:[1,0,0]
	s_cmp_lt_i32 s16, s23
	s_mov_b64 s[50:51], -1
	s_cbranch_scc0 .LBB0_933

; __device__ __forceinline__ float bf_lo(unsigned w) { return __uint_as_float(w << 16); }
; __device__ __forceinline__ float bf_hi(unsigned w) { return __uint_as_float(w & 0xffff0000u); }
; #define POOL_LOAD(slot_, r_) do { int e_ = (r_) + HW - 1; e_ = e_ < 0 ? 0 : (e_ > 127 ? 127 : e_); \
;         _Pragma("unroll") for (int j = 0; j < 8; ++j) ring[slot_][j] = *(const GAS unsigned*)(Ub + ((size_t)e_ * 64 + c0 + j) * EI); } while (0)
; template <int W>
; __device__ __forceinline__ void pool_item(const Ctx& F, const bf16* Ub, bf16* Db, int r0, int nr) {
;     ...
;         for (int u = 0; u < NS; ++u) {
;             const int r = base + u;
;             if (r < re) {
;                 POOL_LOAD((u + 2) % NS, r + 2);
;                 const int e = r + HW - 1;
;                 const float me = (e >= 0 && e < 128) ? 1.0f : 0.0f, ml = (r >= r0 && r - HW >= 0) ? 1.0f : 0.0f;
; #pragma unroll
;                 for (int j = 0; j < 8; ++j) { Vv[j].x += me * bf_lo(ring[u][j]); Vv[j].y += me * bf_hi(ring[u][j]); }
.LBB0_934:
	s_min_i32 s46, s16, 0x7c
	s_ashr_i32 s47, s46, 31
	s_lshl_b64 s[46:47], s[46:47], 20
	v_lshl_add_u64 v[48:49], v[12:13], 0, s[46:47]
	v_add_co_u32_e32 v136, vcc, 0x300000, v48
	s_add_i32 s46, s42, 2
	s_nop 0
	v_addc_co_u32_e32 v137, vcc, 0, v49, vcc
	global_load_dword v106, v[136:137], off
	v_add_co_u32_e32 v136, vcc, 0x304000, v48
	s_cmpk_lt_u32 s46, 0x80
	s_nop 0
	v_addc_co_u32_e32 v137, vcc, 0, v49, vcc
	global_load_dword v109, v[136:137], off
	v_add_co_u32_e32 v136, vcc, 0x308000, v48
	s_cselect_b64 s[50:51], -1, 0
	s_nop 0
	v_addc_co_u32_e32 v137, vcc, 0, v49, vcc
	global_load_dword v113, v[136:137], off
	v_add_co_u32_e32 v136, vcc, 0x30c000, v48
	v_cndmask_b32_e64 v2, 0, 1.0, s[50:51]
	s_nop 0
	v_addc_co_u32_e32 v137, vcc, 0, v49, vcc
	global_load_dword v116, v[136:137], off
	v_add_co_u32_e32 v136, vcc, 0x310000, v48
	s_cmp_lt_i32 s16, s62
	s_nop 0
	v_addc_co_u32_e32 v137, vcc, 0, v49, vcc
	global_load_dword v119, v[136:137], off
	v_add_co_u32_e32 v136, vcc, 0x314000, v48
	s_nop 1
	v_addc_co_u32_e32 v137, vcc, 0, v49, vcc
	global_load_dword v121, v[136:137], off
	v_add_co_u32_e32 v136, vcc, 0x318000, v48
	s_nop 1
	v_addc_co_u32_e32 v137, vcc, 0, v49, vcc
	v_add_co_u32_e32 v48, vcc, 0x31c000, v48
	global_load_dword v124, v[136:137], off
	s_nop 0
	v_addc_co_u32_e32 v49, vcc, 0, v49, vcc
	global_load_dword v127, v[48:49], off
	s_waitcnt vmcnt(16)
	v_lshlrev_b32_e32 v48, 16, v95
	v_and_b32_e32 v49, 0xffff0000, v95
	v_pk_fma_f32 v[16:17], v[2:3], v[48:49], v[16:17] op_sel_hi:[0,1,1]
	v_lshlrev_b32_e32 v48, 16, v96
	v_and_b32_e32 v49, 0xffff0000, v96
	v_pk_fma_f32 v[18:19], v[2:3], v[48:49], v[18:19] op_sel_hi:[0,1,1]
	v_lshlrev_b32_e32 v48, 16, v97
	v_and_b32_e32 v49, 0xffff0000, v97
	v_pk_fma_f32 v[20:21], v[2:3], v[48:49], v[20:21] op_sel_hi:[0,1,1]
	v_lshlrev_b32_e32 v48, 16, v98
	v_and_b32_e32 v49, 0xffff0000, v98
	v_pk_fma_f32 v[22:23], v[2:3], v[48:49], v[22:23] op_sel_hi:[0,1,1]
	v_lshlrev_b32_e32 v48, 16, v102
	v_and_b32_e32 v49, 0xffff0000, v102
	v_pk_fma_f32 v[24:25], v[2:3], v[48:49], v[24:25] op_sel_hi:[0,1,1]
	v_lshlrev_b32_e32 v48, 16, v105
	v_and_b32_e32 v49, 0xffff0000, v105
	v_pk_fma_f32 v[26:27], v[2:3], v[48:49], v[26:27] op_sel_hi:[0,1,1]
	v_lshlrev_b32_e32 v48, 16, v111
	v_and_b32_e32 v49, 0xffff0000, v111
	v_pk_fma_f32 v[28:29], v[2:3], v[48:49], v[28:29] op_sel_hi:[0,1,1]
	v_lshlrev_b32_e32 v48, 16, v123
	v_and_b32_e32 v49, 0xffff0000, v123
	v_pk_fma_f32 v[30:31], v[2:3], v[48:49], v[30:31] op_sel_hi:[0,1,1]
	s_cbranch_scc1 .LBB0_936
	ds_write2st64_b64 v92, v[16:17], v[18:19] offset0:8 offset1:9
	ds_write2st64_b64 v92, v[20:21], v[22:23] offset0:10 offset1:11
	ds_write2st64_b64 v92, v[24:25], v[26:27] offset0:12 offset1:13
	ds_write2st64_b64 v92, v[28:29], v[30:31] offset0:14 offset1:15
	s_waitcnt lgkmcnt(0)
	s_barrier
; #define GAS __attribute__((address_space(1)))
; #define LAS __attribute__((address_space(3)))
; __device__ __forceinline__ unsigned cvt_pk_bf16(float lo, float hi) { unsigned r; asm volatile("v_cvt_pk_bf16_f32 %0, %1, %2" : "=v"(r) : "v"(lo), "v"(hi)); return r; }
; __device__ __forceinline__ float bf_lo(unsigned w) { return __uint_as_float(w << 16); }
; __device__ __forceinline__ float bf_hi(unsigned w) { return __uint_as_float(w & 0xffff0000u); }
; template <int W>
; __device__ __forceinline__ void pool_item(const Ctx& F, const bf16* Ub, bf16* Db, int r0, int nr) {
;     ...
;                 if (r >= r0) {
;                     LAS f32x2* row = buf + ((r & 1) * 80 + 8) * 64 + lane;
; #pragma unroll
;                     for (int j = 0; j < 8; ++j) row[(c0 + j) * 64] = Vv[j];
;                     asm volatile("s_waitcnt lgkmcnt(0)" ::: "memory"); __builtin_amdgcn_s_barrier(); asm volatile("" ::: "memory");
;                     const int rlo = r - HW > 0 ? r - HW : 0, rhi = r + HW < 128 ? r + HW : 128; const float icr = 1.0f / (float)(rhi - rlo);
;                     f32x2 h = (f32x2){0.f, 0.f};
; #pragma unroll
;                     for (int c = -HW; c < HW; ++c) h += row[(c0 + c) * 64];
; #pragma unroll
;                     for (int j = 0; j < 8; ++j) {
;                         const float ic = icr * icc[j]; const unsigned m = ring[(u + NS - HW + 1) % NS][j];
;                         *(GAS unsigned*)(Db + ((size_t)r * 64 + c0 + j) * EI) = cvt_pk_bf16(h.x * ic - bf_lo(m), h.y * ic - bf_hi(m));
;                         h += row[(c0 + j + HW) * 64] - row[(c0 + j - HW) * 64];
;                     }
; #pragma unroll
;                     for (int j = 0; j < 8; ++j) { const unsigned l = ring[(u + NS - W + 1) % NS][j]; Vv[j].x -= ml * bf_lo(l); Vv[j].y -= ml * bf_hi(l); }
;                 }
	ds_read2st64_b64 v[136:139], v92 offset0:6 offset1:7
	s_cmp_gt_i32 s42, 0
	s_cselect_b64 s[50:51], -1, 0
	s_max_i32 s43, s16, 2
	s_min_i32 s47, s16, 0x7e
	s_sub_i32 s43, s47, s43
	s_waitcnt lgkmcnt(0)
	v_pk_add_f32 v[48:49], v[136:137], 0 op_sel_hi:[1,0]
	s_add_i32 s43, s43, 4
	v_pk_add_f32 v[48:49], v[48:49], v[138:139]
	ds_read2st64_b64 v[136:139], v92 offset0:8 offset1:9
	v_cvt_f32_i32_e32 v140, s43
	v_cndmask_b32_e64 v2, 0, 1.0, s[50:51]
	s_waitcnt lgkmcnt(0)
	v_pk_add_f32 v[48:49], v[48:49], v[136:137]
	v_div_scale_f32 v136, s[50:51], v140, v140, 1.0
	v_rcp_f32_e32 v137, v136
	v_pk_add_f32 v[48:49], v[48:49], v[138:139]
	s_lshl_b64 s[50:51], s[16:17], 20
	v_fma_f32 v138, -v136, v137, 1.0
	v_fmac_f32_e32 v137, v138, v137
	v_div_scale_f32 v138, vcc, 1.0, v140, 1.0
	v_mul_f32_e32 v139, v138, v137
	v_fma_f32 v141, -v136, v139, v138
	v_fmac_f32_e32 v139, v141, v137
	v_fma_f32 v136, -v136, v139, v138
	v_div_fmas_f32 v136, v136, v137, v139
	v_div_fixup_f32 v142, v136, v140, 1.0
	v_mul_f32_e32 v136, v66, v142
	v_fma_f32 v137, v136, v48, -v32
	v_fma_f32 v136, v136, v49, -v33
	v_cvt_pk_bf16_f32 v136, v137, v136
	v_lshl_add_u64 v[140:141], v[10:11], 0, s[50:51]
	global_store_dword v[140:141], v136, off
	ds_read2st64_b64 v[136:139], v92 offset0:6 offset1:10
	s_waitcnt lgkmcnt(0)
	v_pk_add_f32 v[136:137], v[138:139], v[136:137] neg_lo:[0,1] neg_hi:[0,1]
	s_nop 0
	v_pk_add_f32 v[48:49], v[48:49], v[136:137]
	v_mul_f32_e32 v136, v67, v142
	v_fma_f32 v137, v136, v48, -v34
	v_fma_f32 v136, v136, v49, -v35
	v_cvt_pk_bf16_f32 v138, v137, v136
	v_add_co_u32_e32 v136, vcc, s54, v140
	s_nop 1
	v_addc_co_u32_e32 v137, vcc, 0, v141, vcc
	global_store_dword v[136:137], v138, off
	ds_read2st64_b64 v[136:139], v92 offset0:7 offset1:11
	s_waitcnt lgkmcnt(0)
	v_pk_add_f32 v[136:137], v[138:139], v[136:137] neg_lo:[0,1] neg_hi:[0,1]
	s_nop 0
	v_pk_add_f32 v[48:49], v[48:49], v[136:137]
	v_mul_f32_e32 v136, v68, v142
	v_fma_f32 v137, v136, v48, -v36
	v_fma_f32 v136, v136, v49, -v37
	v_cvt_pk_bf16_f32 v138, v137, v136
	v_add_co_u32_e32 v136, vcc, s55, v140
	s_nop 1
	v_addc_co_u32_e32 v137, vcc, 0, v141, vcc
	global_store_dword v[136:137], v138, off
	ds_read2st64_b64 v[136:139], v92 offset0:8 offset1:12
	s_waitcnt lgkmcnt(0)
	v_pk_add_f32 v[136:137], v[138:139], v[136:137] neg_lo:[0,1] neg_hi:[0,1]
	s_nop 0
	v_pk_add_f32 v[48:49], v[48:49], v[136:137]
	v_mul_f32_e32 v136, v69, v142
	v_fma_f32 v137, v136, v48, -v38
	v_fma_f32 v136, v136, v49, -v39
	v_cvt_pk_bf16_f32 v138, v137, v136
	v_add_co_u32_e32 v136, vcc, s56, v140
	s_nop 1
	v_addc_co_u32_e32 v137, vcc, 0, v141, vcc
	global_store_dword v[136:137], v138, off
	ds_read2st64_b64 v[136:139], v92 offset0:9 offset1:13
	s_waitcnt lgkmcnt(0)
	v_pk_add_f32 v[136:137], v[138:139], v[136:137] neg_lo:[0,1] neg_hi:[0,1]
	s_nop 0
	v_pk_add_f32 v[48:49], v[48:49], v[136:137]
	v_mul_f32_e32 v136, v70, v142
	v_fma_f32 v137, v136, v48, -v40
	v_fma_f32 v136, v136, v49, -v41
	v_cvt_pk_bf16_f32 v138, v137, v136
	v_add_co_u32_e32 v136, vcc, s57, v140
	s_nop 1
	v_addc_co_u32_e32 v137, vcc, 0, v141, vcc
	global_store_dword v[136:137], v138, off
	ds_read2st64_b64 v[136:139], v92 offset0:10 offset1:14
	s_waitcnt lgkmcnt(0)
	v_pk_add_f32 v[136:137], v[138:139], v[136:137] neg_lo:[0,1] neg_hi:[0,1]
	s_nop 0
	v_pk_add_f32 v[48:49], v[48:49], v[136:137]
	v_mul_f32_e32 v136, v71, v142
	v_fma_f32 v137, v136, v48, -v42
	v_fma_f32 v136, v136, v49, -v43
	v_cvt_pk_bf16_f32 v138, v137, v136
	v_add_co_u32_e32 v136, vcc, s58, v140
	s_nop 1
	v_addc_co_u32_e32 v137, vcc, 0, v141, vcc
	global_store_dword v[136:137], v138, off
	ds_read2st64_b64 v[136:139], v92 offset0:11 offset1:15
	s_waitcnt lgkmcnt(0)
	v_pk_add_f32 v[136:137], v[138:139], v[136:137] neg_lo:[0,1] neg_hi:[0,1]
	s_nop 0
	v_pk_add_f32 v[48:49], v[48:49], v[136:137]
	v_mul_f32_e32 v136, v72, v142
	v_fma_f32 v137, v136, v48, -v44
	v_fma_f32 v136, v136, v49, -v45
	v_cvt_pk_bf16_f32 v138, v137, v136
	v_add_co_u32_e32 v136, vcc, s59, v140
	s_nop 1
	v_addc_co_u32_e32 v137, vcc, 0, v141, vcc
	global_store_dword v[136:137], v138, off
	ds_read2st64_b64 v[136:139], v92 offset0:12 offset1:16
	s_waitcnt lgkmcnt(0)
	v_pk_add_f32 v[136:137], v[138:139], v[136:137] neg_lo:[0,1] neg_hi:[0,1]
	s_nop 0
	v_pk_add_f32 v[48:49], v[48:49], v[136:137]
	v_mul_f32_e32 v136, v73, v142
	v_fma_f32 v48, v136, v48, -v46
	v_fma_f32 v49, v136, v49, -v47
	v_cvt_pk_bf16_f32 v136, v48, v49
	v_add_co_u32_e32 v48, vcc, s60, v140
	s_nop 1
	v_addc_co_u32_e32 v49, vcc, 0, v141, vcc
	global_store_dword v[48:49], v136, off
	v_lshlrev_b32_e32 v48, 16, v103
	v_and_b32_e32 v49, 0xffff0000, v103
	v_pk_fma_f32 v[16:17], v[2:3], v[48:49], v[16:17] op_sel_hi:[0,1,1] neg_lo:[1,0,0] neg_hi:[1,0,0]
	v_lshlrev_b32_e32 v48, 16, v107
	v_and_b32_e32 v49, 0xffff0000, v107
	v_pk_fma_f32 v[18:19], v[2:3], v[48:49], v[18:19] op_sel_hi:[0,1,1] neg_lo:[1,0,0] neg_hi:[1,0,0]
	v_lshlrev_b32_e32 v48, 16, v110
	v_and_b32_e32 v49, 0xffff0000, v110
	v_pk_fma_f32 v[20:21], v[2:3], v[48:49], v[20:21] op_sel_hi:[0,1,1] neg_lo:[1,0,0] neg_hi:[1,0,0]
	v_lshlrev_b32_e32 v48, 16, v114
	v_and_b32_e32 v49, 0xffff0000, v114
	v_pk_fma_f32 v[22:23], v[2:3], v[48:49], v[22:23] op_sel_hi:[0,1,1] neg_lo:[1,0,0] neg_hi:[1,0,0]
	v_lshlrev_b32_e32 v48, 16, v117
	v_and_b32_e32 v49, 0xffff0000, v117
	v_pk_fma_f32 v[24:25], v[2:3], v[48:49], v[24:25] op_sel_hi:[0,1,1] neg_lo:[1,0,0] neg_hi:[1,0,0]
	v_lshlrev_b32_e32 v48, 16, v120
	v_and_b32_e32 v49, 0xffff0000, v120
	v_pk_fma_f32 v[26:27], v[2:3], v[48:49], v[26:27] op_sel_hi:[0,1,1] neg_lo:[1,0,0] neg_hi:[1,0,0]
	v_lshlrev_b32_e32 v48, 16, v122
	v_and_b32_e32 v49, 0xffff0000, v122
	v_pk_fma_f32 v[28:29], v[2:3], v[48:49], v[28:29] op_sel_hi:[0,1,1] neg_lo:[1,0,0] neg_hi:[1,0,0]
	v_lshlrev_b32_e32 v48, 16, v126
	v_and_b32_e32 v49, 0xffff0000, v126
	v_pk_fma_f32 v[30:31], v[2:3], v[48:49], v[30:31] op_sel_hi:[0,1,1] neg_lo:[1,0,0] neg_hi:[1,0,0]

; #define GAS __attribute__((address_space(1)))
; #define LAS __attribute__((address_space(3)))
; __device__ __forceinline__ unsigned cvt_pk_bf16(float lo, float hi) { unsigned r; asm volatile("v_cvt_pk_bf16_f32 %0, %1, %2" : "=v"(r) : "v"(lo), "v"(hi)); return r; }
; __device__ __forceinline__ float bf_lo(unsigned w) { return __uint_as_float(w << 16); }
; __device__ __forceinline__ float bf_hi(unsigned w) { return __uint_as_float(w & 0xffff0000u); }
; template <int W>
; __device__ __forceinline__ void pool_item(const Ctx& F, const bf16* Ub, bf16* Db, int r0, int nr) {
;     ...
;         for (int u = 0; u < NS; ++u) {
;             const int r = base + u;
;             if (r < re) {
;                 POOL_LOAD((u + 2) % NS, r + 2);
;                 const int e = r + HW - 1;
;                 const float me = (e >= 0 && e < 128) ? 1.0f : 0.0f, ml = (r >= r0 && r - HW >= 0) ? 1.0f : 0.0f;
; #pragma unroll
;                 for (int j = 0; j < 8; ++j) { Vv[j].x += me * bf_lo(ring[u][j]); Vv[j].y += me * bf_hi(ring[u][j]); }
;                 if (r >= r0) {
;                     LAS f32x2* row = buf + ((r & 1) * 80 + 8) * 64 + lane;
; #pragma unroll
;                     for (int j = 0; j < 8; ++j) row[(c0 + j) * 64] = Vv[j];
;                     asm volatile("s_waitcnt lgkmcnt(0)" ::: "memory"); __builtin_amdgcn_s_barrier(); asm volatile("" ::: "memory");
;                     const int rlo = r - HW > 0 ? r - HW : 0, rhi = r + HW < 128 ? r + HW : 128; const float icr = 1.0f / (float)(rhi - rlo);
;                     f32x2 h = (f32x2){0.f, 0.f};
; #pragma unroll
;                     for (int c = -HW; c < HW; ++c) h += row[(c0 + c) * 64];
; #pragma unroll
;                     for (int j = 0; j < 8; ++j) {
;                         const float ic = icr * icc[j]; const unsigned m = ring[(u + NS - HW + 1) % NS][j];
;                         *(GAS unsigned*)(Db + ((size_t)r * 64 + c0 + j) * EI) = cvt_pk_bf16(h.x * ic - bf_lo(m), h.y * ic - bf_hi(m));
;                         h += row[(c0 + j + HW) * 64] - row[(c0 + j - HW) * 64];
;                     }
; #pragma unroll
;                     for (int j = 0; j < 8; ++j) { const unsigned l = ring[(u + NS - W + 1) % NS][j]; Vv[j].x -= ml * bf_lo(l); Vv[j].y -= ml * bf_hi(l); }
;                 }
.LBB0_938:
	s_andn2_b64 vcc, exec, s[50:51]
	s_cbranch_vccnz .LBB0_941
	s_min_i32 s50, s46, 0x7c
	s_ashr_i32 s51, s50, 31
	s_lshl_b64 s[50:51], s[50:51], 20
	v_lshl_add_u64 v[48:49], v[12:13], 0, s[50:51]
	v_add_co_u32_e32 v136, vcc, 0x300000, v48
	s_add_i32 s43, s42, 3
	s_nop 0
	v_addc_co_u32_e32 v137, vcc, 0, v49, vcc
	global_load_dword v103, v[136:137], off
	v_add_co_u32_e32 v136, vcc, 0x304000, v48
	s_cmpk_lt_u32 s43, 0x80
	s_nop 0
	v_addc_co_u32_e32 v137, vcc, 0, v49, vcc
	global_load_dword v107, v[136:137], off
	v_add_co_u32_e32 v136, vcc, 0x308000, v48
	s_cselect_b64 s[50:51], -1, 0
	s_nop 0
	v_addc_co_u32_e32 v137, vcc, 0, v49, vcc
	global_load_dword v110, v[136:137], off
	v_add_co_u32_e32 v136, vcc, 0x30c000, v48
	v_cndmask_b32_e64 v2, 0, 1.0, s[50:51]
	s_nop 0
	v_addc_co_u32_e32 v137, vcc, 0, v49, vcc
	global_load_dword v114, v[136:137], off
	v_add_co_u32_e32 v136, vcc, 0x310000, v48
	s_cmp_lt_i32 s46, s62
	s_nop 0
	v_addc_co_u32_e32 v137, vcc, 0, v49, vcc
	global_load_dword v117, v[136:137], off
	v_add_co_u32_e32 v136, vcc, 0x314000, v48
	s_nop 1
	v_addc_co_u32_e32 v137, vcc, 0, v49, vcc
	global_load_dword v120, v[136:137], off
	v_add_co_u32_e32 v136, vcc, 0x318000, v48
	s_nop 1
	v_addc_co_u32_e32 v137, vcc, 0, v49, vcc
	v_add_co_u32_e32 v48, vcc, 0x31c000, v48
	global_load_dword v122, v[136:137], off
	s_nop 0
	v_addc_co_u32_e32 v49, vcc, 0, v49, vcc
	global_load_dword v126, v[48:49], off
	s_waitcnt vmcnt(23)
	v_lshlrev_b32_e32 v48, 16, v135
	v_and_b32_e32 v49, 0xffff0000, v135
	v_pk_fma_f32 v[16:17], v[2:3], v[48:49], v[16:17] op_sel_hi:[0,1,1]
	s_waitcnt vmcnt(22)
	v_lshlrev_b32_e32 v48, 16, v134
	v_and_b32_e32 v49, 0xffff0000, v134
	v_pk_fma_f32 v[18:19], v[2:3], v[48:49], v[18:19] op_sel_hi:[0,1,1]
	s_waitcnt vmcnt(21)
	v_lshlrev_b32_e32 v48, 16, v133
	v_and_b32_e32 v49, 0xffff0000, v133
	v_pk_fma_f32 v[20:21], v[2:3], v[48:49], v[20:21] op_sel_hi:[0,1,1]
	s_waitcnt vmcnt(20)
	v_lshlrev_b32_e32 v48, 16, v132
	v_and_b32_e32 v49, 0xffff0000, v132
	v_pk_fma_f32 v[22:23], v[2:3], v[48:49], v[22:23] op_sel_hi:[0,1,1]
	s_waitcnt vmcnt(19)
	v_lshlrev_b32_e32 v48, 16, v131
	v_and_b32_e32 v49, 0xffff0000, v131
	v_pk_fma_f32 v[24:25], v[2:3], v[48:49], v[24:25] op_sel_hi:[0,1,1]
	s_waitcnt vmcnt(18)
	v_lshlrev_b32_e32 v48, 16, v130
	v_and_b32_e32 v49, 0xffff0000, v130
	v_pk_fma_f32 v[26:27], v[2:3], v[48:49], v[26:27] op_sel_hi:[0,1,1]
	s_waitcnt vmcnt(17)
	v_lshlrev_b32_e32 v48, 16, v129
	v_and_b32_e32 v49, 0xffff0000, v129
	v_pk_fma_f32 v[28:29], v[2:3], v[48:49], v[28:29] op_sel_hi:[0,1,1]
	s_waitcnt vmcnt(16)
	v_lshlrev_b32_e32 v48, 16, v128
	v_and_b32_e32 v49, 0xffff0000, v128
	v_pk_fma_f32 v[30:31], v[2:3], v[48:49], v[30:31] op_sel_hi:[0,1,1]
	s_cbranch_scc1 .LBB0_941
	ds_write2st64_b64 v92, v[16:17], v[18:19] offset0:88 offset1:89
	ds_write2st64_b64 v92, v[20:21], v[22:23] offset0:90 offset1:91
	ds_write2st64_b64 v92, v[24:25], v[26:27] offset0:92 offset1:93
	ds_write2st64_b64 v92, v[28:29], v[30:31] offset0:94 offset1:95
	s_waitcnt lgkmcnt(0)
	s_barrier
	ds_read2st64_b64 v[136:139], v92 offset0:86 offset1:87
	s_cmp_gt_i32 s42, -1
	s_cselect_b64 s[50:51], -1, 0
	s_max_i32 s16, s46, 2
	s_min_i32 s47, s46, 0x7e
	s_waitcnt lgkmcnt(0)
	v_pk_add_f32 v[48:49], v[136:137], 0 op_sel_hi:[1,0]
	s_sub_i32 s16, s47, s16
	v_pk_add_f32 v[48:49], v[48:49], v[138:139]
	ds_read2st64_b64 v[136:139], v92 offset0:88 offset1:89
	s_add_i32 s16, s16, 4
	v_cvt_f32_i32_e32 v142, s16
	v_cndmask_b32_e64 v2, 0, 1.0, s[50:51]
	s_mov_b32 s47, s17
	s_waitcnt lgkmcnt(0)
	v_pk_add_f32 v[48:49], v[48:49], v[136:137]
	s_lshl_b64 s[46:47], s[46:47], 20
	v_pk_add_f32 v[140:141], v[48:49], v[138:139]
	v_div_scale_f32 v48, s[50:51], v142, v142, 1.0
	v_rcp_f32_e32 v49, v48
	s_nop 0
	v_fma_f32 v136, -v48, v49, 1.0
	v_fmac_f32_e32 v49, v136, v49
	v_div_scale_f32 v136, vcc, 1.0, v142, 1.0
	v_mul_f32_e32 v137, v136, v49
	v_fma_f32 v138, -v48, v137, v136
	v_fmac_f32_e32 v137, v138, v49
	v_fma_f32 v48, -v48, v137, v136
	v_div_fmas_f32 v48, v48, v49, v137
	v_div_fixup_f32 v142, v48, v142, 1.0
	v_mul_f32_e32 v48, v66, v142
	v_lshlrev_b32_e32 v49, 16, v95
	v_and_b32_e32 v136, 0xffff0000, v95
	v_fma_f32 v49, v48, v140, -v49
	v_fma_f32 v48, v48, v141, -v136
	v_cvt_pk_bf16_f32 v136, v49, v48
	v_lshl_add_u64 v[48:49], v[10:11], 0, s[46:47]
	global_store_dword v[48:49], v136, off
	ds_read2st64_b64 v[136:139], v92 offset0:86 offset1:90
	s_waitcnt lgkmcnt(0)
	v_pk_add_f32 v[136:137], v[138:139], v[136:137] neg_lo:[0,1] neg_hi:[0,1]
	s_nop 0
	v_pk_add_f32 v[140:141], v[140:141], v[136:137]
	v_mul_f32_e32 v136, v67, v142
	v_lshlrev_b32_e32 v137, 16, v96
	v_and_b32_e32 v138, 0xffff0000, v96
	v_fma_f32 v137, v136, v140, -v137
	v_fma_f32 v136, v136, v141, -v138
	v_cvt_pk_bf16_f32 v138, v137, v136
	v_add_co_u32_e32 v136, vcc, s54, v48
	s_nop 1
	v_addc_co_u32_e32 v137, vcc, 0, v49, vcc
	global_store_dword v[136:137], v138, off
	ds_read2st64_b64 v[136:139], v92 offset0:87 offset1:91
	s_waitcnt lgkmcnt(0)
	v_pk_add_f32 v[136:137], v[138:139], v[136:137] neg_lo:[0,1] neg_hi:[0,1]
	s_nop 0
	v_pk_add_f32 v[140:141], v[140:141], v[136:137]
	v_mul_f32_e32 v136, v68, v142
	v_lshlrev_b32_e32 v137, 16, v97
	v_and_b32_e32 v138, 0xffff0000, v97
	v_fma_f32 v137, v136, v140, -v137
	v_fma_f32 v136, v136, v141, -v138
	v_cvt_pk_bf16_f32 v138, v137, v136
	v_add_co_u32_e32 v136, vcc, s55, v48
	s_nop 1
	v_addc_co_u32_e32 v137, vcc, 0, v49, vcc
	global_store_dword v[136:137], v138, off
	ds_read2st64_b64 v[136:139], v92 offset0:88 offset1:92
	s_waitcnt lgkmcnt(0)
; #define GAS __attribute__((address_space(1)))
; #define LAS __attribute__((address_space(3)))
; __device__ __forceinline__ unsigned cvt_pk_bf16(float lo, float hi) { unsigned r; asm volatile("v_cvt_pk_bf16_f32 %0, %1, %2" : "=v"(r) : "v"(lo), "v"(hi)); return r; }
; __device__ __forceinline__ float bf_lo(unsigned w) { return __uint_as_float(w << 16); }
; __device__ __forceinline__ float bf_hi(unsigned w) { return __uint_as_float(w & 0xffff0000u); }
; template <int W>
; __device__ __forceinline__ void pool_item(const Ctx& F, const bf16* Ub, bf16* Db, int r0, int nr) {
;     ...
;         for (int u = 0; u < NS; ++u) {
;             const int r = base + u;
;             if (r < re) {
;                 POOL_LOAD((u + 2) % NS, r + 2);
;                 const int e = r + HW - 1;
;                 const float me = (e >= 0 && e < 128) ? 1.0f : 0.0f, ml = (r >= r0 && r - HW >= 0) ? 1.0f : 0.0f;
; #pragma unroll
;                 for (int j = 0; j < 8; ++j) { Vv[j].x += me * bf_lo(ring[u][j]); Vv[j].y += me * bf_hi(ring[u][j]); }
;                 if (r >= r0) {
;                     LAS f32x2* row = buf + ((r & 1) * 80 + 8) * 64 + lane;
; #pragma unroll
;                     for (int j = 0; j < 8; ++j) row[(c0 + j) * 64] = Vv[j];
;                     asm volatile("s_waitcnt lgkmcnt(0)" ::: "memory"); __builtin_amdgcn_s_barrier(); asm volatile("" ::: "memory");
;                     const int rlo = r - HW > 0 ? r - HW : 0, rhi = r + HW < 128 ? r + HW : 128; const float icr = 1.0f / (float)(rhi - rlo);
;                     f32x2 h = (f32x2){0.f, 0.f};
; #pragma unroll
;                     for (int c = -HW; c < HW; ++c) h += row[(c0 + c) * 64];
; #pragma unroll
;                     for (int j = 0; j < 8; ++j) {
;                         const float ic = icr * icc[j]; const unsigned m = ring[(u + NS - HW + 1) % NS][j];
;                         *(GAS unsigned*)(Db + ((size_t)r * 64 + c0 + j) * EI) = cvt_pk_bf16(h.x * ic - bf_lo(m), h.y * ic - bf_hi(m));
;                         h += row[(c0 + j + HW) * 64] - row[(c0 + j - HW) * 64];
;                     }
; #pragma unroll
;                     for (int j = 0; j < 8; ++j) { const unsigned l = ring[(u + NS - W + 1) % NS][j]; Vv[j].x -= ml * bf_lo(l); Vv[j].y -= ml * bf_hi(l); }
;                 }
	v_pk_add_f32 v[136:137], v[138:139], v[136:137] neg_lo:[0,1] neg_hi:[0,1]
	s_nop 0
	v_pk_add_f32 v[140:141], v[140:141], v[136:137]
	v_mul_f32_e32 v136, v69, v142
	v_lshlrev_b32_e32 v137, 16, v98
	v_and_b32_e32 v138, 0xffff0000, v98
	v_fma_f32 v137, v136, v140, -v137
	v_fma_f32 v136, v136, v141, -v138
	v_cvt_pk_bf16_f32 v138, v137, v136
	v_add_co_u32_e32 v136, vcc, s56, v48
	s_nop 1
	v_addc_co_u32_e32 v137, vcc, 0, v49, vcc
	global_store_dword v[136:137], v138, off
	ds_read2st64_b64 v[136:139], v92 offset0:89 offset1:93
	s_waitcnt lgkmcnt(0)
	v_pk_add_f32 v[136:137], v[138:139], v[136:137] neg_lo:[0,1] neg_hi:[0,1]
	s_nop 0
	v_pk_add_f32 v[140:141], v[140:141], v[136:137]
	v_mul_f32_e32 v136, v70, v142
	v_lshlrev_b32_e32 v137, 16, v102
	v_and_b32_e32 v138, 0xffff0000, v102
	v_fma_f32 v137, v136, v140, -v137
	v_fma_f32 v136, v136, v141, -v138
	v_cvt_pk_bf16_f32 v138, v137, v136
	v_add_co_u32_e32 v136, vcc, s57, v48
	s_nop 1
	v_addc_co_u32_e32 v137, vcc, 0, v49, vcc
	global_store_dword v[136:137], v138, off
	ds_read2st64_b64 v[136:139], v92 offset0:90 offset1:94
	s_waitcnt lgkmcnt(0)
	v_pk_add_f32 v[136:137], v[138:139], v[136:137] neg_lo:[0,1] neg_hi:[0,1]
	s_nop 0
	v_pk_add_f32 v[140:141], v[140:141], v[136:137]
	v_mul_f32_e32 v136, v71, v142
	v_lshlrev_b32_e32 v137, 16, v105
	v_and_b32_e32 v138, 0xffff0000, v105
	v_fma_f32 v137, v136, v140, -v137
	v_fma_f32 v136, v136, v141, -v138
	v_cvt_pk_bf16_f32 v138, v137, v136
	v_add_co_u32_e32 v136, vcc, s58, v48
	s_nop 1
	v_addc_co_u32_e32 v137, vcc, 0, v49, vcc
	global_store_dword v[136:137], v138, off
	ds_read2st64_b64 v[136:139], v92 offset0:91 offset1:95
	s_waitcnt lgkmcnt(0)
	v_pk_add_f32 v[136:137], v[138:139], v[136:137] neg_lo:[0,1] neg_hi:[0,1]
	s_nop 0
	v_pk_add_f32 v[140:141], v[140:141], v[136:137]
	v_mul_f32_e32 v136, v72, v142
	v_lshlrev_b32_e32 v137, 16, v111
	v_and_b32_e32 v138, 0xffff0000, v111
	v_fma_f32 v137, v136, v140, -v137
	v_fma_f32 v136, v136, v141, -v138
	v_cvt_pk_bf16_f32 v138, v137, v136
	v_add_co_u32_e32 v136, vcc, s59, v48
	s_nop 1
	v_addc_co_u32_e32 v137, vcc, 0, v49, vcc
	global_store_dword v[136:137], v138, off
	ds_read2st64_b64 v[136:139], v92 offset0:92 offset1:96
	v_add_co_u32_e32 v48, vcc, s60, v48
	s_waitcnt lgkmcnt(0)
	v_pk_add_f32 v[136:137], v[138:139], v[136:137] neg_lo:[0,1] neg_hi:[0,1]
	s_nop 0
	v_pk_add_f32 v[136:137], v[140:141], v[136:137]
	v_mul_f32_e32 v138, v73, v142
	v_lshlrev_b32_e32 v139, 16, v123
	v_fma_f32 v136, v138, v136, -v139
	v_and_b32_e32 v139, 0xffff0000, v123
	v_addc_co_u32_e32 v49, vcc, 0, v49, vcc
	v_fma_f32 v137, v138, v137, -v139
	v_cvt_pk_bf16_f32 v136, v136, v137
	global_store_dword v[48:49], v136, off
	v_lshlrev_b32_e32 v48, 16, v99
	v_and_b32_e32 v49, 0xffff0000, v99
	v_pk_fma_f32 v[16:17], v[2:3], v[48:49], v[16:17] op_sel_hi:[0,1,1] neg_lo:[1,0,0] neg_hi:[1,0,0]
	v_lshlrev_b32_e32 v48, 16, v101
	v_and_b32_e32 v49, 0xffff0000, v101
	v_pk_fma_f32 v[18:19], v[2:3], v[48:49], v[18:19] op_sel_hi:[0,1,1] neg_lo:[1,0,0] neg_hi:[1,0,0]
	v_lshlrev_b32_e32 v48, 16, v104
	v_and_b32_e32 v49, 0xffff0000, v104
	v_pk_fma_f32 v[20:21], v[2:3], v[48:49], v[20:21] op_sel_hi:[0,1,1] neg_lo:[1,0,0] neg_hi:[1,0,0]
	v_lshlrev_b32_e32 v48, 16, v108
	v_and_b32_e32 v49, 0xffff0000, v108
	v_pk_fma_f32 v[22:23], v[2:3], v[48:49], v[22:23] op_sel_hi:[0,1,1] neg_lo:[1,0,0] neg_hi:[1,0,0]
	v_lshlrev_b32_e32 v48, 16, v112
	v_and_b32_e32 v49, 0xffff0000, v112
	v_pk_fma_f32 v[24:25], v[2:3], v[48:49], v[24:25] op_sel_hi:[0,1,1] neg_lo:[1,0,0] neg_hi:[1,0,0]
	v_lshlrev_b32_e32 v48, 16, v115
	v_and_b32_e32 v49, 0xffff0000, v115
	v_pk_fma_f32 v[26:27], v[2:3], v[48:49], v[26:27] op_sel_hi:[0,1,1] neg_lo:[1,0,0] neg_hi:[1,0,0]
	v_lshlrev_b32_e32 v48, 16, v118
	v_and_b32_e32 v49, 0xffff0000, v118
	v_pk_fma_f32 v[28:29], v[2:3], v[48:49], v[28:29] op_sel_hi:[0,1,1] neg_lo:[1,0,0] neg_hi:[1,0,0]
	v_lshlrev_b32_e32 v48, 16, v125
	v_and_b32_e32 v49, 0xffff0000, v125
	v_pk_fma_f32 v[30:31], v[2:3], v[48:49], v[30:31] op_sel_hi:[0,1,1] neg_lo:[1,0,0] neg_hi:[1,0,0]
.LBB0_941:
	s_cmp_ge_u32 s43, s23
	s_cbranch_scc1 .LBB0_944
	s_min_i32 s16, s43, 0x7c
	s_add_i32 s16, s16, 3
	s_lshl_b64 s[46:47], s[16:17], 20
	v_lshl_add_u64 v[48:49], v[12:13], 0, s[46:47]
	v_add_co_u32_e32 v136, vcc, 0x4000, v48
	global_load_dword v99, v[48:49], off
	s_nop 0
	v_addc_co_u32_e32 v137, vcc, 0, v49, vcc
	global_load_dword v101, v[136:137], off
	v_add_co_u32_e32 v136, vcc, 0x8000, v48
	s_cmp_lt_u32 s43, s62
	s_nop 0
	v_addc_co_u32_e32 v137, vcc, 0, v49, vcc
	global_load_dword v104, v[136:137], off
	v_add_co_u32_e32 v136, vcc, 0xc000, v48
	s_nop 1
	v_addc_co_u32_e32 v137, vcc, 0, v49, vcc
	global_load_dword v108, v[136:137], off
	v_add_co_u32_e32 v136, vcc, 0x10000, v48
	s_nop 1
	v_addc_co_u32_e32 v137, vcc, 0, v49, vcc
	global_load_dword v112, v[136:137], off
	v_add_co_u32_e32 v136, vcc, 0x14000, v48
	s_nop 1
	v_addc_co_u32_e32 v137, vcc, 0, v49, vcc
	global_load_dword v115, v[136:137], off
	v_add_co_u32_e32 v136, vcc, 0x18000, v48
	s_nop 1
	v_addc_co_u32_e32 v137, vcc, 0, v49, vcc
	v_add_co_u32_e32 v48, vcc, 0x1c000, v48
	global_load_dword v118, v[136:137], off
	s_nop 0
	v_addc_co_u32_e32 v49, vcc, 0, v49, vcc
	global_load_dword v125, v[48:49], off
	s_waitcnt vmcnt(23)
	v_lshlrev_b32_e32 v48, 16, v106
	v_and_b32_e32 v49, 0xffff0000, v106
	v_pk_add_f32 v[16:17], v[48:49], v[16:17]
	s_waitcnt vmcnt(22)
	v_lshlrev_b32_e32 v48, 16, v109
	v_and_b32_e32 v49, 0xffff0000, v109
	v_pk_add_f32 v[18:19], v[48:49], v[18:19]
	s_waitcnt vmcnt(21)
	v_lshlrev_b32_e32 v48, 16, v113
	v_and_b32_e32 v49, 0xffff0000, v113
	v_pk_add_f32 v[20:21], v[48:49], v[20:21]
	s_waitcnt vmcnt(20)
	v_lshlrev_b32_e32 v48, 16, v116
	v_and_b32_e32 v49, 0xffff0000, v116
	v_pk_add_f32 v[22:23], v[48:49], v[22:23]
	s_waitcnt vmcnt(19)
	v_lshlrev_b32_e32 v48, 16, v119
	v_and_b32_e32 v49, 0xffff0000, v119
	v_pk_add_f32 v[24:25], v[48:49], v[24:25]
	s_waitcnt vmcnt(18)
	v_lshlrev_b32_e32 v48, 16, v121
	v_and_b32_e32 v49, 0xffff0000, v121
	v_pk_add_f32 v[26:27], v[48:49], v[26:27]
	s_waitcnt vmcnt(17)
	v_lshlrev_b32_e32 v48, 16, v124
	v_and_b32_e32 v49, 0xffff0000, v124
	v_pk_add_f32 v[28:29], v[48:49], v[28:29]
	s_waitcnt vmcnt(16)
	v_lshlrev_b32_e32 v48, 16, v127
	v_and_b32_e32 v49, 0xffff0000, v127
	v_pk_add_f32 v[30:31], v[48:49], v[30:31]
	s_cbranch_scc1 .LBB0_944
; #define GAS __attribute__((address_space(1)))
; #define LAS __attribute__((address_space(3)))
; __device__ __forceinline__ unsigned cvt_pk_bf16(float lo, float hi) { unsigned r; asm volatile("v_cvt_pk_bf16_f32 %0, %1, %2" : "=v"(r) : "v"(lo), "v"(hi)); return r; }
; __device__ __forceinline__ float bf_lo(unsigned w) { return __uint_as_float(w << 16); }
; __device__ __forceinline__ float bf_hi(unsigned w) { return __uint_as_float(w & 0xffff0000u); }
; template <int W>
; __device__ __forceinline__ void pool_item(const Ctx& F, const bf16* Ub, bf16* Db, int r0, int nr) {
;     ...
;                 if (r >= r0) {
;                     LAS f32x2* row = buf + ((r & 1) * 80 + 8) * 64 + lane;
; #pragma unroll
;                     for (int j = 0; j < 8; ++j) row[(c0 + j) * 64] = Vv[j];
;                     asm volatile("s_waitcnt lgkmcnt(0)" ::: "memory"); __builtin_amdgcn_s_barrier(); asm volatile("" ::: "memory");
;                     const int rlo = r - HW > 0 ? r - HW : 0, rhi = r + HW < 128 ? r + HW : 128; const float icr = 1.0f / (float)(rhi - rlo);
;                     f32x2 h = (f32x2){0.f, 0.f};
; #pragma unroll
;                     for (int c = -HW; c < HW; ++c) h += row[(c0 + c) * 64];
; #pragma unroll
;                     for (int j = 0; j < 8; ++j) {
;                         const float ic = icr * icc[j]; const unsigned m = ring[(u + NS - HW + 1) % NS][j];
;                         *(GAS unsigned*)(Db + ((size_t)r * 64 + c0 + j) * EI) = cvt_pk_bf16(h.x * ic - bf_lo(m), h.y * ic - bf_hi(m));
;                         h += row[(c0 + j + HW) * 64] - row[(c0 + j - HW) * 64];
;                     }
; #pragma unroll
;                     for (int j = 0; j < 8; ++j) { const unsigned l = ring[(u + NS - W + 1) % NS][j]; Vv[j].x -= ml * bf_lo(l); Vv[j].y -= ml * bf_hi(l); }
;                 }
	ds_write2st64_b64 v92, v[16:17], v[18:19] offset0:8 offset1:9
	ds_write2st64_b64 v92, v[20:21], v[22:23] offset0:10 offset1:11
	ds_write2st64_b64 v92, v[24:25], v[26:27] offset0:12 offset1:13
	ds_write2st64_b64 v92, v[28:29], v[30:31] offset0:14 offset1:15
	s_waitcnt lgkmcnt(0)
	s_barrier
	ds_read2st64_b64 v[136:139], v92 offset0:6 offset1:7
	s_cmp_gt_u32 s43, 1
	s_cselect_b64 s[46:47], -1, 0
	s_max_i32 s16, s43, 2
	s_min_i32 s43, s43, 0x7e
	s_waitcnt lgkmcnt(0)
	v_pk_add_f32 v[48:49], v[136:137], 0 op_sel_hi:[1,0]
	s_sub_i32 s16, s43, s16
	v_pk_add_f32 v[48:49], v[48:49], v[138:139]
	ds_read2st64_b64 v[136:139], v92 offset0:8 offset1:9
	s_add_i32 s16, s16, 4
	v_cvt_f32_i32_e32 v142, s16
	v_cndmask_b32_e64 v2, 0, 1.0, s[46:47]
	v_pk_fma_f32 v[30:31], v[2:3], v[46:47], v[30:31] op_sel_hi:[0,1,1] neg_lo:[1,0,0] neg_hi:[1,0,0]
	s_waitcnt lgkmcnt(0)
	v_pk_add_f32 v[48:49], v[48:49], v[136:137]
	v_pk_fma_f32 v[28:29], v[2:3], v[44:45], v[28:29] op_sel_hi:[0,1,1] neg_lo:[1,0,0] neg_hi:[1,0,0]
	v_pk_add_f32 v[140:141], v[48:49], v[138:139]
	v_div_scale_f32 v48, s[46:47], v142, v142, 1.0
	v_rcp_f32_e32 v49, v48
	v_pk_fma_f32 v[26:27], v[2:3], v[42:43], v[26:27] op_sel_hi:[0,1,1] neg_lo:[1,0,0] neg_hi:[1,0,0]
	v_pk_fma_f32 v[24:25], v[2:3], v[40:41], v[24:25] op_sel_hi:[0,1,1] neg_lo:[1,0,0] neg_hi:[1,0,0]
	v_pk_fma_f32 v[22:23], v[2:3], v[38:39], v[22:23] op_sel_hi:[0,1,1] neg_lo:[1,0,0] neg_hi:[1,0,0]
	v_fma_f32 v136, -v48, v49, 1.0
	v_fmac_f32_e32 v49, v136, v49
	v_div_scale_f32 v136, vcc, 1.0, v142, 1.0
	v_mul_f32_e32 v137, v136, v49
	v_fma_f32 v138, -v48, v137, v136
	v_fmac_f32_e32 v137, v138, v49
	v_fma_f32 v48, -v48, v137, v136
	v_div_fmas_f32 v48, v48, v49, v137
	v_div_fixup_f32 v142, v48, v142, 1.0
	v_mul_f32_e32 v48, v66, v142
	v_lshlrev_b32_e32 v49, 16, v135
	v_and_b32_e32 v136, 0xffff0000, v135
	v_fma_f32 v49, v48, v140, -v49
	v_fma_f32 v48, v48, v141, -v136
	v_cvt_pk_bf16_f32 v138, v49, v48
	v_lshl_add_u64 v[48:49], v[14:15], 0, s[40:41]
	v_add_co_u32_e32 v136, vcc, s87, v48
	v_pk_fma_f32 v[20:21], v[2:3], v[36:37], v[20:21] op_sel_hi:[0,1,1] neg_lo:[1,0,0] neg_hi:[1,0,0]
	s_nop 0
	v_addc_co_u32_e32 v137, vcc, 0, v49, vcc
	global_store_dword v[136:137], v138, off
	ds_read2st64_b64 v[136:139], v92 offset0:6 offset1:10
	v_pk_fma_f32 v[18:19], v[2:3], v[34:35], v[18:19] op_sel_hi:[0,1,1] neg_lo:[1,0,0] neg_hi:[1,0,0]
	v_pk_fma_f32 v[16:17], v[2:3], v[32:33], v[16:17] op_sel_hi:[0,1,1] neg_lo:[1,0,0] neg_hi:[1,0,0]
	s_waitcnt lgkmcnt(0)
	v_pk_add_f32 v[136:137], v[138:139], v[136:137] neg_lo:[0,1] neg_hi:[0,1]
	s_nop 0
	v_pk_add_f32 v[140:141], v[140:141], v[136:137]
	v_mul_f32_e32 v136, v67, v142
	v_lshlrev_b32_e32 v137, 16, v134
	v_and_b32_e32 v138, 0xffff0000, v134
	v_fma_f32 v137, v136, v140, -v137
	v_fma_f32 v136, v136, v141, -v138
	v_cvt_pk_bf16_f32 v138, v137, v136
	v_add_co_u32_e32 v136, vcc, s88, v48
	s_nop 1
	v_addc_co_u32_e32 v137, vcc, 0, v49, vcc
	global_store_dword v[136:137], v138, off
	ds_read2st64_b64 v[136:139], v92 offset0:7 offset1:11
	s_waitcnt lgkmcnt(0)
	v_pk_add_f32 v[136:137], v[138:139], v[136:137] neg_lo:[0,1] neg_hi:[0,1]
	s_nop 0
	v_pk_add_f32 v[140:141], v[140:141], v[136:137]
	v_mul_f32_e32 v136, v68, v142
	v_lshlrev_b32_e32 v137, 16, v133
	v_and_b32_e32 v138, 0xffff0000, v133
	v_fma_f32 v137, v136, v140, -v137
	v_fma_f32 v136, v136, v141, -v138
	v_cvt_pk_bf16_f32 v138, v137, v136
	v_add_co_u32_e32 v136, vcc, s89, v48
	s_nop 1
	v_addc_co_u32_e32 v137, vcc, 0, v49, vcc
	global_store_dword v[136:137], v138, off
	ds_read2st64_b64 v[136:139], v92 offset0:8 offset1:12
	s_waitcnt lgkmcnt(0)
	v_pk_add_f32 v[136:137], v[138:139], v[136:137] neg_lo:[0,1] neg_hi:[0,1]
	s_nop 0
	v_pk_add_f32 v[140:141], v[140:141], v[136:137]
	v_mul_f32_e32 v136, v69, v142
	v_lshlrev_b32_e32 v137, 16, v132
	v_and_b32_e32 v138, 0xffff0000, v132
	v_fma_f32 v137, v136, v140, -v137
	v_fma_f32 v136, v136, v141, -v138
	v_cvt_pk_bf16_f32 v138, v137, v136
	v_add_co_u32_e32 v136, vcc, s90, v48
	s_nop 1
	v_addc_co_u32_e32 v137, vcc, 0, v49, vcc
	global_store_dword v[136:137], v138, off
	ds_read2st64_b64 v[136:139], v92 offset0:9 offset1:13
	s_waitcnt lgkmcnt(0)
	v_pk_add_f32 v[136:137], v[138:139], v[136:137] neg_lo:[0,1] neg_hi:[0,1]
	s_nop 0
	v_pk_add_f32 v[140:141], v[140:141], v[136:137]
	v_mul_f32_e32 v136, v70, v142
	v_lshlrev_b32_e32 v137, 16, v131
	v_and_b32_e32 v138, 0xffff0000, v131
	v_fma_f32 v137, v136, v140, -v137
	v_fma_f32 v136, v136, v141, -v138
	v_cvt_pk_bf16_f32 v138, v137, v136
	v_add_co_u32_e32 v136, vcc, s91, v48
	s_nop 1
	v_addc_co_u32_e32 v137, vcc, 0, v49, vcc
	global_store_dword v[136:137], v138, off
	ds_read2st64_b64 v[136:139], v92 offset0:10 offset1:14
	s_waitcnt lgkmcnt(0)
	v_pk_add_f32 v[136:137], v[138:139], v[136:137] neg_lo:[0,1] neg_hi:[0,1]
	s_nop 0
	v_pk_add_f32 v[140:141], v[140:141], v[136:137]
	v_mul_f32_e32 v136, v71, v142
	v_lshlrev_b32_e32 v137, 16, v130
	v_and_b32_e32 v138, 0xffff0000, v130
	v_fma_f32 v137, v136, v140, -v137
	v_fma_f32 v136, v136, v141, -v138
	v_cvt_pk_bf16_f32 v138, v137, v136
	v_add_co_u32_e32 v136, vcc, s92, v48
	s_nop 1
	v_addc_co_u32_e32 v137, vcc, 0, v49, vcc
	global_store_dword v[136:137], v138, off
	ds_read2st64_b64 v[136:139], v92 offset0:11 offset1:15
	s_waitcnt lgkmcnt(0)
	v_pk_add_f32 v[136:137], v[138:139], v[136:137] neg_lo:[0,1] neg_hi:[0,1]
	s_nop 0
	v_pk_add_f32 v[140:141], v[140:141], v[136:137]
	v_mul_f32_e32 v136, v72, v142
	v_lshlrev_b32_e32 v137, 16, v129
	v_and_b32_e32 v138, 0xffff0000, v129
	v_fma_f32 v137, v136, v140, -v137
	v_fma_f32 v136, v136, v141, -v138
	v_cvt_pk_bf16_f32 v138, v137, v136
	v_add_co_u32_e32 v136, vcc, s93, v48
	s_nop 1
	v_addc_co_u32_e32 v137, vcc, 0, v49, vcc
	global_store_dword v[136:137], v138, off
	ds_read2st64_b64 v[136:139], v92 offset0:12 offset1:16
	v_add_co_u32_e32 v48, vcc, s94, v48
	s_waitcnt lgkmcnt(0)
	v_pk_add_f32 v[136:137], v[138:139], v[136:137] neg_lo:[0,1] neg_hi:[0,1]
	s_nop 0
	v_pk_add_f32 v[136:137], v[140:141], v[136:137]
	v_mul_f32_e32 v138, v73, v142
	v_lshlrev_b32_e32 v139, 16, v128
	v_fma_f32 v136, v138, v136, -v139
	v_and_b32_e32 v139, 0xffff0000, v128
	v_addc_co_u32_e32 v49, vcc, 0, v49, vcc
	v_fma_f32 v137, v138, v137, -v139
	v_cvt_pk_bf16_f32 v136, v136, v137
	global_store_dword v[48:49], v136, off
; #define GAS __attribute__((address_space(1)))
; #define LAS __attribute__((address_space(3)))
; __device__ __forceinline__ unsigned cvt_pk_bf16(float lo, float hi) { unsigned r; asm volatile("v_cvt_pk_bf16_f32 %0, %1, %2" : "=v"(r) : "v"(lo), "v"(hi)); return r; }
; __device__ __forceinline__ float bf_lo(unsigned w) { return __uint_as_float(w << 16); }
; __device__ __forceinline__ float bf_hi(unsigned w) { return __uint_as_float(w & 0xffff0000u); }
; template <int W>
; __device__ __forceinline__ void pool_item(const Ctx& F, const bf16* Ub, bf16* Db, int r0, int nr) {
;     ...
;         for (int u = 0; u < NS; ++u) {
;             const int r = base + u;
;             if (r < re) {
;                 POOL_LOAD((u + 2) % NS, r + 2);
;                 const int e = r + HW - 1;
;                 const float me = (e >= 0 && e < 128) ? 1.0f : 0.0f, ml = (r >= r0 && r - HW >= 0) ? 1.0f : 0.0f;
; #pragma unroll
;                 for (int j = 0; j < 8; ++j) { Vv[j].x += me * bf_lo(ring[u][j]); Vv[j].y += me * bf_hi(ring[u][j]); }
;                 if (r >= r0) {
;                     LAS f32x2* row = buf + ((r & 1) * 80 + 8) * 64 + lane;
; #pragma unroll
;                     for (int j = 0; j < 8; ++j) row[(c0 + j) * 64] = Vv[j];
;                     asm volatile("s_waitcnt lgkmcnt(0)" ::: "memory"); __builtin_amdgcn_s_barrier(); asm volatile("" ::: "memory");
;                     const int rlo = r - HW > 0 ? r - HW : 0, rhi = r + HW < 128 ? r + HW : 128; const float icr = 1.0f / (float)(rhi - rlo);
;                     f32x2 h = (f32x2){0.f, 0.f};
; #pragma unroll
;                     for (int c = -HW; c < HW; ++c) h += row[(c0 + c) * 64];
; #pragma unroll
;                     for (int j = 0; j < 8; ++j) {
;                         const float ic = icr * icc[j]; const unsigned m = ring[(u + NS - HW + 1) % NS][j];
;                         *(GAS unsigned*)(Db + ((size_t)r * 64 + c0 + j) * EI) = cvt_pk_bf16(h.x * ic - bf_lo(m), h.y * ic - bf_hi(m));
;                         h += row[(c0 + j + HW) * 64] - row[(c0 + j - HW) * 64];
;                     }
; #pragma unroll
;                     for (int j = 0; j < 8; ++j) { const unsigned l = ring[(u + NS - W + 1) % NS][j]; Vv[j].x -= ml * bf_lo(l); Vv[j].y -= ml * bf_hi(l); }
;                 }
.LBB0_944:
	s_add_i32 s43, s42, 4
	s_cmp_ge_u32 s43, s23
	s_cbranch_scc1 .LBB0_947
	s_min_i32 s16, s43, 0x7c
	s_add_i32 s16, s16, 3
	s_lshl_b64 s[46:47], s[16:17], 20
	v_lshl_add_u64 v[32:33], v[12:13], 0, s[46:47]
	v_add_co_u32_e32 v34, vcc, 0x4000, v32
	global_load_dword v50, v[32:33], off
	s_nop 0
	v_addc_co_u32_e32 v35, vcc, 0, v33, vcc
	global_load_dword v51, v[34:35], off
	v_add_co_u32_e32 v34, vcc, 0x8000, v32
	s_cmp_eq_u32 s63, s44
	s_nop 0
	v_addc_co_u32_e32 v35, vcc, 0, v33, vcc
	global_load_dword v53, v[34:35], off
	v_add_co_u32_e32 v34, vcc, 0xc000, v32
	s_cselect_b64 s[46:47], -1, 0
	s_nop 0
	v_addc_co_u32_e32 v35, vcc, 0, v33, vcc
	global_load_dword v54, v[34:35], off
	v_add_co_u32_e32 v34, vcc, 0x10000, v32
	v_cndmask_b32_e64 v2, 1.0, 0, s[46:47]
	s_nop 0
	v_addc_co_u32_e32 v35, vcc, 0, v33, vcc
	global_load_dword v55, v[34:35], off
	v_add_co_u32_e32 v34, vcc, 0x14000, v32
	s_cmp_lt_u32 s43, s62
	s_nop 0
	v_addc_co_u32_e32 v35, vcc, 0, v33, vcc
	global_load_dword v56, v[34:35], off
	v_add_co_u32_e32 v34, vcc, 0x18000, v32
	s_nop 1
	v_addc_co_u32_e32 v35, vcc, 0, v33, vcc
	v_add_co_u32_e32 v32, vcc, 0x1c000, v32
	global_load_dword v57, v[34:35], off
	s_nop 0
	v_addc_co_u32_e32 v33, vcc, 0, v33, vcc
	global_load_dword v100, v[32:33], off
	s_waitcnt vmcnt(23)
	v_lshlrev_b32_e32 v32, 16, v103
	v_and_b32_e32 v33, 0xffff0000, v103
	v_pk_fma_f32 v[16:17], v[2:3], v[32:33], v[16:17] op_sel_hi:[0,1,1]
	s_waitcnt vmcnt(22)
	v_lshlrev_b32_e32 v32, 16, v107
	v_and_b32_e32 v33, 0xffff0000, v107
	v_pk_fma_f32 v[18:19], v[2:3], v[32:33], v[18:19] op_sel_hi:[0,1,1]
	s_waitcnt vmcnt(21)
	v_lshlrev_b32_e32 v32, 16, v110
	v_and_b32_e32 v33, 0xffff0000, v110
	v_pk_fma_f32 v[20:21], v[2:3], v[32:33], v[20:21] op_sel_hi:[0,1,1]
	s_waitcnt vmcnt(20)
	v_lshlrev_b32_e32 v32, 16, v114
	v_and_b32_e32 v33, 0xffff0000, v114
	v_pk_fma_f32 v[22:23], v[2:3], v[32:33], v[22:23] op_sel_hi:[0,1,1]
	s_waitcnt vmcnt(19)
	v_lshlrev_b32_e32 v32, 16, v117
	v_and_b32_e32 v33, 0xffff0000, v117
	v_pk_fma_f32 v[24:25], v[2:3], v[32:33], v[24:25] op_sel_hi:[0,1,1]
	s_waitcnt vmcnt(18)
	v_lshlrev_b32_e32 v32, 16, v120
	v_and_b32_e32 v33, 0xffff0000, v120
	v_pk_fma_f32 v[26:27], v[2:3], v[32:33], v[26:27] op_sel_hi:[0,1,1]
	s_waitcnt vmcnt(17)
	v_lshlrev_b32_e32 v32, 16, v122
	v_and_b32_e32 v33, 0xffff0000, v122
	v_pk_fma_f32 v[28:29], v[2:3], v[32:33], v[28:29] op_sel_hi:[0,1,1]
	s_waitcnt vmcnt(16)
	v_lshlrev_b32_e32 v32, 16, v126
	v_and_b32_e32 v33, 0xffff0000, v126
	v_pk_fma_f32 v[30:31], v[2:3], v[32:33], v[30:31] op_sel_hi:[0,1,1]
	s_cbranch_scc1 .LBB0_947
	ds_write2st64_b64 v92, v[16:17], v[18:19] offset0:88 offset1:89
	ds_write2st64_b64 v92, v[20:21], v[22:23] offset0:90 offset1:91
	ds_write2st64_b64 v92, v[24:25], v[26:27] offset0:92 offset1:93
	ds_write2st64_b64 v92, v[28:29], v[30:31] offset0:94 offset1:95
	s_waitcnt lgkmcnt(0)
	s_barrier
	ds_read2st64_b64 v[32:35], v92 offset0:86 offset1:87
	s_cmp_gt_u32 s43, 1
	s_cselect_b64 s[46:47], -1, 0
	s_max_i32 s16, s43, 2
	s_min_i32 s43, s43, 0x7e
	s_waitcnt lgkmcnt(0)
	v_pk_add_f32 v[32:33], v[32:33], 0 op_sel_hi:[1,0]
	s_sub_i32 s16, s43, s16
	v_pk_add_f32 v[36:37], v[32:33], v[34:35]
	ds_read2st64_b64 v[32:35], v92 offset0:88 offset1:89
	s_add_i32 s16, s16, 4
	v_cvt_f32_i32_e32 v40, s16
	v_cndmask_b32_e64 v2, 0, 1.0, s[46:47]
	s_waitcnt lgkmcnt(0)
	v_pk_add_f32 v[32:33], v[36:37], v[32:33]
	s_nop 0
	v_pk_add_f32 v[38:39], v[32:33], v[34:35]
	v_div_scale_f32 v32, s[46:47], v40, v40, 1.0
	v_rcp_f32_e32 v33, v32
	s_nop 0
	v_fma_f32 v34, -v32, v33, 1.0
	v_fmac_f32_e32 v33, v34, v33
	v_div_scale_f32 v34, vcc, 1.0, v40, 1.0
	v_mul_f32_e32 v35, v34, v33
	v_fma_f32 v36, -v32, v35, v34
	v_fmac_f32_e32 v35, v36, v33
	v_fma_f32 v32, -v32, v35, v34
	v_div_fmas_f32 v32, v32, v33, v35
	v_div_fixup_f32 v40, v32, v40, 1.0
	v_mul_f32_e32 v32, v66, v40
	v_lshlrev_b32_e32 v33, 16, v106
	v_and_b32_e32 v34, 0xffff0000, v106
	v_fma_f32 v33, v32, v38, -v33
	v_fma_f32 v32, v32, v39, -v34
	v_cvt_pk_bf16_f32 v36, v33, v32
	v_lshl_add_u64 v[32:33], v[14:15], 0, s[40:41]
	v_add_co_u32_e32 v34, vcc, s95, v32
	s_nop 1
	v_addc_co_u32_e32 v35, vcc, 0, v33, vcc
	global_store_dword v[34:35], v36, off
	ds_read2st64_b64 v[34:37], v92 offset0:86 offset1:90
	s_waitcnt lgkmcnt(0)
	v_pk_add_f32 v[34:35], v[36:37], v[34:35] neg_lo:[0,1] neg_hi:[0,1]
	s_nop 0
	v_pk_add_f32 v[38:39], v[38:39], v[34:35]
	v_mul_f32_e32 v34, v67, v40
	v_lshlrev_b32_e32 v35, 16, v109
	v_and_b32_e32 v36, 0xffff0000, v109
	v_fma_f32 v35, v34, v38, -v35
	v_fma_f32 v34, v34, v39, -v36
	v_cvt_pk_bf16_f32 v36, v35, v34
	v_add_co_u32_e32 v34, vcc, s96, v32
	s_nop 1
	v_addc_co_u32_e32 v35, vcc, 0, v33, vcc
	global_store_dword v[34:35], v36, off
	ds_read2st64_b64 v[34:37], v92 offset0:87 offset1:91
	s_waitcnt lgkmcnt(0)
	v_pk_add_f32 v[34:35], v[36:37], v[34:35] neg_lo:[0,1] neg_hi:[0,1]
	s_nop 0
	v_pk_add_f32 v[38:39], v[38:39], v[34:35]
	v_mul_f32_e32 v34, v68, v40
	v_lshlrev_b32_e32 v35, 16, v113
	v_and_b32_e32 v36, 0xffff0000, v113
	v_fma_f32 v35, v34, v38, -v35
	v_fma_f32 v34, v34, v39, -v36
	v_cvt_pk_bf16_f32 v36, v35, v34
	v_add_co_u32_e32 v34, vcc, s97, v32
	s_nop 1
	v_addc_co_u32_e32 v35, vcc, 0, v33, vcc
	global_store_dword v[34:35], v36, off
	ds_read2st64_b64 v[34:37], v92 offset0:88 offset1:92
	s_waitcnt lgkmcnt(0)
	v_pk_add_f32 v[34:35], v[36:37], v[34:35] neg_lo:[0,1] neg_hi:[0,1]
	s_nop 0
	v_pk_add_f32 v[38:39], v[38:39], v[34:35]
	v_mul_f32_e32 v34, v69, v40
	v_lshlrev_b32_e32 v35, 16, v116
	v_and_b32_e32 v36, 0xffff0000, v116
	v_fma_f32 v35, v34, v38, -v35
	v_fma_f32 v34, v34, v39, -v36
	v_cvt_pk_bf16_f32 v36, v35, v34
	v_add_co_u32_e32 v34, vcc, s68, v32
	s_nop 1
	v_addc_co_u32_e32 v35, vcc, 0, v33, vcc
	global_store_dword v[34:35], v36, off
	ds_read2st64_b64 v[34:37], v92 offset0:89 offset1:93
	s_waitcnt lgkmcnt(0)
; #define GAS __attribute__((address_space(1)))
; #define LAS __attribute__((address_space(3)))
; __device__ __forceinline__ unsigned cvt_pk_bf16(float lo, float hi) { unsigned r; asm volatile("v_cvt_pk_bf16_f32 %0, %1, %2" : "=v"(r) : "v"(lo), "v"(hi)); return r; }
; __device__ __forceinline__ float bf_lo(unsigned w) { return __uint_as_float(w << 16); }
; __device__ __forceinline__ float bf_hi(unsigned w) { return __uint_as_float(w & 0xffff0000u); }
; template <int W>
; __device__ __forceinline__ void pool_item(const Ctx& F, const bf16* Ub, bf16* Db, int r0, int nr) {
;     ...
;         for (int u = 0; u < NS; ++u) {
;             const int r = base + u;
;             if (r < re) {
;                 POOL_LOAD((u + 2) % NS, r + 2);
;                 const int e = r + HW - 1;
;                 const float me = (e >= 0 && e < 128) ? 1.0f : 0.0f, ml = (r >= r0 && r - HW >= 0) ? 1.0f : 0.0f;
; #pragma unroll
;                 for (int j = 0; j < 8; ++j) { Vv[j].x += me * bf_lo(ring[u][j]); Vv[j].y += me * bf_hi(ring[u][j]); }
;                 if (r >= r0) {
;                     LAS f32x2* row = buf + ((r & 1) * 80 + 8) * 64 + lane;
; #pragma unroll
;                     for (int j = 0; j < 8; ++j) row[(c0 + j) * 64] = Vv[j];
;                     asm volatile("s_waitcnt lgkmcnt(0)" ::: "memory"); __builtin_amdgcn_s_barrier(); asm volatile("" ::: "memory");
;                     const int rlo = r - HW > 0 ? r - HW : 0, rhi = r + HW < 128 ? r + HW : 128; const float icr = 1.0f / (float)(rhi - rlo);
;                     f32x2 h = (f32x2){0.f, 0.f};
; #pragma unroll
;                     for (int c = -HW; c < HW; ++c) h += row[(c0 + c) * 64];
; #pragma unroll
;                     for (int j = 0; j < 8; ++j) {
;                         const float ic = icr * icc[j]; const unsigned m = ring[(u + NS - HW + 1) % NS][j];
;                         *(GAS unsigned*)(Db + ((size_t)r * 64 + c0 + j) * EI) = cvt_pk_bf16(h.x * ic - bf_lo(m), h.y * ic - bf_hi(m));
;                         h += row[(c0 + j + HW) * 64] - row[(c0 + j - HW) * 64];
;                     }
; #pragma unroll
;                     for (int j = 0; j < 8; ++j) { const unsigned l = ring[(u + NS - W + 1) % NS][j]; Vv[j].x -= ml * bf_lo(l); Vv[j].y -= ml * bf_hi(l); }
;                 }
	v_pk_add_f32 v[34:35], v[36:37], v[34:35] neg_lo:[0,1] neg_hi:[0,1]
	s_nop 0
	v_pk_add_f32 v[38:39], v[38:39], v[34:35]
	v_mul_f32_e32 v34, v70, v40
	v_lshlrev_b32_e32 v35, 16, v119
	v_and_b32_e32 v36, 0xffff0000, v119
	v_fma_f32 v35, v34, v38, -v35
	v_fma_f32 v34, v34, v39, -v36
	v_cvt_pk_bf16_f32 v36, v35, v34
	v_add_co_u32_e32 v34, vcc, s69, v32
	s_nop 1
	v_addc_co_u32_e32 v35, vcc, 0, v33, vcc
	global_store_dword v[34:35], v36, off
	ds_read2st64_b64 v[34:37], v92 offset0:90 offset1:94
	s_waitcnt lgkmcnt(0)
	v_pk_add_f32 v[34:35], v[36:37], v[34:35] neg_lo:[0,1] neg_hi:[0,1]
	s_nop 0
	v_pk_add_f32 v[38:39], v[38:39], v[34:35]
	v_mul_f32_e32 v34, v71, v40
	v_lshlrev_b32_e32 v35, 16, v121
	v_and_b32_e32 v36, 0xffff0000, v121
	v_fma_f32 v35, v34, v38, -v35
	v_fma_f32 v34, v34, v39, -v36
	v_cvt_pk_bf16_f32 v36, v35, v34
	v_add_co_u32_e32 v34, vcc, s13, v32
	s_nop 1
	v_addc_co_u32_e32 v35, vcc, 0, v33, vcc
	global_store_dword v[34:35], v36, off
	ds_read2st64_b64 v[34:37], v92 offset0:91 offset1:95
	s_waitcnt lgkmcnt(0)
	v_pk_add_f32 v[34:35], v[36:37], v[34:35] neg_lo:[0,1] neg_hi:[0,1]
	s_nop 0
	v_pk_add_f32 v[38:39], v[38:39], v[34:35]
	v_mul_f32_e32 v34, v72, v40
	v_lshlrev_b32_e32 v35, 16, v124
	v_and_b32_e32 v36, 0xffff0000, v124
	v_fma_f32 v35, v34, v38, -v35
	v_fma_f32 v34, v34, v39, -v36
	v_cvt_pk_bf16_f32 v36, v35, v34
	v_add_co_u32_e32 v34, vcc, s52, v32
	s_nop 1
	v_addc_co_u32_e32 v35, vcc, 0, v33, vcc
	global_store_dword v[34:35], v36, off
	ds_read2st64_b64 v[34:37], v92 offset0:92 offset1:96
	v_add_co_u32_e32 v32, vcc, s4, v32
	s_waitcnt lgkmcnt(0)
	v_pk_add_f32 v[34:35], v[36:37], v[34:35] neg_lo:[0,1] neg_hi:[0,1]
	s_nop 0
	v_pk_add_f32 v[34:35], v[38:39], v[34:35]
	v_mul_f32_e32 v36, v73, v40
	v_lshlrev_b32_e32 v37, 16, v127
	v_fma_f32 v34, v36, v34, -v37
	v_and_b32_e32 v37, 0xffff0000, v127
	v_addc_co_u32_e32 v33, vcc, 0, v33, vcc
	v_fma_f32 v35, v36, v35, -v37
	v_cvt_pk_bf16_f32 v34, v34, v35
	global_store_dword v[32:33], v34, off
	v_lshlrev_b32_e32 v32, 16, v95
	v_and_b32_e32 v33, 0xffff0000, v95
	v_pk_fma_f32 v[16:17], v[2:3], v[32:33], v[16:17] op_sel_hi:[0,1,1] neg_lo:[1,0,0] neg_hi:[1,0,0]
	v_lshlrev_b32_e32 v32, 16, v96
	v_and_b32_e32 v33, 0xffff0000, v96
	v_pk_fma_f32 v[18:19], v[2:3], v[32:33], v[18:19] op_sel_hi:[0,1,1] neg_lo:[1,0,0] neg_hi:[1,0,0]
	v_lshlrev_b32_e32 v32, 16, v97
	v_and_b32_e32 v33, 0xffff0000, v97
	v_pk_fma_f32 v[20:21], v[2:3], v[32:33], v[20:21] op_sel_hi:[0,1,1] neg_lo:[1,0,0] neg_hi:[1,0,0]
	v_lshlrev_b32_e32 v32, 16, v98
	v_and_b32_e32 v33, 0xffff0000, v98
	v_pk_fma_f32 v[22:23], v[2:3], v[32:33], v[22:23] op_sel_hi:[0,1,1] neg_lo:[1,0,0] neg_hi:[1,0,0]
	v_lshlrev_b32_e32 v32, 16, v102
	v_and_b32_e32 v33, 0xffff0000, v102
	v_pk_fma_f32 v[24:25], v[2:3], v[32:33], v[24:25] op_sel_hi:[0,1,1] neg_lo:[1,0,0] neg_hi:[1,0,0]
	v_lshlrev_b32_e32 v32, 16, v105
	v_and_b32_e32 v33, 0xffff0000, v105
	v_pk_fma_f32 v[26:27], v[2:3], v[32:33], v[26:27] op_sel_hi:[0,1,1] neg_lo:[1,0,0] neg_hi:[1,0,0]
	v_lshlrev_b32_e32 v32, 16, v111
	v_and_b32_e32 v33, 0xffff0000, v111
	v_pk_fma_f32 v[28:29], v[2:3], v[32:33], v[28:29] op_sel_hi:[0,1,1] neg_lo:[1,0,0] neg_hi:[1,0,0]
	v_lshlrev_b32_e32 v32, 16, v123
	v_and_b32_e32 v33, 0xffff0000, v123
	v_pk_fma_f32 v[30:31], v[2:3], v[32:33], v[30:31] op_sel_hi:[0,1,1] neg_lo:[1,0,0] neg_hi:[1,0,0]
.LBB0_947:
	s_add_i32 s43, s42, 5
	s_cmp_ge_u32 s43, s23
	s_cbranch_scc1 .LBB0_928
	s_min_i32 s16, s43, 0x7c
	s_add_i32 s16, s16, 3
	s_lshl_b64 s[46:47], s[16:17], 20
	v_lshl_add_u64 v[32:33], v[12:13], 0, s[46:47]
	v_add_co_u32_e32 v34, vcc, 0x4000, v32
	global_load_dword v95, v[32:33], off
	s_nop 0
	v_addc_co_u32_e32 v35, vcc, 0, v33, vcc
	global_load_dword v96, v[34:35], off
	v_add_co_u32_e32 v34, vcc, 0x8000, v32
	s_cmp_lt_u32 s43, s62
	s_nop 0
	v_addc_co_u32_e32 v35, vcc, 0, v33, vcc
	global_load_dword v97, v[34:35], off
	v_add_co_u32_e32 v34, vcc, 0xc000, v32
	s_nop 1
	v_addc_co_u32_e32 v35, vcc, 0, v33, vcc
	global_load_dword v98, v[34:35], off
	v_add_co_u32_e32 v34, vcc, 0x10000, v32
	s_nop 1
	v_addc_co_u32_e32 v35, vcc, 0, v33, vcc
	global_load_dword v102, v[34:35], off
	v_add_co_u32_e32 v34, vcc, 0x14000, v32
	s_nop 1
	v_addc_co_u32_e32 v35, vcc, 0, v33, vcc
	global_load_dword v105, v[34:35], off
	v_add_co_u32_e32 v34, vcc, 0x18000, v32
	s_nop 1
	v_addc_co_u32_e32 v35, vcc, 0, v33, vcc
	v_add_co_u32_e32 v32, vcc, 0x1c000, v32
	global_load_dword v111, v[34:35], off
	s_nop 0
	v_addc_co_u32_e32 v33, vcc, 0, v33, vcc
	global_load_dword v123, v[32:33], off
	s_waitcnt vmcnt(23)
	v_lshlrev_b32_e32 v32, 16, v99
	v_and_b32_e32 v33, 0xffff0000, v99
	v_pk_add_f32 v[16:17], v[32:33], v[16:17]
	s_waitcnt vmcnt(22)
	v_lshlrev_b32_e32 v32, 16, v101
	v_and_b32_e32 v33, 0xffff0000, v101
	v_pk_add_f32 v[18:19], v[32:33], v[18:19]
	s_waitcnt vmcnt(21)
	v_lshlrev_b32_e32 v32, 16, v104
	v_and_b32_e32 v33, 0xffff0000, v104
	v_pk_add_f32 v[20:21], v[32:33], v[20:21]
	s_waitcnt vmcnt(20)
	v_lshlrev_b32_e32 v32, 16, v108
	v_and_b32_e32 v33, 0xffff0000, v108
	v_pk_add_f32 v[22:23], v[32:33], v[22:23]
	s_waitcnt vmcnt(19)
	v_lshlrev_b32_e32 v32, 16, v112
	v_and_b32_e32 v33, 0xffff0000, v112
	v_pk_add_f32 v[24:25], v[32:33], v[24:25]
	s_waitcnt vmcnt(18)
	v_lshlrev_b32_e32 v32, 16, v115
	v_and_b32_e32 v33, 0xffff0000, v115
	v_pk_add_f32 v[26:27], v[32:33], v[26:27]
	s_waitcnt vmcnt(17)
	v_lshlrev_b32_e32 v32, 16, v118
	v_and_b32_e32 v33, 0xffff0000, v118
	v_pk_add_f32 v[28:29], v[32:33], v[28:29]
	s_waitcnt vmcnt(16)
	v_lshlrev_b32_e32 v32, 16, v125
	v_and_b32_e32 v33, 0xffff0000, v125
	v_pk_add_f32 v[30:31], v[32:33], v[30:31]
	s_cbranch_scc1 .LBB0_928
; #define GAS __attribute__((address_space(1)))
; #define LAS __attribute__((address_space(3)))
; __device__ __forceinline__ unsigned cvt_pk_bf16(float lo, float hi) { unsigned r; asm volatile("v_cvt_pk_bf16_f32 %0, %1, %2" : "=v"(r) : "v"(lo), "v"(hi)); return r; }
; __device__ __forceinline__ float bf_lo(unsigned w) { return __uint_as_float(w << 16); }
; __device__ __forceinline__ float bf_hi(unsigned w) { return __uint_as_float(w & 0xffff0000u); }
; template <int W>
; __device__ __forceinline__ void pool_item(const Ctx& F, const bf16* Ub, bf16* Db, int r0, int nr) {
;     ...
;                 if (r >= r0) {
;                     LAS f32x2* row = buf + ((r & 1) * 80 + 8) * 64 + lane;
; #pragma unroll
;                     for (int j = 0; j < 8; ++j) row[(c0 + j) * 64] = Vv[j];
;                     asm volatile("s_waitcnt lgkmcnt(0)" ::: "memory"); __builtin_amdgcn_s_barrier(); asm volatile("" ::: "memory");
;                     const int rlo = r - HW > 0 ? r - HW : 0, rhi = r + HW < 128 ? r + HW : 128; const float icr = 1.0f / (float)(rhi - rlo);
;                     f32x2 h = (f32x2){0.f, 0.f};
; #pragma unroll
;                     for (int c = -HW; c < HW; ++c) h += row[(c0 + c) * 64];
; #pragma unroll
;                     for (int j = 0; j < 8; ++j) {
;                         const float ic = icr * icc[j]; const unsigned m = ring[(u + NS - HW + 1) % NS][j];
;                         *(GAS unsigned*)(Db + ((size_t)r * 64 + c0 + j) * EI) = cvt_pk_bf16(h.x * ic - bf_lo(m), h.y * ic - bf_hi(m));
;                         h += row[(c0 + j + HW) * 64] - row[(c0 + j - HW) * 64];
;                     }
; #pragma unroll
;                     for (int j = 0; j < 8; ++j) { const unsigned l = ring[(u + NS - W + 1) % NS][j]; Vv[j].x -= ml * bf_lo(l); Vv[j].y -= ml * bf_hi(l); }
;                 }
	ds_write2st64_b64 v92, v[16:17], v[18:19] offset0:8 offset1:9
	ds_write2st64_b64 v92, v[20:21], v[22:23] offset0:10 offset1:11
	ds_write2st64_b64 v92, v[24:25], v[26:27] offset0:12 offset1:13
	ds_write2st64_b64 v92, v[28:29], v[30:31] offset0:14 offset1:15
	s_waitcnt lgkmcnt(0)
	s_barrier
	ds_read2st64_b64 v[32:35], v92 offset0:6 offset1:7
	s_min_i32 s16, s10, 0x7e
	s_add_i32 s16, s16, s61
	v_cvt_f32_i32_e32 v2, s16
	s_waitcnt lgkmcnt(0)
	v_pk_add_f32 v[32:33], v[32:33], 0 op_sel_hi:[1,0]
	s_nop 0
	v_pk_add_f32 v[36:37], v[32:33], v[34:35]
	ds_read2st64_b64 v[32:35], v92 offset0:8 offset1:9
	s_waitcnt lgkmcnt(0)
	v_pk_add_f32 v[32:33], v[36:37], v[32:33]
	s_nop 0
	v_pk_add_f32 v[38:39], v[32:33], v[34:35]
	v_div_scale_f32 v32, s[46:47], v2, v2, 1.0
	v_rcp_f32_e32 v33, v32
	s_nop 0
	v_fma_f32 v34, -v32, v33, 1.0
	v_fmac_f32_e32 v33, v34, v33
	v_div_scale_f32 v34, vcc, 1.0, v2, 1.0
	v_mul_f32_e32 v35, v34, v33
	v_fma_f32 v36, -v32, v35, v34
	v_fmac_f32_e32 v35, v36, v33
	v_fma_f32 v32, -v32, v35, v34
	v_div_fmas_f32 v32, v32, v33, v35
	v_div_fixup_f32 v2, v32, v2, 1.0
	v_mul_f32_e32 v32, v66, v2
	v_lshlrev_b32_e32 v33, 16, v103
	v_and_b32_e32 v34, 0xffff0000, v103
	v_fma_f32 v33, v32, v38, -v33
	v_fma_f32 v32, v32, v39, -v34
	v_cvt_pk_bf16_f32 v36, v33, v32
	v_lshl_add_u64 v[32:33], v[14:15], 0, s[40:41]
	v_add_co_u32_e32 v34, vcc, s5, v32
	s_nop 1
	v_addc_co_u32_e32 v35, vcc, 0, v33, vcc
	global_store_dword v[34:35], v36, off
	ds_read2st64_b64 v[34:37], v92 offset0:6 offset1:10
	s_waitcnt lgkmcnt(0)
	v_pk_add_f32 v[34:35], v[36:37], v[34:35] neg_lo:[0,1] neg_hi:[0,1]
	s_nop 0
	v_pk_add_f32 v[38:39], v[38:39], v[34:35]
	v_mul_f32_e32 v34, v67, v2
	v_lshlrev_b32_e32 v35, 16, v107
	v_and_b32_e32 v36, 0xffff0000, v107
	v_fma_f32 v35, v34, v38, -v35
	v_fma_f32 v34, v34, v39, -v36
	v_cvt_pk_bf16_f32 v36, v35, v34
	v_add_co_u32_e32 v34, vcc, s6, v32
	s_nop 1
	v_addc_co_u32_e32 v35, vcc, 0, v33, vcc
	global_store_dword v[34:35], v36, off
	ds_read2st64_b64 v[34:37], v92 offset0:7 offset1:11
	s_waitcnt lgkmcnt(0)
	v_pk_add_f32 v[34:35], v[36:37], v[34:35] neg_lo:[0,1] neg_hi:[0,1]
	s_nop 0
	v_pk_add_f32 v[38:39], v[38:39], v[34:35]
	v_mul_f32_e32 v34, v68, v2
	v_lshlrev_b32_e32 v35, 16, v110
	v_and_b32_e32 v36, 0xffff0000, v110
	v_fma_f32 v35, v34, v38, -v35
	v_fma_f32 v34, v34, v39, -v36
	v_cvt_pk_bf16_f32 v36, v35, v34
	v_add_co_u32_e32 v34, vcc, s7, v32
	s_nop 1
	v_addc_co_u32_e32 v35, vcc, 0, v33, vcc
	global_store_dword v[34:35], v36, off
	ds_read2st64_b64 v[34:37], v92 offset0:8 offset1:12
	s_waitcnt lgkmcnt(0)
	v_pk_add_f32 v[34:35], v[36:37], v[34:35] neg_lo:[0,1] neg_hi:[0,1]
	s_nop 0
	v_pk_add_f32 v[38:39], v[38:39], v[34:35]
	v_mul_f32_e32 v34, v69, v2
	v_lshlrev_b32_e32 v35, 16, v114
	v_and_b32_e32 v36, 0xffff0000, v114
	v_fma_f32 v35, v34, v38, -v35
	v_fma_f32 v34, v34, v39, -v36
	v_cvt_pk_bf16_f32 v36, v35, v34
	v_add_co_u32_e32 v34, vcc, s86, v32
	s_nop 1
	v_addc_co_u32_e32 v35, vcc, 0, v33, vcc
	global_store_dword v[34:35], v36, off
	ds_read2st64_b64 v[34:37], v92 offset0:9 offset1:13
	s_waitcnt lgkmcnt(0)
	v_pk_add_f32 v[34:35], v[36:37], v[34:35] neg_lo:[0,1] neg_hi:[0,1]
	s_nop 0
	v_pk_add_f32 v[38:39], v[38:39], v[34:35]
	v_mul_f32_e32 v34, v70, v2
	v_lshlrev_b32_e32 v35, 16, v117
	v_and_b32_e32 v36, 0xffff0000, v117
	v_fma_f32 v35, v34, v38, -v35
	v_fma_f32 v34, v34, v39, -v36
	v_cvt_pk_bf16_f32 v36, v35, v34
	v_add_co_u32_e32 v34, vcc, s34, v32
	s_nop 1
	v_addc_co_u32_e32 v35, vcc, 0, v33, vcc
	global_store_dword v[34:35], v36, off
	ds_read2st64_b64 v[34:37], v92 offset0:10 offset1:14
	s_waitcnt lgkmcnt(0)
	v_pk_add_f32 v[34:35], v[36:37], v[34:35] neg_lo:[0,1] neg_hi:[0,1]
	s_nop 0
	v_pk_add_f32 v[38:39], v[38:39], v[34:35]
	v_mul_f32_e32 v34, v71, v2
	v_lshlrev_b32_e32 v35, 16, v120
	v_and_b32_e32 v36, 0xffff0000, v120
	v_fma_f32 v35, v34, v38, -v35
	v_fma_f32 v34, v34, v39, -v36
	v_cvt_pk_bf16_f32 v36, v35, v34
	v_add_co_u32_e32 v34, vcc, s35, v32
	s_nop 1
	v_addc_co_u32_e32 v35, vcc, 0, v33, vcc
	global_store_dword v[34:35], v36, off
	ds_read2st64_b64 v[34:37], v92 offset0:11 offset1:15
	s_waitcnt lgkmcnt(0)
	v_pk_add_f32 v[34:35], v[36:37], v[34:35] neg_lo:[0,1] neg_hi:[0,1]
	s_nop 0
	v_pk_add_f32 v[38:39], v[38:39], v[34:35]
	v_mul_f32_e32 v34, v72, v2
	v_lshlrev_b32_e32 v35, 16, v122
	v_and_b32_e32 v36, 0xffff0000, v122
	v_fma_f32 v35, v34, v38, -v35
	v_fma_f32 v34, v34, v39, -v36
	v_cvt_pk_bf16_f32 v36, v35, v34
	v_add_co_u32_e32 v34, vcc, s33, v32
	v_mul_f32_e32 v2, v73, v2
	s_nop 0
	v_addc_co_u32_e32 v35, vcc, 0, v33, vcc
	global_store_dword v[34:35], v36, off
	ds_read2st64_b64 v[34:37], v92 offset0:12 offset1:16
	v_add_co_u32_e32 v32, vcc, s20, v32
	s_waitcnt lgkmcnt(0)
	v_pk_add_f32 v[34:35], v[36:37], v[34:35] neg_lo:[0,1] neg_hi:[0,1]
	s_nop 0
	v_pk_add_f32 v[34:35], v[38:39], v[34:35]
	v_lshlrev_b32_e32 v36, 16, v126
	v_fma_f32 v34, v2, v34, -v36
	v_and_b32_e32 v36, 0xffff0000, v126
	v_fma_f32 v2, v2, v35, -v36
	v_addc_co_u32_e32 v33, vcc, 0, v33, vcc
	v_cvt_pk_bf16_f32 v2, v34, v2
	global_store_dword v[32:33], v2, off
	v_lshlrev_b32_e32 v32, 16, v135
	v_and_b32_e32 v33, 0xffff0000, v135
	v_pk_add_f32 v[16:17], v[16:17], v[32:33] neg_lo:[0,1] neg_hi:[0,1]
	v_lshlrev_b32_e32 v32, 16, v134
	v_and_b32_e32 v33, 0xffff0000, v134
	v_pk_add_f32 v[18:19], v[18:19], v[32:33] neg_lo:[0,1] neg_hi:[0,1]
	v_lshlrev_b32_e32 v32, 16, v133
	v_and_b32_e32 v33, 0xffff0000, v133
	v_pk_add_f32 v[20:21], v[20:21], v[32:33] neg_lo:[0,1] neg_hi:[0,1]
	v_lshlrev_b32_e32 v32, 16, v132
	v_and_b32_e32 v33, 0xffff0000, v132
	v_pk_add_f32 v[22:23], v[22:23], v[32:33] neg_lo:[0,1] neg_hi:[0,1]
	v_lshlrev_b32_e32 v32, 16, v131
	v_and_b32_e32 v33, 0xffff0000, v131
	v_pk_add_f32 v[24:25], v[24:25], v[32:33] neg_lo:[0,1] neg_hi:[0,1]
	v_lshlrev_b32_e32 v32, 16, v130
	v_and_b32_e32 v33, 0xffff0000, v130
	v_pk_add_f32 v[26:27], v[26:27], v[32:33] neg_lo:[0,1] neg_hi:[0,1]
	v_lshlrev_b32_e32 v32, 16, v129
	v_and_b32_e32 v33, 0xffff0000, v129
	v_pk_add_f32 v[28:29], v[28:29], v[32:33] neg_lo:[0,1] neg_hi:[0,1]
	v_lshlrev_b32_e32 v32, 16, v128
	v_and_b32_e32 v33, 0xffff0000, v128
	v_pk_add_f32 v[30:31], v[30:31], v[32:33] neg_lo:[0,1] neg_hi:[0,1]
	s_branch .LBB0_928
